# K-loop DMA for stage k+2 issued right after the mid-step barrier of step k (one full k-step of lead time instead of 3/4)
# speedup vs baseline: 1.0670x; 1.0214x over previous
; template <int BK> DI int swz(int row) { constexpr int CPR = BK / 8; return (row / (16 / CPR)) % CPR; }
; DI void wait_vm0() { asm volatile("s_waitcnt vmcnt(0)" ::: "memory"); }
;   DI void pre(int grow0, int gcol0, int lane, int w, char* lds) { xpass(0, grow0, gcol0, lane, w, lds); }
; template <int ROWS, int BK>
; DI void stage_tile(const bf16_t* g, int ld, char* l, int tid) {
;   constexpr int CPR = BK / 8, TOT = ROWS * CPR, N = (TOT + NT - 1) / NT;
;   const int row0 = tid / CPR, pc = tid % CPR; const int c = pc ^ swz<BK>(row0);
;   const unsigned voff = (unsigned)(row0 * ld + c * 8) * 2u;
; #pragma unroll
;   for (int i = 0; i < N; ++i) {
;     if (TOT % NT == 0 || tid + i * NT < TOT) {
;       const char* gb = (const char*)g + (size_t)i * (NT / CPR) * ld * 2;
;       __builtin_amdgcn_global_load_lds((const unsigned*)(gb + voff), (__attribute__((address_space(3))) unsigned*)(l + i * NT * 16 + __builtin_amdgcn_readfirstlane(tid >> 6) * 1024), 16, 0, 0);
;     }
;   }
; }
;     ...
;   const bf16_t* Ag = A + (size_t)row0 * lda; const bf16_t* Bg = Bt + (size_t)col0 * ldb;
;   const int wv = __builtin_amdgcn_readfirstlane(tid >> 6);
;   __syncthreads();
;   if (!pre) { stage_tile<BM, BK>(Ag, lda, lds, tid); stage_tile<BN, BK>(Bg, ldb, lds + ABYTES, tid); }
;   wait_vm0();
;   __syncthreads();
;   const int nk = K / BK;
;   for (int kt = 0; kt < nk; ++kt) {
;     char* cur = lds + (kt & 1) * STG; char* nxt = lds + ((kt + 1) & 1) * STG;
;     const bool more = kt + 1 < nk;
;     const bf16_t* An = Ag + (kt + 1) * BK; const bf16_t* Bn = Bg + (kt + 1) * BK;
;     if (!more) epi.pre(row0 + wm * 64, col0 + wn * (32 * NTW), lane, w, lds);
;     bf16x8 fa[2][2], fb[2][NTW];
; #pragma unroll
;     for (int mt = 0; mt < 2; ++mt) { int row = wm * 64 + mt * 32 + l31; fa[0][mt] = *(const bf16x8*)(cur + row * (BK * 2) + ((hh ^ swz<BK>(row)) << 4)); }
; #pragma unroll
;     for (int nt = 0; nt < NTW; ++nt) { int row = wn * (32 * NTW) + nt * 32 + l31; fb[0][nt] = *(const bf16x8*)(cur + ABYTES + row * (BK * 2) + ((hh ^ swz<BK>(row)) << 4)); }
.LBB0_168:
	s_mov_b64 s[30:31], -1
	s_waitcnt lgkmcnt(0)
	s_mov_b64 s[42:43], 0
	s_cmp_lt_i32 s70, 2
	s_mov_b64 s[6:7], 0
	v_writelane_b32 v255, s71, 50
	s_cbranch_scc1 .LBB0_243
	s_cmp_eq_u32 s70, 2
	s_mov_b64 s[6:7], -1
	s_cbranch_scc0 .LBB0_288
	s_cmp_lt_i32 s71, 1
	s_cbranch_scc1 .LBB0_277
	s_cmp_lg_u32 s71, 1
	s_cbranch_scc0 .LBB0_259
	v_readlane_b32 s2, v254, 61
	v_readlane_b32 s3, v254, 62
	v_mov_b32_e32 v8, v216
	s_load_dwordx2 s[2:3], s[2:3], 0x1f8
	v_readlane_b32 s6, v253, 13
	v_ashrrev_i32_e32 v2, 31, v8
	v_lshrrev_b32_e32 v3, 29, v2
	v_lshrrev_b32_e32 v2, 28, v2
	v_add_u32_e32 v2, v8, v2
	v_ashrrev_i32_e32 v2, 4, v2
	v_lshrrev_b32_e32 v5, 29, v2
	v_add_u32_e32 v3, v8, v3
	v_add_u32_e32 v5, v2, v5
	v_readlane_b32 s7, v253, 14
	s_waitcnt lgkmcnt(0)
	s_add_u32 s2, s2, s6
	v_and_b32_e32 v4, 0xffffff8, v3
	v_and_b32_e32 v5, 0xffffff8, v5
	s_addc_u32 s3, s3, s7
	v_sub_u32_e32 v4, v8, v4
	v_sub_u32_e32 v2, v2, v5
	v_lshlrev_b32_e32 v3, 8, v3
	v_readfirstlane_b32 s7, v8
	v_xor_b32_e32 v2, v2, v4
	v_and_b32_e32 v3, 0xfffff800, v3
	v_readlane_b32 s30, v253, 11
	s_lshl_b32 s7, s7, 4
	v_lshl_add_u32 v2, v2, 4, v3
	v_mov_b32_e32 v3, v1
	v_readlane_b32 s31, v253, 12
	s_and_b32 s7, s7, 0xfffffc00
	s_mov_b32 m0, s7
	v_lshl_add_u64 v[4:5], s[30:31], 0, v[2:3]
	s_barrier
	s_nop 0
	global_load_lds_dwordx4 v2, s[30:31]
	v_lshl_add_u64 v[6:7], v[4:5], 0, s[58:59]
	s_add_i32 m0, s7, 0x2000
	s_waitcnt vmcnt(0)
	v_lshl_add_u64 v[130:131], s[2:3], 0, v[2:3]
	global_load_lds_dwordx4 v[6:7], off
	v_lshl_add_u64 v[6:7], v[4:5], 0, s[48:49]
	s_add_i32 m0, s7, 0x4000
	v_lshl_add_u64 v[4:5], v[4:5], 0, s[50:51]
	global_load_lds_dwordx4 v[6:7], off
	s_add_i32 m0, s7, 0x6000
	v_ashrrev_i32_e32 v134, 6, v8
	global_load_lds_dwordx4 v[4:5], off
	s_add_i32 m0, s7, 0x8000
	v_lshl_add_u64 v[4:5], v[130:131], 0, s[58:59]
	global_load_lds_dwordx4 v2, s[2:3]
	s_add_i32 m0, s7, 0xa000
	v_and_b32_e32 v6, 31, v8
	global_load_lds_dwordx4 v[4:5], off
	v_lshl_add_u64 v[4:5], v[130:131], 0, s[48:49]
	s_add_i32 m0, s7, 0xc000
	v_and_b32_e32 v0, 63, v8
	global_load_lds_dwordx4 v[4:5], off
	v_lshl_add_u64 v[4:5], v[130:131], 0, s[50:51]
	s_add_i32 m0, s7, 0xe000
	v_bfe_u32 v135, v8, 5, 1
	global_load_lds_dwordx4 v[4:5], off
	v_lshrrev_b32_e32 v4, 30, v134
	v_add_u32_e32 v4, v134, v4
	v_ashrrev_i32_e32 v5, 2, v4
	v_mul_i32_i24_e32 v7, 4, v5
	v_sub_u32_e32 v7, v134, v7
	v_lshlrev_b32_e32 v169, 6, v7
	v_lshlrev_b32_e32 v164, 7, v5
	v_or_b32_e32 v5, v169, v6
	v_bfe_u32 v7, v7, 25, 1
	v_lshlrev_b32_e32 v136, 7, v5
	v_add_u32_e32 v8, v5, v7
	v_or_b32_e32 v5, 32, v5
	v_lshlrev_b32_e32 v144, 7, v5
	v_add_u32_e32 v5, v5, v7
	v_ashrrev_i32_e32 v7, 1, v5
	v_ashrrev_i32_e32 v5, 31, v5
	v_ashrrev_i32_e32 v9, 1, v8
	v_ashrrev_i32_e32 v8, 31, v8
	v_lshrrev_b32_e32 v5, 29, v5
	v_lshrrev_b32_e32 v8, 29, v8
	v_add_u32_e32 v5, v7, v5
	v_add_u32_e32 v8, v9, v8
	v_and_b32_e32 v5, -8, v5
	v_and_b32_e32 v8, -8, v8
	v_sub_u32_e32 v5, v7, v5
	v_or_b32_e32 v6, v164, v6
	v_sub_u32_e32 v8, v9, v8
	v_xor_b32_e32 v7, v5, v135
	v_lshrrev_b32_e32 v4, 31, v4
	v_xor_b32_e32 v9, v8, v135
	v_lshlrev_b32_e32 v146, 4, v7
	v_add_u32_e32 v7, v6, v4
	v_lshlrev_b32_e32 v143, 4, v9
	v_ashrrev_i32_e32 v9, 1, v7
	v_ashrrev_i32_e32 v7, 31, v7
	v_lshrrev_b32_e32 v7, 29, v7
	v_add_u32_e32 v7, v9, v7
	v_and_b32_e32 v7, -8, v7
	v_sub_u32_e32 v7, v9, v7
	v_xor_b32_e32 v9, v7, v135
	v_lshlrev_b32_e32 v151, 4, v9
	v_or_b32_e32 v9, 32, v6
	v_lshlrev_b32_e32 v152, 7, v9
	v_add_u32_e32 v9, v9, v4
	v_ashrrev_i32_e32 v10, 1, v9
	v_ashrrev_i32_e32 v9, 31, v9
	v_lshrrev_b32_e32 v9, 29, v9
	v_add_u32_e32 v9, v10, v9
	v_and_b32_e32 v9, -8, v9
	v_sub_u32_e32 v9, v10, v9
	v_xor_b32_e32 v10, v9, v135
	v_lshlrev_b32_e32 v145, 7, v6
	v_lshlrev_b32_e32 v156, 4, v10
	v_or_b32_e32 v10, 64, v6
	v_or_b32_e32 v6, 0x60, v6
	v_lshlrev_b32_e32 v155, 7, v10
	v_add_u32_e32 v10, v10, v4
	v_add_u32_e32 v4, v6, v4
	v_lshlrev_b32_e32 v158, 7, v6
	v_ashrrev_i32_e32 v6, 1, v4
	v_ashrrev_i32_e32 v4, 31, v4
	v_lshrrev_b32_e32 v4, 29, v4
	v_add_u32_e32 v4, v6, v4
	v_and_b32_e32 v4, -8, v4
	v_sub_u32_e32 v4, v6, v4
	v_ashrrev_i32_e32 v11, 1, v10
	v_ashrrev_i32_e32 v10, 31, v10
	v_xor_b32_e32 v6, v4, v135
	v_lshrrev_b32_e32 v10, 29, v10
	v_lshlrev_b32_e32 v168, 4, v6
	v_bitop3_b32 v6, v8, v135, 2 bitop3:0x1e
	v_add_u32_e32 v10, v11, v10
	v_lshlrev_b32_e32 v166, 4, v6
	v_bitop3_b32 v6, v5, v135, 2 bitop3:0x1e
	v_and_b32_e32 v10, -8, v10
	v_lshlrev_b32_e32 v167, 4, v6
	v_bitop3_b32 v6, v7, v135, 2 bitop3:0x1e
	v_sub_u32_e32 v10, v11, v10
	v_lshlrev_b32_e32 v161, 4, v6
	v_bitop3_b32 v6, v9, v135, 2 bitop3:0x1e
	v_lshlrev_b32_e32 v163, 4, v6
	v_bitop3_b32 v6, v10, v135, 2 bitop3:0x1e
	v_lshlrev_b32_e32 v159, 4, v6
	v_bitop3_b32 v6, v4, v135, 2 bitop3:0x1e
	v_lshlrev_b32_e32 v160, 4, v6
	v_bitop3_b32 v6, v8, v135, 4 bitop3:0x1e
	v_lshlrev_b32_e32 v153, 4, v6
	v_bitop3_b32 v6, v5, v135, 4 bitop3:0x1e
	v_lshlrev_b32_e32 v154, 4, v6
	v_bitop3_b32 v6, v7, v135, 4 bitop3:0x1e
	v_readfirstlane_b32 s6, v134
	v_lshlrev_b32_e32 v149, 4, v6
	v_bitop3_b32 v6, v9, v135, 4 bitop3:0x1e
	v_bitop3_b32 v5, v5, v135, 6 bitop3:0x1e
	s_lshl_b32 s2, s6, 10
	v_lshlrev_b32_e32 v150, 4, v6
	v_bitop3_b32 v6, v10, v135, 4 bitop3:0x1e
	v_lshlrev_b32_e32 v142, 4, v5
	v_bitop3_b32 v5, v7, v135, 6 bitop3:0x1e
	v_readlane_b32 s6, v254, 28
	s_waitcnt vmcnt(0)
; DI f32x16 zero16() { f32x16 z; for (int i = 0; i < 16; ++i) z[i] = 0.f; return z; }
; template <int BK> DI int swz(int row) { constexpr int CPR = BK / 8; return (row / (16 / CPR)) % CPR; }
; DI void wait_vm0() { asm volatile("s_waitcnt vmcnt(0)" ::: "memory"); }
;     ...
;   f32x16 acc[2][NTW];
; #pragma unroll
;   for (int a = 0; a < 2; ++a)
; #pragma unroll
;     for (int b = 0; b < NTW; ++b) acc[a][b] = zero16();
;   const bf16_t* Ag = A + (size_t)row0 * lda; const bf16_t* Bg = Bt + (size_t)col0 * ldb;
;   const int wv = __builtin_amdgcn_readfirstlane(tid >> 6);
;   __syncthreads();
;   if (!pre) { stage_tile<BM, BK>(Ag, lda, lds, tid); stage_tile<BN, BK>(Bg, ldb, lds + ABYTES, tid); }
;   wait_vm0();
;   __syncthreads();
;   const int nk = K / BK;
;   for (int kt = 0; kt < nk; ++kt) {
;     char* cur = lds + (kt & 1) * STG; char* nxt = lds + ((kt + 1) & 1) * STG;
;     const bool more = kt + 1 < nk;
;     const bf16_t* An = Ag + (kt + 1) * BK; const bf16_t* Bn = Bg + (kt + 1) * BK;
;     if (!more) epi.pre(row0 + wm * 64, col0 + wn * (32 * NTW), lane, w, lds);
;     bf16x8 fa[2][2], fb[2][NTW];
; #pragma unroll
;     for (int mt = 0; mt < 2; ++mt) { int row = wm * 64 + mt * 32 + l31; fa[0][mt] = *(const bf16x8*)(cur + row * (BK * 2) + ((hh ^ swz<BK>(row)) << 4)); }
; #pragma unroll
;     for (int nt = 0; nt < NTW; ++nt) { int row = wn * (32 * NTW) + nt * 32 + l31; fb[0][nt] = *(const bf16x8*)(cur + ABYTES + row * (BK * 2) + ((hh ^ swz<BK>(row)) << 4)); }
; #pragma unroll
;     for (int kk = 0; kk < NKK; ++kk) {
;       if (kk + 1 < NKK) {
;         const int ch = (kk + 1) * 2 + hh;
; #pragma unroll
;         for (int mt = 0; mt < 2; ++mt) { int row = wm * 64 + mt * 32 + l31; fa[(kk + 1) & 1][mt] = *(const bf16x8*)(cur + row * (BK * 2) + ((ch ^ swz<BK>(row)) << 4)); }
; #pragma unroll
;         for (int nt = 0; nt < NTW; ++nt) { int row = wn * (32 * NTW) + nt * 32 + l31; fb[(kk + 1) & 1][nt] = *(const bf16x8*)(cur + ABYTES + row * (BK * 2) + ((ch ^ swz<BK>(row)) << 4)); }
;       }
;       if (more) {
; #pragma unroll
;         for (int q = 0; q < PPK; ++q) {
;           const int pi = kk * PPK + q;
;           if (pi < NPA) stage_piece<BM, BK>(An, lda, nxt, tid, pi, wv);
;           else if (pi < NP) stage_piece<BN, BK>(Bn, ldb, nxt + ABYTES, tid, pi - NPA, wv);
;         }
	v_lshlrev_b32_e32 v147, 4, v6
	v_bitop3_b32 v6, v4, v135, 4 bitop3:0x1e
	v_lshlrev_b32_e32 v139, 4, v5
	v_bitop3_b32 v5, v9, v135, 6 bitop3:0x1e
	v_readlane_b32 s7, v254, 29
	v_xor_b32_e32 v11, v10, v135
	v_lshlrev_b32_e32 v148, 4, v6
	v_bitop3_b32 v6, v8, v135, 6 bitop3:0x1e
	v_lshlrev_b32_e32 v140, 4, v5
	v_bitop3_b32 v5, v10, v135, 6 bitop3:0x1e
	v_bitop3_b32 v4, v4, v135, 6 bitop3:0x1e
	v_lshl_add_u64 v[132:133], s[6:7], 0, v[2:3]
	v_mov_b32_e32 v2, 0
	v_lshlrev_b32_e32 v157, 4, v11
	v_lshlrev_b32_e32 v141, 4, v6
	v_lshlrev_b32_e32 v137, 4, v5
	v_lshlrev_b32_e32 v138, 4, v4
	s_mov_b64 s[6:7], 0
	s_mov_b32 s3, 0x10000
	v_mov_b32_e32 v3, v2
	v_mov_b32_e32 v4, v2
	v_mov_b32_e32 v5, v2
	v_mov_b32_e32 v6, v2
	v_mov_b32_e32 v7, v2
	v_mov_b32_e32 v8, v2
	v_mov_b32_e32 v9, v2
	v_mov_b32_e32 v10, v2
	v_mov_b32_e32 v11, v2
	v_mov_b32_e32 v12, v2
	v_mov_b32_e32 v13, v2
	v_mov_b32_e32 v14, v2
	v_mov_b32_e32 v15, v2
	v_mov_b32_e32 v16, v2
	v_mov_b32_e32 v17, v2
	v_mov_b32_e32 v18, v2
	v_mov_b32_e32 v19, v2
	v_mov_b32_e32 v20, v2
	v_mov_b32_e32 v21, v2
	v_mov_b32_e32 v22, v2
	v_mov_b32_e32 v23, v2
	v_mov_b32_e32 v24, v2
	v_mov_b32_e32 v25, v2
	v_mov_b32_e32 v26, v2
	v_mov_b32_e32 v27, v2
	v_mov_b32_e32 v28, v2
	v_mov_b32_e32 v29, v2
	v_mov_b32_e32 v30, v2
	v_mov_b32_e32 v31, v2
	v_mov_b32_e32 v32, v2
	v_mov_b32_e32 v33, v2
	v_mov_b32_e32 v34, v2
	v_mov_b32_e32 v35, v2
	v_mov_b32_e32 v36, v2
	v_mov_b32_e32 v37, v2
	v_mov_b32_e32 v38, v2
	v_mov_b32_e32 v39, v2
	v_mov_b32_e32 v40, v2
	v_mov_b32_e32 v41, v2
	v_mov_b32_e32 v42, v2
	v_mov_b32_e32 v43, v2
	v_mov_b32_e32 v44, v2
	v_mov_b32_e32 v45, v2
	v_mov_b32_e32 v46, v2
	v_mov_b32_e32 v47, v2
	v_mov_b32_e32 v48, v2
	v_mov_b32_e32 v49, v2
	v_mov_b32_e32 v50, v2
	v_mov_b32_e32 v51, v2
	v_mov_b32_e32 v52, v2
	v_mov_b32_e32 v53, v2
	v_mov_b32_e32 v54, v2
	v_mov_b32_e32 v55, v2
	v_mov_b32_e32 v56, v2
	v_mov_b32_e32 v57, v2
	v_mov_b32_e32 v58, v2
	v_mov_b32_e32 v59, v2
	v_mov_b32_e32 v60, v2
	v_mov_b32_e32 v61, v2
	v_mov_b32_e32 v62, v2
	v_mov_b32_e32 v63, v2
	v_mov_b32_e32 v64, v2
	v_mov_b32_e32 v65, v2
	v_mov_b32_e32 v66, v2
	v_mov_b32_e32 v67, v2
	v_mov_b32_e32 v68, v2
	v_mov_b32_e32 v69, v2
	v_mov_b32_e32 v70, v2
	v_mov_b32_e32 v71, v2
	v_mov_b32_e32 v72, v2
	v_mov_b32_e32 v73, v2
	v_mov_b32_e32 v74, v2
	v_mov_b32_e32 v75, v2
	v_mov_b32_e32 v76, v2
	v_mov_b32_e32 v77, v2
	v_mov_b32_e32 v78, v2
	v_mov_b32_e32 v79, v2
	v_mov_b32_e32 v80, v2
	v_mov_b32_e32 v81, v2
	v_mov_b32_e32 v82, v2
	v_mov_b32_e32 v83, v2
	v_mov_b32_e32 v84, v2
	v_mov_b32_e32 v85, v2
	v_mov_b32_e32 v86, v2
	v_mov_b32_e32 v87, v2
	v_mov_b32_e32 v88, v2
	v_mov_b32_e32 v89, v2
	v_mov_b32_e32 v90, v2
	v_mov_b32_e32 v91, v2
	v_mov_b32_e32 v92, v2
	v_mov_b32_e32 v93, v2
	v_mov_b32_e32 v94, v2
	v_mov_b32_e32 v95, v2
	v_mov_b32_e32 v96, v2
	v_mov_b32_e32 v97, v2
	v_mov_b32_e32 v98, v2
	v_mov_b32_e32 v99, v2
	v_mov_b32_e32 v100, v2
	v_mov_b32_e32 v101, v2
	v_mov_b32_e32 v102, v2
	v_mov_b32_e32 v103, v2
	v_mov_b32_e32 v104, v2
	v_mov_b32_e32 v105, v2
	v_mov_b32_e32 v106, v2
	v_mov_b32_e32 v107, v2
	v_mov_b32_e32 v108, v2
	v_mov_b32_e32 v109, v2
	v_mov_b32_e32 v110, v2
	v_mov_b32_e32 v111, v2
	v_mov_b32_e32 v112, v2
	v_mov_b32_e32 v113, v2
	v_mov_b32_e32 v114, v2
	v_mov_b32_e32 v115, v2
	v_mov_b32_e32 v116, v2
	v_mov_b32_e32 v117, v2
	v_mov_b32_e32 v118, v2
	v_mov_b32_e32 v119, v2
	v_mov_b32_e32 v120, v2
	v_mov_b32_e32 v121, v2
	v_mov_b32_e32 v122, v2
	v_mov_b32_e32 v123, v2
	v_mov_b32_e32 v124, v2
	v_mov_b32_e32 v125, v2
	v_mov_b32_e32 v126, v2
	v_mov_b32_e32 v127, v2
	v_mov_b32_e32 v128, v2
	v_mov_b32_e32 v129, v2
	s_waitcnt vmcnt(0) lgkmcnt(0)
	s_barrier
	v_add_u32_e32 v170, v136, v143
	v_add_u32_e32 v174, v144, v146
	ds_read_b128 v[170:173], v170
	v_add_u32_e32 v178, v145, v151
	ds_read_b128 v[174:177], v174
	v_add_u32_e32 v182, v152, v156
	ds_read_b128 v[178:181], v178 offset:32768
	v_add_u32_e32 v186, v155, v157
	ds_read_b128 v[182:185], v182 offset:32768
	v_add_u32_e32 v190, v158, v168
	ds_read_b128 v[186:189], v186 offset:32768
	ds_read_b128 v[190:193], v190 offset:32768
	s_and_b32 s30, s3, 0x10000
	s_add_i32 s31, s30, s2
	v_lshl_add_u64 v[214:215], v[132:133], 0, s[6:7]
	v_lshl_add_u64 v[230:231], v[130:131], 0, s[6:7]
	s_mov_b32 m0, s31
	v_lshl_add_u64 v[232:233], v[214:215], 0, s[28:29]
	global_load_lds_dwordx4 v[232:233], off
	s_add_i32 m0, s31, 0x2000
	v_lshl_add_u64 v[232:233], v[214:215], 0, s[24:25]
	global_load_lds_dwordx4 v[232:233], off
	s_add_i32 m0, s31, 0x4000
	v_lshl_add_u64 v[232:233], v[214:215], 0, s[26:27]
	global_load_lds_dwordx4 v[232:233], off
	s_add_i32 m0, s31, 0x6000
	v_lshl_add_u64 v[232:233], v[214:215], 0, s[38:39]
	global_load_lds_dwordx4 v[232:233], off
	s_add_i32 m0, s31, 0x8000
	v_lshl_add_u64 v[232:233], v[230:231], 0, s[28:29]
	global_load_lds_dwordx4 v[232:233], off
	s_add_i32 m0, s31, 0xa000
	v_lshl_add_u64 v[232:233], v[230:231], 0, s[24:25]
	global_load_lds_dwordx4 v[232:233], off
	s_add_i32 m0, s31, 0xc000
	v_lshl_add_u64 v[232:233], v[230:231], 0, s[26:27]
	global_load_lds_dwordx4 v[232:233], off
	s_add_i32 m0, s31, 0xe000
	v_lshl_add_u64 v[232:233], v[230:231], 0, s[38:39]
	global_load_lds_dwordx4 v[232:233], off
; DI f32x16 mfma(bf16x8 a, bf16x8 b, f32x16 c) { return __builtin_amdgcn_mfma_f32_32x32x16_bf16(a, b, c, 0, 0, 0); }
; template <int BK> DI int swz(int row) { constexpr int CPR = BK / 8; return (row / (16 / CPR)) % CPR; }
;   DI void pre(int grow0, int gcol0, int lane, int w, char* lds) { xpass(0, grow0, gcol0, lane, w, lds); }
;     ...
;   for (int kt = 0; kt < nk; ++kt) {
;     char* cur = lds + (kt & 1) * STG; char* nxt = lds + ((kt + 1) & 1) * STG;
;     const bool more = kt + 1 < nk;
;     const bf16_t* An = Ag + (kt + 1) * BK; const bf16_t* Bn = Bg + (kt + 1) * BK;
;     if (!more) epi.pre(row0 + wm * 64, col0 + wn * (32 * NTW), lane, w, lds);
;     bf16x8 fa[2][2], fb[2][NTW];
; #pragma unroll
;     for (int mt = 0; mt < 2; ++mt) { int row = wm * 64 + mt * 32 + l31; fa[0][mt] = *(const bf16x8*)(cur + row * (BK * 2) + ((hh ^ swz<BK>(row)) << 4)); }
; #pragma unroll
;     for (int nt = 0; nt < NTW; ++nt) { int row = wn * (32 * NTW) + nt * 32 + l31; fb[0][nt] = *(const bf16x8*)(cur + ABYTES + row * (BK * 2) + ((hh ^ swz<BK>(row)) << 4)); }
; #pragma unroll
;     for (int kk = 0; kk < NKK; ++kk) {
;       if (kk + 1 < NKK) {
;         const int ch = (kk + 1) * 2 + hh;
; #pragma unroll
;         for (int mt = 0; mt < 2; ++mt) { int row = wm * 64 + mt * 32 + l31; fa[(kk + 1) & 1][mt] = *(const bf16x8*)(cur + row * (BK * 2) + ((ch ^ swz<BK>(row)) << 4)); }
; #pragma unroll
;         for (int nt = 0; nt < NTW; ++nt) { int row = wn * (32 * NTW) + nt * 32 + l31; fb[(kk + 1) & 1][nt] = *(const bf16x8*)(cur + ABYTES + row * (BK * 2) + ((ch ^ swz<BK>(row)) << 4)); }
;       }
;       if (more) {
; #pragma unroll
;         for (int q = 0; q < PPK; ++q) {
;           const int pi = kk * PPK + q;
;           if (pi < NPA) stage_piece<BM, BK>(An, lda, nxt, tid, pi, wv);
;           else if (pi < NP) stage_piece<BN, BK>(Bn, ldb, nxt + ABYTES, tid, pi - NPA, wv);
;         }
;       }
;       __builtin_amdgcn_s_setprio(1);
; #pragma unroll
;       for (int mt = 0; mt < 2; ++mt)
; #pragma unroll
;         for (int nt = 0; nt < NTW; ++nt) acc[mt][nt] = mfma(fa[kk & 1][mt], fb[kk & 1][nt], acc[mt][nt]);
;       __builtin_amdgcn_s_setprio(0);
;       __builtin_amdgcn_sched_barrier(0);
;     }
.LBB0_173:
	s_and_b32 s30, s3, 0x10000
	s_xor_b32 s100, s30, 0x10000
	v_add3_u32 v194, s100, v136, v166
	v_add3_u32 v198, s100, v144, v167
	ds_read_b128 v[194:197], v194
	v_add3_u32 v202, s100, v145, v161
	ds_read_b128 v[198:201], v198
	v_add3_u32 v206, s100, v152, v163
	ds_read_b128 v[202:205], v202 offset:32768
	v_add3_u32 v210, s100, v155, v159
	ds_read_b128 v[206:209], v206 offset:32768
	v_add3_u32 v226, s100, v158, v160
	ds_read_b128 v[210:213], v210 offset:32768
	ds_read_b128 v[226:229], v226 offset:32768
	s_waitcnt lgkmcnt(6)
	v_mfma_f32_32x32x16_bf16 v[114:129], v[170:173], v[178:181], v[114:129]
	v_mfma_f32_32x32x16_bf16 v[98:113], v[170:173], v[182:185], v[98:113]
	v_mfma_f32_32x32x16_bf16 v[82:97], v[170:173], v[186:189], v[82:97]
	v_mfma_f32_32x32x16_bf16 v[66:81], v[170:173], v[190:193], v[66:81]
	v_mfma_f32_32x32x16_bf16 v[50:65], v[174:177], v[178:181], v[50:65]
	v_mfma_f32_32x32x16_bf16 v[34:49], v[174:177], v[182:185], v[34:49]
	v_mfma_f32_32x32x16_bf16 v[18:33], v[174:177], v[186:189], v[18:33]
	v_mfma_f32_32x32x16_bf16 v[2:17], v[174:177], v[190:193], v[2:17]
	v_add3_u32 v170, s100, v136, v153
	v_add3_u32 v174, s100, v144, v154
	ds_read_b128 v[170:173], v170
	v_add3_u32 v178, s100, v145, v149
	ds_read_b128 v[174:177], v174
	v_add3_u32 v182, s100, v152, v150
	ds_read_b128 v[178:181], v178 offset:32768
	v_add3_u32 v186, s100, v155, v147
	ds_read_b128 v[182:185], v182 offset:32768
	v_add3_u32 v190, s100, v158, v148
	ds_read_b128 v[186:189], v186 offset:32768
	ds_read_b128 v[190:193], v190 offset:32768
	s_waitcnt lgkmcnt(6)
	v_mfma_f32_32x32x16_bf16 v[114:129], v[194:197], v[202:205], v[114:129]
	v_mfma_f32_32x32x16_bf16 v[98:113], v[194:197], v[206:209], v[98:113]
	v_mfma_f32_32x32x16_bf16 v[82:97], v[194:197], v[210:213], v[82:97]
	v_mfma_f32_32x32x16_bf16 v[66:81], v[194:197], v[226:229], v[66:81]
	v_mfma_f32_32x32x16_bf16 v[50:65], v[198:201], v[202:205], v[50:65]
	v_mfma_f32_32x32x16_bf16 v[34:49], v[198:201], v[206:209], v[34:49]
	v_mfma_f32_32x32x16_bf16 v[18:33], v[198:201], v[210:213], v[18:33]
	v_mfma_f32_32x32x16_bf16 v[2:17], v[198:201], v[226:229], v[2:17]
	v_add3_u32 v194, s100, v136, v141
	v_add3_u32 v198, s100, v144, v142
	ds_read_b128 v[194:197], v194
	v_add3_u32 v202, s100, v145, v139
	ds_read_b128 v[198:201], v198
	v_add3_u32 v206, s100, v152, v140
	ds_read_b128 v[202:205], v202 offset:32768
	v_add3_u32 v210, s100, v155, v137
	ds_read_b128 v[206:209], v206 offset:32768
	v_add3_u32 v226, s100, v158, v138
	ds_read_b128 v[210:213], v210 offset:32768
	ds_read_b128 v[226:229], v226 offset:32768
	s_waitcnt lgkmcnt(6)
	v_mfma_f32_32x32x16_bf16 v[114:129], v[170:173], v[178:181], v[114:129]
	v_mfma_f32_32x32x16_bf16 v[98:113], v[170:173], v[182:185], v[98:113]
	v_mfma_f32_32x32x16_bf16 v[82:97], v[170:173], v[186:189], v[82:97]
	v_mfma_f32_32x32x16_bf16 v[66:81], v[170:173], v[190:193], v[66:81]
	v_mfma_f32_32x32x16_bf16 v[50:65], v[174:177], v[178:181], v[50:65]
	v_mfma_f32_32x32x16_bf16 v[34:49], v[174:177], v[182:185], v[34:49]
	v_mfma_f32_32x32x16_bf16 v[18:33], v[174:177], v[186:189], v[18:33]
	v_mfma_f32_32x32x16_bf16 v[2:17], v[174:177], v[190:193], v[2:17]
	s_add_u32 s6, s6, 0x80
	s_addc_u32 s7, s7, 0
	s_add_i32 s3, s3, 0x10000
	s_waitcnt vmcnt(0) lgkmcnt(0)
	s_barrier
	v_add3_u32 v170, s30, v136, v143
	v_add3_u32 v174, s30, v144, v146
	ds_read_b128 v[170:173], v170
	v_add3_u32 v178, s30, v145, v151
	ds_read_b128 v[174:177], v174
	v_add3_u32 v182, s30, v152, v156
	ds_read_b128 v[178:181], v178 offset:32768
	v_add3_u32 v186, s30, v155, v157
	ds_read_b128 v[182:185], v182 offset:32768
	v_add3_u32 v190, s30, v158, v168
	ds_read_b128 v[186:189], v186 offset:32768
	ds_read_b128 v[190:193], v190 offset:32768
	s_cmpk_lg_i32 s6, 0x780
	s_cbranch_scc0 .Lk173_exit
	s_add_i32 s31, s100, s2
	v_lshl_add_u64 v[214:215], v[132:133], 0, s[6:7]
	v_lshl_add_u64 v[230:231], v[130:131], 0, s[6:7]
	s_mov_b32 m0, s31
	v_lshl_add_u64 v[232:233], v[214:215], 0, s[28:29]
	v_mfma_f32_32x32x16_bf16 v[114:129], v[194:197], v[202:205], v[114:129]
	global_load_lds_dwordx4 v[232:233], off
	v_lshl_add_u64 v[232:233], v[214:215], 0, s[24:25]
	s_add_i32 m0, s31, 0x2000
	v_mfma_f32_32x32x16_bf16 v[98:113], v[194:197], v[206:209], v[98:113]
	global_load_lds_dwordx4 v[232:233], off
	v_lshl_add_u64 v[232:233], v[214:215], 0, s[26:27]
	s_add_i32 m0, s31, 0x4000
	v_mfma_f32_32x32x16_bf16 v[82:97], v[194:197], v[210:213], v[82:97]
	global_load_lds_dwordx4 v[232:233], off
	v_lshl_add_u64 v[232:233], v[214:215], 0, s[38:39]
	s_add_i32 m0, s31, 0x6000
	v_mfma_f32_32x32x16_bf16 v[66:81], v[194:197], v[226:229], v[66:81]
	global_load_lds_dwordx4 v[232:233], off
	v_lshl_add_u64 v[232:233], v[230:231], 0, s[28:29]
	s_add_i32 m0, s31, 0x8000
	v_mfma_f32_32x32x16_bf16 v[50:65], v[198:201], v[202:205], v[50:65]
	global_load_lds_dwordx4 v[232:233], off
	v_lshl_add_u64 v[232:233], v[230:231], 0, s[24:25]
	s_add_i32 m0, s31, 0xa000
	v_mfma_f32_32x32x16_bf16 v[34:49], v[198:201], v[206:209], v[34:49]
	global_load_lds_dwordx4 v[232:233], off
	v_lshl_add_u64 v[232:233], v[230:231], 0, s[26:27]
	s_add_i32 m0, s31, 0xc000
	v_mfma_f32_32x32x16_bf16 v[18:33], v[198:201], v[210:213], v[18:33]
	global_load_lds_dwordx4 v[232:233], off
	v_lshl_add_u64 v[232:233], v[230:231], 0, s[38:39]
	s_add_i32 m0, s31, 0xe000
	v_mfma_f32_32x32x16_bf16 v[2:17], v[198:201], v[226:229], v[2:17]
	global_load_lds_dwordx4 v[232:233], off
	s_branch .LBB0_173
; DI f32x16 mfma(bf16x8 a, bf16x8 b, f32x16 c) { return __builtin_amdgcn_mfma_f32_32x32x16_bf16(a, b, c, 0, 0, 0); }
;     ...
;   for (int kt = 0; kt < nk; ++kt) {
;     char* cur = lds + (kt & 1) * STG; char* nxt = lds + ((kt + 1) & 1) * STG;
;     const bool more = kt + 1 < nk;
;     const bf16_t* An = Ag + (kt + 1) * BK; const bf16_t* Bn = Bg + (kt + 1) * BK;
;     if (!more) epi.pre(row0 + wm * 64, col0 + wn * (32 * NTW), lane, w, lds);
;     bf16x8 fa[2][2], fb[2][NTW];
; #pragma unroll
;     for (int mt = 0; mt < 2; ++mt) { int row = wm * 64 + mt * 32 + l31; fa[0][mt] = *(const bf16x8*)(cur + row * (BK * 2) + ((hh ^ swz<BK>(row)) << 4)); }
; #pragma unroll
;     for (int nt = 0; nt < NTW; ++nt) { int row = wn * (32 * NTW) + nt * 32 + l31; fb[0][nt] = *(const bf16x8*)(cur + ABYTES + row * (BK * 2) + ((hh ^ swz<BK>(row)) << 4)); }
; #pragma unroll
;     for (int kk = 0; kk < NKK; ++kk) {
;       if (kk + 1 < NKK) {
;         const int ch = (kk + 1) * 2 + hh;
; #pragma unroll
;         for (int mt = 0; mt < 2; ++mt) { int row = wm * 64 + mt * 32 + l31; fa[(kk + 1) & 1][mt] = *(const bf16x8*)(cur + row * (BK * 2) + ((ch ^ swz<BK>(row)) << 4)); }
; #pragma unroll
;         for (int nt = 0; nt < NTW; ++nt) { int row = wn * (32 * NTW) + nt * 32 + l31; fb[(kk + 1) & 1][nt] = *(const bf16x8*)(cur + ABYTES + row * (BK * 2) + ((ch ^ swz<BK>(row)) << 4)); }
;       }
;       if (more) {
; #pragma unroll
;         for (int q = 0; q < PPK; ++q) {
;           const int pi = kk * PPK + q;
;           if (pi < NPA) stage_piece<BM, BK>(An, lda, nxt, tid, pi, wv);
;           else if (pi < NP) stage_piece<BN, BK>(Bn, ldb, nxt + ABYTES, tid, pi - NPA, wv);
;         }
;       }
;       __builtin_amdgcn_s_setprio(1);
; #pragma unroll
;       for (int mt = 0; mt < 2; ++mt)
; #pragma unroll
;         for (int nt = 0; nt < NTW; ++nt) acc[mt][nt] = mfma(fa[kk & 1][mt], fb[kk & 1][nt], acc[mt][nt]);
;       __builtin_amdgcn_s_setprio(0);
;       __builtin_amdgcn_sched_barrier(0);
;     }
;     wait_vm0();
;     __syncthreads();
;   DI void xpass(int ps, int grow0, int gcol0, int lane, int w, char* lds) const {
;     char* xs = lds + (ps & 1) * 65536 + __builtin_amdgcn_readfirstlane(w) * 8192;
;     const float* xsrc = Xin + (size_t)(grow0 + (ps >> 1) * 32 + (ps & 1) * 16 + (lane >> 5)) * D_ + gcol0 + (lane & 31) * 4;
; #pragma unroll
;     for (int pc = 0; pc < 8; ++pc)
.Lk173_exit:
	v_mfma_f32_32x32x16_bf16 v[114:129], v[194:197], v[202:205], v[114:129]
	v_mfma_f32_32x32x16_bf16 v[98:113], v[194:197], v[206:209], v[98:113]
	v_mfma_f32_32x32x16_bf16 v[82:97], v[194:197], v[210:213], v[82:97]
	v_mfma_f32_32x32x16_bf16 v[66:81], v[194:197], v[226:229], v[66:81]
	v_mfma_f32_32x32x16_bf16 v[50:65], v[198:201], v[202:205], v[50:65]
	v_mfma_f32_32x32x16_bf16 v[34:49], v[198:201], v[206:209], v[34:49]
	v_mfma_f32_32x32x16_bf16 v[18:33], v[198:201], v[210:213], v[18:33]
	v_mfma_f32_32x32x16_bf16 v[2:17], v[198:201], v[226:229], v[2:17]
	s_waitcnt lgkmcnt(0)
	v_readlane_b32 s3, v253, 9
	v_readlane_b32 s6, v253, 27
	v_readfirstlane_b32 s2, v134
	v_or_b32_e32 v130, s3, v135
	v_add_u32_e32 v130, v130, v169
	v_ashrrev_i32_e32 v131, 31, v130
	v_lshlrev_b64 v[130:131], 12, v[130:131]
	v_add_u32_e32 v132, s6, v164
	v_ashrrev_i32_e32 v133, 31, v132
	v_lshl_add_u64 v[130:131], s[10:11], 0, v[130:131]
	v_lshlrev_b32_e32 v0, 4, v0
	s_lshl_b32 s2, s2, 13
	v_lshl_add_u64 v[130:131], v[132:133], 2, v[130:131]
	v_and_b32_e32 v132, 0x1f0, v0
	v_mov_b32_e32 v133, v1
	v_lshl_add_u64 v[130:131], v[130:131], 0, v[132:133]
	s_mov_b32 m0, s2
	s_mov_b64 s[34:35], 0x2000
	global_load_lds_dwordx4 v[130:131], off
	v_lshl_add_u64 v[132:133], v[130:131], 0, s[34:35]
	s_or_b32 m0, s2, 0x400
	s_mov_b64 s[36:37], 0x4000
	global_load_lds_dwordx4 v[132:133], off
	v_lshl_add_u64 v[132:133], v[130:131], 0, s[36:37]
	s_or_b32 m0, s2, 0x800
	s_mov_b64 s[40:41], 0x6000
	global_load_lds_dwordx4 v[132:133], off
	v_lshl_add_u64 v[132:133], v[130:131], 0, s[40:41]
	s_or_b32 m0, s2, 0xc00
	s_mov_b64 s[44:45], 0x8000
	global_load_lds_dwordx4 v[132:133], off
	v_lshl_add_u64 v[132:133], v[130:131], 0, s[44:45]
	s_or_b32 m0, s2, 0x1000
	s_mov_b64 s[46:47], 0xa000
	global_load_lds_dwordx4 v[132:133], off
	v_lshl_add_u64 v[132:133], v[130:131], 0, s[46:47]
	s_or_b32 m0, s2, 0x1400
	s_mov_b64 s[52:53], 0xc000
	global_load_lds_dwordx4 v[132:133], off
	v_lshl_add_u64 v[132:133], v[130:131], 0, s[52:53]
	s_or_b32 m0, s2, 0x1800
	s_mov_b64 s[54:55], 0xe000
	global_load_lds_dwordx4 v[132:133], off
	v_lshl_add_u64 v[130:131], v[130:131], 0, s[54:55]
	s_or_b32 m0, s2, 0x1c00
	v_add_u32_e32 v0, s30, v136
	global_load_lds_dwordx4 v[130:131], off
	v_add_u32_e32 v134, s30, v144
	v_add_u32_e32 v130, v0, v143
	v_add_u32_e32 v135, v134, v146
	ds_read_b128 v[130:133], v130
	ds_read_b128 v[170:173], v135
	v_add_u32_e32 v135, s30, v145
	v_add_u32_e32 v136, v135, v151
	v_add_u32_e32 v143, s30, v152
	v_add_u32_e32 v144, v143, v156
	ds_read_b128 v[174:177], v136 offset:32768
	ds_read_b128 v[178:181], v144 offset:32768
	v_add_u32_e32 v136, s30, v155
	v_add_u32_e32 v144, v136, v157
	v_add_u32_e32 v164, s30, v158
	v_add_u32_e32 v145, v164, v168
	ds_read_b128 v[182:185], v144 offset:32768
	ds_read_b128 v[186:189], v145 offset:32768
	v_add_u32_e32 v144, v0, v166
	v_add_u32_e32 v145, v134, v167
	ds_read_b128 v[166:169], v144
	ds_read_b128 v[190:193], v145
	v_add_u32_e32 v144, v135, v161
	v_add_u32_e32 v145, v143, v163
	ds_read_b128 v[194:197], v144 offset:32768
	ds_read_b128 v[198:201], v145 offset:32768
	v_add_u32_e32 v144, v136, v159
	v_add_u32_e32 v145, v164, v160
	ds_read_b128 v[156:159], v144 offset:32768
	ds_read_b128 v[202:205], v145 offset:32768
	v_readlane_b32 s7, v253, 28
	s_setprio 1
	s_waitcnt lgkmcnt(0)
	v_mfma_f32_32x32x16_bf16 v[114:129], v[130:133], v[174:177], v[114:129]
	v_mfma_f32_32x32x16_bf16 v[98:113], v[130:133], v[178:181], v[98:113]
	v_mfma_f32_32x32x16_bf16 v[82:97], v[130:133], v[182:185], v[82:97]
	v_mfma_f32_32x32x16_bf16 v[66:81], v[130:133], v[186:189], v[66:81]
	v_mfma_f32_32x32x16_bf16 v[50:65], v[170:173], v[174:177], v[50:65]
	v_mfma_f32_32x32x16_bf16 v[34:49], v[170:173], v[178:181], v[34:49]
	v_mfma_f32_32x32x16_bf16 v[18:33], v[170:173], v[182:185], v[18:33]
	v_mfma_f32_32x32x16_bf16 v[2:17], v[170:173], v[186:189], v[2:17]
	s_setprio 0
	v_add_u32_e32 v130, v0, v153
	v_add_u32_e32 v144, v134, v154
	ds_read_b128 v[130:133], v130
	ds_read_b128 v[152:155], v144
	v_add_u32_e32 v144, v135, v149
	v_add_u32_e32 v145, v143, v150
	ds_read_b128 v[170:173], v144 offset:32768
	ds_read_b128 v[174:177], v145 offset:32768
	v_add_u32_e32 v144, v136, v147
	v_add_u32_e32 v148, v164, v148
	ds_read_b128 v[144:147], v144 offset:32768
	ds_read_b128 v[148:151], v148 offset:32768
	s_setprio 1
	v_mfma_f32_32x32x16_bf16 v[114:129], v[166:169], v[194:197], v[114:129]
	v_mfma_f32_32x32x16_bf16 v[98:113], v[166:169], v[198:201], v[98:113]
	v_mfma_f32_32x32x16_bf16 v[82:97], v[166:169], v[156:159], v[82:97]
	v_mfma_f32_32x32x16_bf16 v[66:81], v[166:169], v[202:205], v[66:81]
	v_mfma_f32_32x32x16_bf16 v[50:65], v[190:193], v[194:197], v[50:65]
	v_mfma_f32_32x32x16_bf16 v[34:49], v[190:193], v[198:201], v[34:49]
	v_mfma_f32_32x32x16_bf16 v[18:33], v[190:193], v[156:159], v[18:33]
	v_mfma_f32_32x32x16_bf16 v[2:17], v[190:193], v[202:205], v[2:17]
	s_setprio 0
	v_add_u32_e32 v0, v0, v141
	v_add_u32_e32 v134, v134, v142
	ds_read_b128 v[156:159], v0
	ds_read_b128 v[166:169], v134
	v_add_u32_e32 v0, v135, v139
	v_add_u32_e32 v134, v143, v140
	ds_read_b128 v[140:143], v0 offset:32768
	ds_read_b128 v[178:181], v134 offset:32768
	v_add_u32_e32 v0, v136, v137
	v_add_u32_e32 v138, v164, v138
	ds_read_b128 v[134:137], v0 offset:32768
	ds_read_b128 v[182:185], v138 offset:32768
	s_setprio 1
	s_waitcnt lgkmcnt(9)
	v_mfma_f32_32x32x16_bf16 v[114:129], v[130:133], v[170:173], v[114:129]
	s_waitcnt lgkmcnt(8)
	v_mfma_f32_32x32x16_bf16 v[98:113], v[130:133], v[174:177], v[98:113]
	s_waitcnt lgkmcnt(7)
	v_mfma_f32_32x32x16_bf16 v[82:97], v[130:133], v[144:147], v[82:97]
	s_waitcnt lgkmcnt(6)
	v_mfma_f32_32x32x16_bf16 v[66:81], v[130:133], v[148:151], v[66:81]
	v_mfma_f32_32x32x16_bf16 v[50:65], v[152:155], v[170:173], v[50:65]
	v_mfma_f32_32x32x16_bf16 v[34:49], v[152:155], v[174:177], v[34:49]
	v_mfma_f32_32x32x16_bf16 v[18:33], v[152:155], v[144:147], v[18:33]
	v_mfma_f32_32x32x16_bf16 v[2:17], v[152:155], v[148:151], v[2:17]
	s_setprio 0
	s_setprio 1
	s_waitcnt lgkmcnt(3)
	v_mfma_f32_32x32x16_bf16 v[114:129], v[156:159], v[140:143], v[114:129]
	s_waitcnt lgkmcnt(2)
	v_mfma_f32_32x32x16_bf16 v[98:113], v[156:159], v[178:181], v[98:113]
	s_waitcnt lgkmcnt(1)
	v_mfma_f32_32x32x16_bf16 v[82:97], v[156:159], v[134:137], v[82:97]
	s_waitcnt lgkmcnt(0)
	v_mfma_f32_32x32x16_bf16 v[66:81], v[156:159], v[182:185], v[66:81]
	v_mfma_f32_32x32x16_bf16 v[50:65], v[166:169], v[140:143], v[50:65]
	v_mfma_f32_32x32x16_bf16 v[34:49], v[166:169], v[178:181], v[34:49]
	v_mfma_f32_32x32x16_bf16 v[18:33], v[166:169], v[134:137], v[18:33]
	v_mfma_f32_32x32x16_bf16 v[2:17], v[166:169], v[182:185], v[2:17]
	s_setprio 0
	v_mov_b32_e32 v164, v216
	s_waitcnt vmcnt(0)
	s_barrier
;   DI void xpass(int ps, int grow0, int gcol0, int lane, int w, char* lds) const {
;     char* xs = lds + (ps & 1) * 65536 + __builtin_amdgcn_readfirstlane(w) * 8192;
;     const float* xsrc = Xin + (size_t)(grow0 + (ps >> 1) * 32 + (ps & 1) * 16 + (lane >> 5)) * D_ + gcol0 + (lane & 31) * 4;
; #pragma unroll
;     for (int pc = 0; pc < 8; ++pc)
;       __builtin_amdgcn_global_load_lds((const unsigned*)(xsrc + (size_t)(2 * pc) * D_), (__attribute__((address_space(3))) unsigned*)(xs + pc * 1024), 16, 0, 0);
;   }
;   DI void pre(int grow0, int gcol0, int lane, int w, char* lds) { xpass(0, grow0, gcol0, lane, w, lds); }
;   DI void operator()(f32x16 (&acc)[2][4], int grow0, int gcol0, int lane, int w, char* lds) {
;     float* red = (float*)(lds + 131072); float* stat = (float*)lds;
;     const int l31 = lane & 31, hh = lane >> 5, tid = w * 64 + lane;
;     const int pm = grow0 >> 8, pn = gcol0 >> 8, wn = (gcol0 >> 7) & 1, lrow0 = grow0 & 255;
;     float bia[4], csc[4];
; #pragma unroll
;     for (int nt = 0; nt < 4; ++nt) { int c = gcol0 + nt * 32 + l31; bia[nt] = bias ? bias[c] : 0.f; csc[nt] = cscale ? cscale[c] : 1.f; }
;     float* redw = red + ((wn * 2 + ((lane >> 4) & 1)) * 256 + lrow0 + 4 * hh) * 2;
; #pragma unroll
;     for (int ps = 0; ps < 4; ++ps) {
;       const int mt = ps >> 1;
;       if (ps + 1 < 4) {
;         if (ps >= 1) asm volatile("s_waitcnt lgkmcnt(0)" ::: "memory");
;         xpass(ps + 1, grow0, gcol0, lane, w, lds);
;         if (ps >= 1) asm volatile("s_waitcnt vmcnt(8)" ::: "memory");
;       } else asm volatile("s_waitcnt vmcnt(0)" ::: "memory");
;       const char* xs = lds + (ps & 1) * 65536 + w * 8192;
; #pragma unroll
;       for (int qq = 0; qq < 2; ++qq)
; #pragma unroll
;         for (int e = 0; e < 4; ++e) {
;           const int i = 4 * (2 * (ps & 1) + qq) + e;
;           const float* xr = (const float*)(xs + (8 * qq + 4 * hh + e) * 512) + l31;
;           float s1 = 0.f, s2 = 0.f;
; #pragma unroll
;           for (int nt = 0; nt < 4; ++nt) {
;             float v = (acc[mt][nt][i] + bia[nt]) * csc[nt];
;             float z = ALPHA * xr[nt * 32] + hs * v;
;             acc[mt][nt][i] = z; s1 += z; s2 += z * z;
;           }
;           s1 = row16_sum(s1); s2 = row16_sum(s2);
;           if ((lane & 15) == 0) { f32x2 sv = {s1, s2}; *(f32x2*)(redw + (mt * 32 + (i & 3) + 8 * (i >> 2)) * 2) = sv; }
;         }
	v_mov_b32_e32 v133, v1
	v_ashrrev_i32_e32 v158, 6, v164
	v_lshrrev_b32_e32 v0, 30, v158
	v_add_u32_e32 v0, v158, v0
	v_ashrrev_i32_e32 v134, 2, v0
	v_mul_i32_i24_e32 v0, 4, v134
	v_sub_u32_e32 v0, v158, v0
	v_lshlrev_b32_e32 v135, 6, v0
	v_add_u32_e32 v163, s3, v135
	v_bfe_u32 v0, v164, 5, 1
	v_or_b32_e32 v159, v163, v0
	v_or_b32_e32 v130, 16, v159
	v_lshlrev_b32_e32 v200, 2, v164
	v_ashrrev_i32_e32 v131, 31, v130
	v_lshl_add_u32 v184, v134, 7, s6
	v_and_b32_e32 v0, 0x7c, v200
	v_lshlrev_b64 v[130:131], 12, v[130:131]
	v_ashrrev_i32_e32 v185, 31, v184
	v_readfirstlane_b32 s2, v158
	v_lshl_add_u64 v[130:131], s[10:11], 0, v[130:131]
	v_lshlrev_b32_e32 v0, 2, v0
	s_lshl_b32 s2, s2, 13
	v_lshl_add_u64 v[130:131], v[184:185], 2, v[130:131]
	v_mov_b32_e32 v132, v0
	s_add_i32 m0, s2, 0x10000
	v_lshl_add_u64 v[130:131], v[130:131], 0, v[132:133]
	global_load_lds_dwordx4 v[130:131], off
	v_lshl_add_u64 v[132:133], v[130:131], 0, s[34:35]
	s_add_i32 m0, s2, 0x10400
	v_and_b32_e32 v210, 0xc0, v135
	global_load_lds_dwordx4 v[132:133], off
	v_lshl_add_u64 v[132:133], v[130:131], 0, s[36:37]
	s_add_i32 m0, s2, 0x10800
	v_mov_b32_e32 v136, v114
	global_load_lds_dwordx4 v[132:133], off
	v_lshl_add_u64 v[132:133], v[130:131], 0, s[40:41]
	s_add_i32 m0, s2, 0x10c00
	v_mov_b32_e32 v137, v82
	global_load_lds_dwordx4 v[132:133], off
	v_lshl_add_u64 v[132:133], v[130:131], 0, s[44:45]
	s_add_i32 m0, s2, 0x11000
	v_mov_b32_e32 v140, v98
	global_load_lds_dwordx4 v[132:133], off
	v_lshl_add_u64 v[132:133], v[130:131], 0, s[46:47]
	s_add_i32 m0, s2, 0x11400
	v_mov_b32_e32 v141, v82
	global_load_lds_dwordx4 v[132:133], off
	v_lshl_add_u64 v[132:133], v[130:131], 0, s[52:53]
	s_add_i32 m0, s2, 0x11800
	v_lshl_add_u64 v[130:131], v[130:131], 0, s[54:55]
	global_load_lds_dwordx4 v[132:133], off
	s_add_i32 m0, s2, 0x11c00
	v_bfe_u32 v132, v164, 4, 1
	global_load_lds_dwordx4 v[130:131], off
	v_and_b32_e32 v130, 31, v164
	v_lshlrev_b32_e32 v131, 1, v134
	v_bfe_u32 v134, v164, 3, 3
	v_and_or_b32 v131, v131, 2, v132
	v_and_b32_e32 v132, 4, v134
	v_lshlrev_b32_e32 v130, 2, v130
	v_lshl_or_b32 v138, v158, 13, v130
	v_lshlrev_b32_e32 v154, 9, v132
	v_or_b32_e32 v133, v210, v132
	v_and_b32_e32 v130, 15, v164
	v_or_b32_e32 v132, v138, v154
	v_lshlrev_b32_e32 v135, 3, v133
	v_lshl_or_b32 v139, v131, 11, v221
	v_cmp_eq_u32_e32 vcc, 0, v130
	s_waitcnt vmcnt(8)
	ds_read2_b32 v[130:131], v132 offset1:32
	ds_read2_b32 v[132:133], v132 offset0:64 offset1:96
	v_pk_add_f32 v[136:137], v[136:137], 0 op_sel_hi:[1,0]
	v_pk_add_f32 v[140:141], v[140:141], 0 op_sel_hi:[1,0]
	s_mov_b32 s2, s67
	s_waitcnt lgkmcnt(0)
	v_mov_b32_e32 v142, v130
	v_mov_b32_e32 v143, v132
	v_mov_b32_e32 v130, v131
	v_mov_b32_e32 v131, v132
	v_pk_fma_f32 v[186:187], v[142:143], s[2:3], v[136:137] op_sel_hi:[1,0,1]
	v_pk_fma_f32 v[188:189], v[130:131], s[2:3], v[140:141] op_sel_hi:[1,0,1]
	v_pk_mul_f32 v[144:145], v[142:143], s[2:3] op_sel_hi:[1,0]
	v_pk_mul_f32 v[142:143], v[186:187], v[186:187]
	v_pk_mul_f32 v[130:131], v[188:189], v[188:189]
	v_pk_mov_b32 v[136:137], v[136:137], v[142:143] op_sel:[1,0]
	v_pk_mov_b32 v[130:131], v[144:145], v[130:131] op_sel:[1,0]
	v_add_f32_e32 v180, 0, v66
	v_pk_add_f32 v[130:131], v[136:137], v[130:131]
	v_pk_add_f32 v[136:137], v[186:187], v[188:189]
	v_pk_mul_f32 v[140:141], v[186:187], v[188:189]
	v_fmac_f32_e32 v180, 0x3fd744fd, v133
	v_mov_b32_e32 v137, v141
	v_pk_add_f32 v[130:131], v[136:137], v[130:131]
	v_mul_f32_e32 v181, v180, v180
	v_pk_add_f32 v[130:131], v[130:131], v[180:181]
	v_add_u32_e32 v181, v139, v135
	s_nop 0
	v_mov_b32_dpp v132, v130 quad_perm:[1,0,3,2] row_mask:0xf bank_mask:0xf bound_ctrl:1
	v_mov_b32_dpp v133, v131 quad_perm:[1,0,3,2] row_mask:0xf bank_mask:0xf bound_ctrl:1
	v_pk_add_f32 v[130:131], v[130:131], v[132:133]
	s_nop 1
	v_mov_b32_dpp v132, v130 quad_perm:[2,3,0,1] row_mask:0xf bank_mask:0xf bound_ctrl:1
	v_mov_b32_dpp v133, v131 quad_perm:[2,3,0,1] row_mask:0xf bank_mask:0xf bound_ctrl:1
	v_pk_add_f32 v[130:131], v[130:131], v[132:133]
	s_nop 1
	v_mov_b32_dpp v132, v130 row_half_mirror row_mask:0xf bank_mask:0xf bound_ctrl:1
	v_mov_b32_dpp v133, v131 row_half_mirror row_mask:0xf bank_mask:0xf bound_ctrl:1
	v_pk_add_f32 v[130:131], v[130:131], v[132:133]
	s_nop 1
	v_mov_b32_dpp v132, v130 row_mirror row_mask:0xf bank_mask:0xf bound_ctrl:1
	v_mov_b32_dpp v133, v131 row_mirror row_mask:0xf bank_mask:0xf bound_ctrl:1
	s_and_saveexec_b64 s[6:7], vcc
	v_pk_add_f32 v[130:131], v[130:131], v[132:133]
	ds_write_b64 v181, v[130:131]
	s_or_b64 exec, exec, s[6:7]
	v_add_u32_e32 v168, v138, v154
	ds_read2_b32 v[130:131], v168 offset0:128 offset1:160
	ds_read2_b32 v[132:133], v168 offset0:192 offset1:224
	v_mov_b32_e32 v82, v115
	v_add_f32_e32 v152, 0, v67
	v_pk_add_f32 v[66:67], v[82:83], 0 op_sel_hi:[1,0]
	v_mov_b32_e32 v82, v99
	v_pk_add_f32 v[82:83], v[82:83], 0 op_sel_hi:[1,0]
	s_waitcnt lgkmcnt(1)
	v_mov_b32_e32 v98, v130
	s_waitcnt lgkmcnt(0)
;   DI void operator()(f32x16 (&acc)[2][4], int grow0, int gcol0, int lane, int w, char* lds) {
;     ...
; #pragma unroll
;       for (int qq = 0; qq < 2; ++qq)
; #pragma unroll
;         for (int e = 0; e < 4; ++e) {
;           const int i = 4 * (2 * (ps & 1) + qq) + e;
;           const float* xr = (const float*)(xs + (8 * qq + 4 * hh + e) * 512) + l31;
;           float s1 = 0.f, s2 = 0.f;
; #pragma unroll
;           for (int nt = 0; nt < 4; ++nt) {
;             float v = (acc[mt][nt][i] + bia[nt]) * csc[nt];
;             float z = ALPHA * xr[nt * 32] + hs * v;
;             acc[mt][nt][i] = z; s1 += z; s2 += z * z;
;           }
;           s1 = row16_sum(s1); s2 = row16_sum(s2);
;           if ((lane & 15) == 0) { f32x2 sv = {s1, s2}; *(f32x2*)(redw + (mt * 32 + (i & 3) + 8 * (i >> 2)) * 2) = sv; }
;         }
	v_mov_b32_e32 v99, v132
	s_mov_b32 s2, s67
	v_mov_b32_e32 v130, v131
	v_mov_b32_e32 v131, v132
	v_pk_fma_f32 v[166:167], v[98:99], s[2:3], v[66:67] op_sel_hi:[1,0,1]
	v_pk_fma_f32 v[172:173], v[130:131], s[2:3], v[82:83] op_sel_hi:[1,0,1]
	v_pk_mul_f32 v[114:115], v[98:99], s[2:3] op_sel_hi:[1,0]
	v_pk_mul_f32 v[98:99], v[166:167], v[166:167]
	v_pk_mul_f32 v[82:83], v[172:173], v[172:173]
	v_pk_mov_b32 v[66:67], v[66:67], v[98:99] op_sel:[1,0]
	v_pk_mov_b32 v[82:83], v[114:115], v[82:83] op_sel:[1,0]
	v_pk_mul_f32 v[98:99], v[166:167], v[172:173]
	v_pk_add_f32 v[66:67], v[66:67], v[82:83]
	v_pk_add_f32 v[82:83], v[166:167], v[172:173]
	v_fmac_f32_e32 v152, 0x3fd744fd, v133
	v_mov_b32_e32 v83, v99
	v_pk_add_f32 v[66:67], v[82:83], v[66:67]
	v_mul_f32_e32 v153, v152, v152
	v_pk_add_f32 v[66:67], v[66:67], v[152:153]
	s_nop 1
	v_mov_b32_dpp v82, v66 quad_perm:[1,0,3,2] row_mask:0xf bank_mask:0xf bound_ctrl:1
	v_mov_b32_dpp v83, v67 quad_perm:[1,0,3,2] row_mask:0xf bank_mask:0xf bound_ctrl:1
	v_pk_add_f32 v[66:67], v[66:67], v[82:83]
	s_nop 1
	v_mov_b32_dpp v82, v66 quad_perm:[2,3,0,1] row_mask:0xf bank_mask:0xf bound_ctrl:1
	v_mov_b32_dpp v83, v67 quad_perm:[2,3,0,1] row_mask:0xf bank_mask:0xf bound_ctrl:1
	v_pk_add_f32 v[66:67], v[66:67], v[82:83]
	s_nop 1
	v_mov_b32_dpp v82, v66 row_half_mirror row_mask:0xf bank_mask:0xf bound_ctrl:1
	v_mov_b32_dpp v83, v67 row_half_mirror row_mask:0xf bank_mask:0xf bound_ctrl:1
	v_pk_add_f32 v[66:67], v[66:67], v[82:83]
	s_nop 1
	v_mov_b32_dpp v82, v66 row_mirror row_mask:0xf bank_mask:0xf bound_ctrl:1
	v_mov_b32_dpp v83, v67 row_mirror row_mask:0xf bank_mask:0xf bound_ctrl:1
	s_and_saveexec_b64 s[6:7], vcc
	v_pk_add_f32 v[66:67], v[66:67], v[82:83]
	ds_write_b64 v181, v[66:67] offset:8
	s_or_b64 exec, exec, s[6:7]
	v_add_u32_e32 v153, 0x400, v168
	ds_read2_b32 v[82:83], v153 offset1:32
	ds_read2_b32 v[98:99], v153 offset0:64 offset1:96
	v_mov_b32_e32 v114, v116
	v_mov_b32_e32 v115, v84
	v_mov_b32_e32 v130, v100
	v_mov_b32_e32 v131, v84
	v_pk_add_f32 v[114:115], v[114:115], 0 op_sel_hi:[1,0]
	v_pk_add_f32 v[130:131], v[130:131], 0 op_sel_hi:[1,0]
	s_waitcnt lgkmcnt(1)
	v_mov_b32_e32 v132, v82
	s_waitcnt lgkmcnt(0)
	v_mov_b32_e32 v133, v98
	s_mov_b32 s2, s67
	v_mov_b32_e32 v140, v83
	v_mov_b32_e32 v141, v98
	v_pk_fma_f32 v[82:83], v[132:133], s[2:3], v[114:115] op_sel_hi:[1,0,1]
	v_pk_fma_f32 v[150:151], v[140:141], s[2:3], v[130:131] op_sel_hi:[1,0,1]
	v_pk_mul_f32 v[136:137], v[132:133], s[2:3] op_sel_hi:[1,0]
	v_pk_mul_f32 v[132:133], v[82:83], v[82:83]
	v_pk_mul_f32 v[130:131], v[150:151], v[150:151]
	v_pk_mov_b32 v[114:115], v[114:115], v[132:133] op_sel:[1,0]
	v_pk_mov_b32 v[130:131], v[136:137], v[130:131] op_sel:[1,0]
	v_add_f32_e32 v66, 0, v68
	v_pk_add_f32 v[114:115], v[114:115], v[130:131]
	v_pk_add_f32 v[130:131], v[82:83], v[150:151]
	v_pk_mul_f32 v[132:133], v[82:83], v[150:151]
	v_fmac_f32_e32 v66, 0x3fd744fd, v99
	v_mov_b32_e32 v131, v133
	v_pk_add_f32 v[114:115], v[130:131], v[114:115]
	v_mul_f32_e32 v67, v66, v66
	v_pk_add_f32 v[98:99], v[114:115], v[66:67]
	s_nop 1
	v_mov_b32_dpp v114, v98 quad_perm:[1,0,3,2] row_mask:0xf bank_mask:0xf bound_ctrl:1
	v_mov_b32_dpp v115, v99 quad_perm:[1,0,3,2] row_mask:0xf bank_mask:0xf bound_ctrl:1
	v_pk_add_f32 v[98:99], v[98:99], v[114:115]
	s_nop 1
	v_mov_b32_dpp v114, v98 quad_perm:[2,3,0,1] row_mask:0xf bank_mask:0xf bound_ctrl:1
	v_mov_b32_dpp v115, v99 quad_perm:[2,3,0,1] row_mask:0xf bank_mask:0xf bound_ctrl:1
	v_pk_add_f32 v[98:99], v[98:99], v[114:115]
	s_nop 1
	v_mov_b32_dpp v114, v98 row_half_mirror row_mask:0xf bank_mask:0xf bound_ctrl:1
	v_mov_b32_dpp v115, v99 row_half_mirror row_mask:0xf bank_mask:0xf bound_ctrl:1
	v_pk_add_f32 v[98:99], v[98:99], v[114:115]
	s_nop 1
	v_mov_b32_dpp v114, v98 row_mirror row_mask:0xf bank_mask:0xf bound_ctrl:1
	v_mov_b32_dpp v115, v99 row_mirror row_mask:0xf bank_mask:0xf bound_ctrl:1
	s_and_saveexec_b64 s[6:7], vcc
	v_pk_add_f32 v[98:99], v[98:99], v[114:115]
	ds_write_b64 v181, v[98:99] offset:16
	s_or_b64 exec, exec, s[6:7]
	v_lshlrev_b32_e32 v139, 9, v134
	v_or_b32_e32 v146, 0x600, v139
	v_add_u32_e32 v151, v138, v146
	ds_read2_b32 v[98:99], v151 offset1:32
	ds_read2_b32 v[114:115], v151 offset0:64 offset1:96
	v_mov_b32_e32 v84, v117
	v_pk_add_f32 v[116:117], v[84:85], 0 op_sel_hi:[1,0]
	v_mov_b32_e32 v84, v101
	v_pk_add_f32 v[84:85], v[84:85], 0 op_sel_hi:[1,0]
	s_waitcnt lgkmcnt(1)
	v_mov_b32_e32 v100, v98
	s_waitcnt lgkmcnt(0)
	v_mov_b32_e32 v101, v114
	s_mov_b32 s2, s67
	v_mov_b32_e32 v132, v99
	v_mov_b32_e32 v133, v114
	v_pk_mul_f32 v[130:131], v[100:101], s[2:3] op_sel_hi:[1,0]
	v_pk_fma_f32 v[98:99], v[100:101], s[2:3], v[116:117] op_sel_hi:[1,0,1]
	v_pk_fma_f32 v[100:101], v[132:133], s[2:3], v[84:85] op_sel_hi:[1,0,1]
	v_pk_mul_f32 v[134:135], v[98:99], v[98:99]
	v_pk_mul_f32 v[84:85], v[100:101], v[100:101]
	v_pk_mov_b32 v[116:117], v[116:117], v[134:135] op_sel:[1,0]
	v_pk_mov_b32 v[84:85], v[130:131], v[84:85] op_sel:[1,0]
	v_add_f32_e32 v68, 0, v69
	v_pk_add_f32 v[84:85], v[116:117], v[84:85]
	v_pk_add_f32 v[116:117], v[98:99], v[100:101]
	v_pk_mul_f32 v[130:131], v[98:99], v[100:101]
	v_fmac_f32_e32 v68, 0x3fd744fd, v115
	v_mov_b32_e32 v117, v131
	v_pk_add_f32 v[84:85], v[116:117], v[84:85]
	v_mul_f32_e32 v69, v68, v68
	v_pk_add_f32 v[84:85], v[84:85], v[68:69]
	s_nop 1
	v_mov_b32_dpp v114, v84 quad_perm:[1,0,3,2] row_mask:0xf bank_mask:0xf bound_ctrl:1
	v_mov_b32_dpp v115, v85 quad_perm:[1,0,3,2] row_mask:0xf bank_mask:0xf bound_ctrl:1
	v_pk_add_f32 v[84:85], v[84:85], v[114:115]
	s_nop 1
	v_mov_b32_dpp v114, v84 quad_perm:[2,3,0,1] row_mask:0xf bank_mask:0xf bound_ctrl:1
	v_mov_b32_dpp v115, v85 quad_perm:[2,3,0,1] row_mask:0xf bank_mask:0xf bound_ctrl:1
	v_pk_add_f32 v[84:85], v[84:85], v[114:115]
	s_nop 1
	v_mov_b32_dpp v114, v84 row_half_mirror row_mask:0xf bank_mask:0xf bound_ctrl:1
	v_mov_b32_dpp v115, v85 row_half_mirror row_mask:0xf bank_mask:0xf bound_ctrl:1
	v_pk_add_f32 v[84:85], v[84:85], v[114:115]
	s_nop 1
	v_mov_b32_dpp v114, v84 row_mirror row_mask:0xf bank_mask:0xf bound_ctrl:1
	v_mov_b32_dpp v115, v85 row_mirror row_mask:0xf bank_mask:0xf bound_ctrl:1
	s_and_saveexec_b64 s[6:7], vcc
	v_pk_add_f32 v[84:85], v[84:85], v[114:115]
	ds_write_b64 v181, v[84:85] offset:24
	s_or_b64 exec, exec, s[6:7]
	v_add_u32_e32 v67, 0x1000, v168
	ds_read2_b32 v[114:115], v67 offset1:32
	ds_read2_b32 v[130:131], v67 offset0:64 offset1:96
	v_mov_b32_e32 v116, v118
	v_mov_b32_e32 v117, v86
	v_pk_add_f32 v[132:133], v[116:117], 0 op_sel_hi:[1,0]
	v_mov_b32_e32 v116, v102
	v_pk_add_f32 v[116:117], v[116:117], 0 op_sel_hi:[1,0]
	s_waitcnt lgkmcnt(1)
;   DI void operator()(f32x16 (&acc)[2][4], int grow0, int gcol0, int lane, int w, char* lds) {
;     ...
; #pragma unroll
;       for (int qq = 0; qq < 2; ++qq)
; #pragma unroll
;         for (int e = 0; e < 4; ++e) {
;           const int i = 4 * (2 * (ps & 1) + qq) + e;
;           const float* xr = (const float*)(xs + (8 * qq + 4 * hh + e) * 512) + l31;
;           float s1 = 0.f, s2 = 0.f;
; #pragma unroll
;           for (int nt = 0; nt < 4; ++nt) {
;             float v = (acc[mt][nt][i] + bia[nt]) * csc[nt];
;             float z = ALPHA * xr[nt * 32] + hs * v;
;             acc[mt][nt][i] = z; s1 += z; s2 += z * z;
;           }
;           s1 = row16_sum(s1); s2 = row16_sum(s2);
;           if ((lane & 15) == 0) { f32x2 sv = {s1, s2}; *(f32x2*)(redw + (mt * 32 + (i & 3) + 8 * (i >> 2)) * 2) = sv; }
;         }
	v_mov_b32_e32 v134, v114
	s_waitcnt lgkmcnt(0)
	v_mov_b32_e32 v135, v130
	s_mov_b32 s2, s67
	v_mov_b32_e32 v140, v115
	v_mov_b32_e32 v141, v130
	v_pk_fma_f32 v[114:115], v[134:135], s[2:3], v[132:133] op_sel_hi:[1,0,1]
	v_pk_fma_f32 v[116:117], v[140:141], s[2:3], v[116:117] op_sel_hi:[1,0,1]
	v_pk_mul_f32 v[136:137], v[134:135], s[2:3] op_sel_hi:[1,0]
	v_pk_mul_f32 v[134:135], v[114:115], v[114:115]
	v_pk_mul_f32 v[140:141], v[116:117], v[116:117]
	v_pk_mov_b32 v[132:133], v[132:133], v[134:135] op_sel:[1,0]
	v_pk_mov_b32 v[134:135], v[136:137], v[140:141] op_sel:[1,0]
	v_add_f32_e32 v84, 0, v70
	v_pk_add_f32 v[132:133], v[132:133], v[134:135]
	v_pk_add_f32 v[134:135], v[114:115], v[116:117]
	v_pk_mul_f32 v[136:137], v[114:115], v[116:117]
	v_fmac_f32_e32 v84, 0x3fd744fd, v131
	v_mov_b32_e32 v135, v137
	v_pk_add_f32 v[132:133], v[134:135], v[132:133]
	v_mul_f32_e32 v85, v84, v84
	v_pk_add_f32 v[130:131], v[132:133], v[84:85]
	s_nop 1
	v_mov_b32_dpp v132, v130 quad_perm:[1,0,3,2] row_mask:0xf bank_mask:0xf bound_ctrl:1
	v_mov_b32_dpp v133, v131 quad_perm:[1,0,3,2] row_mask:0xf bank_mask:0xf bound_ctrl:1
	v_pk_add_f32 v[130:131], v[130:131], v[132:133]
	s_nop 1
	v_mov_b32_dpp v132, v130 quad_perm:[2,3,0,1] row_mask:0xf bank_mask:0xf bound_ctrl:1
	v_mov_b32_dpp v133, v131 quad_perm:[2,3,0,1] row_mask:0xf bank_mask:0xf bound_ctrl:1
	v_pk_add_f32 v[130:131], v[130:131], v[132:133]
	s_nop 1
	v_mov_b32_dpp v132, v130 row_half_mirror row_mask:0xf bank_mask:0xf bound_ctrl:1
	v_mov_b32_dpp v133, v131 row_half_mirror row_mask:0xf bank_mask:0xf bound_ctrl:1
	v_pk_add_f32 v[130:131], v[130:131], v[132:133]
	s_nop 1
	v_mov_b32_dpp v132, v130 row_mirror row_mask:0xf bank_mask:0xf bound_ctrl:1
	v_mov_b32_dpp v133, v131 row_mirror row_mask:0xf bank_mask:0xf bound_ctrl:1
	s_and_saveexec_b64 s[6:7], vcc
	v_pk_add_f32 v[130:131], v[130:131], v[132:133]
	ds_write_b64 v181, v[130:131] offset:64
	s_or_b64 exec, exec, s[6:7]
	ds_read2_b32 v[130:131], v67 offset0:128 offset1:160
	ds_read2_b32 v[132:133], v67 offset0:192 offset1:224
	v_mov_b32_e32 v86, v119
	v_pk_add_f32 v[134:135], v[86:87], 0 op_sel_hi:[1,0]
	v_mov_b32_e32 v86, v103
	v_pk_add_f32 v[86:87], v[86:87], 0 op_sel_hi:[1,0]
	s_waitcnt lgkmcnt(1)
	v_mov_b32_e32 v102, v130
	s_waitcnt lgkmcnt(0)
	v_mov_b32_e32 v103, v132
	s_mov_b32 s2, s67
	v_mov_b32_e32 v118, v131
	v_mov_b32_e32 v119, v132
	v_pk_mul_f32 v[136:137], v[102:103], s[2:3] op_sel_hi:[1,0]
	v_pk_fma_f32 v[102:103], v[102:103], s[2:3], v[134:135] op_sel_hi:[1,0,1]
	v_pk_fma_f32 v[118:119], v[118:119], s[2:3], v[86:87] op_sel_hi:[1,0,1]
	v_pk_mul_f32 v[130:131], v[102:103], v[102:103]
	v_pk_mul_f32 v[86:87], v[118:119], v[118:119]
	v_pk_mov_b32 v[130:131], v[134:135], v[130:131] op_sel:[1,0]
	v_pk_mov_b32 v[86:87], v[136:137], v[86:87] op_sel:[1,0]
	v_add_f32_e32 v70, 0, v71
	v_pk_add_f32 v[86:87], v[130:131], v[86:87]
	v_pk_add_f32 v[130:131], v[102:103], v[118:119]
	v_pk_mul_f32 v[134:135], v[102:103], v[118:119]
	v_fmac_f32_e32 v70, 0x3fd744fd, v133
	v_mov_b32_e32 v131, v135
	v_pk_add_f32 v[86:87], v[130:131], v[86:87]
	v_mul_f32_e32 v71, v70, v70
	v_pk_add_f32 v[86:87], v[86:87], v[70:71]
	s_nop 1
	v_mov_b32_dpp v130, v86 quad_perm:[1,0,3,2] row_mask:0xf bank_mask:0xf bound_ctrl:1
	v_mov_b32_dpp v131, v87 quad_perm:[1,0,3,2] row_mask:0xf bank_mask:0xf bound_ctrl:1
	v_pk_add_f32 v[86:87], v[86:87], v[130:131]
	s_nop 1
	v_mov_b32_dpp v130, v86 quad_perm:[2,3,0,1] row_mask:0xf bank_mask:0xf bound_ctrl:1
	v_mov_b32_dpp v131, v87 quad_perm:[2,3,0,1] row_mask:0xf bank_mask:0xf bound_ctrl:1
	v_pk_add_f32 v[86:87], v[86:87], v[130:131]
	s_nop 1
	v_mov_b32_dpp v130, v86 row_half_mirror row_mask:0xf bank_mask:0xf bound_ctrl:1
	v_mov_b32_dpp v131, v87 row_half_mirror row_mask:0xf bank_mask:0xf bound_ctrl:1
	v_pk_add_f32 v[86:87], v[86:87], v[130:131]
	s_nop 1
	v_mov_b32_dpp v130, v86 row_mirror row_mask:0xf bank_mask:0xf bound_ctrl:1
	v_mov_b32_dpp v131, v87 row_mirror row_mask:0xf bank_mask:0xf bound_ctrl:1
	s_and_saveexec_b64 s[6:7], vcc
	v_pk_add_f32 v[86:87], v[86:87], v[130:131]
	ds_write_b64 v181, v[86:87] offset:72
	s_or_b64 exec, exec, s[6:7]
	v_add_u32_e32 v69, 0x1400, v168
	ds_read2_b32 v[130:131], v69 offset1:32
	ds_read2_b32 v[134:135], v69 offset0:64 offset1:96
	v_mov_b32_e32 v132, v120
	v_mov_b32_e32 v133, v88
	v_pk_add_f32 v[136:137], v[132:133], 0 op_sel_hi:[1,0]
	v_mov_b32_e32 v132, v104
	v_pk_add_f32 v[132:133], v[132:133], 0 op_sel_hi:[1,0]
	s_waitcnt lgkmcnt(1)
	v_mov_b32_e32 v140, v130
	s_waitcnt lgkmcnt(0)
	v_mov_b32_e32 v141, v134
	s_mov_b32 s2, s67
	v_mov_b32_e32 v144, v131
	v_mov_b32_e32 v145, v134
	v_pk_fma_f32 v[130:131], v[140:141], s[2:3], v[136:137] op_sel_hi:[1,0,1]
	v_pk_fma_f32 v[132:133], v[144:145], s[2:3], v[132:133] op_sel_hi:[1,0,1]
	v_pk_mul_f32 v[142:143], v[140:141], s[2:3] op_sel_hi:[1,0]
	v_pk_mul_f32 v[140:141], v[130:131], v[130:131]
	v_pk_mul_f32 v[144:145], v[132:133], v[132:133]
	v_pk_mov_b32 v[136:137], v[136:137], v[140:141] op_sel:[1,0]
	v_pk_mov_b32 v[140:141], v[142:143], v[144:145] op_sel:[1,0]
	v_add_f32_e32 v86, 0, v72
	v_pk_add_f32 v[136:137], v[136:137], v[140:141]
	v_pk_add_f32 v[140:141], v[130:131], v[132:133]
	v_pk_mul_f32 v[142:143], v[130:131], v[132:133]
	v_fmac_f32_e32 v86, 0x3fd744fd, v135
	v_mov_b32_e32 v141, v143
	v_pk_add_f32 v[136:137], v[140:141], v[136:137]
	v_mul_f32_e32 v87, v86, v86
	v_pk_add_f32 v[134:135], v[136:137], v[86:87]
	s_nop 1
	v_mov_b32_dpp v136, v134 quad_perm:[1,0,3,2] row_mask:0xf bank_mask:0xf bound_ctrl:1
	v_mov_b32_dpp v137, v135 quad_perm:[1,0,3,2] row_mask:0xf bank_mask:0xf bound_ctrl:1
	v_pk_add_f32 v[134:135], v[134:135], v[136:137]
	s_nop 1
	v_mov_b32_dpp v136, v134 quad_perm:[2,3,0,1] row_mask:0xf bank_mask:0xf bound_ctrl:1
	v_mov_b32_dpp v137, v135 quad_perm:[2,3,0,1] row_mask:0xf bank_mask:0xf bound_ctrl:1
	v_pk_add_f32 v[134:135], v[134:135], v[136:137]
	s_nop 1
	v_mov_b32_dpp v136, v134 row_half_mirror row_mask:0xf bank_mask:0xf bound_ctrl:1
	v_mov_b32_dpp v137, v135 row_half_mirror row_mask:0xf bank_mask:0xf bound_ctrl:1
	v_pk_add_f32 v[134:135], v[134:135], v[136:137]
	s_nop 1
	v_mov_b32_dpp v136, v134 row_mirror row_mask:0xf bank_mask:0xf bound_ctrl:1
	v_mov_b32_dpp v137, v135 row_mirror row_mask:0xf bank_mask:0xf bound_ctrl:1
	s_and_saveexec_b64 s[6:7], vcc
	v_pk_add_f32 v[134:135], v[134:135], v[136:137]
	ds_write_b64 v181, v[134:135] offset:80
	s_or_b64 exec, exec, s[6:7]
	v_or_b32_e32 v101, 0x1600, v139
	v_add_u32_e32 v71, v138, v101
	ds_read2_b32 v[134:135], v71 offset1:32
	ds_read2_b32 v[136:137], v71 offset0:64 offset1:96
	v_mov_b32_e32 v88, v121
	v_pk_add_f32 v[120:121], v[88:89], 0 op_sel_hi:[1,0]
	v_mov_b32_e32 v88, v105
	v_pk_add_f32 v[104:105], v[88:89], 0 op_sel_hi:[1,0]
	s_waitcnt lgkmcnt(1)
;   DI void xpass(int ps, int grow0, int gcol0, int lane, int w, char* lds) const {
;     char* xs = lds + (ps & 1) * 65536 + __builtin_amdgcn_readfirstlane(w) * 8192;
;     const float* xsrc = Xin + (size_t)(grow0 + (ps >> 1) * 32 + (ps & 1) * 16 + (lane >> 5)) * D_ + gcol0 + (lane & 31) * 4;
; #pragma unroll
;     for (int pc = 0; pc < 8; ++pc)
;       __builtin_amdgcn_global_load_lds((const unsigned*)(xsrc + (size_t)(2 * pc) * D_), (__attribute__((address_space(3))) unsigned*)(xs + pc * 1024), 16, 0, 0);
;   }
;   DI void operator()(f32x16 (&acc)[2][4], int grow0, int gcol0, int lane, int w, char* lds) {
;     ...
;     for (int ps = 0; ps < 4; ++ps) {
;       const int mt = ps >> 1;
;       if (ps + 1 < 4) {
;         if (ps >= 1) asm volatile("s_waitcnt lgkmcnt(0)" ::: "memory");
;         xpass(ps + 1, grow0, gcol0, lane, w, lds);
;         if (ps >= 1) asm volatile("s_waitcnt vmcnt(8)" ::: "memory");
;       } else asm volatile("s_waitcnt vmcnt(0)" ::: "memory");
;       const char* xs = lds + (ps & 1) * 65536 + w * 8192;
; #pragma unroll
;       for (int qq = 0; qq < 2; ++qq)
; #pragma unroll
;         for (int e = 0; e < 4; ++e) {
;           const int i = 4 * (2 * (ps & 1) + qq) + e;
;           const float* xr = (const float*)(xs + (8 * qq + 4 * hh + e) * 512) + l31;
;           float s1 = 0.f, s2 = 0.f;
; #pragma unroll
;           for (int nt = 0; nt < 4; ++nt) {
;             float v = (acc[mt][nt][i] + bia[nt]) * csc[nt];
;             float z = ALPHA * xr[nt * 32] + hs * v;
;             acc[mt][nt][i] = z; s1 += z; s2 += z * z;
;           }
;           s1 = row16_sum(s1); s2 = row16_sum(s2);
;           if ((lane & 15) == 0) { f32x2 sv = {s1, s2}; *(f32x2*)(redw + (mt * 32 + (i & 3) + 8 * (i >> 2)) * 2) = sv; }
;         }
	v_mov_b32_e32 v88, v134
	s_waitcnt lgkmcnt(0)
	v_mov_b32_e32 v89, v136
	s_mov_b32 s2, s67
	v_mov_b32_e32 v134, v135
	v_mov_b32_e32 v135, v136
	v_pk_mul_f32 v[140:141], v[88:89], s[2:3] op_sel_hi:[1,0]
	v_pk_fma_f32 v[88:89], v[88:89], s[2:3], v[120:121] op_sel_hi:[1,0,1]
	v_pk_fma_f32 v[104:105], v[134:135], s[2:3], v[104:105] op_sel_hi:[1,0,1]
	v_pk_mul_f32 v[142:143], v[88:89], v[88:89]
	v_pk_mul_f32 v[134:135], v[104:105], v[104:105]
	v_pk_mov_b32 v[120:121], v[120:121], v[142:143] op_sel:[1,0]
	v_pk_mov_b32 v[134:135], v[140:141], v[134:135] op_sel:[1,0]
	v_add_f32_e32 v72, 0, v73
	v_pk_add_f32 v[120:121], v[120:121], v[134:135]
	v_pk_add_f32 v[134:135], v[88:89], v[104:105]
	v_pk_mul_f32 v[140:141], v[88:89], v[104:105]
	v_fmac_f32_e32 v72, 0x3fd744fd, v137
	v_mov_b32_e32 v135, v141
	v_pk_add_f32 v[120:121], v[134:135], v[120:121]
	v_mul_f32_e32 v73, v72, v72
	v_pk_add_f32 v[120:121], v[120:121], v[72:73]
	s_nop 1
	v_mov_b32_dpp v134, v120 quad_perm:[1,0,3,2] row_mask:0xf bank_mask:0xf bound_ctrl:1
	v_mov_b32_dpp v135, v121 quad_perm:[1,0,3,2] row_mask:0xf bank_mask:0xf bound_ctrl:1
	v_pk_add_f32 v[120:121], v[120:121], v[134:135]
	s_nop 1
	v_mov_b32_dpp v134, v120 quad_perm:[2,3,0,1] row_mask:0xf bank_mask:0xf bound_ctrl:1
	v_mov_b32_dpp v135, v121 quad_perm:[2,3,0,1] row_mask:0xf bank_mask:0xf bound_ctrl:1
	v_pk_add_f32 v[120:121], v[120:121], v[134:135]
	s_nop 1
	v_mov_b32_dpp v134, v120 row_half_mirror row_mask:0xf bank_mask:0xf bound_ctrl:1
	v_mov_b32_dpp v135, v121 row_half_mirror row_mask:0xf bank_mask:0xf bound_ctrl:1
	v_pk_add_f32 v[120:121], v[120:121], v[134:135]
	s_nop 1
	v_mov_b32_dpp v134, v120 row_mirror row_mask:0xf bank_mask:0xf bound_ctrl:1
	v_mov_b32_dpp v135, v121 row_mirror row_mask:0xf bank_mask:0xf bound_ctrl:1
	s_and_saveexec_b64 s[6:7], vcc
	v_pk_add_f32 v[120:121], v[120:121], v[134:135]
	ds_write_b64 v181, v[120:121] offset:88
	s_or_b64 exec, exec, s[6:7]
	v_or_b32_e32 v120, 32, v159
	v_ashrrev_i32_e32 v121, 31, v120
	v_lshlrev_b64 v[120:121], 12, v[120:121]
	v_readfirstlane_b32 s2, v158
	v_lshl_add_u64 v[120:121], s[10:11], 0, v[120:121]
	s_lshl_b32 s2, s2, 13
	v_lshl_add_u64 v[120:121], v[184:185], 2, v[120:121]
	s_waitcnt lgkmcnt(0)
	v_lshl_add_u64 v[120:121], v[120:121], 0, v[0:1]
	s_mov_b32 m0, s2
	s_mov_b64 s[6:7], 0x2000
	global_load_lds_dwordx4 v[120:121], off
	v_lshl_add_u64 v[134:135], v[120:121], 0, s[6:7]
	s_or_b32 m0, s2, 0x400
	s_mov_b64 s[6:7], 0x4000
	global_load_lds_dwordx4 v[134:135], off
	v_lshl_add_u64 v[134:135], v[120:121], 0, s[6:7]
	s_or_b32 m0, s2, 0x800
	s_mov_b64 s[6:7], 0x6000
	global_load_lds_dwordx4 v[134:135], off
	v_lshl_add_u64 v[134:135], v[120:121], 0, s[6:7]
	s_or_b32 m0, s2, 0xc00
	s_mov_b64 s[6:7], 0x8000
	global_load_lds_dwordx4 v[134:135], off
	v_lshl_add_u64 v[134:135], v[120:121], 0, s[6:7]
	s_or_b32 m0, s2, 0x1000
	s_mov_b64 s[6:7], 0xa000
	global_load_lds_dwordx4 v[134:135], off
	v_lshl_add_u64 v[134:135], v[120:121], 0, s[6:7]
	s_or_b32 m0, s2, 0x1400
	s_mov_b64 s[6:7], 0xc000
	global_load_lds_dwordx4 v[134:135], off
	v_lshl_add_u64 v[134:135], v[120:121], 0, s[6:7]
	s_or_b32 m0, s2, 0x1800
	s_mov_b64 s[6:7], 0xe000
	global_load_lds_dwordx4 v[134:135], off
	v_lshl_add_u64 v[120:121], v[120:121], 0, s[6:7]
	s_or_b32 m0, s2, 0x1c00
	v_add_u32_e32 v105, 0x10000, v138
	global_load_lds_dwordx4 v[120:121], off
	s_waitcnt vmcnt(8)
	v_add_u32_e32 v73, v105, v154
	ds_read2_b32 v[134:135], v73 offset1:32
	ds_read2_b32 v[138:139], v73 offset0:64 offset1:96
	v_mov_b32_e32 v136, v122
	v_mov_b32_e32 v137, v90
	v_pk_add_f32 v[140:141], v[136:137], 0 op_sel_hi:[1,0]
	v_mov_b32_e32 v136, v106
	v_pk_add_f32 v[136:137], v[136:137], 0 op_sel_hi:[1,0]
	s_waitcnt lgkmcnt(0)
	v_mov_b32_e32 v142, v134
	v_mov_b32_e32 v143, v138
	s_mov_b32 s2, s67
	v_mov_b32_e32 v148, v135
	v_mov_b32_e32 v149, v138
	v_pk_fma_f32 v[134:135], v[142:143], s[2:3], v[140:141] op_sel_hi:[1,0,1]
	v_pk_fma_f32 v[136:137], v[148:149], s[2:3], v[136:137] op_sel_hi:[1,0,1]
	v_pk_mul_f32 v[144:145], v[142:143], s[2:3] op_sel_hi:[1,0]
	v_pk_mul_f32 v[142:143], v[134:135], v[134:135]
	v_pk_mul_f32 v[148:149], v[136:137], v[136:137]
	v_pk_mov_b32 v[140:141], v[140:141], v[142:143] op_sel:[1,0]
	v_pk_mov_b32 v[142:143], v[144:145], v[148:149] op_sel:[1,0]
	v_add_f32_e32 v120, 0, v74
	v_pk_add_f32 v[140:141], v[140:141], v[142:143]
	v_pk_add_f32 v[142:143], v[134:135], v[136:137]
	v_pk_mul_f32 v[144:145], v[134:135], v[136:137]
	v_fmac_f32_e32 v120, 0x3fd744fd, v139
	v_mov_b32_e32 v143, v145
	v_pk_add_f32 v[140:141], v[142:143], v[140:141]
	v_mul_f32_e32 v121, v120, v120
	v_pk_add_f32 v[138:139], v[140:141], v[120:121]
	s_nop 1
	v_mov_b32_dpp v140, v138 quad_perm:[1,0,3,2] row_mask:0xf bank_mask:0xf bound_ctrl:1
	v_mov_b32_dpp v141, v139 quad_perm:[1,0,3,2] row_mask:0xf bank_mask:0xf bound_ctrl:1
	v_pk_add_f32 v[138:139], v[138:139], v[140:141]
	s_nop 1
	v_mov_b32_dpp v140, v138 quad_perm:[2,3,0,1] row_mask:0xf bank_mask:0xf bound_ctrl:1
	v_mov_b32_dpp v141, v139 quad_perm:[2,3,0,1] row_mask:0xf bank_mask:0xf bound_ctrl:1
	v_pk_add_f32 v[138:139], v[138:139], v[140:141]
	s_nop 1
	v_mov_b32_dpp v140, v138 row_half_mirror row_mask:0xf bank_mask:0xf bound_ctrl:1
	v_mov_b32_dpp v141, v139 row_half_mirror row_mask:0xf bank_mask:0xf bound_ctrl:1
	v_pk_add_f32 v[138:139], v[138:139], v[140:141]
	s_nop 1
	v_mov_b32_dpp v140, v138 row_mirror row_mask:0xf bank_mask:0xf bound_ctrl:1
	v_mov_b32_dpp v141, v139 row_mirror row_mask:0xf bank_mask:0xf bound_ctrl:1
	s_and_saveexec_b64 s[6:7], vcc
	v_pk_add_f32 v[138:139], v[138:139], v[140:141]
	ds_write_b64 v181, v[138:139] offset:128
	s_or_b64 exec, exec, s[6:7]
	v_or_b32_e32 v74, 0x200, v154
	v_add_u32_e32 v85, v105, v74
	ds_read2_b32 v[138:139], v85 offset1:32
	ds_read2_b32 v[140:141], v85 offset0:64 offset1:96
	v_mov_b32_e32 v90, v123
	v_pk_add_f32 v[142:143], v[90:91], 0 op_sel_hi:[1,0]
	v_mov_b32_e32 v90, v107
	v_pk_add_f32 v[90:91], v[90:91], 0 op_sel_hi:[1,0]
	s_waitcnt lgkmcnt(1)
;   DI void operator()(f32x16 (&acc)[2][4], int grow0, int gcol0, int lane, int w, char* lds) {
;     ...
; #pragma unroll
;       for (int qq = 0; qq < 2; ++qq)
; #pragma unroll
;         for (int e = 0; e < 4; ++e) {
;           const int i = 4 * (2 * (ps & 1) + qq) + e;
;           const float* xr = (const float*)(xs + (8 * qq + 4 * hh + e) * 512) + l31;
;           float s1 = 0.f, s2 = 0.f;
; #pragma unroll
;           for (int nt = 0; nt < 4; ++nt) {
;             float v = (acc[mt][nt][i] + bia[nt]) * csc[nt];
;             float z = ALPHA * xr[nt * 32] + hs * v;
;             acc[mt][nt][i] = z; s1 += z; s2 += z * z;
;           }
;           s1 = row16_sum(s1); s2 = row16_sum(s2);
;           if ((lane & 15) == 0) { f32x2 sv = {s1, s2}; *(f32x2*)(redw + (mt * 32 + (i & 3) + 8 * (i >> 2)) * 2) = sv; }
;         }
	v_mov_b32_e32 v106, v138
	s_waitcnt lgkmcnt(0)
	v_mov_b32_e32 v107, v140
	s_mov_b32 s2, s67
	v_mov_b32_e32 v122, v139
	v_mov_b32_e32 v123, v140
	v_pk_mul_f32 v[144:145], v[106:107], s[2:3] op_sel_hi:[1,0]
	v_pk_fma_f32 v[106:107], v[106:107], s[2:3], v[142:143] op_sel_hi:[1,0,1]
	v_pk_fma_f32 v[122:123], v[122:123], s[2:3], v[90:91] op_sel_hi:[1,0,1]
	v_pk_mul_f32 v[138:139], v[106:107], v[106:107]
	v_pk_mul_f32 v[90:91], v[122:123], v[122:123]
	v_pk_mov_b32 v[138:139], v[142:143], v[138:139] op_sel:[1,0]
	v_pk_mov_b32 v[90:91], v[144:145], v[90:91] op_sel:[1,0]
	v_add_f32_e32 v74, 0, v75
	v_pk_add_f32 v[90:91], v[138:139], v[90:91]
	v_pk_add_f32 v[138:139], v[106:107], v[122:123]
	v_pk_mul_f32 v[142:143], v[106:107], v[122:123]
	v_fmac_f32_e32 v74, 0x3fd744fd, v141
	v_mov_b32_e32 v139, v143
	v_pk_add_f32 v[90:91], v[138:139], v[90:91]
	v_mul_f32_e32 v75, v74, v74
	v_pk_add_f32 v[90:91], v[90:91], v[74:75]
	s_nop 1
	v_mov_b32_dpp v138, v90 quad_perm:[1,0,3,2] row_mask:0xf bank_mask:0xf bound_ctrl:1
	v_mov_b32_dpp v139, v91 quad_perm:[1,0,3,2] row_mask:0xf bank_mask:0xf bound_ctrl:1
	v_pk_add_f32 v[90:91], v[90:91], v[138:139]
	s_nop 1
	v_mov_b32_dpp v138, v90 quad_perm:[2,3,0,1] row_mask:0xf bank_mask:0xf bound_ctrl:1
	v_mov_b32_dpp v139, v91 quad_perm:[2,3,0,1] row_mask:0xf bank_mask:0xf bound_ctrl:1
	v_pk_add_f32 v[90:91], v[90:91], v[138:139]
	s_nop 1
	v_mov_b32_dpp v138, v90 row_half_mirror row_mask:0xf bank_mask:0xf bound_ctrl:1
	v_mov_b32_dpp v139, v91 row_half_mirror row_mask:0xf bank_mask:0xf bound_ctrl:1
	v_pk_add_f32 v[90:91], v[90:91], v[138:139]
	s_nop 1
	v_mov_b32_dpp v138, v90 row_mirror row_mask:0xf bank_mask:0xf bound_ctrl:1
	v_mov_b32_dpp v139, v91 row_mirror row_mask:0xf bank_mask:0xf bound_ctrl:1
	s_and_saveexec_b64 s[6:7], vcc
	v_pk_add_f32 v[90:91], v[90:91], v[138:139]
	ds_write_b64 v181, v[90:91] offset:136
	s_or_b64 exec, exec, s[6:7]
	v_or_b32_e32 v75, 0x400, v154
	v_add_u32_e32 v75, v105, v75
	ds_read2_b32 v[138:139], v75 offset1:32
	ds_read2_b32 v[142:143], v75 offset0:64 offset1:96
	v_mov_b32_e32 v140, v124
	v_mov_b32_e32 v141, v92
	v_pk_add_f32 v[144:145], v[140:141], 0 op_sel_hi:[1,0]
	v_mov_b32_e32 v140, v108
	v_pk_add_f32 v[140:141], v[140:141], 0 op_sel_hi:[1,0]
	s_waitcnt lgkmcnt(1)
	v_mov_b32_e32 v148, v138
	s_waitcnt lgkmcnt(0)
	v_mov_b32_e32 v149, v142
	s_mov_b32 s2, s67
	v_mov_b32_e32 v160, v139
	v_mov_b32_e32 v161, v142
	v_pk_fma_f32 v[138:139], v[148:149], s[2:3], v[144:145] op_sel_hi:[1,0,1]
	v_pk_fma_f32 v[140:141], v[160:161], s[2:3], v[140:141] op_sel_hi:[1,0,1]
	v_pk_mul_f32 v[156:157], v[148:149], s[2:3] op_sel_hi:[1,0]
	v_pk_mul_f32 v[148:149], v[138:139], v[138:139]
	v_pk_mul_f32 v[160:161], v[140:141], v[140:141]
	v_pk_mov_b32 v[144:145], v[144:145], v[148:149] op_sel:[1,0]
	v_pk_mov_b32 v[148:149], v[156:157], v[160:161] op_sel:[1,0]
	v_add_f32_e32 v90, 0, v76
	v_pk_add_f32 v[144:145], v[144:145], v[148:149]
	v_pk_add_f32 v[148:149], v[138:139], v[140:141]
	v_pk_mul_f32 v[156:157], v[138:139], v[140:141]
	v_fmac_f32_e32 v90, 0x3fd744fd, v143
	v_mov_b32_e32 v149, v157
	v_pk_add_f32 v[144:145], v[148:149], v[144:145]
	v_mul_f32_e32 v91, v90, v90
	v_pk_add_f32 v[142:143], v[144:145], v[90:91]
	s_nop 1
	v_mov_b32_dpp v144, v142 quad_perm:[1,0,3,2] row_mask:0xf bank_mask:0xf bound_ctrl:1
	v_mov_b32_dpp v145, v143 quad_perm:[1,0,3,2] row_mask:0xf bank_mask:0xf bound_ctrl:1
	v_pk_add_f32 v[142:143], v[142:143], v[144:145]
	s_nop 1
	v_mov_b32_dpp v144, v142 quad_perm:[2,3,0,1] row_mask:0xf bank_mask:0xf bound_ctrl:1
	v_mov_b32_dpp v145, v143 quad_perm:[2,3,0,1] row_mask:0xf bank_mask:0xf bound_ctrl:1
	v_pk_add_f32 v[142:143], v[142:143], v[144:145]
	s_nop 1
	v_mov_b32_dpp v144, v142 row_half_mirror row_mask:0xf bank_mask:0xf bound_ctrl:1
	v_mov_b32_dpp v145, v143 row_half_mirror row_mask:0xf bank_mask:0xf bound_ctrl:1
	v_pk_add_f32 v[142:143], v[142:143], v[144:145]
	s_nop 1
	v_mov_b32_dpp v144, v142 row_mirror row_mask:0xf bank_mask:0xf bound_ctrl:1
	v_mov_b32_dpp v145, v143 row_mirror row_mask:0xf bank_mask:0xf bound_ctrl:1
	s_and_saveexec_b64 s[6:7], vcc
	v_pk_add_f32 v[142:143], v[142:143], v[144:145]
	ds_write_b64 v181, v[142:143] offset:144
	s_or_b64 exec, exec, s[6:7]
	v_add_u32_e32 v87, v105, v146
	ds_read2_b32 v[142:143], v87 offset1:32
	ds_read2_b32 v[144:145], v87 offset0:64 offset1:96
	v_mov_b32_e32 v92, v125
	v_pk_add_f32 v[146:147], v[92:93], 0 op_sel_hi:[1,0]
	v_mov_b32_e32 v92, v109
	v_pk_add_f32 v[92:93], v[92:93], 0 op_sel_hi:[1,0]
	s_waitcnt lgkmcnt(1)
	v_mov_b32_e32 v108, v142
	s_waitcnt lgkmcnt(0)
; template <int CTRL> DI float dpp_f(float v) { return __int_as_float(__builtin_amdgcn_update_dpp(0, __float_as_int(v), CTRL, 0xF, 0xF, true)); }
; DI float row16_sum(float v) {
;   v += dpp_f<0xB1>(v);
;   v += dpp_f<0x4E>(v);
;   v += dpp_f<0x141>(v);
;   v += dpp_f<0x140>(v);
;   return v;
; }
;   DI void operator()(f32x16 (&acc)[2][4], int grow0, int gcol0, int lane, int w, char* lds) {
;     ...
;     for (int ps = 0; ps < 4; ++ps) {
;       const int mt = ps >> 1;
;       if (ps + 1 < 4) {
;         if (ps >= 1) asm volatile("s_waitcnt lgkmcnt(0)" ::: "memory");
;         xpass(ps + 1, grow0, gcol0, lane, w, lds);
;         if (ps >= 1) asm volatile("s_waitcnt vmcnt(8)" ::: "memory");
;       } else asm volatile("s_waitcnt vmcnt(0)" ::: "memory");
;       const char* xs = lds + (ps & 1) * 65536 + w * 8192;
; #pragma unroll
;       for (int qq = 0; qq < 2; ++qq)
; #pragma unroll
;         for (int e = 0; e < 4; ++e) {
;           const int i = 4 * (2 * (ps & 1) + qq) + e;
;           const float* xr = (const float*)(xs + (8 * qq + 4 * hh + e) * 512) + l31;
;           float s1 = 0.f, s2 = 0.f;
; #pragma unroll
;           for (int nt = 0; nt < 4; ++nt) {
;             float v = (acc[mt][nt][i] + bia[nt]) * csc[nt];
;             float z = ALPHA * xr[nt * 32] + hs * v;
;             acc[mt][nt][i] = z; s1 += z; s2 += z * z;
;           }
;           s1 = row16_sum(s1); s2 = row16_sum(s2);
;           if ((lane & 15) == 0) { f32x2 sv = {s1, s2}; *(f32x2*)(redw + (mt * 32 + (i & 3) + 8 * (i >> 2)) * 2) = sv; }
;         }
	v_mov_b32_e32 v109, v144
	s_mov_b32 s2, s67
	v_mov_b32_e32 v124, v143
	v_mov_b32_e32 v125, v144
	v_pk_mul_f32 v[148:149], v[108:109], s[2:3] op_sel_hi:[1,0]
	v_pk_fma_f32 v[108:109], v[108:109], s[2:3], v[146:147] op_sel_hi:[1,0,1]
	v_pk_fma_f32 v[124:125], v[124:125], s[2:3], v[92:93] op_sel_hi:[1,0,1]
	v_pk_mul_f32 v[142:143], v[108:109], v[108:109]
	v_pk_mul_f32 v[92:93], v[124:125], v[124:125]
	v_pk_mov_b32 v[142:143], v[146:147], v[142:143] op_sel:[1,0]
	v_pk_mov_b32 v[92:93], v[148:149], v[92:93] op_sel:[1,0]
	v_add_f32_e32 v76, 0, v77
	v_pk_add_f32 v[92:93], v[142:143], v[92:93]
	v_pk_add_f32 v[142:143], v[108:109], v[124:125]
	v_pk_mul_f32 v[146:147], v[108:109], v[124:125]
	v_fmac_f32_e32 v76, 0x3fd744fd, v145
	v_mov_b32_e32 v143, v147
	v_pk_add_f32 v[92:93], v[142:143], v[92:93]
	v_mul_f32_e32 v77, v76, v76
	v_pk_add_f32 v[92:93], v[92:93], v[76:77]
	s_nop 1
	v_mov_b32_dpp v142, v92 quad_perm:[1,0,3,2] row_mask:0xf bank_mask:0xf bound_ctrl:1
	v_mov_b32_dpp v143, v93 quad_perm:[1,0,3,2] row_mask:0xf bank_mask:0xf bound_ctrl:1
	v_pk_add_f32 v[92:93], v[92:93], v[142:143]
	s_nop 1
	v_mov_b32_dpp v142, v92 quad_perm:[2,3,0,1] row_mask:0xf bank_mask:0xf bound_ctrl:1
	v_mov_b32_dpp v143, v93 quad_perm:[2,3,0,1] row_mask:0xf bank_mask:0xf bound_ctrl:1
	v_pk_add_f32 v[92:93], v[92:93], v[142:143]
	s_nop 1
	v_mov_b32_dpp v142, v92 row_half_mirror row_mask:0xf bank_mask:0xf bound_ctrl:1
	v_mov_b32_dpp v143, v93 row_half_mirror row_mask:0xf bank_mask:0xf bound_ctrl:1
	v_pk_add_f32 v[92:93], v[92:93], v[142:143]
	s_nop 1
	v_mov_b32_dpp v142, v92 row_mirror row_mask:0xf bank_mask:0xf bound_ctrl:1
	v_mov_b32_dpp v143, v93 row_mirror row_mask:0xf bank_mask:0xf bound_ctrl:1
	s_and_saveexec_b64 s[6:7], vcc
	v_pk_add_f32 v[92:93], v[92:93], v[142:143]
	ds_write_b64 v181, v[92:93] offset:152
	s_or_b64 exec, exec, s[6:7]
	v_or_b32_e32 v77, 0x1000, v154
	v_add_u32_e32 v77, v105, v77
	ds_read2_b32 v[142:143], v77 offset1:32
	ds_read2_b32 v[146:147], v77 offset0:64 offset1:96
	v_mov_b32_e32 v144, v126
	v_mov_b32_e32 v145, v94
	v_pk_add_f32 v[148:149], v[144:145], 0 op_sel_hi:[1,0]
	v_mov_b32_e32 v144, v110
	v_pk_add_f32 v[144:145], v[144:145], 0 op_sel_hi:[1,0]
	s_waitcnt lgkmcnt(1)
	v_mov_b32_e32 v156, v142
	s_waitcnt lgkmcnt(0)
	v_mov_b32_e32 v157, v146
	s_mov_b32 s2, s67
	v_mov_b32_e32 v170, v143
	v_mov_b32_e32 v171, v146
	v_pk_fma_f32 v[142:143], v[156:157], s[2:3], v[148:149] op_sel_hi:[1,0,1]
	v_pk_fma_f32 v[144:145], v[170:171], s[2:3], v[144:145] op_sel_hi:[1,0,1]
	v_pk_mul_f32 v[160:161], v[156:157], s[2:3] op_sel_hi:[1,0]
	v_pk_mul_f32 v[156:157], v[142:143], v[142:143]
	v_pk_mul_f32 v[170:171], v[144:145], v[144:145]
	v_pk_mov_b32 v[148:149], v[148:149], v[156:157] op_sel:[1,0]
	v_pk_mov_b32 v[156:157], v[160:161], v[170:171] op_sel:[1,0]
	v_add_f32_e32 v92, 0, v78
	v_pk_add_f32 v[148:149], v[148:149], v[156:157]
	v_pk_add_f32 v[156:157], v[142:143], v[144:145]
	v_pk_mul_f32 v[160:161], v[142:143], v[144:145]
	v_fmac_f32_e32 v92, 0x3fd744fd, v147
	v_mov_b32_e32 v157, v161
	v_pk_add_f32 v[148:149], v[156:157], v[148:149]
	v_mul_f32_e32 v93, v92, v92
	v_pk_add_f32 v[146:147], v[148:149], v[92:93]
	s_nop 1
	v_mov_b32_dpp v148, v146 quad_perm:[1,0,3,2] row_mask:0xf bank_mask:0xf bound_ctrl:1
	v_mov_b32_dpp v149, v147 quad_perm:[1,0,3,2] row_mask:0xf bank_mask:0xf bound_ctrl:1
	v_pk_add_f32 v[146:147], v[146:147], v[148:149]
	s_nop 1
	v_mov_b32_dpp v148, v146 quad_perm:[2,3,0,1] row_mask:0xf bank_mask:0xf bound_ctrl:1
	v_mov_b32_dpp v149, v147 quad_perm:[2,3,0,1] row_mask:0xf bank_mask:0xf bound_ctrl:1
	v_pk_add_f32 v[146:147], v[146:147], v[148:149]
	s_nop 1
	v_mov_b32_dpp v148, v146 row_half_mirror row_mask:0xf bank_mask:0xf bound_ctrl:1
	v_mov_b32_dpp v149, v147 row_half_mirror row_mask:0xf bank_mask:0xf bound_ctrl:1
	v_pk_add_f32 v[146:147], v[146:147], v[148:149]
	s_nop 1
	v_mov_b32_dpp v148, v146 row_mirror row_mask:0xf bank_mask:0xf bound_ctrl:1
	v_mov_b32_dpp v149, v147 row_mirror row_mask:0xf bank_mask:0xf bound_ctrl:1
	s_and_saveexec_b64 s[6:7], vcc
	v_pk_add_f32 v[146:147], v[146:147], v[148:149]
	ds_write_b64 v181, v[146:147] offset:192
	s_or_b64 exec, exec, s[6:7]
	v_or_b32_e32 v78, 0x1200, v154
	v_add_u32_e32 v91, v105, v78
	ds_read2_b32 v[146:147], v91 offset1:32
	ds_read2_b32 v[148:149], v91 offset0:64 offset1:96
	v_mov_b32_e32 v94, v127
	v_pk_add_f32 v[156:157], v[94:95], 0 op_sel_hi:[1,0]
	v_mov_b32_e32 v94, v111
	v_pk_add_f32 v[94:95], v[94:95], 0 op_sel_hi:[1,0]
	s_waitcnt lgkmcnt(1)
	v_mov_b32_e32 v110, v146
	s_waitcnt lgkmcnt(0)
	v_mov_b32_e32 v111, v148
	s_mov_b32 s2, s67
	v_mov_b32_e32 v126, v147
	v_mov_b32_e32 v127, v148
	v_pk_mul_f32 v[160:161], v[110:111], s[2:3] op_sel_hi:[1,0]
	v_pk_fma_f32 v[110:111], v[110:111], s[2:3], v[156:157] op_sel_hi:[1,0,1]
	v_pk_fma_f32 v[126:127], v[126:127], s[2:3], v[94:95] op_sel_hi:[1,0,1]
	v_pk_mul_f32 v[146:147], v[110:111], v[110:111]
	v_pk_mul_f32 v[94:95], v[126:127], v[126:127]
	v_pk_mov_b32 v[146:147], v[156:157], v[146:147] op_sel:[1,0]
	v_pk_mov_b32 v[94:95], v[160:161], v[94:95] op_sel:[1,0]
	v_add_f32_e32 v78, 0, v79
	v_pk_add_f32 v[94:95], v[146:147], v[94:95]
	v_pk_add_f32 v[146:147], v[110:111], v[126:127]
	v_pk_mul_f32 v[156:157], v[110:111], v[126:127]
	v_fmac_f32_e32 v78, 0x3fd744fd, v149
	v_mov_b32_e32 v147, v157
	v_pk_add_f32 v[94:95], v[146:147], v[94:95]
	v_mul_f32_e32 v79, v78, v78
	v_pk_add_f32 v[94:95], v[94:95], v[78:79]
	s_nop 1
	v_mov_b32_dpp v146, v94 quad_perm:[1,0,3,2] row_mask:0xf bank_mask:0xf bound_ctrl:1
	v_mov_b32_dpp v147, v95 quad_perm:[1,0,3,2] row_mask:0xf bank_mask:0xf bound_ctrl:1
	v_pk_add_f32 v[94:95], v[94:95], v[146:147]
	s_nop 1
	v_mov_b32_dpp v146, v94 quad_perm:[2,3,0,1] row_mask:0xf bank_mask:0xf bound_ctrl:1
	v_mov_b32_dpp v147, v95 quad_perm:[2,3,0,1] row_mask:0xf bank_mask:0xf bound_ctrl:1
	v_pk_add_f32 v[94:95], v[94:95], v[146:147]
	s_nop 1
	v_mov_b32_dpp v146, v94 row_half_mirror row_mask:0xf bank_mask:0xf bound_ctrl:1
	v_mov_b32_dpp v147, v95 row_half_mirror row_mask:0xf bank_mask:0xf bound_ctrl:1
	v_pk_add_f32 v[94:95], v[94:95], v[146:147]
	s_nop 1
	v_mov_b32_dpp v146, v94 row_mirror row_mask:0xf bank_mask:0xf bound_ctrl:1
	v_mov_b32_dpp v147, v95 row_mirror row_mask:0xf bank_mask:0xf bound_ctrl:1
	s_and_saveexec_b64 s[6:7], vcc
	v_pk_add_f32 v[94:95], v[94:95], v[146:147]
	ds_write_b64 v181, v[94:95] offset:200
	s_or_b64 exec, exec, s[6:7]
	v_or_b32_e32 v79, 0x1400, v154
	v_add_u32_e32 v79, v105, v79
	ds_read2_b32 v[146:147], v79 offset1:32
	ds_read2_b32 v[154:155], v79 offset0:64 offset1:96
	v_mov_b32_e32 v148, v128
	v_mov_b32_e32 v149, v96
	v_pk_add_f32 v[156:157], v[148:149], 0 op_sel_hi:[1,0]
	v_mov_b32_e32 v148, v112
	v_pk_add_f32 v[148:149], v[148:149], 0 op_sel_hi:[1,0]
	s_waitcnt lgkmcnt(1)
;   DI void xpass(int ps, int grow0, int gcol0, int lane, int w, char* lds) const {
;     char* xs = lds + (ps & 1) * 65536 + __builtin_amdgcn_readfirstlane(w) * 8192;
;     const float* xsrc = Xin + (size_t)(grow0 + (ps >> 1) * 32 + (ps & 1) * 16 + (lane >> 5)) * D_ + gcol0 + (lane & 31) * 4;
; #pragma unroll
;     for (int pc = 0; pc < 8; ++pc)
;       __builtin_amdgcn_global_load_lds((const unsigned*)(xsrc + (size_t)(2 * pc) * D_), (__attribute__((address_space(3))) unsigned*)(xs + pc * 1024), 16, 0, 0);
;   }
;   DI void operator()(f32x16 (&acc)[2][4], int grow0, int gcol0, int lane, int w, char* lds) {
;     ...
;     for (int ps = 0; ps < 4; ++ps) {
;       const int mt = ps >> 1;
;       if (ps + 1 < 4) {
;         if (ps >= 1) asm volatile("s_waitcnt lgkmcnt(0)" ::: "memory");
;         xpass(ps + 1, grow0, gcol0, lane, w, lds);
;         if (ps >= 1) asm volatile("s_waitcnt vmcnt(8)" ::: "memory");
;       } else asm volatile("s_waitcnt vmcnt(0)" ::: "memory");
;       const char* xs = lds + (ps & 1) * 65536 + w * 8192;
; #pragma unroll
;       for (int qq = 0; qq < 2; ++qq)
; #pragma unroll
;         for (int e = 0; e < 4; ++e) {
;           const int i = 4 * (2 * (ps & 1) + qq) + e;
;           const float* xr = (const float*)(xs + (8 * qq + 4 * hh + e) * 512) + l31;
;           float s1 = 0.f, s2 = 0.f;
; #pragma unroll
;           for (int nt = 0; nt < 4; ++nt) {
;             float v = (acc[mt][nt][i] + bia[nt]) * csc[nt];
;             float z = ALPHA * xr[nt * 32] + hs * v;
;             acc[mt][nt][i] = z; s1 += z; s2 += z * z;
;           }
;           s1 = row16_sum(s1); s2 = row16_sum(s2);
;           if ((lane & 15) == 0) { f32x2 sv = {s1, s2}; *(f32x2*)(redw + (mt * 32 + (i & 3) + 8 * (i >> 2)) * 2) = sv; }
;         }
	v_mov_b32_e32 v160, v146
	s_waitcnt lgkmcnt(0)
	v_mov_b32_e32 v161, v154
	s_mov_b32 s2, s67
	v_mov_b32_e32 v174, v147
	v_mov_b32_e32 v175, v154
	v_pk_fma_f32 v[146:147], v[160:161], s[2:3], v[156:157] op_sel_hi:[1,0,1]
	v_pk_fma_f32 v[148:149], v[174:175], s[2:3], v[148:149] op_sel_hi:[1,0,1]
	v_pk_mul_f32 v[170:171], v[160:161], s[2:3] op_sel_hi:[1,0]
	v_pk_mul_f32 v[160:161], v[146:147], v[146:147]
	v_pk_mul_f32 v[174:175], v[148:149], v[148:149]
	v_pk_mov_b32 v[156:157], v[156:157], v[160:161] op_sel:[1,0]
	v_pk_mov_b32 v[160:161], v[170:171], v[174:175] op_sel:[1,0]
	v_add_f32_e32 v94, 0, v80
	v_pk_add_f32 v[156:157], v[156:157], v[160:161]
	v_pk_add_f32 v[160:161], v[146:147], v[148:149]
	v_pk_mul_f32 v[170:171], v[146:147], v[148:149]
	v_fmac_f32_e32 v94, 0x3fd744fd, v155
	v_mov_b32_e32 v161, v171
	v_pk_add_f32 v[156:157], v[160:161], v[156:157]
	v_mul_f32_e32 v95, v94, v94
	v_pk_add_f32 v[154:155], v[156:157], v[94:95]
	s_nop 1
	v_mov_b32_dpp v156, v154 quad_perm:[1,0,3,2] row_mask:0xf bank_mask:0xf bound_ctrl:1
	v_mov_b32_dpp v157, v155 quad_perm:[1,0,3,2] row_mask:0xf bank_mask:0xf bound_ctrl:1
	v_pk_add_f32 v[154:155], v[154:155], v[156:157]
	s_nop 1
	v_mov_b32_dpp v156, v154 quad_perm:[2,3,0,1] row_mask:0xf bank_mask:0xf bound_ctrl:1
	v_mov_b32_dpp v157, v155 quad_perm:[2,3,0,1] row_mask:0xf bank_mask:0xf bound_ctrl:1
	v_pk_add_f32 v[154:155], v[154:155], v[156:157]
	s_nop 1
	v_mov_b32_dpp v156, v154 row_half_mirror row_mask:0xf bank_mask:0xf bound_ctrl:1
	v_mov_b32_dpp v157, v155 row_half_mirror row_mask:0xf bank_mask:0xf bound_ctrl:1
	v_pk_add_f32 v[154:155], v[154:155], v[156:157]
	s_nop 1
	v_mov_b32_dpp v156, v154 row_mirror row_mask:0xf bank_mask:0xf bound_ctrl:1
	v_mov_b32_dpp v157, v155 row_mirror row_mask:0xf bank_mask:0xf bound_ctrl:1
	s_and_saveexec_b64 s[6:7], vcc
	v_pk_add_f32 v[154:155], v[154:155], v[156:157]
	ds_write_b64 v181, v[154:155] offset:208
	s_or_b64 exec, exec, s[6:7]
	v_add_u32_e32 v93, v105, v101
	ds_read2_b32 v[154:155], v93 offset1:32
	ds_read2_b32 v[156:157], v93 offset0:64 offset1:96
	v_mov_b32_e32 v96, v129
	v_pk_add_f32 v[128:129], v[96:97], 0 op_sel_hi:[1,0]
	v_mov_b32_e32 v96, v113
	v_pk_add_f32 v[112:113], v[96:97], 0 op_sel_hi:[1,0]
	s_waitcnt lgkmcnt(1)
	v_mov_b32_e32 v96, v154
	s_waitcnt lgkmcnt(0)
	v_mov_b32_e32 v97, v156
	s_mov_b32 s2, s67
	v_mov_b32_e32 v154, v155
	v_mov_b32_e32 v155, v156
	v_pk_mul_f32 v[160:161], v[96:97], s[2:3] op_sel_hi:[1,0]
	v_pk_fma_f32 v[96:97], v[96:97], s[2:3], v[128:129] op_sel_hi:[1,0,1]
	v_pk_fma_f32 v[112:113], v[154:155], s[2:3], v[112:113] op_sel_hi:[1,0,1]
	v_pk_mul_f32 v[170:171], v[96:97], v[96:97]
	v_pk_mul_f32 v[154:155], v[112:113], v[112:113]
	v_pk_mov_b32 v[128:129], v[128:129], v[170:171] op_sel:[1,0]
	v_pk_mov_b32 v[154:155], v[160:161], v[154:155] op_sel:[1,0]
	v_add_f32_e32 v80, 0, v81
	v_pk_add_f32 v[128:129], v[128:129], v[154:155]
	v_pk_add_f32 v[154:155], v[96:97], v[112:113]
	v_pk_mul_f32 v[160:161], v[96:97], v[112:113]
	v_fmac_f32_e32 v80, 0x3fd744fd, v157
	v_mov_b32_e32 v155, v161
	v_pk_add_f32 v[128:129], v[154:155], v[128:129]
	v_mul_f32_e32 v81, v80, v80
	v_pk_add_f32 v[128:129], v[128:129], v[80:81]
	s_nop 1
	v_mov_b32_dpp v154, v128 quad_perm:[1,0,3,2] row_mask:0xf bank_mask:0xf bound_ctrl:1
	v_mov_b32_dpp v155, v129 quad_perm:[1,0,3,2] row_mask:0xf bank_mask:0xf bound_ctrl:1
	v_pk_add_f32 v[128:129], v[128:129], v[154:155]
	s_nop 1
	v_mov_b32_dpp v154, v128 quad_perm:[2,3,0,1] row_mask:0xf bank_mask:0xf bound_ctrl:1
	v_mov_b32_dpp v155, v129 quad_perm:[2,3,0,1] row_mask:0xf bank_mask:0xf bound_ctrl:1
	v_pk_add_f32 v[128:129], v[128:129], v[154:155]
	s_nop 1
	v_mov_b32_dpp v154, v128 row_half_mirror row_mask:0xf bank_mask:0xf bound_ctrl:1
	v_mov_b32_dpp v155, v129 row_half_mirror row_mask:0xf bank_mask:0xf bound_ctrl:1
	v_pk_add_f32 v[128:129], v[128:129], v[154:155]
	s_nop 1
	v_mov_b32_dpp v154, v128 row_mirror row_mask:0xf bank_mask:0xf bound_ctrl:1
	v_mov_b32_dpp v155, v129 row_mirror row_mask:0xf bank_mask:0xf bound_ctrl:1
	s_and_saveexec_b64 s[6:7], vcc
	v_pk_add_f32 v[128:129], v[128:129], v[154:155]
	ds_write_b64 v181, v[128:129] offset:216
	s_or_b64 exec, exec, s[6:7]
	v_or_b32_e32 v128, 48, v159
	v_ashrrev_i32_e32 v129, 31, v128
	v_lshlrev_b64 v[128:129], 12, v[128:129]
	v_readfirstlane_b32 s2, v158
	v_lshl_add_u64 v[128:129], s[10:11], 0, v[128:129]
	s_lshl_b32 s2, s2, 13
	v_lshl_add_u64 v[128:129], v[184:185], 2, v[128:129]
	s_waitcnt lgkmcnt(0)
	s_add_i32 m0, s2, 0x10000
	v_lshl_add_u64 v[128:129], v[128:129], 0, v[0:1]
	s_mov_b64 s[6:7], 0x2000
	global_load_lds_dwordx4 v[128:129], off
	v_lshl_add_u64 v[154:155], v[128:129], 0, s[6:7]
	s_add_i32 m0, s2, 0x10400
	s_mov_b64 s[6:7], 0x4000
	global_load_lds_dwordx4 v[154:155], off
	v_lshl_add_u64 v[154:155], v[128:129], 0, s[6:7]
	s_add_i32 m0, s2, 0x10800
	s_mov_b64 s[6:7], 0x6000
	global_load_lds_dwordx4 v[154:155], off
	v_lshl_add_u64 v[154:155], v[128:129], 0, s[6:7]
	s_add_i32 m0, s2, 0x10c00
	s_mov_b64 s[6:7], 0x8000
	global_load_lds_dwordx4 v[154:155], off
	v_lshl_add_u64 v[154:155], v[128:129], 0, s[6:7]
	s_add_i32 m0, s2, 0x11000
	s_mov_b64 s[6:7], 0xa000
	global_load_lds_dwordx4 v[154:155], off
	v_lshl_add_u64 v[154:155], v[128:129], 0, s[6:7]
	s_add_i32 m0, s2, 0x11400
	s_mov_b64 s[6:7], 0xc000
	global_load_lds_dwordx4 v[154:155], off
	v_lshl_add_u64 v[154:155], v[128:129], 0, s[6:7]
	s_add_i32 m0, s2, 0x11800
	s_mov_b64 s[6:7], 0xe000
	global_load_lds_dwordx4 v[154:155], off
	v_lshl_add_u64 v[128:129], v[128:129], 0, s[6:7]
	s_add_i32 m0, s2, 0x11c00
	v_mov_b32_e32 v156, v50
	global_load_lds_dwordx4 v[128:129], off
	s_waitcnt vmcnt(8)
;   DI void operator()(f32x16 (&acc)[2][4], int grow0, int gcol0, int lane, int w, char* lds) {
;     ...
; #pragma unroll
;       for (int qq = 0; qq < 2; ++qq)
; #pragma unroll
;         for (int e = 0; e < 4; ++e) {
;           const int i = 4 * (2 * (ps & 1) + qq) + e;
;           const float* xr = (const float*)(xs + (8 * qq + 4 * hh + e) * 512) + l31;
;           float s1 = 0.f, s2 = 0.f;
; #pragma unroll
;           for (int nt = 0; nt < 4; ++nt) {
;             float v = (acc[mt][nt][i] + bia[nt]) * csc[nt];
;             float z = ALPHA * xr[nt * 32] + hs * v;
;             acc[mt][nt][i] = z; s1 += z; s2 += z * z;
;           }
;           s1 = row16_sum(s1); s2 = row16_sum(s2);
;           if ((lane & 15) == 0) { f32x2 sv = {s1, s2}; *(f32x2*)(redw + (mt * 32 + (i & 3) + 8 * (i >> 2)) * 2) = sv; }
;         }
	ds_read2_b32 v[154:155], v168 offset1:32
	ds_read2_b32 v[158:159], v168 offset0:64 offset1:96
	v_mov_b32_e32 v157, v18
	v_pk_add_f32 v[160:161], v[156:157], 0 op_sel_hi:[1,0]
	v_mov_b32_e32 v156, v34
	v_pk_add_f32 v[156:157], v[156:157], 0 op_sel_hi:[1,0]
	s_waitcnt lgkmcnt(0)
	v_mov_b32_e32 v170, v154
	v_mov_b32_e32 v171, v158
	s_mov_b32 s2, s67
	v_mov_b32_e32 v176, v155
	v_mov_b32_e32 v177, v158
	v_pk_fma_f32 v[154:155], v[170:171], s[2:3], v[160:161] op_sel_hi:[1,0,1]
	v_pk_fma_f32 v[156:157], v[176:177], s[2:3], v[156:157] op_sel_hi:[1,0,1]
	v_pk_mul_f32 v[174:175], v[170:171], s[2:3] op_sel_hi:[1,0]
	v_pk_mul_f32 v[170:171], v[154:155], v[154:155]
	v_pk_mul_f32 v[176:177], v[156:157], v[156:157]
	v_pk_mov_b32 v[160:161], v[160:161], v[170:171] op_sel:[1,0]
	v_pk_mov_b32 v[170:171], v[174:175], v[176:177] op_sel:[1,0]
	v_add_f32_e32 v128, 0, v2
	v_pk_add_f32 v[160:161], v[160:161], v[170:171]
	v_pk_add_f32 v[170:171], v[154:155], v[156:157]
	v_pk_mul_f32 v[174:175], v[154:155], v[156:157]
	v_fmac_f32_e32 v128, 0x3fd744fd, v159
	v_mov_b32_e32 v171, v175
	v_pk_add_f32 v[160:161], v[170:171], v[160:161]
	v_mul_f32_e32 v129, v128, v128
	v_pk_add_f32 v[158:159], v[160:161], v[128:129]
	s_nop 1
	v_mov_b32_dpp v160, v158 quad_perm:[1,0,3,2] row_mask:0xf bank_mask:0xf bound_ctrl:1
	v_mov_b32_dpp v161, v159 quad_perm:[1,0,3,2] row_mask:0xf bank_mask:0xf bound_ctrl:1
	v_pk_add_f32 v[158:159], v[158:159], v[160:161]
	s_nop 1
	v_mov_b32_dpp v160, v158 quad_perm:[2,3,0,1] row_mask:0xf bank_mask:0xf bound_ctrl:1
	v_mov_b32_dpp v161, v159 quad_perm:[2,3,0,1] row_mask:0xf bank_mask:0xf bound_ctrl:1
	v_pk_add_f32 v[158:159], v[158:159], v[160:161]
	s_nop 1
	v_mov_b32_dpp v160, v158 row_half_mirror row_mask:0xf bank_mask:0xf bound_ctrl:1
	v_mov_b32_dpp v161, v159 row_half_mirror row_mask:0xf bank_mask:0xf bound_ctrl:1
	v_pk_add_f32 v[158:159], v[158:159], v[160:161]
	s_nop 1
	v_mov_b32_dpp v160, v158 row_mirror row_mask:0xf bank_mask:0xf bound_ctrl:1
	v_mov_b32_dpp v161, v159 row_mirror row_mask:0xf bank_mask:0xf bound_ctrl:1
	s_and_saveexec_b64 s[6:7], vcc
	v_pk_add_f32 v[158:159], v[158:159], v[160:161]
	ds_write_b64 v181, v[158:159] offset:256
	s_or_b64 exec, exec, s[6:7]
	ds_read2_b32 v[158:159], v168 offset0:128 offset1:160
	ds_read2_b32 v[160:161], v168 offset0:192 offset1:224
	v_mov_b32_e32 v18, v51
	v_pk_add_f32 v[168:169], v[18:19], 0 op_sel_hi:[1,0]
	v_mov_b32_e32 v18, v35
	v_pk_add_f32 v[18:19], v[18:19], 0 op_sel_hi:[1,0]
	s_waitcnt lgkmcnt(1)
	v_mov_b32_e32 v34, v158
	s_waitcnt lgkmcnt(0)
	v_mov_b32_e32 v35, v160
	s_mov_b32 s2, s67
	v_mov_b32_e32 v50, v159
	v_mov_b32_e32 v51, v160
	v_pk_mul_f32 v[170:171], v[34:35], s[2:3] op_sel_hi:[1,0]
	v_pk_fma_f32 v[34:35], v[34:35], s[2:3], v[168:169] op_sel_hi:[1,0,1]
	v_pk_fma_f32 v[50:51], v[50:51], s[2:3], v[18:19] op_sel_hi:[1,0,1]
	v_pk_mul_f32 v[158:159], v[34:35], v[34:35]
	v_pk_mul_f32 v[18:19], v[50:51], v[50:51]
	v_pk_mov_b32 v[158:159], v[168:169], v[158:159] op_sel:[1,0]
	v_pk_mov_b32 v[18:19], v[170:171], v[18:19] op_sel:[1,0]
	v_add_f32_e32 v2, 0, v3
	v_pk_add_f32 v[18:19], v[158:159], v[18:19]
	v_pk_add_f32 v[158:159], v[34:35], v[50:51]
	v_pk_mul_f32 v[168:169], v[34:35], v[50:51]
	v_fmac_f32_e32 v2, 0x3fd744fd, v161
	v_mov_b32_e32 v159, v169
	v_pk_add_f32 v[18:19], v[158:159], v[18:19]
	v_mul_f32_e32 v3, v2, v2
	v_pk_add_f32 v[18:19], v[18:19], v[2:3]
	s_nop 1
	v_mov_b32_dpp v158, v18 quad_perm:[1,0,3,2] row_mask:0xf bank_mask:0xf bound_ctrl:1
	v_mov_b32_dpp v159, v19 quad_perm:[1,0,3,2] row_mask:0xf bank_mask:0xf bound_ctrl:1
	v_pk_add_f32 v[18:19], v[18:19], v[158:159]
	s_nop 1
	v_mov_b32_dpp v158, v18 quad_perm:[2,3,0,1] row_mask:0xf bank_mask:0xf bound_ctrl:1
	v_mov_b32_dpp v159, v19 quad_perm:[2,3,0,1] row_mask:0xf bank_mask:0xf bound_ctrl:1
	v_pk_add_f32 v[18:19], v[18:19], v[158:159]
	s_nop 1
	v_mov_b32_dpp v158, v18 row_half_mirror row_mask:0xf bank_mask:0xf bound_ctrl:1
	v_mov_b32_dpp v159, v19 row_half_mirror row_mask:0xf bank_mask:0xf bound_ctrl:1
	v_pk_add_f32 v[18:19], v[18:19], v[158:159]
	s_nop 1
	v_mov_b32_dpp v158, v18 row_mirror row_mask:0xf bank_mask:0xf bound_ctrl:1
	v_mov_b32_dpp v159, v19 row_mirror row_mask:0xf bank_mask:0xf bound_ctrl:1
	s_and_saveexec_b64 s[6:7], vcc
	v_pk_add_f32 v[18:19], v[18:19], v[158:159]
	ds_write_b64 v181, v[18:19] offset:264
	s_or_b64 exec, exec, s[6:7]
	ds_read2_b32 v[158:159], v153 offset1:32
	ds_read2_b32 v[168:169], v153 offset0:64 offset1:96
	v_mov_b32_e32 v160, v52
	v_mov_b32_e32 v161, v20
	v_pk_add_f32 v[170:171], v[160:161], 0 op_sel_hi:[1,0]
	v_mov_b32_e32 v160, v36
	v_pk_add_f32 v[160:161], v[160:161], 0 op_sel_hi:[1,0]
	s_waitcnt lgkmcnt(1)
	v_mov_b32_e32 v174, v158
	s_waitcnt lgkmcnt(0)
;   DI void operator()(f32x16 (&acc)[2][4], int grow0, int gcol0, int lane, int w, char* lds) {
;     ...
; #pragma unroll
;       for (int qq = 0; qq < 2; ++qq)
; #pragma unroll
;         for (int e = 0; e < 4; ++e) {
;           const int i = 4 * (2 * (ps & 1) + qq) + e;
;           const float* xr = (const float*)(xs + (8 * qq + 4 * hh + e) * 512) + l31;
;           float s1 = 0.f, s2 = 0.f;
; #pragma unroll
;           for (int nt = 0; nt < 4; ++nt) {
;             float v = (acc[mt][nt][i] + bia[nt]) * csc[nt];
;             float z = ALPHA * xr[nt * 32] + hs * v;
;             acc[mt][nt][i] = z; s1 += z; s2 += z * z;
;           }
;           s1 = row16_sum(s1); s2 = row16_sum(s2);
;           if ((lane & 15) == 0) { f32x2 sv = {s1, s2}; *(f32x2*)(redw + (mt * 32 + (i & 3) + 8 * (i >> 2)) * 2) = sv; }
;         }
	v_mov_b32_e32 v175, v168
	s_mov_b32 s2, s67
	v_mov_b32_e32 v178, v159
	v_mov_b32_e32 v179, v168
	v_pk_fma_f32 v[158:159], v[174:175], s[2:3], v[170:171] op_sel_hi:[1,0,1]
	v_pk_fma_f32 v[160:161], v[178:179], s[2:3], v[160:161] op_sel_hi:[1,0,1]
	v_pk_mul_f32 v[176:177], v[174:175], s[2:3] op_sel_hi:[1,0]
	v_pk_mul_f32 v[174:175], v[158:159], v[158:159]
	v_pk_mul_f32 v[178:179], v[160:161], v[160:161]
	v_pk_mov_b32 v[170:171], v[170:171], v[174:175] op_sel:[1,0]
	v_pk_mov_b32 v[174:175], v[176:177], v[178:179] op_sel:[1,0]
	v_add_f32_e32 v18, 0, v4
	v_pk_add_f32 v[170:171], v[170:171], v[174:175]
	v_pk_add_f32 v[174:175], v[158:159], v[160:161]
	v_pk_mul_f32 v[176:177], v[158:159], v[160:161]
	v_fmac_f32_e32 v18, 0x3fd744fd, v169
	v_mov_b32_e32 v175, v177
	v_pk_add_f32 v[170:171], v[174:175], v[170:171]
	v_mul_f32_e32 v19, v18, v18
	v_pk_add_f32 v[168:169], v[170:171], v[18:19]
	s_nop 1
	v_mov_b32_dpp v170, v168 quad_perm:[1,0,3,2] row_mask:0xf bank_mask:0xf bound_ctrl:1
	v_mov_b32_dpp v171, v169 quad_perm:[1,0,3,2] row_mask:0xf bank_mask:0xf bound_ctrl:1
	v_pk_add_f32 v[168:169], v[168:169], v[170:171]
	s_nop 1
	v_mov_b32_dpp v170, v168 quad_perm:[2,3,0,1] row_mask:0xf bank_mask:0xf bound_ctrl:1
	v_mov_b32_dpp v171, v169 quad_perm:[2,3,0,1] row_mask:0xf bank_mask:0xf bound_ctrl:1
	v_pk_add_f32 v[168:169], v[168:169], v[170:171]
	s_nop 1
	v_mov_b32_dpp v170, v168 row_half_mirror row_mask:0xf bank_mask:0xf bound_ctrl:1
	v_mov_b32_dpp v171, v169 row_half_mirror row_mask:0xf bank_mask:0xf bound_ctrl:1
	v_pk_add_f32 v[168:169], v[168:169], v[170:171]
	s_nop 1
	v_mov_b32_dpp v170, v168 row_mirror row_mask:0xf bank_mask:0xf bound_ctrl:1
	v_mov_b32_dpp v171, v169 row_mirror row_mask:0xf bank_mask:0xf bound_ctrl:1
	s_and_saveexec_b64 s[6:7], vcc
	v_pk_add_f32 v[168:169], v[168:169], v[170:171]
	ds_write_b64 v181, v[168:169] offset:272
	s_or_b64 exec, exec, s[6:7]
	ds_read2_b32 v[168:169], v151 offset1:32
	ds_read2_b32 v[170:171], v151 offset0:64 offset1:96
	v_mov_b32_e32 v20, v53
	v_pk_add_f32 v[174:175], v[20:21], 0 op_sel_hi:[1,0]
	v_mov_b32_e32 v20, v37
	v_pk_add_f32 v[20:21], v[20:21], 0 op_sel_hi:[1,0]
	s_waitcnt lgkmcnt(1)
	v_mov_b32_e32 v36, v168
	s_waitcnt lgkmcnt(0)
	v_mov_b32_e32 v37, v170
	s_mov_b32 s2, s67
	v_mov_b32_e32 v52, v169
	v_mov_b32_e32 v53, v170
	v_pk_mul_f32 v[176:177], v[36:37], s[2:3] op_sel_hi:[1,0]
	v_pk_fma_f32 v[36:37], v[36:37], s[2:3], v[174:175] op_sel_hi:[1,0,1]
	v_pk_fma_f32 v[52:53], v[52:53], s[2:3], v[20:21] op_sel_hi:[1,0,1]
	v_pk_mul_f32 v[168:169], v[36:37], v[36:37]
	v_pk_mul_f32 v[20:21], v[52:53], v[52:53]
	v_pk_mov_b32 v[168:169], v[174:175], v[168:169] op_sel:[1,0]
	v_pk_mov_b32 v[20:21], v[176:177], v[20:21] op_sel:[1,0]
	v_add_f32_e32 v4, 0, v5
	v_pk_add_f32 v[20:21], v[168:169], v[20:21]
	v_pk_add_f32 v[168:169], v[36:37], v[52:53]
	v_pk_mul_f32 v[174:175], v[36:37], v[52:53]
	v_fmac_f32_e32 v4, 0x3fd744fd, v171
	v_mov_b32_e32 v169, v175
	v_pk_add_f32 v[20:21], v[168:169], v[20:21]
	v_mul_f32_e32 v5, v4, v4
	v_pk_add_f32 v[20:21], v[20:21], v[4:5]
	s_nop 1
	v_mov_b32_dpp v168, v20 quad_perm:[1,0,3,2] row_mask:0xf bank_mask:0xf bound_ctrl:1
	v_mov_b32_dpp v169, v21 quad_perm:[1,0,3,2] row_mask:0xf bank_mask:0xf bound_ctrl:1
	v_pk_add_f32 v[20:21], v[20:21], v[168:169]
	s_nop 1
	v_mov_b32_dpp v168, v20 quad_perm:[2,3,0,1] row_mask:0xf bank_mask:0xf bound_ctrl:1
	v_mov_b32_dpp v169, v21 quad_perm:[2,3,0,1] row_mask:0xf bank_mask:0xf bound_ctrl:1
	v_pk_add_f32 v[20:21], v[20:21], v[168:169]
	s_nop 1
	v_mov_b32_dpp v168, v20 row_half_mirror row_mask:0xf bank_mask:0xf bound_ctrl:1
	v_mov_b32_dpp v169, v21 row_half_mirror row_mask:0xf bank_mask:0xf bound_ctrl:1
	v_pk_add_f32 v[20:21], v[20:21], v[168:169]
	s_nop 1
	v_mov_b32_dpp v168, v20 row_mirror row_mask:0xf bank_mask:0xf bound_ctrl:1
	v_mov_b32_dpp v169, v21 row_mirror row_mask:0xf bank_mask:0xf bound_ctrl:1
	s_and_saveexec_b64 s[6:7], vcc
	v_pk_add_f32 v[20:21], v[20:21], v[168:169]
	ds_write_b64 v181, v[20:21] offset:280
	s_or_b64 exec, exec, s[6:7]
	ds_read2_b32 v[168:169], v67 offset1:32
	ds_read2_b32 v[174:175], v67 offset0:64 offset1:96
	v_mov_b32_e32 v170, v54
	v_mov_b32_e32 v171, v22
	v_pk_add_f32 v[176:177], v[170:171], 0 op_sel_hi:[1,0]
	v_mov_b32_e32 v170, v38
	v_pk_add_f32 v[170:171], v[170:171], 0 op_sel_hi:[1,0]
	s_waitcnt lgkmcnt(1)
	v_mov_b32_e32 v178, v168
	s_waitcnt lgkmcnt(0)
	v_mov_b32_e32 v179, v174
	s_mov_b32 s2, s67
	v_mov_b32_e32 v190, v169
	v_mov_b32_e32 v191, v174
	v_pk_fma_f32 v[168:169], v[178:179], s[2:3], v[176:177] op_sel_hi:[1,0,1]
	v_pk_fma_f32 v[170:171], v[190:191], s[2:3], v[170:171] op_sel_hi:[1,0,1]
	v_pk_mul_f32 v[182:183], v[178:179], s[2:3] op_sel_hi:[1,0]
	v_pk_mul_f32 v[178:179], v[168:169], v[168:169]
	v_pk_mul_f32 v[190:191], v[170:171], v[170:171]
	v_pk_mov_b32 v[176:177], v[176:177], v[178:179] op_sel:[1,0]
	v_pk_mov_b32 v[178:179], v[182:183], v[190:191] op_sel:[1,0]
	v_add_f32_e32 v20, 0, v6
	v_pk_add_f32 v[176:177], v[176:177], v[178:179]
	v_pk_add_f32 v[178:179], v[168:169], v[170:171]
	v_pk_mul_f32 v[182:183], v[168:169], v[170:171]
	v_fmac_f32_e32 v20, 0x3fd744fd, v175
	v_mov_b32_e32 v179, v183
	v_pk_add_f32 v[176:177], v[178:179], v[176:177]
	v_mul_f32_e32 v21, v20, v20
	v_pk_add_f32 v[174:175], v[176:177], v[20:21]
	s_nop 1
	v_mov_b32_dpp v176, v174 quad_perm:[1,0,3,2] row_mask:0xf bank_mask:0xf bound_ctrl:1
	v_mov_b32_dpp v177, v175 quad_perm:[1,0,3,2] row_mask:0xf bank_mask:0xf bound_ctrl:1
	v_pk_add_f32 v[174:175], v[174:175], v[176:177]
	s_nop 1
	v_mov_b32_dpp v176, v174 quad_perm:[2,3,0,1] row_mask:0xf bank_mask:0xf bound_ctrl:1
	v_mov_b32_dpp v177, v175 quad_perm:[2,3,0,1] row_mask:0xf bank_mask:0xf bound_ctrl:1
	v_pk_add_f32 v[174:175], v[174:175], v[176:177]
	s_nop 1
	v_mov_b32_dpp v176, v174 row_half_mirror row_mask:0xf bank_mask:0xf bound_ctrl:1
	v_mov_b32_dpp v177, v175 row_half_mirror row_mask:0xf bank_mask:0xf bound_ctrl:1
	v_pk_add_f32 v[174:175], v[174:175], v[176:177]
	s_nop 1
	v_mov_b32_dpp v176, v174 row_mirror row_mask:0xf bank_mask:0xf bound_ctrl:1
	v_mov_b32_dpp v177, v175 row_mirror row_mask:0xf bank_mask:0xf bound_ctrl:1
	s_and_saveexec_b64 s[6:7], vcc
	v_pk_add_f32 v[174:175], v[174:175], v[176:177]
	ds_write_b64 v181, v[174:175] offset:320
	s_or_b64 exec, exec, s[6:7]
	ds_read2_b32 v[174:175], v67 offset0:128 offset1:160
	ds_read2_b32 v[176:177], v67 offset0:192 offset1:224
	v_mov_b32_e32 v22, v55
	v_pk_add_f32 v[178:179], v[22:23], 0 op_sel_hi:[1,0]
	v_mov_b32_e32 v22, v39
	v_pk_add_f32 v[22:23], v[22:23], 0 op_sel_hi:[1,0]
	s_waitcnt lgkmcnt(1)
;   DI void operator()(f32x16 (&acc)[2][4], int grow0, int gcol0, int lane, int w, char* lds) {
;     ...
; #pragma unroll
;       for (int qq = 0; qq < 2; ++qq)
; #pragma unroll
;         for (int e = 0; e < 4; ++e) {
;           const int i = 4 * (2 * (ps & 1) + qq) + e;
;           const float* xr = (const float*)(xs + (8 * qq + 4 * hh + e) * 512) + l31;
;           float s1 = 0.f, s2 = 0.f;
; #pragma unroll
;           for (int nt = 0; nt < 4; ++nt) {
;             float v = (acc[mt][nt][i] + bia[nt]) * csc[nt];
;             float z = ALPHA * xr[nt * 32] + hs * v;
;             acc[mt][nt][i] = z; s1 += z; s2 += z * z;
;           }
;           s1 = row16_sum(s1); s2 = row16_sum(s2);
;           if ((lane & 15) == 0) { f32x2 sv = {s1, s2}; *(f32x2*)(redw + (mt * 32 + (i & 3) + 8 * (i >> 2)) * 2) = sv; }
;         }
	v_mov_b32_e32 v38, v174
	s_waitcnt lgkmcnt(0)
	v_mov_b32_e32 v39, v176
	s_mov_b32 s2, s67
	v_mov_b32_e32 v54, v175
	v_mov_b32_e32 v55, v176
	v_pk_mul_f32 v[182:183], v[38:39], s[2:3] op_sel_hi:[1,0]
	v_pk_fma_f32 v[38:39], v[38:39], s[2:3], v[178:179] op_sel_hi:[1,0,1]
	v_pk_fma_f32 v[54:55], v[54:55], s[2:3], v[22:23] op_sel_hi:[1,0,1]
	v_pk_mul_f32 v[174:175], v[38:39], v[38:39]
	v_pk_mul_f32 v[22:23], v[54:55], v[54:55]
	v_pk_mov_b32 v[174:175], v[178:179], v[174:175] op_sel:[1,0]
	v_pk_mov_b32 v[22:23], v[182:183], v[22:23] op_sel:[1,0]
	v_add_f32_e32 v6, 0, v7
	v_pk_add_f32 v[22:23], v[174:175], v[22:23]
	v_pk_add_f32 v[174:175], v[38:39], v[54:55]
	v_pk_mul_f32 v[178:179], v[38:39], v[54:55]
	v_fmac_f32_e32 v6, 0x3fd744fd, v177
	v_mov_b32_e32 v175, v179
	v_pk_add_f32 v[22:23], v[174:175], v[22:23]
	v_mul_f32_e32 v7, v6, v6
	v_pk_add_f32 v[22:23], v[22:23], v[6:7]
	s_nop 1
	v_mov_b32_dpp v174, v22 quad_perm:[1,0,3,2] row_mask:0xf bank_mask:0xf bound_ctrl:1
	v_mov_b32_dpp v175, v23 quad_perm:[1,0,3,2] row_mask:0xf bank_mask:0xf bound_ctrl:1
	v_pk_add_f32 v[22:23], v[22:23], v[174:175]
	s_nop 1
	v_mov_b32_dpp v174, v22 quad_perm:[2,3,0,1] row_mask:0xf bank_mask:0xf bound_ctrl:1
	v_mov_b32_dpp v175, v23 quad_perm:[2,3,0,1] row_mask:0xf bank_mask:0xf bound_ctrl:1
	v_pk_add_f32 v[22:23], v[22:23], v[174:175]
	s_nop 1
	v_mov_b32_dpp v174, v22 row_half_mirror row_mask:0xf bank_mask:0xf bound_ctrl:1
	v_mov_b32_dpp v175, v23 row_half_mirror row_mask:0xf bank_mask:0xf bound_ctrl:1
	v_pk_add_f32 v[22:23], v[22:23], v[174:175]
	s_nop 1
	v_mov_b32_dpp v174, v22 row_mirror row_mask:0xf bank_mask:0xf bound_ctrl:1
	v_mov_b32_dpp v175, v23 row_mirror row_mask:0xf bank_mask:0xf bound_ctrl:1
	s_and_saveexec_b64 s[6:7], vcc
	v_pk_add_f32 v[22:23], v[22:23], v[174:175]
	ds_write_b64 v181, v[22:23] offset:328
	s_or_b64 exec, exec, s[6:7]
	ds_read2_b32 v[174:175], v69 offset1:32
	ds_read2_b32 v[178:179], v69 offset0:64 offset1:96
	v_mov_b32_e32 v176, v56
	v_mov_b32_e32 v177, v24
	v_pk_add_f32 v[182:183], v[176:177], 0 op_sel_hi:[1,0]
	v_mov_b32_e32 v176, v40
	v_pk_add_f32 v[176:177], v[176:177], 0 op_sel_hi:[1,0]
	s_waitcnt lgkmcnt(1)
	v_mov_b32_e32 v190, v174
	s_waitcnt lgkmcnt(0)
	v_mov_b32_e32 v191, v178
	s_mov_b32 s2, s67
	v_mov_b32_e32 v194, v175
	v_mov_b32_e32 v195, v178
	v_pk_fma_f32 v[174:175], v[190:191], s[2:3], v[182:183] op_sel_hi:[1,0,1]
	v_pk_fma_f32 v[176:177], v[194:195], s[2:3], v[176:177] op_sel_hi:[1,0,1]
	v_pk_mul_f32 v[192:193], v[190:191], s[2:3] op_sel_hi:[1,0]
	v_pk_mul_f32 v[190:191], v[174:175], v[174:175]
	v_pk_mul_f32 v[194:195], v[176:177], v[176:177]
	v_pk_mov_b32 v[182:183], v[182:183], v[190:191] op_sel:[1,0]
	v_pk_mov_b32 v[190:191], v[192:193], v[194:195] op_sel:[1,0]
	v_add_f32_e32 v22, 0, v8
	v_pk_add_f32 v[182:183], v[182:183], v[190:191]
	v_pk_add_f32 v[190:191], v[174:175], v[176:177]
	v_pk_mul_f32 v[192:193], v[174:175], v[176:177]
	v_fmac_f32_e32 v22, 0x3fd744fd, v179
	v_mov_b32_e32 v191, v193
	v_pk_add_f32 v[182:183], v[190:191], v[182:183]
	v_mul_f32_e32 v23, v22, v22
	v_pk_add_f32 v[178:179], v[182:183], v[22:23]
	s_nop 1
	v_mov_b32_dpp v182, v178 quad_perm:[1,0,3,2] row_mask:0xf bank_mask:0xf bound_ctrl:1
	v_mov_b32_dpp v183, v179 quad_perm:[1,0,3,2] row_mask:0xf bank_mask:0xf bound_ctrl:1
	v_pk_add_f32 v[178:179], v[178:179], v[182:183]
	s_nop 1
	v_mov_b32_dpp v182, v178 quad_perm:[2,3,0,1] row_mask:0xf bank_mask:0xf bound_ctrl:1
	v_mov_b32_dpp v183, v179 quad_perm:[2,3,0,1] row_mask:0xf bank_mask:0xf bound_ctrl:1
	v_pk_add_f32 v[178:179], v[178:179], v[182:183]
	s_nop 1
	v_mov_b32_dpp v182, v178 row_half_mirror row_mask:0xf bank_mask:0xf bound_ctrl:1
	v_mov_b32_dpp v183, v179 row_half_mirror row_mask:0xf bank_mask:0xf bound_ctrl:1
	v_pk_add_f32 v[178:179], v[178:179], v[182:183]
	s_nop 1
	v_mov_b32_dpp v182, v178 row_mirror row_mask:0xf bank_mask:0xf bound_ctrl:1
	v_mov_b32_dpp v183, v179 row_mirror row_mask:0xf bank_mask:0xf bound_ctrl:1
	s_and_saveexec_b64 s[6:7], vcc
	v_pk_add_f32 v[178:179], v[178:179], v[182:183]
	ds_write_b64 v181, v[178:179] offset:336
	s_or_b64 exec, exec, s[6:7]
	ds_read2_b32 v[178:179], v71 offset1:32
	ds_read2_b32 v[182:183], v71 offset0:64 offset1:96
	v_mov_b32_e32 v24, v57
	v_pk_add_f32 v[190:191], v[24:25], 0 op_sel_hi:[1,0]
	v_mov_b32_e32 v24, v41
	v_pk_add_f32 v[24:25], v[24:25], 0 op_sel_hi:[1,0]
	s_waitcnt lgkmcnt(1)
	v_mov_b32_e32 v40, v178
	s_waitcnt lgkmcnt(0)
	v_mov_b32_e32 v41, v182
	s_mov_b32 s2, s67
	v_mov_b32_e32 v56, v179
	v_mov_b32_e32 v57, v182
	v_pk_mul_f32 v[192:193], v[40:41], s[2:3] op_sel_hi:[1,0]
	v_pk_fma_f32 v[40:41], v[40:41], s[2:3], v[190:191] op_sel_hi:[1,0,1]
	v_pk_fma_f32 v[56:57], v[56:57], s[2:3], v[24:25] op_sel_hi:[1,0,1]
	v_pk_mul_f32 v[178:179], v[40:41], v[40:41]
	v_pk_mul_f32 v[24:25], v[56:57], v[56:57]
	v_pk_mov_b32 v[178:179], v[190:191], v[178:179] op_sel:[1,0]
	v_pk_mov_b32 v[24:25], v[192:193], v[24:25] op_sel:[1,0]
	v_add_f32_e32 v8, 0, v9
	v_pk_add_f32 v[24:25], v[178:179], v[24:25]
	v_pk_add_f32 v[178:179], v[40:41], v[56:57]
	v_pk_mul_f32 v[190:191], v[40:41], v[56:57]
	v_fmac_f32_e32 v8, 0x3fd744fd, v183
	v_mov_b32_e32 v179, v191
	v_pk_add_f32 v[24:25], v[178:179], v[24:25]
	v_mul_f32_e32 v9, v8, v8
	v_pk_add_f32 v[24:25], v[24:25], v[8:9]
	s_nop 1
	v_mov_b32_dpp v178, v24 quad_perm:[1,0,3,2] row_mask:0xf bank_mask:0xf bound_ctrl:1
	v_mov_b32_dpp v179, v25 quad_perm:[1,0,3,2] row_mask:0xf bank_mask:0xf bound_ctrl:1
	v_pk_add_f32 v[24:25], v[24:25], v[178:179]
	s_nop 1
	v_mov_b32_dpp v178, v24 quad_perm:[2,3,0,1] row_mask:0xf bank_mask:0xf bound_ctrl:1
	v_mov_b32_dpp v179, v25 quad_perm:[2,3,0,1] row_mask:0xf bank_mask:0xf bound_ctrl:1
	v_pk_add_f32 v[24:25], v[24:25], v[178:179]
	s_nop 1
	v_mov_b32_dpp v178, v24 row_half_mirror row_mask:0xf bank_mask:0xf bound_ctrl:1
	v_mov_b32_dpp v179, v25 row_half_mirror row_mask:0xf bank_mask:0xf bound_ctrl:1
	v_pk_add_f32 v[24:25], v[24:25], v[178:179]
	s_nop 1
	v_mov_b32_dpp v178, v24 row_mirror row_mask:0xf bank_mask:0xf bound_ctrl:1
	v_mov_b32_dpp v179, v25 row_mirror row_mask:0xf bank_mask:0xf bound_ctrl:1
	s_and_saveexec_b64 s[6:7], vcc
	v_pk_add_f32 v[24:25], v[24:25], v[178:179]
	ds_write_b64 v181, v[24:25] offset:344
	s_or_b64 exec, exec, s[6:7]
	s_waitcnt vmcnt(0)
;   DI void operator()(f32x16 (&acc)[2][4], int grow0, int gcol0, int lane, int w, char* lds) {
;     ...
; #pragma unroll
;       for (int qq = 0; qq < 2; ++qq)
; #pragma unroll
;         for (int e = 0; e < 4; ++e) {
;           const int i = 4 * (2 * (ps & 1) + qq) + e;
;           const float* xr = (const float*)(xs + (8 * qq + 4 * hh + e) * 512) + l31;
;           float s1 = 0.f, s2 = 0.f;
; #pragma unroll
;           for (int nt = 0; nt < 4; ++nt) {
;             float v = (acc[mt][nt][i] + bia[nt]) * csc[nt];
;             float z = ALPHA * xr[nt * 32] + hs * v;
;             acc[mt][nt][i] = z; s1 += z; s2 += z * z;
;           }
;           s1 = row16_sum(s1); s2 = row16_sum(s2);
;           if ((lane & 15) == 0) { f32x2 sv = {s1, s2}; *(f32x2*)(redw + (mt * 32 + (i & 3) + 8 * (i >> 2)) * 2) = sv; }
;         }
	ds_read2_b32 v[182:183], v73 offset1:32
	ds_read2_b32 v[192:193], v73 offset0:64 offset1:96
	v_add_f32_e32 v179, 0, v42
	v_mov_b32_e32 v190, v58
	v_mov_b32_e32 v191, v26
	s_waitcnt lgkmcnt(1)
	v_fmac_f32_e32 v179, 0x3fd744fd, v183
	v_pk_add_f32 v[194:195], v[190:191], 0 op_sel_hi:[1,0]
	s_waitcnt lgkmcnt(0)
	v_mov_b32_e32 v183, v192
	s_mov_b32 s2, s67
	v_pk_fma_f32 v[190:191], v[182:183], s[2:3], v[194:195] op_sel_hi:[1,0,1]
	v_mov_b32_e32 v178, v192
	v_pk_mul_f32 v[182:183], v[190:191], v[190:191]
	v_mov_b32_e32 v196, v165
	v_mov_b32_e32 v197, v179
	v_pk_mov_b32 v[182:183], v[194:195], v[182:183] op_sel:[1,0]
	v_add_f32_e32 v24, 0, v10
	v_pk_fma_f32 v[182:183], v[178:179], v[196:197], v[182:183]
	v_fmac_f32_e32 v24, 0x3fd744fd, v193
	v_pk_mov_b32 v[194:195], v[178:179], v[182:183] op_sel:[1,0]
	v_mul_f32_e32 v25, v24, v24
	v_pk_add_f32 v[196:197], v[190:191], v[194:195]
	v_pk_mul_f32 v[194:195], v[190:191], v[194:195]
	s_nop 0
	v_mov_b32_e32 v197, v195
	v_pk_add_f32 v[194:195], v[182:183], v[196:197]
	s_nop 0
	v_pk_add_f32 v[192:193], v[194:195], v[24:25]
	s_nop 1
	v_mov_b32_dpp v194, v192 quad_perm:[1,0,3,2] row_mask:0xf bank_mask:0xf bound_ctrl:1
	v_mov_b32_dpp v195, v193 quad_perm:[1,0,3,2] row_mask:0xf bank_mask:0xf bound_ctrl:1
	v_pk_add_f32 v[192:193], v[192:193], v[194:195]
	s_nop 1
	v_mov_b32_dpp v194, v192 quad_perm:[2,3,0,1] row_mask:0xf bank_mask:0xf bound_ctrl:1
	v_mov_b32_dpp v195, v193 quad_perm:[2,3,0,1] row_mask:0xf bank_mask:0xf bound_ctrl:1
	v_pk_add_f32 v[192:193], v[192:193], v[194:195]
	s_nop 1
	v_mov_b32_dpp v194, v192 row_half_mirror row_mask:0xf bank_mask:0xf bound_ctrl:1
	v_mov_b32_dpp v195, v193 row_half_mirror row_mask:0xf bank_mask:0xf bound_ctrl:1
	v_pk_add_f32 v[192:193], v[192:193], v[194:195]
	s_nop 1
	v_mov_b32_dpp v194, v192 row_mirror row_mask:0xf bank_mask:0xf bound_ctrl:1
	v_mov_b32_dpp v195, v193 row_mirror row_mask:0xf bank_mask:0xf bound_ctrl:1
	s_and_saveexec_b64 s[6:7], vcc
	v_pk_add_f32 v[192:193], v[192:193], v[194:195]
	ds_write_b64 v181, v[192:193] offset:384
	s_or_b64 exec, exec, s[6:7]
	ds_read2_b32 v[192:193], v85 offset1:32
	ds_read2_b32 v[194:195], v85 offset0:64 offset1:96
	v_mov_b32_e32 v26, v59
	v_pk_add_f32 v[196:197], v[26:27], 0 op_sel_hi:[1,0]
	v_mov_b32_e32 v26, v43
	v_pk_add_f32 v[26:27], v[26:27], 0 op_sel_hi:[1,0]
	s_waitcnt lgkmcnt(1)
	v_mov_b32_e32 v42, v192
	s_waitcnt lgkmcnt(0)
	v_mov_b32_e32 v43, v194
	s_mov_b32 s2, s67
	v_mov_b32_e32 v58, v193
	v_mov_b32_e32 v59, v194
	v_pk_mul_f32 v[198:199], v[42:43], s[2:3] op_sel_hi:[1,0]
	v_pk_fma_f32 v[42:43], v[42:43], s[2:3], v[196:197] op_sel_hi:[1,0,1]
	v_pk_fma_f32 v[58:59], v[58:59], s[2:3], v[26:27] op_sel_hi:[1,0,1]
	v_pk_mul_f32 v[192:193], v[42:43], v[42:43]
	v_pk_mul_f32 v[26:27], v[58:59], v[58:59]
	v_pk_mov_b32 v[192:193], v[196:197], v[192:193] op_sel:[1,0]
	v_pk_mov_b32 v[26:27], v[198:199], v[26:27] op_sel:[1,0]
	v_add_f32_e32 v10, 0, v11
	v_pk_add_f32 v[26:27], v[192:193], v[26:27]
	v_pk_add_f32 v[192:193], v[42:43], v[58:59]
	v_pk_mul_f32 v[196:197], v[42:43], v[58:59]
	v_fmac_f32_e32 v10, 0x3fd744fd, v195
	v_mov_b32_e32 v193, v197
	v_pk_add_f32 v[26:27], v[192:193], v[26:27]
	v_mul_f32_e32 v11, v10, v10
	v_pk_add_f32 v[26:27], v[26:27], v[10:11]
	s_nop 1
	v_mov_b32_dpp v192, v26 quad_perm:[1,0,3,2] row_mask:0xf bank_mask:0xf bound_ctrl:1
	v_mov_b32_dpp v193, v27 quad_perm:[1,0,3,2] row_mask:0xf bank_mask:0xf bound_ctrl:1
	v_pk_add_f32 v[26:27], v[26:27], v[192:193]
	s_nop 1
	v_mov_b32_dpp v192, v26 quad_perm:[2,3,0,1] row_mask:0xf bank_mask:0xf bound_ctrl:1
	v_mov_b32_dpp v193, v27 quad_perm:[2,3,0,1] row_mask:0xf bank_mask:0xf bound_ctrl:1
	v_pk_add_f32 v[26:27], v[26:27], v[192:193]
	s_nop 1
	v_mov_b32_dpp v192, v26 row_half_mirror row_mask:0xf bank_mask:0xf bound_ctrl:1
	v_mov_b32_dpp v193, v27 row_half_mirror row_mask:0xf bank_mask:0xf bound_ctrl:1
	v_pk_add_f32 v[26:27], v[26:27], v[192:193]
	s_nop 1
	v_mov_b32_dpp v192, v26 row_mirror row_mask:0xf bank_mask:0xf bound_ctrl:1
	v_mov_b32_dpp v193, v27 row_mirror row_mask:0xf bank_mask:0xf bound_ctrl:1
	s_and_saveexec_b64 s[6:7], vcc
	v_pk_add_f32 v[26:27], v[26:27], v[192:193]
	ds_write_b64 v181, v[26:27] offset:392
	s_or_b64 exec, exec, s[6:7]
	ds_read2_b32 v[192:193], v75 offset1:32
	ds_read2_b32 v[196:197], v75 offset0:64 offset1:96
	v_mov_b32_e32 v194, v60
	v_mov_b32_e32 v195, v28
	v_pk_add_f32 v[198:199], v[194:195], 0 op_sel_hi:[1,0]
	v_mov_b32_e32 v194, v44
	v_pk_add_f32 v[194:195], v[194:195], 0 op_sel_hi:[1,0]
	s_waitcnt lgkmcnt(1)
	v_mov_b32_e32 v202, v192
	s_waitcnt lgkmcnt(0)
	v_mov_b32_e32 v203, v196
	s_mov_b32 s2, s67
	v_mov_b32_e32 v206, v193
	v_mov_b32_e32 v207, v196
	v_pk_fma_f32 v[192:193], v[202:203], s[2:3], v[198:199] op_sel_hi:[1,0,1]
	v_pk_fma_f32 v[194:195], v[206:207], s[2:3], v[194:195] op_sel_hi:[1,0,1]
	v_pk_mul_f32 v[204:205], v[202:203], s[2:3] op_sel_hi:[1,0]
	v_pk_mul_f32 v[202:203], v[192:193], v[192:193]
	v_pk_mul_f32 v[206:207], v[194:195], v[194:195]
	v_pk_mov_b32 v[198:199], v[198:199], v[202:203] op_sel:[1,0]
	v_pk_mov_b32 v[202:203], v[204:205], v[206:207] op_sel:[1,0]
	v_add_f32_e32 v26, 0, v12
	v_pk_add_f32 v[198:199], v[198:199], v[202:203]
	v_pk_add_f32 v[202:203], v[192:193], v[194:195]
	v_pk_mul_f32 v[204:205], v[192:193], v[194:195]
	v_fmac_f32_e32 v26, 0x3fd744fd, v197
	v_mov_b32_e32 v203, v205
	v_pk_add_f32 v[198:199], v[202:203], v[198:199]
	v_mul_f32_e32 v27, v26, v26
	v_pk_add_f32 v[196:197], v[198:199], v[26:27]
	s_nop 1
	v_mov_b32_dpp v198, v196 quad_perm:[1,0,3,2] row_mask:0xf bank_mask:0xf bound_ctrl:1
	v_mov_b32_dpp v199, v197 quad_perm:[1,0,3,2] row_mask:0xf bank_mask:0xf bound_ctrl:1
	v_pk_add_f32 v[196:197], v[196:197], v[198:199]
	s_nop 1
	v_mov_b32_dpp v198, v196 quad_perm:[2,3,0,1] row_mask:0xf bank_mask:0xf bound_ctrl:1
	v_mov_b32_dpp v199, v197 quad_perm:[2,3,0,1] row_mask:0xf bank_mask:0xf bound_ctrl:1
	v_pk_add_f32 v[196:197], v[196:197], v[198:199]
	s_nop 1
	v_mov_b32_dpp v198, v196 row_half_mirror row_mask:0xf bank_mask:0xf bound_ctrl:1
	v_mov_b32_dpp v199, v197 row_half_mirror row_mask:0xf bank_mask:0xf bound_ctrl:1
	v_pk_add_f32 v[196:197], v[196:197], v[198:199]
	s_nop 1
	v_mov_b32_dpp v198, v196 row_mirror row_mask:0xf bank_mask:0xf bound_ctrl:1
	v_mov_b32_dpp v199, v197 row_mirror row_mask:0xf bank_mask:0xf bound_ctrl:1
	s_and_saveexec_b64 s[6:7], vcc
	v_pk_add_f32 v[196:197], v[196:197], v[198:199]
	ds_write_b64 v181, v[196:197] offset:400
	s_or_b64 exec, exec, s[6:7]
	ds_read2_b32 v[196:197], v87 offset1:32
	ds_read2_b32 v[198:199], v87 offset0:64 offset1:96
	v_mov_b32_e32 v28, v61
	v_pk_add_f32 v[202:203], v[28:29], 0 op_sel_hi:[1,0]
	v_mov_b32_e32 v28, v45
	v_pk_add_f32 v[28:29], v[28:29], 0 op_sel_hi:[1,0]
	s_waitcnt lgkmcnt(1)
;   DI void operator()(f32x16 (&acc)[2][4], int grow0, int gcol0, int lane, int w, char* lds) {
;     ...
; #pragma unroll
;       for (int qq = 0; qq < 2; ++qq)
; #pragma unroll
;         for (int e = 0; e < 4; ++e) {
;           const int i = 4 * (2 * (ps & 1) + qq) + e;
;           const float* xr = (const float*)(xs + (8 * qq + 4 * hh + e) * 512) + l31;
;           float s1 = 0.f, s2 = 0.f;
; #pragma unroll
;           for (int nt = 0; nt < 4; ++nt) {
;             float v = (acc[mt][nt][i] + bia[nt]) * csc[nt];
;             float z = ALPHA * xr[nt * 32] + hs * v;
;             acc[mt][nt][i] = z; s1 += z; s2 += z * z;
;           }
;           s1 = row16_sum(s1); s2 = row16_sum(s2);
;           if ((lane & 15) == 0) { f32x2 sv = {s1, s2}; *(f32x2*)(redw + (mt * 32 + (i & 3) + 8 * (i >> 2)) * 2) = sv; }
;         }
	v_mov_b32_e32 v44, v196
	s_waitcnt lgkmcnt(0)
	v_mov_b32_e32 v45, v198
	s_mov_b32 s2, s67
	v_mov_b32_e32 v60, v197
	v_mov_b32_e32 v61, v198
	v_pk_mul_f32 v[204:205], v[44:45], s[2:3] op_sel_hi:[1,0]
	v_pk_fma_f32 v[44:45], v[44:45], s[2:3], v[202:203] op_sel_hi:[1,0,1]
	v_pk_fma_f32 v[60:61], v[60:61], s[2:3], v[28:29] op_sel_hi:[1,0,1]
	v_pk_mul_f32 v[196:197], v[44:45], v[44:45]
	v_pk_mul_f32 v[28:29], v[60:61], v[60:61]
	v_pk_mov_b32 v[196:197], v[202:203], v[196:197] op_sel:[1,0]
	v_pk_mov_b32 v[28:29], v[204:205], v[28:29] op_sel:[1,0]
	v_add_f32_e32 v12, 0, v13
	v_pk_add_f32 v[28:29], v[196:197], v[28:29]
	v_pk_add_f32 v[196:197], v[44:45], v[60:61]
	v_pk_mul_f32 v[202:203], v[44:45], v[60:61]
	v_fmac_f32_e32 v12, 0x3fd744fd, v199
	v_mov_b32_e32 v197, v203
	v_pk_add_f32 v[28:29], v[196:197], v[28:29]
	v_mul_f32_e32 v13, v12, v12
	v_pk_add_f32 v[28:29], v[28:29], v[12:13]
	s_nop 1
	v_mov_b32_dpp v196, v28 quad_perm:[1,0,3,2] row_mask:0xf bank_mask:0xf bound_ctrl:1
	v_mov_b32_dpp v197, v29 quad_perm:[1,0,3,2] row_mask:0xf bank_mask:0xf bound_ctrl:1
	v_pk_add_f32 v[28:29], v[28:29], v[196:197]
	s_nop 1
	v_mov_b32_dpp v196, v28 quad_perm:[2,3,0,1] row_mask:0xf bank_mask:0xf bound_ctrl:1
	v_mov_b32_dpp v197, v29 quad_perm:[2,3,0,1] row_mask:0xf bank_mask:0xf bound_ctrl:1
	v_pk_add_f32 v[28:29], v[28:29], v[196:197]
	s_nop 1
	v_mov_b32_dpp v196, v28 row_half_mirror row_mask:0xf bank_mask:0xf bound_ctrl:1
	v_mov_b32_dpp v197, v29 row_half_mirror row_mask:0xf bank_mask:0xf bound_ctrl:1
	v_pk_add_f32 v[28:29], v[28:29], v[196:197]
	s_nop 1
	v_mov_b32_dpp v196, v28 row_mirror row_mask:0xf bank_mask:0xf bound_ctrl:1
	v_mov_b32_dpp v197, v29 row_mirror row_mask:0xf bank_mask:0xf bound_ctrl:1
	s_and_saveexec_b64 s[6:7], vcc
	v_pk_add_f32 v[28:29], v[28:29], v[196:197]
	ds_write_b64 v181, v[28:29] offset:408
	s_or_b64 exec, exec, s[6:7]
	ds_read2_b32 v[196:197], v77 offset1:32
	ds_read2_b32 v[202:203], v77 offset0:64 offset1:96
	v_mov_b32_e32 v198, v62
	v_mov_b32_e32 v199, v30
	v_pk_add_f32 v[204:205], v[198:199], 0 op_sel_hi:[1,0]
	v_mov_b32_e32 v198, v46
	v_pk_add_f32 v[198:199], v[198:199], 0 op_sel_hi:[1,0]
	s_waitcnt lgkmcnt(1)
	v_mov_b32_e32 v206, v196
	s_waitcnt lgkmcnt(0)
	v_mov_b32_e32 v207, v202
	s_mov_b32 s2, s67
	v_mov_b32_e32 v212, v197
	v_mov_b32_e32 v213, v202
	v_pk_fma_f32 v[196:197], v[206:207], s[2:3], v[204:205] op_sel_hi:[1,0,1]
	v_pk_fma_f32 v[198:199], v[212:213], s[2:3], v[198:199] op_sel_hi:[1,0,1]
	v_pk_mul_f32 v[208:209], v[206:207], s[2:3] op_sel_hi:[1,0]
	v_pk_mul_f32 v[206:207], v[196:197], v[196:197]
	v_pk_mul_f32 v[212:213], v[198:199], v[198:199]
	v_pk_mov_b32 v[204:205], v[204:205], v[206:207] op_sel:[1,0]
	v_pk_mov_b32 v[206:207], v[208:209], v[212:213] op_sel:[1,0]
	v_add_f32_e32 v28, 0, v14
	v_pk_add_f32 v[204:205], v[204:205], v[206:207]
	v_pk_add_f32 v[206:207], v[196:197], v[198:199]
	v_pk_mul_f32 v[208:209], v[196:197], v[198:199]
	v_fmac_f32_e32 v28, 0x3fd744fd, v203
	v_mov_b32_e32 v207, v209
	v_pk_add_f32 v[204:205], v[206:207], v[204:205]
	v_mul_f32_e32 v29, v28, v28
	v_pk_add_f32 v[202:203], v[204:205], v[28:29]
	s_nop 1
	v_mov_b32_dpp v204, v202 quad_perm:[1,0,3,2] row_mask:0xf bank_mask:0xf bound_ctrl:1
	v_mov_b32_dpp v205, v203 quad_perm:[1,0,3,2] row_mask:0xf bank_mask:0xf bound_ctrl:1
	v_pk_add_f32 v[202:203], v[202:203], v[204:205]
	s_nop 1
	v_mov_b32_dpp v204, v202 quad_perm:[2,3,0,1] row_mask:0xf bank_mask:0xf bound_ctrl:1
	v_mov_b32_dpp v205, v203 quad_perm:[2,3,0,1] row_mask:0xf bank_mask:0xf bound_ctrl:1
	v_pk_add_f32 v[202:203], v[202:203], v[204:205]
	s_nop 1
	v_mov_b32_dpp v204, v202 row_half_mirror row_mask:0xf bank_mask:0xf bound_ctrl:1
	v_mov_b32_dpp v205, v203 row_half_mirror row_mask:0xf bank_mask:0xf bound_ctrl:1
	v_pk_add_f32 v[202:203], v[202:203], v[204:205]
	s_nop 1
	v_mov_b32_dpp v204, v202 row_mirror row_mask:0xf bank_mask:0xf bound_ctrl:1
	v_mov_b32_dpp v205, v203 row_mirror row_mask:0xf bank_mask:0xf bound_ctrl:1
	s_and_saveexec_b64 s[6:7], vcc
	v_pk_add_f32 v[202:203], v[202:203], v[204:205]
	ds_write_b64 v181, v[202:203] offset:448
	s_or_b64 exec, exec, s[6:7]
	ds_read2_b32 v[202:203], v91 offset1:32
	ds_read2_b32 v[204:205], v91 offset0:64 offset1:96
	v_mov_b32_e32 v30, v63
	v_pk_add_f32 v[206:207], v[30:31], 0 op_sel_hi:[1,0]
	v_mov_b32_e32 v30, v47
	v_pk_add_f32 v[30:31], v[30:31], 0 op_sel_hi:[1,0]
	s_waitcnt lgkmcnt(1)
	v_mov_b32_e32 v46, v202
	s_waitcnt lgkmcnt(0)
	v_mov_b32_e32 v47, v204
	s_mov_b32 s2, s67
	v_mov_b32_e32 v62, v203
	v_mov_b32_e32 v63, v204
	v_pk_mul_f32 v[208:209], v[46:47], s[2:3] op_sel_hi:[1,0]
	v_pk_fma_f32 v[46:47], v[46:47], s[2:3], v[206:207] op_sel_hi:[1,0,1]
	v_pk_fma_f32 v[62:63], v[62:63], s[2:3], v[30:31] op_sel_hi:[1,0,1]
	v_pk_mul_f32 v[202:203], v[46:47], v[46:47]
	v_pk_mul_f32 v[30:31], v[62:63], v[62:63]
	v_pk_mov_b32 v[202:203], v[206:207], v[202:203] op_sel:[1,0]
	v_pk_mov_b32 v[30:31], v[208:209], v[30:31] op_sel:[1,0]
	v_add_f32_e32 v14, 0, v15
	v_pk_add_f32 v[30:31], v[202:203], v[30:31]
	v_pk_add_f32 v[202:203], v[46:47], v[62:63]
	v_pk_mul_f32 v[206:207], v[46:47], v[62:63]
	v_fmac_f32_e32 v14, 0x3fd744fd, v205
	v_mov_b32_e32 v203, v207
	v_pk_add_f32 v[30:31], v[202:203], v[30:31]
	v_mul_f32_e32 v15, v14, v14
	v_pk_add_f32 v[30:31], v[30:31], v[14:15]
	s_nop 1
	v_mov_b32_dpp v202, v30 quad_perm:[1,0,3,2] row_mask:0xf bank_mask:0xf bound_ctrl:1
	v_mov_b32_dpp v203, v31 quad_perm:[1,0,3,2] row_mask:0xf bank_mask:0xf bound_ctrl:1
	v_pk_add_f32 v[30:31], v[30:31], v[202:203]
	s_nop 1
	v_mov_b32_dpp v202, v30 quad_perm:[2,3,0,1] row_mask:0xf bank_mask:0xf bound_ctrl:1
	v_mov_b32_dpp v203, v31 quad_perm:[2,3,0,1] row_mask:0xf bank_mask:0xf bound_ctrl:1
	v_pk_add_f32 v[30:31], v[30:31], v[202:203]
	s_nop 1
	v_mov_b32_dpp v202, v30 row_half_mirror row_mask:0xf bank_mask:0xf bound_ctrl:1
	v_mov_b32_dpp v203, v31 row_half_mirror row_mask:0xf bank_mask:0xf bound_ctrl:1
	v_pk_add_f32 v[30:31], v[30:31], v[202:203]
	s_nop 1
	v_mov_b32_dpp v202, v30 row_mirror row_mask:0xf bank_mask:0xf bound_ctrl:1
	v_mov_b32_dpp v203, v31 row_mirror row_mask:0xf bank_mask:0xf bound_ctrl:1
	s_and_saveexec_b64 s[6:7], vcc
	v_pk_add_f32 v[30:31], v[30:31], v[202:203]
	ds_write_b64 v181, v[30:31] offset:456
	s_or_b64 exec, exec, s[6:7]
	ds_read2_b32 v[202:203], v79 offset1:32
	ds_read2_b32 v[206:207], v79 offset0:64 offset1:96
	v_mov_b32_e32 v204, v64
	v_mov_b32_e32 v205, v32
	v_pk_add_f32 v[208:209], v[204:205], 0 op_sel_hi:[1,0]
	v_mov_b32_e32 v204, v48
	v_pk_add_f32 v[204:205], v[204:205], 0 op_sel_hi:[1,0]
	s_waitcnt lgkmcnt(1)
; DI void ag_st64(u64_t* p, u64_t v) { __hip_atomic_store(p, v, __ATOMIC_RELAXED, __HIP_MEMORY_SCOPE_AGENT); }
;   DI void operator()(f32x16 (&acc)[2][4], int grow0, int gcol0, int lane, int w, char* lds) {
;     ...
;           for (int nt = 0; nt < 4; ++nt) {
;             float v = (acc[mt][nt][i] + bia[nt]) * csc[nt];
;             float z = ALPHA * xr[nt * 32] + hs * v;
;             acc[mt][nt][i] = z; s1 += z; s2 += z * z;
;           }
;           s1 = row16_sum(s1); s2 = row16_sum(s2);
;           if ((lane & 15) == 0) { f32x2 sv = {s1, s2}; *(f32x2*)(redw + (mt * 32 + (i & 3) + 8 * (i >> 2)) * 2) = sv; }
;         }
;     }
;     __syncthreads();
;     u64_t* myslots = xstat + ((size_t)pm * 256) * 4;
;     if (tid < 256) {
;       float s1 = (red[tid * 2] + red[(256 + tid) * 2]) + (red[(512 + tid) * 2] + red[(768 + tid) * 2]);
;       float s2 = (red[tid * 2 + 1] + red[(256 + tid) * 2 + 1]) + (red[(512 + tid) * 2 + 1] + red[(768 + tid) * 2 + 1]);
;       ag_st64(myslots + tid * 4 + pn, ((u64_t)__float_as_uint(s2) << 32) | (u64_t)__float_as_uint(s1));
	v_mov_b32_e32 v212, v202
	s_waitcnt lgkmcnt(0)
	v_mov_b32_e32 v213, v206
	s_mov_b32 s2, s67
	v_mov_b32_e32 v226, v203
	v_mov_b32_e32 v227, v206
	v_pk_fma_f32 v[202:203], v[212:213], s[2:3], v[208:209] op_sel_hi:[1,0,1]
	v_pk_fma_f32 v[204:205], v[226:227], s[2:3], v[204:205] op_sel_hi:[1,0,1]
	v_pk_mul_f32 v[214:215], v[212:213], s[2:3] op_sel_hi:[1,0]
	v_pk_mul_f32 v[212:213], v[202:203], v[202:203]
	v_pk_mul_f32 v[226:227], v[204:205], v[204:205]
	v_pk_mov_b32 v[208:209], v[208:209], v[212:213] op_sel:[1,0]
	v_pk_mov_b32 v[212:213], v[214:215], v[226:227] op_sel:[1,0]
	v_add_f32_e32 v30, 0, v16
	v_pk_add_f32 v[208:209], v[208:209], v[212:213]
	v_pk_add_f32 v[212:213], v[202:203], v[204:205]
	v_pk_mul_f32 v[214:215], v[202:203], v[204:205]
	v_fmac_f32_e32 v30, 0x3fd744fd, v207
	v_mov_b32_e32 v213, v215
	v_pk_add_f32 v[208:209], v[212:213], v[208:209]
	v_mul_f32_e32 v31, v30, v30
	v_pk_add_f32 v[206:207], v[208:209], v[30:31]
	s_nop 1
	v_mov_b32_dpp v208, v206 quad_perm:[1,0,3,2] row_mask:0xf bank_mask:0xf bound_ctrl:1
	v_mov_b32_dpp v209, v207 quad_perm:[1,0,3,2] row_mask:0xf bank_mask:0xf bound_ctrl:1
	v_pk_add_f32 v[206:207], v[206:207], v[208:209]
	s_nop 1
	v_mov_b32_dpp v208, v206 quad_perm:[2,3,0,1] row_mask:0xf bank_mask:0xf bound_ctrl:1
	v_mov_b32_dpp v209, v207 quad_perm:[2,3,0,1] row_mask:0xf bank_mask:0xf bound_ctrl:1
	v_pk_add_f32 v[206:207], v[206:207], v[208:209]
	s_nop 1
	v_mov_b32_dpp v208, v206 row_half_mirror row_mask:0xf bank_mask:0xf bound_ctrl:1
	v_mov_b32_dpp v209, v207 row_half_mirror row_mask:0xf bank_mask:0xf bound_ctrl:1
	v_pk_add_f32 v[206:207], v[206:207], v[208:209]
	s_nop 1
	v_mov_b32_dpp v208, v206 row_mirror row_mask:0xf bank_mask:0xf bound_ctrl:1
	v_mov_b32_dpp v209, v207 row_mirror row_mask:0xf bank_mask:0xf bound_ctrl:1
	s_and_saveexec_b64 s[6:7], vcc
	v_pk_add_f32 v[206:207], v[206:207], v[208:209]
	ds_write_b64 v181, v[206:207] offset:464
	s_or_b64 exec, exec, s[6:7]
	ds_read2_b32 v[206:207], v93 offset1:32
	ds_read2_b32 v[208:209], v93 offset0:64 offset1:96
	v_mov_b32_e32 v32, v65
	v_pk_add_f32 v[64:65], v[32:33], 0 op_sel_hi:[1,0]
	v_mov_b32_e32 v32, v49
	v_pk_add_f32 v[48:49], v[32:33], 0 op_sel_hi:[1,0]
	s_waitcnt lgkmcnt(1)
	v_mov_b32_e32 v32, v206
	s_waitcnt lgkmcnt(0)
	v_mov_b32_e32 v33, v208
	s_mov_b32 s2, s67
	v_mov_b32_e32 v206, v207
	v_mov_b32_e32 v207, v208
	v_pk_mul_f32 v[212:213], v[32:33], s[2:3] op_sel_hi:[1,0]
	v_pk_fma_f32 v[32:33], v[32:33], s[2:3], v[64:65] op_sel_hi:[1,0,1]
	v_pk_fma_f32 v[48:49], v[206:207], s[2:3], v[48:49] op_sel_hi:[1,0,1]
	v_pk_mul_f32 v[214:215], v[32:33], v[32:33]
	v_pk_mul_f32 v[206:207], v[48:49], v[48:49]
	v_pk_mov_b32 v[64:65], v[64:65], v[214:215] op_sel:[1,0]
	v_pk_mov_b32 v[206:207], v[212:213], v[206:207] op_sel:[1,0]
	v_add_f32_e32 v16, 0, v17
	v_pk_add_f32 v[64:65], v[64:65], v[206:207]
	v_pk_add_f32 v[206:207], v[32:33], v[48:49]
	v_pk_mul_f32 v[212:213], v[32:33], v[48:49]
	v_fmac_f32_e32 v16, 0x3fd744fd, v209
	v_mov_b32_e32 v207, v213
	v_pk_add_f32 v[64:65], v[206:207], v[64:65]
	v_mul_f32_e32 v17, v16, v16
	v_pk_add_f32 v[64:65], v[64:65], v[16:17]
	s_nop 1
	v_mov_b32_dpp v206, v64 quad_perm:[1,0,3,2] row_mask:0xf bank_mask:0xf bound_ctrl:1
	v_mov_b32_dpp v207, v65 quad_perm:[1,0,3,2] row_mask:0xf bank_mask:0xf bound_ctrl:1
	v_pk_add_f32 v[64:65], v[64:65], v[206:207]
	s_nop 1
	v_mov_b32_dpp v206, v64 quad_perm:[2,3,0,1] row_mask:0xf bank_mask:0xf bound_ctrl:1
	v_mov_b32_dpp v207, v65 quad_perm:[2,3,0,1] row_mask:0xf bank_mask:0xf bound_ctrl:1
	v_pk_add_f32 v[64:65], v[64:65], v[206:207]
	s_nop 1
	v_mov_b32_dpp v206, v64 row_half_mirror row_mask:0xf bank_mask:0xf bound_ctrl:1
	v_mov_b32_dpp v207, v65 row_half_mirror row_mask:0xf bank_mask:0xf bound_ctrl:1
	v_pk_add_f32 v[64:65], v[64:65], v[206:207]
	s_nop 1
	v_mov_b32_dpp v206, v64 row_mirror row_mask:0xf bank_mask:0xf bound_ctrl:1
	v_mov_b32_dpp v207, v65 row_mirror row_mask:0xf bank_mask:0xf bound_ctrl:1
	s_and_saveexec_b64 s[6:7], vcc
	v_pk_add_f32 v[64:65], v[64:65], v[206:207]
	ds_write_b64 v181, v[64:65] offset:472
	s_or_b64 exec, exec, s[6:7]
	v_ashrrev_i32_e32 v206, 8, v163
	v_ashrrev_i32_e32 v207, 31, v206
	v_lshlrev_b64 v[64:65], 13, v[206:207]
	v_lshl_add_u64 v[64:65], s[8:9], 0, v[64:65]
	v_cmp_gt_i32_e64 s[40:41], s60, v164
	v_ashrrev_i32_e32 v201, 31, v200
	s_waitcnt lgkmcnt(0)
	s_barrier
	s_and_saveexec_b64 s[6:7], s[40:41]
	s_cbranch_execz .LBB0_240
	v_lshl_add_u32 v0, v164, 3, v221
	ds_read2st64_b64 v[212:215], v0 offset1:4
	ds_read2st64_b64 v[226:229], v0 offset0:8 offset1:12
	v_ashrrev_i32_e32 v208, 8, v184
	v_ashrrev_i32_e32 v209, 31, v208
	s_waitcnt lgkmcnt(1)
	v_mov_b32_e32 v230, v212
	s_waitcnt lgkmcnt(0)
	v_mov_b32_e32 v231, v226
	v_mov_b32_e32 v232, v214
	v_mov_b32_e32 v233, v228
	v_mov_b32_e32 v226, v213
	v_mov_b32_e32 v228, v215
	v_pk_add_f32 v[230:231], v[230:231], v[232:233]
	v_pk_add_f32 v[212:213], v[226:227], v[228:229]
	v_pk_add_f32 v[230:231], v[230:231], v[230:231] op_sel:[0,1] op_sel_hi:[1,0]
	v_pk_add_f32 v[212:213], v[212:213], v[212:213] op_sel:[0,1] op_sel_hi:[1,0]
	v_lshl_add_u64 v[214:215], v[200:201], 3, v[64:65]
	v_lshl_add_u64 v[208:209], v[208:209], 3, v[214:215]
	v_mov_b32_e32 v231, v212
	global_store_dwordx2 v[208:209], v[230:231], off sc1

; DI f32x16 zero16() { f32x16 z; for (int i = 0; i < 16; ++i) z[i] = 0.f; return z; }
; DI int launder(int x) { asm volatile("" : "+v"(x)); return x; }
; template <int BK> DI int swz(int row) { constexpr int CPR = BK / 8; return (row / (16 / CPR)) % CPR; }
; DI void wait_vm0() { asm volatile("s_waitcnt vmcnt(0)" ::: "memory"); }
;   DI void pre(int grow0, int gcol0, int lane, int w, char* lds) { xpass(0, grow0, gcol0, lane, w, lds); }
;     ...
;   const int tid = launder(threadIdx.x), lane = tid & 63, w = tid >> 6, wm = w % WM, wn = w / WM;
;   const int l31 = lane & 31, hh = lane >> 5;
;   f32x16 acc[2][NTW];
; #pragma unroll
;   for (int a = 0; a < 2; ++a)
; #pragma unroll
;     for (int b = 0; b < NTW; ++b) acc[a][b] = zero16();
;   const bf16_t* Ag = A + (size_t)row0 * lda; const bf16_t* Bg = Bt + (size_t)col0 * ldb;
;   const int wv = __builtin_amdgcn_readfirstlane(tid >> 6);
;   __syncthreads();
;   if (!pre) { stage_tile<BM, BK>(Ag, lda, lds, tid); stage_tile<BN, BK>(Bg, ldb, lds + ABYTES, tid); }
;   wait_vm0();
;   __syncthreads();
;   const int nk = K / BK;
;   for (int kt = 0; kt < nk; ++kt) {
;     char* cur = lds + (kt & 1) * STG; char* nxt = lds + ((kt + 1) & 1) * STG;
;     const bool more = kt + 1 < nk;
;     const bf16_t* An = Ag + (kt + 1) * BK; const bf16_t* Bn = Bg + (kt + 1) * BK;
;     if (!more) epi.pre(row0 + wm * 64, col0 + wn * (32 * NTW), lane, w, lds);
;     bf16x8 fa[2][2], fb[2][NTW];
; #pragma unroll
;     for (int mt = 0; mt < 2; ++mt) { int row = wm * 64 + mt * 32 + l31; fa[0][mt] = *(const bf16x8*)(cur + row * (BK * 2) + ((hh ^ swz<BK>(row)) << 4)); }
; #pragma unroll
;     for (int nt = 0; nt < NTW; ++nt) { int row = wn * (32 * NTW) + nt * 32 + l31; fb[0][nt] = *(const bf16x8*)(cur + ABYTES + row * (BK * 2) + ((hh ^ swz<BK>(row)) << 4)); }
.LBB0_283:
	v_lshrrev_b32_e32 v4, 30, v3
	v_add_u32_e32 v4, v3, v4
	v_ashrrev_i32_e32 v4, 2, v4
	v_mul_i32_i24_e32 v5, 4, v4
	v_sub_u32_e32 v3, v3, v5
	v_and_b32_e32 v5, 31, v2
	v_lshlrev_b32_e32 v7, 6, v3
	v_or_b32_e32 v7, v7, v5
	v_bfe_u32 v3, v3, 25, 1
	s_waitcnt vmcnt(0)
	v_lshlrev_b32_e32 v140, 7, v7
	v_add_u32_e32 v8, v7, v3
	v_or_b32_e32 v7, 32, v7
	v_add_u32_e32 v3, v7, v3
	v_lshlrev_b32_e32 v142, 7, v7
	v_ashrrev_i32_e32 v7, 1, v3
	v_ashrrev_i32_e32 v3, 31, v3
	v_ashrrev_i32_e32 v9, 1, v8
	v_ashrrev_i32_e32 v8, 31, v8
	v_lshrrev_b32_e32 v3, 29, v3
	v_lshrrev_b32_e32 v8, 29, v8
	v_add_u32_e32 v3, v7, v3
	v_add_u32_e32 v8, v9, v8
	v_and_b32_e32 v3, -8, v3
	v_lshrrev_b32_e32 v6, 5, v2
	v_and_b32_e32 v8, -8, v8
	v_sub_u32_e32 v3, v7, v3
	v_lshl_or_b32 v5, v4, 7, v5
	v_sub_u32_e32 v8, v9, v8
	v_bitop3_b32 v7, v3, v6, 1 bitop3:0x78
	v_lshrrev_b32_e32 v4, 31, v4
	v_bitop3_b32 v9, v8, v6, 1 bitop3:0x78
	v_lshlrev_b32_e32 v144, 4, v7
	v_add_u32_e32 v7, v5, v4
	v_lshlrev_b32_e32 v141, 4, v9
	v_ashrrev_i32_e32 v9, 1, v7
	v_ashrrev_i32_e32 v7, 31, v7
	v_lshrrev_b32_e32 v7, 29, v7
	v_add_u32_e32 v7, v9, v7
	v_and_b32_e32 v7, -8, v7
	v_sub_u32_e32 v7, v9, v7
	v_bitop3_b32 v9, v7, v6, 1 bitop3:0x78
	v_lshlrev_b32_e32 v151, 4, v9
	v_or_b32_e32 v9, 32, v5
	v_lshlrev_b32_e32 v152, 7, v9
	v_add_u32_e32 v9, v9, v4
	v_ashrrev_i32_e32 v10, 1, v9
	v_ashrrev_i32_e32 v9, 31, v9
	v_lshrrev_b32_e32 v9, 29, v9
	v_add_u32_e32 v9, v10, v9
	v_and_b32_e32 v9, -8, v9
	v_sub_u32_e32 v9, v10, v9
	v_bitop3_b32 v10, v9, v6, 1 bitop3:0x78
	v_lshlrev_b32_e32 v143, 7, v5
	v_lshlrev_b32_e32 v154, 4, v10
	v_or_b32_e32 v10, 64, v5
	v_or_b32_e32 v5, 0x60, v5
	v_lshlrev_b32_e32 v153, 7, v10
	v_add_u32_e32 v10, v10, v4
	v_add_u32_e32 v4, v5, v4
	v_lshlrev_b32_e32 v156, 7, v5
	v_ashrrev_i32_e32 v5, 1, v4
	v_ashrrev_i32_e32 v4, 31, v4
	v_lshrrev_b32_e32 v4, 29, v4
	v_add_u32_e32 v4, v5, v4
	v_and_b32_e32 v4, -8, v4
	v_sub_u32_e32 v4, v5, v4
	v_bfe_u32 v2, v2, 5, 1
	v_ashrrev_i32_e32 v11, 1, v10
	v_ashrrev_i32_e32 v10, 31, v10
	v_bitop3_b32 v5, v4, v6, 1 bitop3:0x78
	v_lshrrev_b32_e32 v10, 29, v10
	v_lshlrev_b32_e32 v164, 4, v5
	v_bitop3_b32 v5, v8, v2, 2 bitop3:0x1e
	v_add_u32_e32 v10, v11, v10
	v_lshlrev_b32_e32 v161, 4, v5
	v_bitop3_b32 v5, v3, v2, 2 bitop3:0x1e
	v_and_b32_e32 v10, -8, v10
	v_lshlrev_b32_e32 v163, 4, v5
	v_bitop3_b32 v5, v7, v2, 2 bitop3:0x1e
	v_sub_u32_e32 v10, v11, v10
	v_lshlrev_b32_e32 v159, 4, v5
	v_bitop3_b32 v5, v9, v2, 2 bitop3:0x1e
	s_lshr_b32 s7, s44, 3
	v_lshlrev_b32_e32 v160, 4, v5
	v_bitop3_b32 v5, v10, v2, 2 bitop3:0x1e
	s_and_b32 s7, s7, 7
	s_lshl_b32 s30, s37, 19
	v_lshlrev_b32_e32 v157, 4, v5
	v_bitop3_b32 v5, v4, v2, 2 bitop3:0x1e
	s_lshl_b32 s7, s7, 19
	s_and_b32 s30, s30, 0x1c00000
	v_lshlrev_b32_e32 v158, 4, v5
	v_bitop3_b32 v5, v8, v2, 4 bitop3:0x1e
	s_or_b32 s7, s30, s7
	s_and_b32 s30, s36, 0xffffff00
	v_lshlrev_b32_e32 v149, 4, v5
	v_bitop3_b32 v5, v3, v2, 4 bitop3:0x1e
	s_ashr_i32 s31, s30, 31
	v_lshlrev_b32_e32 v150, 4, v5
	v_bitop3_b32 v5, v7, v2, 4 bitop3:0x1e
	s_lshl_b64 s[30:31], s[30:31], 11
	s_lshl_b32 s3, s3, 10
	v_lshlrev_b32_e32 v147, 4, v5
	v_bitop3_b32 v5, v9, v2, 4 bitop3:0x1e
	v_bitop3_b32 v3, v3, v2, 6 bitop3:0x1e
	v_lshlrev_b32_e32 v148, 4, v5
	v_bitop3_b32 v5, v10, v2, 4 bitop3:0x1e
	v_lshlrev_b32_e32 v139, 4, v3
	v_bitop3_b32 v3, v7, v2, 6 bitop3:0x1e
	s_add_u32 s34, s12, s7
	v_lshlrev_b32_e32 v145, 4, v5
	v_bitop3_b32 v5, v4, v2, 4 bitop3:0x1e
	v_lshlrev_b32_e32 v136, 4, v3
	v_bitop3_b32 v3, v9, v2, 6 bitop3:0x1e
	s_addc_u32 s35, s13, 0
	s_waitcnt vmcnt(0)
	v_lshlrev_b32_e32 v146, 4, v5
	v_bitop3_b32 v5, v8, v2, 6 bitop3:0x1e
	v_lshlrev_b32_e32 v137, 4, v3
	v_bitop3_b32 v3, v10, v2, 6 bitop3:0x1e
	v_bitop3_b32 v2, v4, v2, 6 bitop3:0x1e
	s_add_u32 s30, s40, s30
	v_bitop3_b32 v11, v10, v6, 1 bitop3:0x78
	v_lshlrev_b32_e32 v135, 4, v2
	s_addc_u32 s31, s41, s31
	v_mov_b32_e32 v2, 0
	v_lshlrev_b32_e32 v155, 4, v11
	v_lshlrev_b32_e32 v138, 4, v5
	v_lshlrev_b32_e32 v134, 4, v3
	v_lshl_add_u64 v[130:131], s[34:35], 0, v[0:1]
	v_lshl_add_u64 v[132:133], s[30:31], 0, v[0:1]
	s_mov_b64 s[30:31], 0
	s_mov_b32 s7, 0x10000
	v_mov_b32_e32 v3, v2
	v_mov_b32_e32 v4, v2
	v_mov_b32_e32 v5, v2
	v_mov_b32_e32 v6, v2
	v_mov_b32_e32 v7, v2
	v_mov_b32_e32 v8, v2
	v_mov_b32_e32 v9, v2
	v_mov_b32_e32 v10, v2
	v_mov_b32_e32 v11, v2
	v_mov_b32_e32 v12, v2
	v_mov_b32_e32 v13, v2
	v_mov_b32_e32 v14, v2
	v_mov_b32_e32 v15, v2
	v_mov_b32_e32 v16, v2
	v_mov_b32_e32 v17, v2
	v_mov_b32_e32 v18, v2
	v_mov_b32_e32 v19, v2
	v_mov_b32_e32 v20, v2
	v_mov_b32_e32 v21, v2
	v_mov_b32_e32 v22, v2
	v_mov_b32_e32 v23, v2
	v_mov_b32_e32 v24, v2
	v_mov_b32_e32 v25, v2
	v_mov_b32_e32 v26, v2
	v_mov_b32_e32 v27, v2
	v_mov_b32_e32 v28, v2
	v_mov_b32_e32 v29, v2
	v_mov_b32_e32 v30, v2
	v_mov_b32_e32 v31, v2
	v_mov_b32_e32 v32, v2
	v_mov_b32_e32 v33, v2
	v_mov_b32_e32 v34, v2
	v_mov_b32_e32 v35, v2
	v_mov_b32_e32 v36, v2
	v_mov_b32_e32 v37, v2
	v_mov_b32_e32 v38, v2
	v_mov_b32_e32 v39, v2
	v_mov_b32_e32 v40, v2
	v_mov_b32_e32 v41, v2
	v_mov_b32_e32 v42, v2
	v_mov_b32_e32 v43, v2
	v_mov_b32_e32 v44, v2
	v_mov_b32_e32 v45, v2
	v_mov_b32_e32 v46, v2
	v_mov_b32_e32 v47, v2
	v_mov_b32_e32 v48, v2
	v_mov_b32_e32 v49, v2
	v_mov_b32_e32 v50, v2
	v_mov_b32_e32 v51, v2
	v_mov_b32_e32 v52, v2
	v_mov_b32_e32 v53, v2
	v_mov_b32_e32 v54, v2
	v_mov_b32_e32 v55, v2
	v_mov_b32_e32 v56, v2
	v_mov_b32_e32 v57, v2
	v_mov_b32_e32 v58, v2
	v_mov_b32_e32 v59, v2
	v_mov_b32_e32 v60, v2
	v_mov_b32_e32 v61, v2
	v_mov_b32_e32 v62, v2
	v_mov_b32_e32 v63, v2
	v_mov_b32_e32 v64, v2
	v_mov_b32_e32 v65, v2
	v_mov_b32_e32 v66, v2
	v_mov_b32_e32 v67, v2
	v_mov_b32_e32 v68, v2
	v_mov_b32_e32 v69, v2
;     ...
;   f32x16 acc[2][NTW];
; #pragma unroll
;   for (int a = 0; a < 2; ++a)
; #pragma unroll
;     for (int b = 0; b < NTW; ++b) acc[a][b] = zero16();
;   const bf16_t* Ag = A + (size_t)row0 * lda; const bf16_t* Bg = Bt + (size_t)col0 * ldb;
;   const int wv = __builtin_amdgcn_readfirstlane(tid >> 6);
;   __syncthreads();
;   if (!pre) { stage_tile<BM, BK>(Ag, lda, lds, tid); stage_tile<BN, BK>(Bg, ldb, lds + ABYTES, tid); }
;   wait_vm0();
;   __syncthreads();
;   const int nk = K / BK;
;   for (int kt = 0; kt < nk; ++kt) {
;     char* cur = lds + (kt & 1) * STG; char* nxt = lds + ((kt + 1) & 1) * STG;
;     const bool more = kt + 1 < nk;
;     const bf16_t* An = Ag + (kt + 1) * BK; const bf16_t* Bn = Bg + (kt + 1) * BK;
;     if (!more) epi.pre(row0 + wm * 64, col0 + wn * (32 * NTW), lane, w, lds);
;     bf16x8 fa[2][2], fb[2][NTW];
; #pragma unroll
;     for (int mt = 0; mt < 2; ++mt) { int row = wm * 64 + mt * 32 + l31; fa[0][mt] = *(const bf16x8*)(cur + row * (BK * 2) + ((hh ^ swz<BK>(row)) << 4)); }
; #pragma unroll
;     for (int nt = 0; nt < NTW; ++nt) { int row = wn * (32 * NTW) + nt * 32 + l31; fb[0][nt] = *(const bf16x8*)(cur + ABYTES + row * (BK * 2) + ((hh ^ swz<BK>(row)) << 4)); }
; #pragma unroll
;     for (int kk = 0; kk < NKK; ++kk) {
;       if (kk + 1 < NKK) {
;         const int ch = (kk + 1) * 2 + hh;
; #pragma unroll
;         for (int mt = 0; mt < 2; ++mt) { int row = wm * 64 + mt * 32 + l31; fa[(kk + 1) & 1][mt] = *(const bf16x8*)(cur + row * (BK * 2) + ((ch ^ swz<BK>(row)) << 4)); }
; #pragma unroll
;         for (int nt = 0; nt < NTW; ++nt) { int row = wn * (32 * NTW) + nt * 32 + l31; fb[(kk + 1) & 1][nt] = *(const bf16x8*)(cur + ABYTES + row * (BK * 2) + ((ch ^ swz<BK>(row)) << 4)); }
;       }
;       if (more) {
; #pragma unroll
;         for (int q = 0; q < PPK; ++q) {
;           const int pi = kk * PPK + q;
;           if (pi < NPA) stage_piece<BM, BK>(An, lda, nxt, tid, pi, wv);
;           else if (pi < NP) stage_piece<BN, BK>(Bn, ldb, nxt + ABYTES, tid, pi - NPA, wv);
;         }
;       }
;       __builtin_amdgcn_s_setprio(1);
; #pragma unroll
;       for (int mt = 0; mt < 2; ++mt)
; #pragma unroll
;         for (int nt = 0; nt < NTW; ++nt) acc[mt][nt] = mfma(fa[kk & 1][mt], fb[kk & 1][nt], acc[mt][nt]);
;       __builtin_amdgcn_s_setprio(0);
;       __builtin_amdgcn_sched_barrier(0);
;     }
	v_mov_b32_e32 v70, v2
	v_mov_b32_e32 v71, v2
	v_mov_b32_e32 v72, v2
	v_mov_b32_e32 v73, v2
	v_mov_b32_e32 v74, v2
	v_mov_b32_e32 v75, v2
	v_mov_b32_e32 v76, v2
	v_mov_b32_e32 v77, v2
	v_mov_b32_e32 v78, v2
	v_mov_b32_e32 v79, v2
	v_mov_b32_e32 v80, v2
	v_mov_b32_e32 v81, v2
	v_mov_b32_e32 v82, v2
	v_mov_b32_e32 v83, v2
	v_mov_b32_e32 v84, v2
	v_mov_b32_e32 v85, v2
	v_mov_b32_e32 v86, v2
	v_mov_b32_e32 v87, v2
	v_mov_b32_e32 v88, v2
	v_mov_b32_e32 v89, v2
	v_mov_b32_e32 v90, v2
	v_mov_b32_e32 v91, v2
	v_mov_b32_e32 v92, v2
	v_mov_b32_e32 v93, v2
	v_mov_b32_e32 v94, v2
	v_mov_b32_e32 v95, v2
	v_mov_b32_e32 v96, v2
	v_mov_b32_e32 v97, v2
	v_mov_b32_e32 v98, v2
	v_mov_b32_e32 v99, v2
	v_mov_b32_e32 v100, v2
	v_mov_b32_e32 v101, v2
	v_mov_b32_e32 v102, v2
	v_mov_b32_e32 v103, v2
	v_mov_b32_e32 v104, v2
	v_mov_b32_e32 v105, v2
	v_mov_b32_e32 v106, v2
	v_mov_b32_e32 v107, v2
	v_mov_b32_e32 v108, v2
	v_mov_b32_e32 v109, v2
	v_mov_b32_e32 v110, v2
	v_mov_b32_e32 v111, v2
	v_mov_b32_e32 v112, v2
	v_mov_b32_e32 v113, v2
	v_mov_b32_e32 v114, v2
	v_mov_b32_e32 v115, v2
	v_mov_b32_e32 v116, v2
	v_mov_b32_e32 v117, v2
	v_mov_b32_e32 v118, v2
	v_mov_b32_e32 v119, v2
	v_mov_b32_e32 v120, v2
	v_mov_b32_e32 v121, v2
	v_mov_b32_e32 v122, v2
	v_mov_b32_e32 v123, v2
	v_mov_b32_e32 v124, v2
	v_mov_b32_e32 v125, v2
	v_mov_b32_e32 v126, v2
	v_mov_b32_e32 v127, v2
	v_mov_b32_e32 v128, v2
	v_mov_b32_e32 v129, v2
	s_waitcnt vmcnt(0) lgkmcnt(0)
	s_barrier
	v_add_u32_e32 v166, v140, v141
	v_add_u32_e32 v170, v142, v144
	ds_read_b128 v[166:169], v166
	v_add_u32_e32 v174, v143, v151
	ds_read_b128 v[170:173], v170
	v_add_u32_e32 v178, v152, v154
	ds_read_b128 v[174:177], v174 offset:32768
	v_add_u32_e32 v182, v153, v155
	ds_read_b128 v[178:181], v178 offset:32768
	v_add_u32_e32 v186, v156, v164
	ds_read_b128 v[182:185], v182 offset:32768
	ds_read_b128 v[186:189], v186 offset:32768
	s_and_b32 s35, s7, 0x10000
	s_add_i32 s34, s35, s3
	v_lshl_add_u64 v[214:215], v[130:131], 0, s[30:31]
	v_lshl_add_u64 v[226:227], v[132:133], 0, s[30:31]
	s_mov_b32 m0, s34
	v_lshl_add_u64 v[228:229], v[214:215], 0, s[28:29]
	global_load_lds_dwordx4 v[228:229], off
	s_add_i32 m0, s34, 0x2000
	v_lshl_add_u64 v[228:229], v[214:215], 0, s[24:25]
	global_load_lds_dwordx4 v[228:229], off
	s_add_i32 m0, s34, 0x4000
	v_lshl_add_u64 v[228:229], v[214:215], 0, s[26:27]
	global_load_lds_dwordx4 v[228:229], off
	s_add_i32 m0, s34, 0x6000
	v_lshl_add_u64 v[228:229], v[214:215], 0, s[38:39]
	global_load_lds_dwordx4 v[228:229], off
	s_add_i32 m0, s34, 0x8000
	v_lshl_add_u64 v[228:229], v[226:227], 0, s[28:29]
	global_load_lds_dwordx4 v[228:229], off
	s_add_i32 m0, s34, 0xa000
	v_lshl_add_u64 v[228:229], v[226:227], 0, s[24:25]
	global_load_lds_dwordx4 v[228:229], off
	s_add_i32 m0, s34, 0xc000
	v_lshl_add_u64 v[228:229], v[226:227], 0, s[26:27]
	global_load_lds_dwordx4 v[228:229], off
	s_add_i32 m0, s34, 0xe000
	v_lshl_add_u64 v[228:229], v[226:227], 0, s[38:39]
	global_load_lds_dwordx4 v[228:229], off
.LBB0_284:
	s_and_b32 s35, s7, 0x10000
	s_xor_b32 s100, s35, 0x10000
	v_add3_u32 v190, s100, v140, v161
	v_add3_u32 v194, s100, v142, v163
	ds_read_b128 v[190:193], v190
	v_add3_u32 v198, s100, v143, v159
	ds_read_b128 v[194:197], v194
	v_add3_u32 v202, s100, v152, v160
	ds_read_b128 v[198:201], v198 offset:32768
	v_add3_u32 v206, s100, v153, v157
	ds_read_b128 v[202:205], v202 offset:32768
	v_add3_u32 v210, s100, v156, v158
	ds_read_b128 v[206:209], v206 offset:32768
	ds_read_b128 v[210:213], v210 offset:32768
	s_waitcnt lgkmcnt(6)
	v_mfma_f32_32x32x16_bf16 v[114:129], v[166:169], v[174:177], v[114:129]
	v_mfma_f32_32x32x16_bf16 v[98:113], v[166:169], v[178:181], v[98:113]
	v_mfma_f32_32x32x16_bf16 v[82:97], v[166:169], v[182:185], v[82:97]
	v_mfma_f32_32x32x16_bf16 v[66:81], v[166:169], v[186:189], v[66:81]
	v_mfma_f32_32x32x16_bf16 v[50:65], v[170:173], v[174:177], v[50:65]
	v_mfma_f32_32x32x16_bf16 v[34:49], v[170:173], v[178:181], v[34:49]
	v_mfma_f32_32x32x16_bf16 v[18:33], v[170:173], v[182:185], v[18:33]
	v_mfma_f32_32x32x16_bf16 v[2:17], v[170:173], v[186:189], v[2:17]
	v_add3_u32 v166, s100, v140, v149
	v_add3_u32 v170, s100, v142, v150
	ds_read_b128 v[166:169], v166
	v_add3_u32 v174, s100, v143, v147
	ds_read_b128 v[170:173], v170
	v_add3_u32 v178, s100, v152, v148
	ds_read_b128 v[174:177], v174 offset:32768
	v_add3_u32 v182, s100, v153, v145
	ds_read_b128 v[178:181], v178 offset:32768
	v_add3_u32 v186, s100, v156, v146
	ds_read_b128 v[182:185], v182 offset:32768
	ds_read_b128 v[186:189], v186 offset:32768
	s_waitcnt lgkmcnt(6)
	v_mfma_f32_32x32x16_bf16 v[114:129], v[190:193], v[198:201], v[114:129]
	v_mfma_f32_32x32x16_bf16 v[98:113], v[190:193], v[202:205], v[98:113]
	v_mfma_f32_32x32x16_bf16 v[82:97], v[190:193], v[206:209], v[82:97]
	v_mfma_f32_32x32x16_bf16 v[66:81], v[190:193], v[210:213], v[66:81]
	v_mfma_f32_32x32x16_bf16 v[50:65], v[194:197], v[198:201], v[50:65]
	v_mfma_f32_32x32x16_bf16 v[34:49], v[194:197], v[202:205], v[34:49]
	v_mfma_f32_32x32x16_bf16 v[18:33], v[194:197], v[206:209], v[18:33]
	v_mfma_f32_32x32x16_bf16 v[2:17], v[194:197], v[210:213], v[2:17]
	v_add3_u32 v190, s100, v140, v138
	v_add3_u32 v194, s100, v142, v139
	ds_read_b128 v[190:193], v190
	v_add3_u32 v198, s100, v143, v136
	ds_read_b128 v[194:197], v194
	v_add3_u32 v202, s100, v152, v137
	ds_read_b128 v[198:201], v198 offset:32768
	v_add3_u32 v206, s100, v153, v134
	ds_read_b128 v[202:205], v202 offset:32768
	v_add3_u32 v210, s100, v156, v135
	ds_read_b128 v[206:209], v206 offset:32768
	ds_read_b128 v[210:213], v210 offset:32768
	s_waitcnt lgkmcnt(6)
	v_mfma_f32_32x32x16_bf16 v[114:129], v[166:169], v[174:177], v[114:129]
	v_mfma_f32_32x32x16_bf16 v[98:113], v[166:169], v[178:181], v[98:113]
	v_mfma_f32_32x32x16_bf16 v[82:97], v[166:169], v[182:185], v[82:97]
	v_mfma_f32_32x32x16_bf16 v[66:81], v[166:169], v[186:189], v[66:81]
	v_mfma_f32_32x32x16_bf16 v[50:65], v[170:173], v[174:177], v[50:65]
	v_mfma_f32_32x32x16_bf16 v[34:49], v[170:173], v[178:181], v[34:49]
	v_mfma_f32_32x32x16_bf16 v[18:33], v[170:173], v[182:185], v[18:33]
	v_mfma_f32_32x32x16_bf16 v[2:17], v[170:173], v[186:189], v[2:17]
	s_add_u32 s30, s30, 0x80
	s_addc_u32 s31, s31, 0
	s_add_i32 s7, s7, 0x10000
	s_waitcnt vmcnt(0) lgkmcnt(0)
	s_barrier
; DI f32x16 mfma(bf16x8 a, bf16x8 b, f32x16 c) { return __builtin_amdgcn_mfma_f32_32x32x16_bf16(a, b, c, 0, 0, 0); }
; template <int BK> DI int swz(int row) { constexpr int CPR = BK / 8; return (row / (16 / CPR)) % CPR; }
; DI void wait_vm0() { asm volatile("s_waitcnt vmcnt(0)" ::: "memory"); }
;   DI void pre(int grow0, int gcol0, int lane, int w, char* lds) { xpass(0, grow0, gcol0, lane, w, lds); }
;     ...
;   for (int kt = 0; kt < nk; ++kt) {
;     char* cur = lds + (kt & 1) * STG; char* nxt = lds + ((kt + 1) & 1) * STG;
;     const bool more = kt + 1 < nk;
;     const bf16_t* An = Ag + (kt + 1) * BK; const bf16_t* Bn = Bg + (kt + 1) * BK;
;     if (!more) epi.pre(row0 + wm * 64, col0 + wn * (32 * NTW), lane, w, lds);
;     bf16x8 fa[2][2], fb[2][NTW];
; #pragma unroll
;     for (int mt = 0; mt < 2; ++mt) { int row = wm * 64 + mt * 32 + l31; fa[0][mt] = *(const bf16x8*)(cur + row * (BK * 2) + ((hh ^ swz<BK>(row)) << 4)); }
; #pragma unroll
;     for (int nt = 0; nt < NTW; ++nt) { int row = wn * (32 * NTW) + nt * 32 + l31; fb[0][nt] = *(const bf16x8*)(cur + ABYTES + row * (BK * 2) + ((hh ^ swz<BK>(row)) << 4)); }
; #pragma unroll
;     for (int kk = 0; kk < NKK; ++kk) {
;       if (kk + 1 < NKK) {
;         const int ch = (kk + 1) * 2 + hh;
; #pragma unroll
;         for (int mt = 0; mt < 2; ++mt) { int row = wm * 64 + mt * 32 + l31; fa[(kk + 1) & 1][mt] = *(const bf16x8*)(cur + row * (BK * 2) + ((ch ^ swz<BK>(row)) << 4)); }
; #pragma unroll
;         for (int nt = 0; nt < NTW; ++nt) { int row = wn * (32 * NTW) + nt * 32 + l31; fb[(kk + 1) & 1][nt] = *(const bf16x8*)(cur + ABYTES + row * (BK * 2) + ((ch ^ swz<BK>(row)) << 4)); }
;       }
;       if (more) {
; #pragma unroll
;         for (int q = 0; q < PPK; ++q) {
;           const int pi = kk * PPK + q;
;           if (pi < NPA) stage_piece<BM, BK>(An, lda, nxt, tid, pi, wv);
;           else if (pi < NP) stage_piece<BN, BK>(Bn, ldb, nxt + ABYTES, tid, pi - NPA, wv);
;         }
;       }
;       __builtin_amdgcn_s_setprio(1);
; #pragma unroll
;       for (int mt = 0; mt < 2; ++mt)
; #pragma unroll
;         for (int nt = 0; nt < NTW; ++nt) acc[mt][nt] = mfma(fa[kk & 1][mt], fb[kk & 1][nt], acc[mt][nt]);
;       __builtin_amdgcn_s_setprio(0);
;       __builtin_amdgcn_sched_barrier(0);
;     }
;     wait_vm0();
;     __syncthreads();
	v_add3_u32 v166, s35, v140, v141
	v_add3_u32 v170, s35, v142, v144
	ds_read_b128 v[166:169], v166
	v_add3_u32 v174, s35, v143, v151
	ds_read_b128 v[170:173], v170
	v_add3_u32 v178, s35, v152, v154
	ds_read_b128 v[174:177], v174 offset:32768
	v_add3_u32 v182, s35, v153, v155
	ds_read_b128 v[178:181], v178 offset:32768
	v_add3_u32 v186, s35, v156, v164
	ds_read_b128 v[182:185], v182 offset:32768
	ds_read_b128 v[186:189], v186 offset:32768
	s_cmpk_eq_i32 s30, 0x780
	s_cbranch_scc1 .Lk284_exit
	s_add_i32 s34, s100, s3
	v_lshl_add_u64 v[214:215], v[130:131], 0, s[30:31]
	v_lshl_add_u64 v[226:227], v[132:133], 0, s[30:31]
	s_mov_b32 m0, s34
	v_lshl_add_u64 v[228:229], v[214:215], 0, s[28:29]
	v_mfma_f32_32x32x16_bf16 v[114:129], v[190:193], v[198:201], v[114:129]
	global_load_lds_dwordx4 v[228:229], off
	v_lshl_add_u64 v[228:229], v[214:215], 0, s[24:25]
	s_add_i32 m0, s34, 0x2000
	v_mfma_f32_32x32x16_bf16 v[98:113], v[190:193], v[202:205], v[98:113]
	global_load_lds_dwordx4 v[228:229], off
	v_lshl_add_u64 v[228:229], v[214:215], 0, s[26:27]
	s_add_i32 m0, s34, 0x4000
	v_mfma_f32_32x32x16_bf16 v[82:97], v[190:193], v[206:209], v[82:97]
	global_load_lds_dwordx4 v[228:229], off
	v_lshl_add_u64 v[228:229], v[214:215], 0, s[38:39]
	s_add_i32 m0, s34, 0x6000
	v_mfma_f32_32x32x16_bf16 v[66:81], v[190:193], v[210:213], v[66:81]
	global_load_lds_dwordx4 v[228:229], off
	v_lshl_add_u64 v[228:229], v[226:227], 0, s[28:29]
	s_add_i32 m0, s34, 0x8000
	v_mfma_f32_32x32x16_bf16 v[50:65], v[194:197], v[198:201], v[50:65]
	global_load_lds_dwordx4 v[228:229], off
	v_lshl_add_u64 v[228:229], v[226:227], 0, s[24:25]
	s_add_i32 m0, s34, 0xa000
	v_mfma_f32_32x32x16_bf16 v[34:49], v[194:197], v[202:205], v[34:49]
	global_load_lds_dwordx4 v[228:229], off
	v_lshl_add_u64 v[228:229], v[226:227], 0, s[26:27]
	s_add_i32 m0, s34, 0xc000
	v_mfma_f32_32x32x16_bf16 v[18:33], v[194:197], v[206:209], v[18:33]
	global_load_lds_dwordx4 v[228:229], off
	v_lshl_add_u64 v[228:229], v[226:227], 0, s[38:39]
	s_add_i32 m0, s34, 0xe000
	v_mfma_f32_32x32x16_bf16 v[2:17], v[194:197], v[210:213], v[2:17]
	global_load_lds_dwordx4 v[228:229], off
	s_branch .LBB0_284
.Lk284_exit:
	v_mfma_f32_32x32x16_bf16 v[114:129], v[190:193], v[198:201], v[114:129]
	v_mfma_f32_32x32x16_bf16 v[98:113], v[190:193], v[202:205], v[98:113]
	v_mfma_f32_32x32x16_bf16 v[82:97], v[190:193], v[206:209], v[82:97]
	v_mfma_f32_32x32x16_bf16 v[66:81], v[190:193], v[210:213], v[66:81]
	v_mfma_f32_32x32x16_bf16 v[50:65], v[194:197], v[198:201], v[50:65]
	v_mfma_f32_32x32x16_bf16 v[34:49], v[194:197], v[202:205], v[34:49]
	v_mfma_f32_32x32x16_bf16 v[18:33], v[194:197], v[206:209], v[18:33]
	v_mfma_f32_32x32x16_bf16 v[2:17], v[194:197], v[210:213], v[2:17]
	s_waitcnt lgkmcnt(0)
	v_add_u32_e32 v0, 0x10000, v140
	v_add_u32_e32 v198, 0x10000, v142
	v_add_u32_e32 v130, v0, v141
	v_add_u32_e32 v140, v198, v144
	v_add_u32_e32 v199, 0x18000, v143
	v_add_u32_e32 v200, 0x18000, v152
	ds_read_b128 v[130:133], v130
	ds_read_b128 v[166:169], v140
	v_add_u32_e32 v140, v199, v151
	v_add_u32_e32 v144, v200, v154
	v_add_u32_e32 v201, 0x18000, v153
	ds_read_b128 v[140:143], v140
	ds_read_b128 v[170:173], v144
	v_add_u32_e32 v144, v201, v155
	v_add_u32_e32 v202, 0x18000, v156
	v_add_u32_e32 v151, v202, v164
	ds_read_b128 v[152:155], v144
	ds_read_b128 v[174:177], v151
	v_add_u32_e32 v144, v0, v161
	v_add_u32_e32 v151, v198, v163
	ds_read_b128 v[178:181], v144
	ds_read_b128 v[182:185], v151
	v_add_u32_e32 v144, v199, v159
	v_add_u32_e32 v151, v200, v160
	ds_read_b128 v[186:189], v144
	ds_read_b128 v[190:193], v151
	v_add_u32_e32 v144, v201, v157
	v_add_u32_e32 v151, v202, v158
	ds_read_b128 v[156:159], v144
	ds_read_b128 v[194:197], v151
	s_add_i32 s44, s44, s94
	s_cmpk_gt_i32 s44, 0xff
	s_cselect_b64 s[30:31], -1, 0
	s_cmpk_lt_i32 s44, 0x100
	s_setprio 1
	s_waitcnt lgkmcnt(9)
	v_mfma_f32_32x32x16_bf16 v[114:129], v[130:133], v[140:143], v[114:129]
	s_waitcnt lgkmcnt(8)
	v_mfma_f32_32x32x16_bf16 v[98:113], v[130:133], v[170:173], v[98:113]
	s_waitcnt lgkmcnt(7)
	v_mfma_f32_32x32x16_bf16 v[82:97], v[130:133], v[152:155], v[82:97]
	s_waitcnt lgkmcnt(6)
	v_mfma_f32_32x32x16_bf16 v[66:81], v[130:133], v[174:177], v[66:81]
	v_mfma_f32_32x32x16_bf16 v[50:65], v[166:169], v[140:143], v[50:65]
	v_mfma_f32_32x32x16_bf16 v[34:49], v[166:169], v[170:173], v[34:49]
	v_mfma_f32_32x32x16_bf16 v[18:33], v[166:169], v[152:155], v[18:33]
	v_mfma_f32_32x32x16_bf16 v[2:17], v[166:169], v[174:177], v[2:17]
	s_setprio 0
	v_add_u32_e32 v130, v0, v149
	v_add_u32_e32 v140, v198, v150
	v_add_u32_e32 v144, v199, v147
	ds_read_b128 v[130:133], v130
	ds_read_b128 v[140:143], v140
	v_add_u32_e32 v147, v200, v148
	ds_read_b128 v[148:151], v144
	ds_read_b128 v[152:155], v147
	v_add_u32_e32 v144, v201, v145
	v_add_u32_e32 v160, v202, v146
	ds_read_b128 v[144:147], v144
	ds_read_b128 v[166:169], v160
	s_setprio 1
	s_waitcnt lgkmcnt(9)
;     ...
;   for (int kt = 0; kt < nk; ++kt) {
;     char* cur = lds + (kt & 1) * STG; char* nxt = lds + ((kt + 1) & 1) * STG;
;     const bool more = kt + 1 < nk;
;     const bf16_t* An = Ag + (kt + 1) * BK; const bf16_t* Bn = Bg + (kt + 1) * BK;
;     if (!more) epi.pre(row0 + wm * 64, col0 + wn * (32 * NTW), lane, w, lds);
;     bf16x8 fa[2][2], fb[2][NTW];
; #pragma unroll
;     for (int mt = 0; mt < 2; ++mt) { int row = wm * 64 + mt * 32 + l31; fa[0][mt] = *(const bf16x8*)(cur + row * (BK * 2) + ((hh ^ swz<BK>(row)) << 4)); }
; #pragma unroll
;     for (int nt = 0; nt < NTW; ++nt) { int row = wn * (32 * NTW) + nt * 32 + l31; fb[0][nt] = *(const bf16x8*)(cur + ABYTES + row * (BK * 2) + ((hh ^ swz<BK>(row)) << 4)); }
; #pragma unroll
;     for (int kk = 0; kk < NKK; ++kk) {
;       if (kk + 1 < NKK) {
;         const int ch = (kk + 1) * 2 + hh;
; #pragma unroll
;         for (int mt = 0; mt < 2; ++mt) { int row = wm * 64 + mt * 32 + l31; fa[(kk + 1) & 1][mt] = *(const bf16x8*)(cur + row * (BK * 2) + ((ch ^ swz<BK>(row)) << 4)); }
; #pragma unroll
;         for (int nt = 0; nt < NTW; ++nt) { int row = wn * (32 * NTW) + nt * 32 + l31; fb[(kk + 1) & 1][nt] = *(const bf16x8*)(cur + ABYTES + row * (BK * 2) + ((ch ^ swz<BK>(row)) << 4)); }
;       }
;       if (more) {
; #pragma unroll
;         for (int q = 0; q < PPK; ++q) {
;           const int pi = kk * PPK + q;
;           if (pi < NPA) stage_piece<BM, BK>(An, lda, nxt, tid, pi, wv);
;           else if (pi < NP) stage_piece<BN, BK>(Bn, ldb, nxt + ABYTES, tid, pi - NPA, wv);
;         }
;       }
;       __builtin_amdgcn_s_setprio(1);
; #pragma unroll
;       for (int mt = 0; mt < 2; ++mt)
; #pragma unroll
;         for (int nt = 0; nt < NTW; ++nt) acc[mt][nt] = mfma(fa[kk & 1][mt], fb[kk & 1][nt], acc[mt][nt]);
;       __builtin_amdgcn_s_setprio(0);
;       __builtin_amdgcn_sched_barrier(0);
;     }
;     wait_vm0();
;     __syncthreads();
;   }
;   if (has_next) { const int tid3 = launder(threadIdx.x); stage_tile<BM, BK>(A + (size_t)row0n * lda, lda, lds, tid3); stage_tile<BN, BK>(Bt + (size_t)col0n * ldb, ldb, lds + ABYTES, tid3); }
; template <class Epi>
; DI void gemm_phase256(const bf16_t* A, int lda, const bf16_t* Bt, int K, int nN, char* lds, Epi& epi, int vb) {
;     ...
;   for (int t = vb; t < ntiles; t += gridDim.x) {
;     const int x = t & 7, L = t >> 3; const int pm = 8 * x + (L & 7), pn = L >> 3;
	v_mfma_f32_32x32x16_bf16 v[114:129], v[178:181], v[186:189], v[114:129]
	s_waitcnt lgkmcnt(8)
	v_mfma_f32_32x32x16_bf16 v[98:113], v[178:181], v[190:193], v[98:113]
	s_waitcnt lgkmcnt(7)
	v_mfma_f32_32x32x16_bf16 v[82:97], v[178:181], v[156:159], v[82:97]
	s_waitcnt lgkmcnt(6)
	v_mfma_f32_32x32x16_bf16 v[66:81], v[178:181], v[194:197], v[66:81]
	v_mfma_f32_32x32x16_bf16 v[50:65], v[182:185], v[186:189], v[50:65]
	v_mfma_f32_32x32x16_bf16 v[34:49], v[182:185], v[190:193], v[34:49]
	v_mfma_f32_32x32x16_bf16 v[18:33], v[182:185], v[156:159], v[18:33]
	v_mfma_f32_32x32x16_bf16 v[2:17], v[182:185], v[194:197], v[2:17]
	s_setprio 0
	v_add_u32_e32 v0, v0, v138
	v_add_u32_e32 v138, v198, v139
	ds_read_b128 v[156:159], v0
	ds_read_b128 v[170:173], v138
	v_add_u32_e32 v0, v199, v136
	v_add_u32_e32 v160, v200, v137
	ds_read_b128 v[136:139], v0
	ds_read_b128 v[174:177], v160
	v_add_u32_e32 v0, v201, v134
	v_add_u32_e32 v134, v202, v135
	ds_read_b128 v[178:181], v0
	ds_read_b128 v[182:185], v134
	s_setprio 1
	s_waitcnt lgkmcnt(9)
	v_mfma_f32_32x32x16_bf16 v[114:129], v[130:133], v[148:151], v[114:129]
	s_waitcnt lgkmcnt(8)
	v_mfma_f32_32x32x16_bf16 v[98:113], v[130:133], v[152:155], v[98:113]
	s_waitcnt lgkmcnt(7)
	v_mfma_f32_32x32x16_bf16 v[82:97], v[130:133], v[144:147], v[82:97]
	s_waitcnt lgkmcnt(6)
	v_mfma_f32_32x32x16_bf16 v[66:81], v[130:133], v[166:169], v[66:81]
	v_mfma_f32_32x32x16_bf16 v[50:65], v[140:143], v[148:151], v[50:65]
	v_mfma_f32_32x32x16_bf16 v[34:49], v[140:143], v[152:155], v[34:49]
	v_mfma_f32_32x32x16_bf16 v[18:33], v[140:143], v[144:147], v[18:33]
	v_mfma_f32_32x32x16_bf16 v[2:17], v[140:143], v[166:169], v[2:17]
	s_setprio 0
	s_setprio 1
	s_waitcnt lgkmcnt(3)
	v_mfma_f32_32x32x16_bf16 v[114:129], v[156:159], v[136:139], v[114:129]
	s_waitcnt lgkmcnt(2)
	v_mfma_f32_32x32x16_bf16 v[98:113], v[156:159], v[174:177], v[98:113]
	s_waitcnt lgkmcnt(1)
	v_mfma_f32_32x32x16_bf16 v[82:97], v[156:159], v[178:181], v[82:97]
	s_waitcnt lgkmcnt(0)
	v_mfma_f32_32x32x16_bf16 v[66:81], v[156:159], v[182:185], v[66:81]
	v_mfma_f32_32x32x16_bf16 v[50:65], v[170:173], v[136:139], v[50:65]
	v_mfma_f32_32x32x16_bf16 v[34:49], v[170:173], v[174:177], v[34:49]
	v_mfma_f32_32x32x16_bf16 v[18:33], v[170:173], v[178:181], v[18:33]
	v_mfma_f32_32x32x16_bf16 v[2:17], v[170:173], v[182:185], v[2:17]
	s_setprio 0
	s_waitcnt vmcnt(0)
	s_barrier
	s_cbranch_scc0 .LBB0_280
	v_mov_b32_e32 v132, v216
	s_lshl_b32 s3, s44, 3
	v_ashrrev_i32_e32 v0, 31, v132
	v_lshrrev_b32_e32 v130, 29, v0
	v_lshrrev_b32_e32 v0, 28, v0
	v_add_u32_e32 v0, v132, v0
	v_ashrrev_i32_e32 v0, 4, v0
	s_and_b32 s3, s3, 56
	s_bfe_u32 s7, s44, 0x30003
	v_lshrrev_b32_e32 v133, 29, v0
	s_or_b32 s3, s3, s7
	s_lshl_b32 s7, s44, 2
	v_add_u32_e32 v130, v132, v130
	v_add_u32_e32 v133, v0, v133
	s_and_b32 s34, s7, 0xffffff00
	s_lshl_b32 s3, s3, 19
	v_and_b32_e32 v131, 0xffffff8, v130
	v_and_b32_e32 v133, 0xffffff8, v133
	s_add_u32 s46, s12, s3
	v_sub_u32_e32 v131, v132, v131
	v_sub_u32_e32 v0, v0, v133
	v_lshlrev_b32_e32 v130, 8, v130
	v_readfirstlane_b32 s3, v132
	s_addc_u32 s47, s13, 0
	v_xor_b32_e32 v0, v0, v131
	v_and_b32_e32 v130, 0xfffff800, v130
	s_lshl_b32 s3, s3, 4
	v_lshl_add_u32 v0, v0, 4, v130
	s_and_b32 s3, s3, 0xfffffc00
	v_lshl_add_u64 v[130:131], s[46:47], 0, v[0:1]
	s_mov_b32 m0, s3
	v_lshl_add_u64 v[132:133], v[130:131], 0, s[58:59]
	global_load_lds_dwordx4 v0, s[46:47]
	s_add_i32 m0, s3, 0x2000
	s_ashr_i32 s35, s34, 31
	global_load_lds_dwordx4 v[132:133], off
	v_lshl_add_u64 v[132:133], v[130:131], 0, s[48:49]
	s_add_i32 m0, s3, 0x4000
	s_lshl_b64 s[34:35], s[34:35], 11
	global_load_lds_dwordx4 v[132:133], off
	s_add_i32 m0, s3, 0x6000
	s_add_u32 s34, s40, s34
	v_lshl_add_u64 v[130:131], v[130:131], 0, s[50:51]
	s_addc_u32 s35, s41, s35
	global_load_lds_dwordx4 v[130:131], off
	v_lshl_add_u64 v[130:131], s[34:35], 0, v[0:1]
	s_add_i32 m0, s3, 0x8000
	v_lshl_add_u64 v[132:133], v[130:131], 0, s[58:59]
	global_load_lds_dwordx4 v0, s[34:35]
	s_add_i32 m0, s3, 0xa000
	s_nop 0
	global_load_lds_dwordx4 v[132:133], off
	v_lshl_add_u64 v[132:133], v[130:131], 0, s[48:49]
	s_add_i32 m0, s3, 0xc000
	v_lshl_add_u64 v[130:131], v[130:131], 0, s[50:51]
	global_load_lds_dwordx4 v[132:133], off
	s_add_i32 m0, s3, 0xe000
	s_nop 0
	global_load_lds_dwordx4 v[130:131], off
	s_branch .LBB0_280

; DI f32x16 zero16() { f32x16 z; for (int i = 0; i < 16; ++i) z[i] = 0.f; return z; }
; DI int launder(int x) { asm volatile("" : "+v"(x)); return x; }
; template <int BK> DI int swz(int row) { constexpr int CPR = BK / 8; return (row / (16 / CPR)) % CPR; }
; DI void wait_vm0() { asm volatile("s_waitcnt vmcnt(0)" ::: "memory"); }
; template <int ROWS, int BK>
; DI void stage_tile(const bf16_t* g, int ld, char* l, int tid) {
;   constexpr int CPR = BK / 8, TOT = ROWS * CPR, N = (TOT + NT - 1) / NT;
;   const int row0 = tid / CPR, pc = tid % CPR; const int c = pc ^ swz<BK>(row0);
;   const unsigned voff = (unsigned)(row0 * ld + c * 8) * 2u;
; #pragma unroll
;   for (int i = 0; i < N; ++i) {
;     if (TOT % NT == 0 || tid + i * NT < TOT) {
;       const char* gb = (const char*)g + (size_t)i * (NT / CPR) * ld * 2;
;       __builtin_amdgcn_global_load_lds((const unsigned*)(gb + voff), (__attribute__((address_space(3))) unsigned*)(l + i * NT * 16 + __builtin_amdgcn_readfirstlane(tid >> 6) * 1024), 16, 0, 0);
;     }
;   }
; }
;     ...
;   const int tid = launder(threadIdx.x), lane = tid & 63, w = tid >> 6, wm = w % WM, wn = w / WM;
;   const int l31 = lane & 31, hh = lane >> 5;
;   f32x16 acc[2][NTW];
; #pragma unroll
;   for (int a = 0; a < 2; ++a)
; #pragma unroll
;     for (int b = 0; b < NTW; ++b) acc[a][b] = zero16();
;   const bf16_t* Ag = A + (size_t)row0 * lda; const bf16_t* Bg = Bt + (size_t)col0 * ldb;
;   const int wv = __builtin_amdgcn_readfirstlane(tid >> 6);
;   __syncthreads();
;   if (!pre) { stage_tile<BM, BK>(Ag, lda, lds, tid); stage_tile<BN, BK>(Bg, ldb, lds + ABYTES, tid); }
;   wait_vm0();
;   __syncthreads();
;   const int nk = K / BK;
;   for (int kt = 0; kt < nk; ++kt) {
;     char* cur = lds + (kt & 1) * STG; char* nxt = lds + ((kt + 1) & 1) * STG;
;     const bool more = kt + 1 < nk;
;     const bf16_t* An = Ag + (kt + 1) * BK; const bf16_t* Bn = Bg + (kt + 1) * BK;
;     if (!more) epi.pre(row0 + wm * 64, col0 + wn * (32 * NTW), lane, w, lds);
;     bf16x8 fa[2][2], fb[2][NTW];
; #pragma unroll
;     for (int mt = 0; mt < 2; ++mt) { int row = wm * 64 + mt * 32 + l31; fa[0][mt] = *(const bf16x8*)(cur + row * (BK * 2) + ((hh ^ swz<BK>(row)) << 4)); }
; #pragma unroll
;     for (int nt = 0; nt < NTW; ++nt) { int row = wn * (32 * NTW) + nt * 32 + l31; fb[0][nt] = *(const bf16x8*)(cur + ABYTES + row * (BK * 2) + ((hh ^ swz<BK>(row)) << 4)); }
.LBB0_290:
	s_cmp_lg_u32 s71, 0
	s_cbranch_scc0 .LBB0_369
	v_readlane_b32 s2, v255, 39
	v_readlane_b32 s3, v255, 40
	v_mov_b32_e32 v8, v216
	s_load_dwordx2 s[2:3], s[2:3], 0x140
	v_readlane_b32 s30, v253, 27
	v_ashrrev_i32_e32 v2, 31, v8
	v_lshrrev_b32_e32 v3, 29, v2
	v_lshrrev_b32_e32 v2, 28, v2
	v_add_u32_e32 v2, v8, v2
	v_ashrrev_i32_e32 v2, 4, v2
	v_lshrrev_b32_e32 v5, 29, v2
	v_add_u32_e32 v3, v8, v3
	v_add_u32_e32 v5, v2, v5
	v_lshrrev_b32_e32 v4, 3, v3
	v_and_b32_e32 v3, 0xffffff8, v3
	v_and_b32_e32 v5, 0xffffff8, v5
	s_mul_i32 s6, s30, 0x1600
	v_sub_u32_e32 v3, v8, v3
	v_sub_u32_e32 v2, v2, v5
	s_movk_i32 s7, 0x1600
	s_waitcnt lgkmcnt(0)
	s_add_u32 s2, s2, s6
	s_mul_hi_i32 s6, s30, 0x1600
	v_xor_b32_e32 v2, v2, v3
	v_mul_lo_u32 v3, v4, s7
	v_readfirstlane_b32 s7, v8
	v_readlane_b32 s31, v253, 28
	s_addc_u32 s3, s3, s6
	s_lshl_b32 s7, s7, 4
	v_readlane_b32 s30, v253, 37
	s_and_b32 s7, s7, 0xfffffc00
	v_lshl_add_u32 v2, v2, 4, v3
	v_mov_b32_e32 v3, v1
	v_readlane_b32 s31, v253, 38
	s_mov_b32 m0, s7
	s_waitcnt vmcnt(0)
	s_barrier
	v_lshl_add_u64 v[4:5], s[30:31], 0, v[2:3]
	s_nop 0
	global_load_lds_dwordx4 v2, s[30:31]
	s_mov_b64 s[30:31], 0x58000
	v_lshl_add_u64 v[6:7], v[4:5], 0, s[30:31]
	s_add_i32 m0, s7, 0x2000
	s_mov_b64 s[34:35], 0xb0000
	global_load_lds_dwordx4 v[6:7], off
	v_lshl_add_u64 v[6:7], v[4:5], 0, s[34:35]
	s_add_i32 m0, s7, 0x4000
	s_mov_b64 s[36:37], 0x108000
	global_load_lds_dwordx4 v[6:7], off
	v_lshl_add_u64 v[4:5], v[4:5], 0, s[36:37]
	s_add_i32 m0, s7, 0x6000
	v_lshl_add_u64 v[130:131], s[2:3], 0, v[2:3]
	global_load_lds_dwordx4 v[4:5], off
	s_add_i32 m0, s7, 0x8000
	v_lshl_add_u64 v[4:5], v[130:131], 0, s[30:31]
	global_load_lds_dwordx4 v2, s[2:3]
	s_add_i32 m0, s7, 0xa000
	v_ashrrev_i32_e32 v134, 6, v8
	global_load_lds_dwordx4 v[4:5], off
	v_lshl_add_u64 v[4:5], v[130:131], 0, s[34:35]
	s_add_i32 m0, s7, 0xc000
	v_and_b32_e32 v6, 31, v8
	global_load_lds_dwordx4 v[4:5], off
	v_lshl_add_u64 v[4:5], v[130:131], 0, s[36:37]
	s_add_i32 m0, s7, 0xe000
	v_and_b32_e32 v0, 63, v8
	global_load_lds_dwordx4 v[4:5], off
	v_lshrrev_b32_e32 v4, 30, v134
	v_add_u32_e32 v4, v134, v4
	v_ashrrev_i32_e32 v5, 2, v4
	v_mul_i32_i24_e32 v7, 4, v5
	v_sub_u32_e32 v7, v134, v7
	v_lshlrev_b32_e32 v169, 6, v7
	v_lshlrev_b32_e32 v168, 7, v5
	v_or_b32_e32 v5, v169, v6
	v_bfe_u32 v7, v7, 25, 1
	v_bfe_u32 v135, v8, 5, 1
	v_lshlrev_b32_e32 v136, 7, v5
	v_add_u32_e32 v8, v5, v7
	v_or_b32_e32 v5, 32, v5
	v_lshlrev_b32_e32 v144, 7, v5
	v_add_u32_e32 v5, v5, v7
	v_ashrrev_i32_e32 v7, 1, v5
	v_ashrrev_i32_e32 v5, 31, v5
	v_ashrrev_i32_e32 v9, 1, v8
	v_ashrrev_i32_e32 v8, 31, v8
	v_lshrrev_b32_e32 v5, 29, v5
	v_lshrrev_b32_e32 v8, 29, v8
	v_add_u32_e32 v5, v7, v5
	v_add_u32_e32 v8, v9, v8
	v_and_b32_e32 v5, -8, v5
	v_and_b32_e32 v8, -8, v8
	v_sub_u32_e32 v5, v7, v5
	v_or_b32_e32 v6, v168, v6
	v_sub_u32_e32 v8, v9, v8
	v_xor_b32_e32 v7, v5, v135
	v_lshrrev_b32_e32 v4, 31, v4
	v_xor_b32_e32 v9, v8, v135
	v_lshlrev_b32_e32 v146, 4, v7
	v_add_u32_e32 v7, v6, v4
	v_lshlrev_b32_e32 v143, 4, v9
	v_ashrrev_i32_e32 v9, 1, v7
	v_ashrrev_i32_e32 v7, 31, v7
	v_lshrrev_b32_e32 v7, 29, v7
	v_add_u32_e32 v7, v9, v7
	v_and_b32_e32 v7, -8, v7
	v_sub_u32_e32 v7, v9, v7
	v_xor_b32_e32 v9, v7, v135
	v_lshlrev_b32_e32 v151, 4, v9
	v_or_b32_e32 v9, 32, v6
	v_lshlrev_b32_e32 v152, 7, v9
	v_add_u32_e32 v9, v9, v4
	v_ashrrev_i32_e32 v10, 1, v9
	v_ashrrev_i32_e32 v9, 31, v9
	v_lshrrev_b32_e32 v9, 29, v9
	v_add_u32_e32 v9, v10, v9
	v_and_b32_e32 v9, -8, v9
	v_sub_u32_e32 v9, v10, v9
	v_xor_b32_e32 v10, v9, v135
	v_lshlrev_b32_e32 v145, 7, v6
	v_lshlrev_b32_e32 v156, 4, v10
	v_or_b32_e32 v10, 64, v6
	v_or_b32_e32 v6, 0x60, v6
	v_lshlrev_b32_e32 v155, 7, v10
	v_add_u32_e32 v10, v10, v4
	v_add_u32_e32 v4, v6, v4
	v_lshlrev_b32_e32 v158, 7, v6
	v_ashrrev_i32_e32 v6, 1, v4
	v_ashrrev_i32_e32 v4, 31, v4
	v_lshrrev_b32_e32 v4, 29, v4
	v_add_u32_e32 v4, v6, v4
	v_and_b32_e32 v4, -8, v4
	v_sub_u32_e32 v4, v6, v4
	v_ashrrev_i32_e32 v11, 1, v10
	v_ashrrev_i32_e32 v10, 31, v10
	v_xor_b32_e32 v6, v4, v135
	v_lshrrev_b32_e32 v10, 29, v10
	v_lshlrev_b32_e32 v167, 4, v6
	v_bitop3_b32 v6, v8, v135, 2 bitop3:0x1e
	v_add_u32_e32 v10, v11, v10
	v_lshlrev_b32_e32 v164, 4, v6
	v_bitop3_b32 v6, v5, v135, 2 bitop3:0x1e
	v_and_b32_e32 v10, -8, v10
	v_lshlrev_b32_e32 v166, 4, v6
	v_bitop3_b32 v6, v7, v135, 2 bitop3:0x1e
	v_sub_u32_e32 v10, v11, v10
	v_lshlrev_b32_e32 v161, 4, v6
	v_bitop3_b32 v6, v9, v135, 2 bitop3:0x1e
	v_lshlrev_b32_e32 v163, 4, v6
	v_bitop3_b32 v6, v10, v135, 2 bitop3:0x1e
	v_lshlrev_b32_e32 v159, 4, v6
	v_bitop3_b32 v6, v4, v135, 2 bitop3:0x1e
	v_lshlrev_b32_e32 v160, 4, v6
	v_bitop3_b32 v6, v8, v135, 4 bitop3:0x1e
	v_lshlrev_b32_e32 v153, 4, v6
	v_bitop3_b32 v6, v5, v135, 4 bitop3:0x1e
	v_lshlrev_b32_e32 v154, 4, v6
	v_bitop3_b32 v6, v7, v135, 4 bitop3:0x1e
	v_readfirstlane_b32 s6, v134
	v_lshlrev_b32_e32 v149, 4, v6
	v_bitop3_b32 v6, v9, v135, 4 bitop3:0x1e
	v_bitop3_b32 v5, v5, v135, 6 bitop3:0x1e
	s_lshl_b32 s2, s6, 10
	v_lshlrev_b32_e32 v150, 4, v6
	v_bitop3_b32 v6, v10, v135, 4 bitop3:0x1e
	v_lshlrev_b32_e32 v142, 4, v5
	v_bitop3_b32 v5, v7, v135, 6 bitop3:0x1e
	v_readlane_b32 s6, v254, 36
	s_waitcnt vmcnt(0)
; DI f32x16 zero16() { f32x16 z; for (int i = 0; i < 16; ++i) z[i] = 0.f; return z; }
; template <int BK> DI int swz(int row) { constexpr int CPR = BK / 8; return (row / (16 / CPR)) % CPR; }
; DI void wait_vm0() { asm volatile("s_waitcnt vmcnt(0)" ::: "memory"); }
;   DI void pre(int grow0, int gcol0, int lane, int w, char* lds) { xpass(0, grow0, gcol0, lane, w, lds); }
;     ...
;   f32x16 acc[2][NTW];
; #pragma unroll
;   for (int a = 0; a < 2; ++a)
; #pragma unroll
;     for (int b = 0; b < NTW; ++b) acc[a][b] = zero16();
;   const bf16_t* Ag = A + (size_t)row0 * lda; const bf16_t* Bg = Bt + (size_t)col0 * ldb;
;   const int wv = __builtin_amdgcn_readfirstlane(tid >> 6);
;   __syncthreads();
;   if (!pre) { stage_tile<BM, BK>(Ag, lda, lds, tid); stage_tile<BN, BK>(Bg, ldb, lds + ABYTES, tid); }
;   wait_vm0();
;   __syncthreads();
;   const int nk = K / BK;
;   for (int kt = 0; kt < nk; ++kt) {
;     char* cur = lds + (kt & 1) * STG; char* nxt = lds + ((kt + 1) & 1) * STG;
;     const bool more = kt + 1 < nk;
;     const bf16_t* An = Ag + (kt + 1) * BK; const bf16_t* Bn = Bg + (kt + 1) * BK;
;     if (!more) epi.pre(row0 + wm * 64, col0 + wn * (32 * NTW), lane, w, lds);
;     bf16x8 fa[2][2], fb[2][NTW];
; #pragma unroll
;     for (int mt = 0; mt < 2; ++mt) { int row = wm * 64 + mt * 32 + l31; fa[0][mt] = *(const bf16x8*)(cur + row * (BK * 2) + ((hh ^ swz<BK>(row)) << 4)); }
; #pragma unroll
;     for (int nt = 0; nt < NTW; ++nt) { int row = wn * (32 * NTW) + nt * 32 + l31; fb[0][nt] = *(const bf16x8*)(cur + ABYTES + row * (BK * 2) + ((hh ^ swz<BK>(row)) << 4)); }
; #pragma unroll
;     for (int kk = 0; kk < NKK; ++kk) {
;       if (kk + 1 < NKK) {
;         const int ch = (kk + 1) * 2 + hh;
; #pragma unroll
;         for (int mt = 0; mt < 2; ++mt) { int row = wm * 64 + mt * 32 + l31; fa[(kk + 1) & 1][mt] = *(const bf16x8*)(cur + row * (BK * 2) + ((ch ^ swz<BK>(row)) << 4)); }
; #pragma unroll
;         for (int nt = 0; nt < NTW; ++nt) { int row = wn * (32 * NTW) + nt * 32 + l31; fb[(kk + 1) & 1][nt] = *(const bf16x8*)(cur + ABYTES + row * (BK * 2) + ((ch ^ swz<BK>(row)) << 4)); }
	v_lshlrev_b32_e32 v147, 4, v6
	v_bitop3_b32 v6, v4, v135, 4 bitop3:0x1e
	v_lshlrev_b32_e32 v139, 4, v5
	v_bitop3_b32 v5, v9, v135, 6 bitop3:0x1e
	v_readlane_b32 s7, v254, 37
	v_xor_b32_e32 v11, v10, v135
	v_lshlrev_b32_e32 v148, 4, v6
	v_bitop3_b32 v6, v8, v135, 6 bitop3:0x1e
	v_lshlrev_b32_e32 v140, 4, v5
	v_bitop3_b32 v5, v10, v135, 6 bitop3:0x1e
	v_bitop3_b32 v4, v4, v135, 6 bitop3:0x1e
	v_lshl_add_u64 v[132:133], s[6:7], 0, v[2:3]
	v_mov_b32_e32 v2, 0
	v_lshlrev_b32_e32 v157, 4, v11
	v_lshlrev_b32_e32 v141, 4, v6
	v_lshlrev_b32_e32 v137, 4, v5
	v_lshlrev_b32_e32 v138, 4, v4
	s_mov_b64 s[6:7], 0
	s_mov_b32 s3, 0x10000
	v_mov_b32_e32 v3, v2
	v_mov_b32_e32 v4, v2
	v_mov_b32_e32 v5, v2
	v_mov_b32_e32 v6, v2
	v_mov_b32_e32 v7, v2
	v_mov_b32_e32 v8, v2
	v_mov_b32_e32 v9, v2
	v_mov_b32_e32 v10, v2
	v_mov_b32_e32 v11, v2
	v_mov_b32_e32 v12, v2
	v_mov_b32_e32 v13, v2
	v_mov_b32_e32 v14, v2
	v_mov_b32_e32 v15, v2
	v_mov_b32_e32 v16, v2
	v_mov_b32_e32 v17, v2
	v_mov_b32_e32 v18, v2
	v_mov_b32_e32 v19, v2
	v_mov_b32_e32 v20, v2
	v_mov_b32_e32 v21, v2
	v_mov_b32_e32 v22, v2
	v_mov_b32_e32 v23, v2
	v_mov_b32_e32 v24, v2
	v_mov_b32_e32 v25, v2
	v_mov_b32_e32 v26, v2
	v_mov_b32_e32 v27, v2
	v_mov_b32_e32 v28, v2
	v_mov_b32_e32 v29, v2
	v_mov_b32_e32 v30, v2
	v_mov_b32_e32 v31, v2
	v_mov_b32_e32 v32, v2
	v_mov_b32_e32 v33, v2
	v_mov_b32_e32 v34, v2
	v_mov_b32_e32 v35, v2
	v_mov_b32_e32 v36, v2
	v_mov_b32_e32 v37, v2
	v_mov_b32_e32 v38, v2
	v_mov_b32_e32 v39, v2
	v_mov_b32_e32 v40, v2
	v_mov_b32_e32 v41, v2
	v_mov_b32_e32 v42, v2
	v_mov_b32_e32 v43, v2
	v_mov_b32_e32 v44, v2
	v_mov_b32_e32 v45, v2
	v_mov_b32_e32 v46, v2
	v_mov_b32_e32 v47, v2
	v_mov_b32_e32 v48, v2
	v_mov_b32_e32 v49, v2
	v_mov_b32_e32 v50, v2
	v_mov_b32_e32 v51, v2
	v_mov_b32_e32 v52, v2
	v_mov_b32_e32 v53, v2
	v_mov_b32_e32 v54, v2
	v_mov_b32_e32 v55, v2
	v_mov_b32_e32 v56, v2
	v_mov_b32_e32 v57, v2
	v_mov_b32_e32 v58, v2
	v_mov_b32_e32 v59, v2
	v_mov_b32_e32 v60, v2
	v_mov_b32_e32 v61, v2
	v_mov_b32_e32 v62, v2
	v_mov_b32_e32 v63, v2
	v_mov_b32_e32 v64, v2
	v_mov_b32_e32 v65, v2
	v_mov_b32_e32 v66, v2
	v_mov_b32_e32 v67, v2
	v_mov_b32_e32 v68, v2
	v_mov_b32_e32 v69, v2
	v_mov_b32_e32 v70, v2
	v_mov_b32_e32 v71, v2
	v_mov_b32_e32 v72, v2
	v_mov_b32_e32 v73, v2
	v_mov_b32_e32 v74, v2
	v_mov_b32_e32 v75, v2
	v_mov_b32_e32 v76, v2
	v_mov_b32_e32 v77, v2
	v_mov_b32_e32 v78, v2
	v_mov_b32_e32 v79, v2
	v_mov_b32_e32 v80, v2
	v_mov_b32_e32 v81, v2
	v_mov_b32_e32 v82, v2
	v_mov_b32_e32 v83, v2
	v_mov_b32_e32 v84, v2
	v_mov_b32_e32 v85, v2
	v_mov_b32_e32 v86, v2
	v_mov_b32_e32 v87, v2
	v_mov_b32_e32 v88, v2
	v_mov_b32_e32 v89, v2
	v_mov_b32_e32 v90, v2
	v_mov_b32_e32 v91, v2
	v_mov_b32_e32 v92, v2
	v_mov_b32_e32 v93, v2
	v_mov_b32_e32 v94, v2
	v_mov_b32_e32 v95, v2
	v_mov_b32_e32 v96, v2
	v_mov_b32_e32 v97, v2
	v_mov_b32_e32 v98, v2
	v_mov_b32_e32 v99, v2
	v_mov_b32_e32 v100, v2
	v_mov_b32_e32 v101, v2
	v_mov_b32_e32 v102, v2
	v_mov_b32_e32 v103, v2
	v_mov_b32_e32 v104, v2
	v_mov_b32_e32 v105, v2
	v_mov_b32_e32 v106, v2
	v_mov_b32_e32 v107, v2
	v_mov_b32_e32 v108, v2
	v_mov_b32_e32 v109, v2
	v_mov_b32_e32 v110, v2
	v_mov_b32_e32 v111, v2
	v_mov_b32_e32 v112, v2
	v_mov_b32_e32 v113, v2
	v_mov_b32_e32 v114, v2
	v_mov_b32_e32 v115, v2
	v_mov_b32_e32 v116, v2
	v_mov_b32_e32 v117, v2
	v_mov_b32_e32 v118, v2
	v_mov_b32_e32 v119, v2
	v_mov_b32_e32 v120, v2
	v_mov_b32_e32 v121, v2
	v_mov_b32_e32 v122, v2
	v_mov_b32_e32 v123, v2
	v_mov_b32_e32 v124, v2
	v_mov_b32_e32 v125, v2
	v_mov_b32_e32 v126, v2
	v_mov_b32_e32 v127, v2
	v_mov_b32_e32 v128, v2
	v_mov_b32_e32 v129, v2
	s_mov_b64 s[36:37], 0x58080
	s_mov_b64 s[40:41], 0xb0080
	s_mov_b64 s[42:43], 0x108080
	s_waitcnt vmcnt(0) lgkmcnt(0)
	s_barrier
	v_add_u32_e32 v170, v136, v143
	v_add_u32_e32 v174, v144, v146
	ds_read_b128 v[170:173], v170
	v_add_u32_e32 v178, v145, v151
	ds_read_b128 v[174:177], v174
	v_add_u32_e32 v182, v152, v156
	ds_read_b128 v[178:181], v178 offset:32768
	v_add_u32_e32 v186, v155, v157
	ds_read_b128 v[182:185], v182 offset:32768
	v_add_u32_e32 v190, v158, v167
	ds_read_b128 v[186:189], v186 offset:32768
	ds_read_b128 v[190:193], v190 offset:32768
	s_and_b32 s30, s3, 0x10000
	s_add_i32 s31, s30, s2
	v_lshl_add_u64 v[214:215], v[132:133], 0, s[6:7]
	v_lshl_add_u64 v[230:231], v[130:131], 0, s[6:7]
	s_mov_b32 m0, s31
	v_lshl_add_u64 v[232:233], v[214:215], 0, s[28:29]
	global_load_lds_dwordx4 v[232:233], off
	s_add_i32 m0, s31, 0x2000
	v_lshl_add_u64 v[232:233], v[214:215], 0, s[36:37]
	global_load_lds_dwordx4 v[232:233], off
	s_add_i32 m0, s31, 0x4000
	v_lshl_add_u64 v[232:233], v[214:215], 0, s[40:41]
	global_load_lds_dwordx4 v[232:233], off
	s_add_i32 m0, s31, 0x6000
	v_lshl_add_u64 v[232:233], v[214:215], 0, s[42:43]
	global_load_lds_dwordx4 v[232:233], off
	s_add_i32 m0, s31, 0x8000
	v_lshl_add_u64 v[232:233], v[230:231], 0, s[28:29]
	global_load_lds_dwordx4 v[232:233], off
	s_add_i32 m0, s31, 0xa000
	v_lshl_add_u64 v[232:233], v[230:231], 0, s[36:37]
	global_load_lds_dwordx4 v[232:233], off
	s_add_i32 m0, s31, 0xc000
	v_lshl_add_u64 v[232:233], v[230:231], 0, s[40:41]
	global_load_lds_dwordx4 v[232:233], off
	s_add_i32 m0, s31, 0xe000
	v_lshl_add_u64 v[232:233], v[230:231], 0, s[42:43]
	global_load_lds_dwordx4 v[232:233], off
; DI f32x16 mfma(bf16x8 a, bf16x8 b, f32x16 c) { return __builtin_amdgcn_mfma_f32_32x32x16_bf16(a, b, c, 0, 0, 0); }
; template <int BK> DI int swz(int row) { constexpr int CPR = BK / 8; return (row / (16 / CPR)) % CPR; }
; DI void wait_vm0() { asm volatile("s_waitcnt vmcnt(0)" ::: "memory"); }
;   DI void pre(int grow0, int gcol0, int lane, int w, char* lds) { xpass(0, grow0, gcol0, lane, w, lds); }
;     ...
;   for (int kt = 0; kt < nk; ++kt) {
;     char* cur = lds + (kt & 1) * STG; char* nxt = lds + ((kt + 1) & 1) * STG;
;     const bool more = kt + 1 < nk;
;     const bf16_t* An = Ag + (kt + 1) * BK; const bf16_t* Bn = Bg + (kt + 1) * BK;
;     if (!more) epi.pre(row0 + wm * 64, col0 + wn * (32 * NTW), lane, w, lds);
;     bf16x8 fa[2][2], fb[2][NTW];
; #pragma unroll
;     for (int mt = 0; mt < 2; ++mt) { int row = wm * 64 + mt * 32 + l31; fa[0][mt] = *(const bf16x8*)(cur + row * (BK * 2) + ((hh ^ swz<BK>(row)) << 4)); }
; #pragma unroll
;     for (int nt = 0; nt < NTW; ++nt) { int row = wn * (32 * NTW) + nt * 32 + l31; fb[0][nt] = *(const bf16x8*)(cur + ABYTES + row * (BK * 2) + ((hh ^ swz<BK>(row)) << 4)); }
; #pragma unroll
;     for (int kk = 0; kk < NKK; ++kk) {
;       if (kk + 1 < NKK) {
;         const int ch = (kk + 1) * 2 + hh;
; #pragma unroll
;         for (int mt = 0; mt < 2; ++mt) { int row = wm * 64 + mt * 32 + l31; fa[(kk + 1) & 1][mt] = *(const bf16x8*)(cur + row * (BK * 2) + ((ch ^ swz<BK>(row)) << 4)); }
; #pragma unroll
;         for (int nt = 0; nt < NTW; ++nt) { int row = wn * (32 * NTW) + nt * 32 + l31; fb[(kk + 1) & 1][nt] = *(const bf16x8*)(cur + ABYTES + row * (BK * 2) + ((ch ^ swz<BK>(row)) << 4)); }
;       }
;       if (more) {
; #pragma unroll
;         for (int q = 0; q < PPK; ++q) {
;           const int pi = kk * PPK + q;
;           if (pi < NPA) stage_piece<BM, BK>(An, lda, nxt, tid, pi, wv);
;           else if (pi < NP) stage_piece<BN, BK>(Bn, ldb, nxt + ABYTES, tid, pi - NPA, wv);
;         }
;       }
;       __builtin_amdgcn_s_setprio(1);
; #pragma unroll
;       for (int mt = 0; mt < 2; ++mt)
; #pragma unroll
;         for (int nt = 0; nt < NTW; ++nt) acc[mt][nt] = mfma(fa[kk & 1][mt], fb[kk & 1][nt], acc[mt][nt]);
;       __builtin_amdgcn_s_setprio(0);
;       __builtin_amdgcn_sched_barrier(0);
;     }
;     wait_vm0();
;     __syncthreads();
.LBB0_292:
	s_and_b32 s30, s3, 0x10000
	s_xor_b32 s100, s30, 0x10000
	v_add3_u32 v194, s100, v136, v164
	v_add3_u32 v198, s100, v144, v166
	ds_read_b128 v[194:197], v194
	v_add3_u32 v202, s100, v145, v161
	ds_read_b128 v[198:201], v198
	v_add3_u32 v206, s100, v152, v163
	ds_read_b128 v[202:205], v202 offset:32768
	v_add3_u32 v210, s100, v155, v159
	ds_read_b128 v[206:209], v206 offset:32768
	v_add3_u32 v226, s100, v158, v160
	ds_read_b128 v[210:213], v210 offset:32768
	ds_read_b128 v[226:229], v226 offset:32768
	s_waitcnt lgkmcnt(6)
	v_mfma_f32_32x32x16_bf16 v[114:129], v[170:173], v[178:181], v[114:129]
	v_mfma_f32_32x32x16_bf16 v[98:113], v[170:173], v[182:185], v[98:113]
	v_mfma_f32_32x32x16_bf16 v[82:97], v[170:173], v[186:189], v[82:97]
	v_mfma_f32_32x32x16_bf16 v[66:81], v[170:173], v[190:193], v[66:81]
	v_mfma_f32_32x32x16_bf16 v[50:65], v[174:177], v[178:181], v[50:65]
	v_mfma_f32_32x32x16_bf16 v[34:49], v[174:177], v[182:185], v[34:49]
	v_mfma_f32_32x32x16_bf16 v[18:33], v[174:177], v[186:189], v[18:33]
	v_mfma_f32_32x32x16_bf16 v[2:17], v[174:177], v[190:193], v[2:17]
	v_add3_u32 v170, s100, v136, v153
	v_add3_u32 v174, s100, v144, v154
	ds_read_b128 v[170:173], v170
	v_add3_u32 v178, s100, v145, v149
	ds_read_b128 v[174:177], v174
	v_add3_u32 v182, s100, v152, v150
	ds_read_b128 v[178:181], v178 offset:32768
	v_add3_u32 v186, s100, v155, v147
	ds_read_b128 v[182:185], v182 offset:32768
	v_add3_u32 v190, s100, v158, v148
	ds_read_b128 v[186:189], v186 offset:32768
	ds_read_b128 v[190:193], v190 offset:32768
	s_waitcnt lgkmcnt(6)
	v_mfma_f32_32x32x16_bf16 v[114:129], v[194:197], v[202:205], v[114:129]
	v_mfma_f32_32x32x16_bf16 v[98:113], v[194:197], v[206:209], v[98:113]
	v_mfma_f32_32x32x16_bf16 v[82:97], v[194:197], v[210:213], v[82:97]
	v_mfma_f32_32x32x16_bf16 v[66:81], v[194:197], v[226:229], v[66:81]
	v_mfma_f32_32x32x16_bf16 v[50:65], v[198:201], v[202:205], v[50:65]
	v_mfma_f32_32x32x16_bf16 v[34:49], v[198:201], v[206:209], v[34:49]
	v_mfma_f32_32x32x16_bf16 v[18:33], v[198:201], v[210:213], v[18:33]
	v_mfma_f32_32x32x16_bf16 v[2:17], v[198:201], v[226:229], v[2:17]
	v_add3_u32 v194, s100, v136, v141
	v_add3_u32 v198, s100, v144, v142
	ds_read_b128 v[194:197], v194
	v_add3_u32 v202, s100, v145, v139
	ds_read_b128 v[198:201], v198
	v_add3_u32 v206, s100, v152, v140
	ds_read_b128 v[202:205], v202 offset:32768
	v_add3_u32 v210, s100, v155, v137
	ds_read_b128 v[206:209], v206 offset:32768
	v_add3_u32 v226, s100, v158, v138
	ds_read_b128 v[210:213], v210 offset:32768
	ds_read_b128 v[226:229], v226 offset:32768
	s_waitcnt lgkmcnt(6)
	v_mfma_f32_32x32x16_bf16 v[114:129], v[170:173], v[178:181], v[114:129]
	v_mfma_f32_32x32x16_bf16 v[98:113], v[170:173], v[182:185], v[98:113]
	v_mfma_f32_32x32x16_bf16 v[82:97], v[170:173], v[186:189], v[82:97]
	v_mfma_f32_32x32x16_bf16 v[66:81], v[170:173], v[190:193], v[66:81]
	v_mfma_f32_32x32x16_bf16 v[50:65], v[174:177], v[178:181], v[50:65]
	v_mfma_f32_32x32x16_bf16 v[34:49], v[174:177], v[182:185], v[34:49]
	v_mfma_f32_32x32x16_bf16 v[18:33], v[174:177], v[186:189], v[18:33]
	v_mfma_f32_32x32x16_bf16 v[2:17], v[174:177], v[190:193], v[2:17]
	s_add_u32 s6, s6, 0x80
	s_addc_u32 s7, s7, 0
	s_add_i32 s3, s3, 0x10000
	s_waitcnt vmcnt(0) lgkmcnt(0)
	s_barrier
	v_add3_u32 v170, s30, v136, v143
	v_add3_u32 v174, s30, v144, v146
	ds_read_b128 v[170:173], v170
	v_add3_u32 v178, s30, v145, v151
	ds_read_b128 v[174:177], v174
	v_add3_u32 v182, s30, v152, v156
	ds_read_b128 v[178:181], v178 offset:32768
	v_add3_u32 v186, s30, v155, v157
	ds_read_b128 v[182:185], v182 offset:32768
	v_add3_u32 v190, s30, v158, v167
	ds_read_b128 v[186:189], v186 offset:32768
	ds_read_b128 v[190:193], v190 offset:32768
	s_cmpk_lg_i32 s6, 0x1580
	s_cbranch_scc0 .Lk292_exit
	s_add_i32 s31, s100, s2
	v_lshl_add_u64 v[214:215], v[132:133], 0, s[6:7]
	v_lshl_add_u64 v[230:231], v[130:131], 0, s[6:7]
	s_mov_b32 m0, s31
	v_lshl_add_u64 v[232:233], v[214:215], 0, s[28:29]
	v_mfma_f32_32x32x16_bf16 v[114:129], v[194:197], v[202:205], v[114:129]
	global_load_lds_dwordx4 v[232:233], off
	v_lshl_add_u64 v[232:233], v[214:215], 0, s[36:37]
	s_add_i32 m0, s31, 0x2000
	v_mfma_f32_32x32x16_bf16 v[98:113], v[194:197], v[206:209], v[98:113]
	global_load_lds_dwordx4 v[232:233], off
	v_lshl_add_u64 v[232:233], v[214:215], 0, s[40:41]
	s_add_i32 m0, s31, 0x4000
	v_mfma_f32_32x32x16_bf16 v[82:97], v[194:197], v[210:213], v[82:97]
	global_load_lds_dwordx4 v[232:233], off
	v_lshl_add_u64 v[232:233], v[214:215], 0, s[42:43]
	s_add_i32 m0, s31, 0x6000
	v_mfma_f32_32x32x16_bf16 v[66:81], v[194:197], v[226:229], v[66:81]
	global_load_lds_dwordx4 v[232:233], off
	v_lshl_add_u64 v[232:233], v[230:231], 0, s[28:29]
	s_add_i32 m0, s31, 0x8000
	v_mfma_f32_32x32x16_bf16 v[50:65], v[198:201], v[202:205], v[50:65]
	global_load_lds_dwordx4 v[232:233], off
	v_lshl_add_u64 v[232:233], v[230:231], 0, s[36:37]
	s_add_i32 m0, s31, 0xa000
	v_mfma_f32_32x32x16_bf16 v[34:49], v[198:201], v[206:209], v[34:49]
	global_load_lds_dwordx4 v[232:233], off
	v_lshl_add_u64 v[232:233], v[230:231], 0, s[40:41]
	s_add_i32 m0, s31, 0xc000
	v_mfma_f32_32x32x16_bf16 v[18:33], v[198:201], v[210:213], v[18:33]
	global_load_lds_dwordx4 v[232:233], off
	v_lshl_add_u64 v[232:233], v[230:231], 0, s[42:43]
	s_add_i32 m0, s31, 0xe000
	v_mfma_f32_32x32x16_bf16 v[2:17], v[198:201], v[226:229], v[2:17]
	global_load_lds_dwordx4 v[232:233], off
	s_branch .LBB0_292
; DI f32x16 mfma(bf16x8 a, bf16x8 b, f32x16 c) { return __builtin_amdgcn_mfma_f32_32x32x16_bf16(a, b, c, 0, 0, 0); }
;     ...
;   for (int kt = 0; kt < nk; ++kt) {
;     char* cur = lds + (kt & 1) * STG; char* nxt = lds + ((kt + 1) & 1) * STG;
;     const bool more = kt + 1 < nk;
;     const bf16_t* An = Ag + (kt + 1) * BK; const bf16_t* Bn = Bg + (kt + 1) * BK;
;     if (!more) epi.pre(row0 + wm * 64, col0 + wn * (32 * NTW), lane, w, lds);
;     bf16x8 fa[2][2], fb[2][NTW];
; #pragma unroll
;     for (int mt = 0; mt < 2; ++mt) { int row = wm * 64 + mt * 32 + l31; fa[0][mt] = *(const bf16x8*)(cur + row * (BK * 2) + ((hh ^ swz<BK>(row)) << 4)); }
; #pragma unroll
;     for (int nt = 0; nt < NTW; ++nt) { int row = wn * (32 * NTW) + nt * 32 + l31; fb[0][nt] = *(const bf16x8*)(cur + ABYTES + row * (BK * 2) + ((hh ^ swz<BK>(row)) << 4)); }
; #pragma unroll
;     for (int kk = 0; kk < NKK; ++kk) {
;       if (kk + 1 < NKK) {
;         const int ch = (kk + 1) * 2 + hh;
; #pragma unroll
;         for (int mt = 0; mt < 2; ++mt) { int row = wm * 64 + mt * 32 + l31; fa[(kk + 1) & 1][mt] = *(const bf16x8*)(cur + row * (BK * 2) + ((ch ^ swz<BK>(row)) << 4)); }
; #pragma unroll
;         for (int nt = 0; nt < NTW; ++nt) { int row = wn * (32 * NTW) + nt * 32 + l31; fb[(kk + 1) & 1][nt] = *(const bf16x8*)(cur + ABYTES + row * (BK * 2) + ((ch ^ swz<BK>(row)) << 4)); }
;       }
;       if (more) {
; #pragma unroll
;         for (int q = 0; q < PPK; ++q) {
;           const int pi = kk * PPK + q;
;           if (pi < NPA) stage_piece<BM, BK>(An, lda, nxt, tid, pi, wv);
;           else if (pi < NP) stage_piece<BN, BK>(Bn, ldb, nxt + ABYTES, tid, pi - NPA, wv);
;         }
;       }
;       __builtin_amdgcn_s_setprio(1);
; #pragma unroll
;       for (int mt = 0; mt < 2; ++mt)
; #pragma unroll
;         for (int nt = 0; nt < NTW; ++nt) acc[mt][nt] = mfma(fa[kk & 1][mt], fb[kk & 1][nt], acc[mt][nt]);
;       __builtin_amdgcn_s_setprio(0);
;       __builtin_amdgcn_sched_barrier(0);
;     }
;     wait_vm0();
;     __syncthreads();
;   DI void xpass(int ps, int grow0, int gcol0, int lane, int w, char* lds) const {
;     char* xs = lds + (ps & 1) * 65536 + __builtin_amdgcn_readfirstlane(w) * 8192;
;     const float* xsrc = Xin + (size_t)(grow0 + (ps >> 1) * 32 + (ps & 1) * 16 + (lane >> 5)) * D_ + gcol0 + (lane & 31) * 4;
; #pragma unroll
;     for (int pc = 0; pc < 8; ++pc)
.Lk292_exit:
	v_mfma_f32_32x32x16_bf16 v[114:129], v[194:197], v[202:205], v[114:129]
	v_mfma_f32_32x32x16_bf16 v[98:113], v[194:197], v[206:209], v[98:113]
	v_mfma_f32_32x32x16_bf16 v[82:97], v[194:197], v[210:213], v[82:97]
	v_mfma_f32_32x32x16_bf16 v[66:81], v[194:197], v[226:229], v[66:81]
	v_mfma_f32_32x32x16_bf16 v[50:65], v[198:201], v[202:205], v[50:65]
	v_mfma_f32_32x32x16_bf16 v[34:49], v[198:201], v[206:209], v[34:49]
	v_mfma_f32_32x32x16_bf16 v[18:33], v[198:201], v[210:213], v[18:33]
	v_mfma_f32_32x32x16_bf16 v[2:17], v[198:201], v[226:229], v[2:17]
	s_waitcnt lgkmcnt(0)
	v_readlane_b32 s3, v253, 9
	v_readlane_b32 s6, v253, 27
	v_readlane_b32 s54, v255, 29
	v_or_b32_e32 v130, s3, v135
	v_add_u32_e32 v130, v130, v169
	v_ashrrev_i32_e32 v131, 31, v130
	v_lshlrev_b64 v[130:131], 12, v[130:131]
	v_add_u32_e32 v132, s6, v168
	v_readlane_b32 s55, v255, 30
	v_ashrrev_i32_e32 v133, 31, v132
	v_readfirstlane_b32 s2, v134
	v_lshl_add_u64 v[130:131], s[54:55], 0, v[130:131]
	v_lshlrev_b32_e32 v0, 4, v0
	s_lshl_b32 s2, s2, 13
	v_lshl_add_u64 v[130:131], v[132:133], 2, v[130:131]
	v_and_b32_e32 v0, 0x1f0, v0
	v_lshl_add_u64 v[130:131], v[130:131], 0, v[0:1]
	s_mov_b32 m0, s2
	s_mov_b64 s[34:35], 0x2000
	global_load_lds_dwordx4 v[130:131], off
	v_lshl_add_u64 v[132:133], v[130:131], 0, s[34:35]
	s_or_b32 m0, s2, 0x400
	s_mov_b64 s[36:37], 0x4000
	global_load_lds_dwordx4 v[132:133], off
	v_lshl_add_u64 v[132:133], v[130:131], 0, s[36:37]
	s_or_b32 m0, s2, 0x800
	s_mov_b64 s[40:41], 0x6000
	global_load_lds_dwordx4 v[132:133], off
	v_lshl_add_u64 v[132:133], v[130:131], 0, s[40:41]
	s_or_b32 m0, s2, 0xc00
	s_mov_b64 s[42:43], 0x8000
	global_load_lds_dwordx4 v[132:133], off
	v_lshl_add_u64 v[132:133], v[130:131], 0, s[42:43]
	s_or_b32 m0, s2, 0x1000
	s_mov_b64 s[44:45], 0xa000
	global_load_lds_dwordx4 v[132:133], off
	v_lshl_add_u64 v[132:133], v[130:131], 0, s[44:45]
	s_or_b32 m0, s2, 0x1400
	s_mov_b64 s[46:47], 0xc000
	global_load_lds_dwordx4 v[132:133], off
	v_lshl_add_u64 v[132:133], v[130:131], 0, s[46:47]
	s_or_b32 m0, s2, 0x1800
	s_mov_b64 s[52:53], 0xe000
	global_load_lds_dwordx4 v[132:133], off
	v_lshl_add_u64 v[130:131], v[130:131], 0, s[52:53]
	s_or_b32 m0, s2, 0x1c00
	v_add_u32_e32 v0, s30, v136
	global_load_lds_dwordx4 v[130:131], off
	v_add_u32_e32 v134, s30, v144
	v_add_u32_e32 v130, v0, v143
	v_add_u32_e32 v135, v134, v146
	ds_read_b128 v[130:133], v130
	ds_read_b128 v[168:171], v135
	v_add_u32_e32 v135, s30, v145
	v_add_u32_e32 v136, v135, v151
	v_add_u32_e32 v143, s30, v152
	v_add_u32_e32 v144, v143, v156
	ds_read_b128 v[172:175], v136 offset:32768
	ds_read_b128 v[176:179], v144 offset:32768
	v_add_u32_e32 v136, s30, v155
	v_add_u32_e32 v144, v136, v157
	v_add_u32_e32 v208, s30, v158
	v_add_u32_e32 v145, v208, v167
	ds_read_b128 v[180:183], v144 offset:32768
	ds_read_b128 v[184:187], v145 offset:32768
	v_add_u32_e32 v144, v0, v164
	v_add_u32_e32 v145, v134, v166
	ds_read_b128 v[188:191], v144
	ds_read_b128 v[192:195], v145
	v_add_u32_e32 v144, v135, v161
	v_add_u32_e32 v145, v143, v163
	ds_read_b128 v[196:199], v144 offset:32768
	ds_read_b128 v[200:203], v145 offset:32768
	v_add_u32_e32 v144, v136, v159
	v_add_u32_e32 v145, v208, v160
	ds_read_b128 v[156:159], v144 offset:32768
	ds_read_b128 v[204:207], v145 offset:32768
	v_readlane_b32 s7, v253, 28
	s_setprio 1
	s_waitcnt lgkmcnt(0)
	v_mfma_f32_32x32x16_bf16 v[114:129], v[130:133], v[172:175], v[114:129]
	v_mfma_f32_32x32x16_bf16 v[98:113], v[130:133], v[176:179], v[98:113]
	v_mfma_f32_32x32x16_bf16 v[82:97], v[130:133], v[180:183], v[82:97]
	v_mfma_f32_32x32x16_bf16 v[66:81], v[130:133], v[184:187], v[66:81]
	v_mfma_f32_32x32x16_bf16 v[50:65], v[168:171], v[172:175], v[50:65]
	v_mfma_f32_32x32x16_bf16 v[34:49], v[168:171], v[176:179], v[34:49]
	v_mfma_f32_32x32x16_bf16 v[18:33], v[168:171], v[180:183], v[18:33]
	v_mfma_f32_32x32x16_bf16 v[2:17], v[168:171], v[184:187], v[2:17]
	s_setprio 0
	v_add_u32_e32 v130, v0, v153
	v_add_u32_e32 v144, v134, v154
	ds_read_b128 v[130:133], v130
	ds_read_b128 v[152:155], v144
	v_add_u32_e32 v144, v135, v149
	v_add_u32_e32 v145, v143, v150
	ds_read_b128 v[166:169], v144 offset:32768
	ds_read_b128 v[170:173], v145 offset:32768
	v_add_u32_e32 v144, v136, v147
	v_add_u32_e32 v148, v208, v148
	ds_read_b128 v[144:147], v144 offset:32768
	ds_read_b128 v[148:151], v148 offset:32768
	s_setprio 1
	v_mfma_f32_32x32x16_bf16 v[114:129], v[188:191], v[196:199], v[114:129]
	v_mfma_f32_32x32x16_bf16 v[98:113], v[188:191], v[200:203], v[98:113]
	v_mfma_f32_32x32x16_bf16 v[82:97], v[188:191], v[156:159], v[82:97]
	v_mfma_f32_32x32x16_bf16 v[66:81], v[188:191], v[204:207], v[66:81]
	v_mfma_f32_32x32x16_bf16 v[50:65], v[192:195], v[196:199], v[50:65]
	v_mfma_f32_32x32x16_bf16 v[34:49], v[192:195], v[200:203], v[34:49]
	v_mfma_f32_32x32x16_bf16 v[18:33], v[192:195], v[156:159], v[18:33]
	v_mfma_f32_32x32x16_bf16 v[2:17], v[192:195], v[204:207], v[2:17]
	s_setprio 0
	v_add_u32_e32 v0, v0, v141
	v_add_u32_e32 v134, v134, v142
	ds_read_b128 v[156:159], v0
	ds_read_b128 v[174:177], v134
	v_add_u32_e32 v0, v135, v139
	v_add_u32_e32 v134, v143, v140
	ds_read_b128 v[140:143], v0 offset:32768
	ds_read_b128 v[178:181], v134 offset:32768
	v_add_u32_e32 v0, v136, v137
	v_add_u32_e32 v138, v208, v138
	ds_read_b128 v[134:137], v0 offset:32768
	ds_read_b128 v[182:185], v138 offset:32768
	s_setprio 1
	s_waitcnt lgkmcnt(9)
	v_mfma_f32_32x32x16_bf16 v[114:129], v[130:133], v[166:169], v[114:129]
	s_waitcnt lgkmcnt(8)
	v_mfma_f32_32x32x16_bf16 v[98:113], v[130:133], v[170:173], v[98:113]
	s_waitcnt lgkmcnt(7)
	v_mfma_f32_32x32x16_bf16 v[82:97], v[130:133], v[144:147], v[82:97]
	s_waitcnt lgkmcnt(6)
	v_mfma_f32_32x32x16_bf16 v[66:81], v[130:133], v[148:151], v[66:81]
	v_mfma_f32_32x32x16_bf16 v[50:65], v[152:155], v[166:169], v[50:65]
	v_mfma_f32_32x32x16_bf16 v[34:49], v[152:155], v[170:173], v[34:49]
	v_mfma_f32_32x32x16_bf16 v[18:33], v[152:155], v[144:147], v[18:33]
	v_mfma_f32_32x32x16_bf16 v[2:17], v[152:155], v[148:151], v[2:17]
	s_setprio 0
	s_setprio 1
	s_waitcnt lgkmcnt(3)
	v_mfma_f32_32x32x16_bf16 v[114:129], v[156:159], v[140:143], v[114:129]
	s_waitcnt lgkmcnt(2)
	v_mfma_f32_32x32x16_bf16 v[98:113], v[156:159], v[178:181], v[98:113]
	s_waitcnt lgkmcnt(1)
	v_mfma_f32_32x32x16_bf16 v[82:97], v[156:159], v[134:137], v[82:97]
	s_waitcnt lgkmcnt(0)
	v_mfma_f32_32x32x16_bf16 v[66:81], v[156:159], v[182:185], v[66:81]
	v_mfma_f32_32x32x16_bf16 v[50:65], v[174:177], v[140:143], v[50:65]
	v_mfma_f32_32x32x16_bf16 v[34:49], v[174:177], v[178:181], v[34:49]
	v_mfma_f32_32x32x16_bf16 v[18:33], v[174:177], v[134:137], v[18:33]
	v_mfma_f32_32x32x16_bf16 v[2:17], v[174:177], v[182:185], v[2:17]
	s_setprio 0
	v_mov_b32_e32 v210, v216
	s_waitcnt vmcnt(0)
	s_barrier
;   DI void xpass(int ps, int grow0, int gcol0, int lane, int w, char* lds) const {
;     char* xs = lds + (ps & 1) * 65536 + __builtin_amdgcn_readfirstlane(w) * 8192;
;     const float* xsrc = Xin + (size_t)(grow0 + (ps >> 1) * 32 + (ps & 1) * 16 + (lane >> 5)) * D_ + gcol0 + (lane & 31) * 4;
; #pragma unroll
;     for (int pc = 0; pc < 8; ++pc)
;       __builtin_amdgcn_global_load_lds((const unsigned*)(xsrc + (size_t)(2 * pc) * D_), (__attribute__((address_space(3))) unsigned*)(xs + pc * 1024), 16, 0, 0);
;   }
;   DI void pre(int grow0, int gcol0, int lane, int w, char* lds) { xpass(0, grow0, gcol0, lane, w, lds); }
;   DI void operator()(f32x16 (&acc)[2][4], int grow0, int gcol0, int lane, int w, char* lds) {
;     float* red = (float*)(lds + 131072); float* stat = (float*)lds;
;     const int l31 = lane & 31, hh = lane >> 5, tid = w * 64 + lane;
;     const int pm = grow0 >> 8, pn = gcol0 >> 8, wn = (gcol0 >> 7) & 1, lrow0 = grow0 & 255;
;     float bia[4], csc[4];
; #pragma unroll
;     for (int nt = 0; nt < 4; ++nt) { int c = gcol0 + nt * 32 + l31; bia[nt] = bias ? bias[c] : 0.f; csc[nt] = cscale ? cscale[c] : 1.f; }
;     float* redw = red + ((wn * 2 + ((lane >> 4) & 1)) * 256 + lrow0 + 4 * hh) * 2;
; #pragma unroll
;     for (int ps = 0; ps < 4; ++ps) {
;       const int mt = ps >> 1;
;       if (ps + 1 < 4) {
;         if (ps >= 1) asm volatile("s_waitcnt lgkmcnt(0)" ::: "memory");
;         xpass(ps + 1, grow0, gcol0, lane, w, lds);
;         if (ps >= 1) asm volatile("s_waitcnt vmcnt(8)" ::: "memory");
;       } else asm volatile("s_waitcnt vmcnt(0)" ::: "memory");
;       const char* xs = lds + (ps & 1) * 65536 + w * 8192;
; #pragma unroll
;       for (int qq = 0; qq < 2; ++qq)
; #pragma unroll
;         for (int e = 0; e < 4; ++e) {
;           const int i = 4 * (2 * (ps & 1) + qq) + e;
;           const float* xr = (const float*)(xs + (8 * qq + 4 * hh + e) * 512) + l31;
;           float s1 = 0.f, s2 = 0.f;
; #pragma unroll
;           for (int nt = 0; nt < 4; ++nt) {
;             float v = (acc[mt][nt][i] + bia[nt]) * csc[nt];
;             float z = ALPHA * xr[nt * 32] + hs * v;
;             acc[mt][nt][i] = z; s1 += z; s2 += z * z;
;           }
;           s1 = row16_sum(s1); s2 = row16_sum(s2);
;           if ((lane & 15) == 0) { f32x2 sv = {s1, s2}; *(f32x2*)(redw + (mt * 32 + (i & 3) + 8 * (i >> 2)) * 2) = sv; }
;         }
	v_add_f32_e32 v114, 0, v114
	v_ashrrev_i32_e32 v169, 6, v210
	v_lshrrev_b32_e32 v0, 30, v169
	v_add_u32_e32 v0, v169, v0
	v_ashrrev_i32_e32 v134, 2, v0
	v_mul_i32_i24_e32 v0, 4, v134
	v_sub_u32_e32 v0, v169, v0
	v_lshlrev_b32_e32 v135, 6, v0
	v_add_u32_e32 v164, s3, v135
	v_bfe_u32 v0, v210, 5, 1
	v_or_b32_e32 v176, v164, v0
	v_or_b32_e32 v130, 16, v176
	v_ashrrev_i32_e32 v131, 31, v130
	v_lshl_add_u32 v154, v134, 7, s6
	v_lshlrev_b32_e32 v168, 2, v210
	v_lshlrev_b64 v[130:131], 12, v[130:131]
	v_ashrrev_i32_e32 v155, 31, v154
	v_and_b32_e32 v0, 0x7c, v168
	v_readfirstlane_b32 s2, v169
	v_lshl_add_u64 v[130:131], s[54:55], 0, v[130:131]
	s_lshl_b32 s2, s2, 13
	v_lshl_add_u64 v[130:131], v[154:155], 2, v[130:131]
	v_lshlrev_b32_e32 v0, 2, v0
	s_add_i32 m0, s2, 0x10000
	v_lshl_add_u64 v[130:131], v[130:131], 0, v[0:1]
	global_load_lds_dwordx4 v[130:131], off
	v_lshl_add_u64 v[132:133], v[130:131], 0, s[34:35]
	s_add_i32 m0, s2, 0x10400
	v_and_b32_e32 v211, 0xc0, v135
	global_load_lds_dwordx4 v[132:133], off
	v_lshl_add_u64 v[132:133], v[130:131], 0, s[36:37]
	s_add_i32 m0, s2, 0x10800
	v_mov_b32_e32 v144, v98
	global_load_lds_dwordx4 v[132:133], off
	v_lshl_add_u64 v[132:133], v[130:131], 0, s[40:41]
	s_add_i32 m0, s2, 0x10c00
	v_mov_b32_e32 v145, v82
	global_load_lds_dwordx4 v[132:133], off
	v_lshl_add_u64 v[132:133], v[130:131], 0, s[42:43]
	s_add_i32 m0, s2, 0x11000
	v_mul_f32_e32 v141, 0.5, v114
	global_load_lds_dwordx4 v[132:133], off
	v_lshl_add_u64 v[132:133], v[130:131], 0, s[44:45]
	s_add_i32 m0, s2, 0x11400
	v_pk_add_f32 v[144:145], v[144:145], 0 op_sel_hi:[1,0]
	global_load_lds_dwordx4 v[132:133], off
	v_lshl_add_u64 v[132:133], v[130:131], 0, s[46:47]
	s_add_i32 m0, s2, 0x11800
	v_lshl_add_u64 v[130:131], v[130:131], 0, s[52:53]
	global_load_lds_dwordx4 v[132:133], off
	s_add_i32 m0, s2, 0x11c00
	v_bfe_u32 v132, v210, 4, 1
	global_load_lds_dwordx4 v[130:131], off
	v_and_b32_e32 v130, 31, v210
	v_lshlrev_b32_e32 v131, 1, v134
	v_bfe_u32 v134, v210, 3, 3
	v_and_or_b32 v131, v131, 2, v132
	v_and_b32_e32 v132, 4, v134
	v_lshlrev_b32_e32 v130, 2, v130
	v_or_b32_e32 v133, v211, v132
	v_lshl_or_b32 v138, v169, 13, v130
	v_lshlrev_b32_e32 v172, 9, v132
	v_lshlrev_b32_e32 v135, 3, v133
	v_or_b32_e32 v132, v138, v172
	v_and_b32_e32 v133, 15, v210
	v_lshl_or_b32 v139, v131, 11, v221
	s_waitcnt vmcnt(8)
	ds_read2_b32 v[130:131], v132 offset1:32
	v_cmp_eq_u32_e32 vcc, 0, v133
	ds_read2_b32 v[132:133], v132 offset0:64 offset1:96
	v_mov_b32_e32 v140, v82
	v_mov_b32_e32 v136, v1
	s_waitcnt lgkmcnt(0)
	v_mul_f32_e32 v137, 0x3fd744fd, v130
	v_mov_b32_e32 v130, v131
	v_mov_b32_e32 v131, v132
	s_mov_b32 s2, s67
	v_pk_add_f32 v[160:161], v[140:141], v[136:137]
	v_pk_mul_f32 v[130:131], v[130:131], s[2:3] op_sel_hi:[1,0]
	v_pk_mul_f32 v[136:137], v[144:145], 0.5 op_sel_hi:[1,0]
	v_pk_fma_f32 v[158:159], v[144:145], 0.5, v[130:131] op_sel_hi:[1,0,1]
	v_mov_b32_e32 v136, v161
	v_mov_b32_e32 v144, v1
	v_mov_b32_e32 v145, v131
	v_add_f32_e32 v142, 0, v66
	v_mov_b32_e32 v143, v133
	v_pk_mul_f32 v[140:141], v[158:159], v[158:159]
	v_pk_add_f32 v[136:137], v[136:137], v[144:145]
	v_mul_f32_e32 v66, 0x3fd744fd, v133
	v_mov_b32_e32 v163, v161
	v_pk_mov_b32 v[130:131], v[130:131], v[140:141] op_sel:[1,0]
	v_pk_add_f32 v[140:141], v[158:159], v[136:137]
	v_pk_mul_f32 v[136:137], v[158:159], v[136:137]
	v_pk_fma_f32 v[166:167], v[142:143], s[66:67], v[66:67] op_sel_hi:[1,1,0]
	v_pk_fma_f32 v[130:131], v[160:161], v[162:163], v[130:131]
	v_mov_b32_e32 v141, v137
	v_pk_mul_f32 v[132:133], v[166:167], v[166:167]
	v_pk_add_f32 v[130:131], v[140:141], v[130:131]
	v_mov_b32_e32 v167, v132
	v_pk_add_f32 v[130:131], v[130:131], v[166:167]
	v_add_u32_e32 v160, v139, v135
	s_nop 0
	v_mov_b32_dpp v132, v130 quad_perm:[1,0,3,2] row_mask:0xf bank_mask:0xf bound_ctrl:1
	v_mov_b32_dpp v133, v131 quad_perm:[1,0,3,2] row_mask:0xf bank_mask:0xf bound_ctrl:1
	v_pk_add_f32 v[130:131], v[130:131], v[132:133]
	s_nop 1
	v_mov_b32_dpp v132, v130 quad_perm:[2,3,0,1] row_mask:0xf bank_mask:0xf bound_ctrl:1
	v_mov_b32_dpp v133, v131 quad_perm:[2,3,0,1] row_mask:0xf bank_mask:0xf bound_ctrl:1
	v_pk_add_f32 v[130:131], v[130:131], v[132:133]
	s_nop 1
	v_mov_b32_dpp v132, v130 row_half_mirror row_mask:0xf bank_mask:0xf bound_ctrl:1
	v_mov_b32_dpp v133, v131 row_half_mirror row_mask:0xf bank_mask:0xf bound_ctrl:1
	v_pk_add_f32 v[130:131], v[130:131], v[132:133]
	s_nop 1
	v_mov_b32_dpp v132, v130 row_mirror row_mask:0xf bank_mask:0xf bound_ctrl:1
	v_mov_b32_dpp v133, v131 row_mirror row_mask:0xf bank_mask:0xf bound_ctrl:1
	s_and_saveexec_b64 s[6:7], vcc
	v_pk_add_f32 v[130:131], v[130:131], v[132:133]
	ds_write_b64 v160, v[130:131]
	s_or_b64 exec, exec, s[6:7]
	v_add_u32_e32 v167, v138, v172
	ds_read2_b32 v[130:131], v167 offset0:128 offset1:160
	ds_read2_b32 v[132:133], v167 offset0:192 offset1:224
	v_add_f32_e32 v82, 0, v115
	v_mul_f32_e32 v115, 0.5, v82
	v_mov_b32_e32 v82, v99
	s_waitcnt lgkmcnt(1)
	v_mul_f32_e32 v137, 0x3fd744fd, v130
	v_pk_add_f32 v[98:99], v[82:83], 0 op_sel_hi:[1,0]
	v_mov_b32_e32 v114, v83
	v_mov_b32_e32 v136, v1
	v_mov_b32_e32 v82, v131
	s_waitcnt lgkmcnt(0)
;   DI void operator()(f32x16 (&acc)[2][4], int grow0, int gcol0, int lane, int w, char* lds) {
;     ...
; #pragma unroll
;       for (int qq = 0; qq < 2; ++qq)
; #pragma unroll
;         for (int e = 0; e < 4; ++e) {
;           const int i = 4 * (2 * (ps & 1) + qq) + e;
;           const float* xr = (const float*)(xs + (8 * qq + 4 * hh + e) * 512) + l31;
;           float s1 = 0.f, s2 = 0.f;
; #pragma unroll
;           for (int nt = 0; nt < 4; ++nt) {
;             float v = (acc[mt][nt][i] + bia[nt]) * csc[nt];
;             float z = ALPHA * xr[nt * 32] + hs * v;
;             acc[mt][nt][i] = z; s1 += z; s2 += z * z;
;           }
;           s1 = row16_sum(s1); s2 = row16_sum(s2);
;           if ((lane & 15) == 0) { f32x2 sv = {s1, s2}; *(f32x2*)(redw + (mt * 32 + (i & 3) + 8 * (i >> 2)) * 2) = sv; }
	v_mov_b32_e32 v83, v132
	s_mov_b32 s2, s67
	v_pk_add_f32 v[170:171], v[114:115], v[136:137]
	v_pk_mul_f32 v[82:83], v[82:83], s[2:3] op_sel_hi:[1,0]
	v_pk_mul_f32 v[114:115], v[98:99], 0.5 op_sel_hi:[1,0]
	v_pk_fma_f32 v[148:149], v[98:99], 0.5, v[82:83] op_sel_hi:[1,0,1]
	v_mov_b32_e32 v114, v171
	v_mov_b32_e32 v130, v1
	v_mov_b32_e32 v131, v83
	v_pk_mul_f32 v[98:99], v[148:149], v[148:149]
	v_pk_add_f32 v[114:115], v[114:115], v[130:131]
	v_mov_b32_e32 v163, v171
	v_pk_mov_b32 v[82:83], v[82:83], v[98:99] op_sel:[1,0]
	v_pk_add_f32 v[98:99], v[148:149], v[114:115]
	v_pk_mul_f32 v[114:115], v[148:149], v[114:115]
	v_pk_fma_f32 v[82:83], v[170:171], v[162:163], v[82:83]
	v_mov_b32_e32 v99, v115
	v_add_f32_e32 v66, 0, v67
	v_mov_b32_e32 v67, v133
	v_pk_add_f32 v[82:83], v[98:99], v[82:83]
	v_mul_f32_e32 v98, 0x3fd744fd, v133
	v_pk_fma_f32 v[142:143], v[66:67], s[66:67], v[98:99] op_sel_hi:[1,1,0]
	s_nop 0
	v_pk_mul_f32 v[66:67], v[142:143], v[142:143]
	s_nop 0
	v_mov_b32_e32 v143, v66
	v_pk_add_f32 v[66:67], v[82:83], v[142:143]
	s_nop 1
	v_mov_b32_dpp v82, v66 quad_perm:[1,0,3,2] row_mask:0xf bank_mask:0xf bound_ctrl:1
	v_mov_b32_dpp v83, v67 quad_perm:[1,0,3,2] row_mask:0xf bank_mask:0xf bound_ctrl:1
	v_pk_add_f32 v[66:67], v[66:67], v[82:83]
	s_nop 1
	v_mov_b32_dpp v82, v66 quad_perm:[2,3,0,1] row_mask:0xf bank_mask:0xf bound_ctrl:1
	v_mov_b32_dpp v83, v67 quad_perm:[2,3,0,1] row_mask:0xf bank_mask:0xf bound_ctrl:1
	v_pk_add_f32 v[66:67], v[66:67], v[82:83]
	s_nop 1
	v_mov_b32_dpp v82, v66 row_half_mirror row_mask:0xf bank_mask:0xf bound_ctrl:1
	v_mov_b32_dpp v83, v67 row_half_mirror row_mask:0xf bank_mask:0xf bound_ctrl:1
	v_pk_add_f32 v[66:67], v[66:67], v[82:83]
	s_nop 1
	v_mov_b32_dpp v82, v66 row_mirror row_mask:0xf bank_mask:0xf bound_ctrl:1
	v_mov_b32_dpp v83, v67 row_mirror row_mask:0xf bank_mask:0xf bound_ctrl:1
	s_and_saveexec_b64 s[6:7], vcc
	v_pk_add_f32 v[66:67], v[66:67], v[82:83]
	ds_write_b64 v160, v[66:67] offset:8
	s_or_b64 exec, exec, s[6:7]
	v_add_u32_e32 v143, 0x400, v167
	ds_read2_b32 v[66:67], v143 offset1:32
	ds_read2_b32 v[82:83], v143 offset0:64 offset1:96
	v_add_f32_e32 v99, 0, v116
	v_mov_b32_e32 v132, v100
	v_mov_b32_e32 v133, v84
	v_mul_f32_e32 v115, 0.5, v99
	s_waitcnt lgkmcnt(1)
	v_mul_f32_e32 v131, 0x3fd744fd, v66
	v_pk_add_f32 v[132:133], v[132:133], 0 op_sel_hi:[1,0]
	v_mov_b32_e32 v114, v84
	v_mov_b32_e32 v130, v1
	v_mov_b32_e32 v66, v67
	s_waitcnt lgkmcnt(0)
	v_mov_b32_e32 v67, v82
	s_mov_b32 s2, s67
	v_pk_add_f32 v[144:145], v[114:115], v[130:131]
	v_pk_mul_f32 v[114:115], v[66:67], s[2:3] op_sel_hi:[1,0]
	v_pk_mul_f32 v[130:131], v[132:133], 0.5 op_sel_hi:[1,0]
	v_pk_fma_f32 v[66:67], v[132:133], 0.5, v[114:115] op_sel_hi:[1,0,1]
	v_mov_b32_e32 v130, v145
	v_mov_b32_e32 v136, v1
	v_mov_b32_e32 v137, v115
	v_add_f32_e32 v98, 0, v68
	v_mov_b32_e32 v99, v83
	v_pk_mul_f32 v[132:133], v[66:67], v[66:67]
	v_pk_add_f32 v[130:131], v[130:131], v[136:137]
	v_mul_f32_e32 v68, 0x3fd744fd, v83
	v_mov_b32_e32 v163, v145
	v_pk_mov_b32 v[114:115], v[114:115], v[132:133] op_sel:[1,0]
	v_pk_add_f32 v[132:133], v[66:67], v[130:131]
	v_pk_mul_f32 v[130:131], v[66:67], v[130:131]
	v_pk_fma_f32 v[82:83], v[98:99], s[66:67], v[68:69] op_sel_hi:[1,1,0]
	v_pk_fma_f32 v[114:115], v[144:145], v[162:163], v[114:115]
	v_mov_b32_e32 v133, v131
	v_pk_mul_f32 v[98:99], v[82:83], v[82:83]
	v_pk_add_f32 v[114:115], v[132:133], v[114:115]
	v_mov_b32_e32 v83, v98
	v_pk_add_f32 v[98:99], v[114:115], v[82:83]
	s_nop 1
	v_mov_b32_dpp v114, v98 quad_perm:[1,0,3,2] row_mask:0xf bank_mask:0xf bound_ctrl:1
	v_mov_b32_dpp v115, v99 quad_perm:[1,0,3,2] row_mask:0xf bank_mask:0xf bound_ctrl:1
	v_pk_add_f32 v[98:99], v[98:99], v[114:115]
	s_nop 1
	v_mov_b32_dpp v114, v98 quad_perm:[2,3,0,1] row_mask:0xf bank_mask:0xf bound_ctrl:1
	v_mov_b32_dpp v115, v99 quad_perm:[2,3,0,1] row_mask:0xf bank_mask:0xf bound_ctrl:1
	v_pk_add_f32 v[98:99], v[98:99], v[114:115]
	s_nop 1
	v_mov_b32_dpp v114, v98 row_half_mirror row_mask:0xf bank_mask:0xf bound_ctrl:1
	v_mov_b32_dpp v115, v99 row_half_mirror row_mask:0xf bank_mask:0xf bound_ctrl:1
	v_pk_add_f32 v[98:99], v[98:99], v[114:115]
	s_nop 1
	v_mov_b32_dpp v114, v98 row_mirror row_mask:0xf bank_mask:0xf bound_ctrl:1
	v_mov_b32_dpp v115, v99 row_mirror row_mask:0xf bank_mask:0xf bound_ctrl:1
	s_and_saveexec_b64 s[6:7], vcc
	v_pk_add_f32 v[98:99], v[98:99], v[114:115]
	ds_write_b64 v160, v[98:99] offset:16
	s_or_b64 exec, exec, s[6:7]
	v_lshlrev_b32_e32 v139, 9, v134
	v_or_b32_e32 v152, 0x600, v139
	v_add_u32_e32 v144, v138, v152
	ds_read2_b32 v[114:115], v144 offset1:32
	ds_read2_b32 v[130:131], v144 offset0:64 offset1:96
	v_add_f32_e32 v68, 0, v117
	v_add_f32_e32 v116, 0, v69
	v_mul_f32_e32 v69, 0.5, v68
	s_waitcnt lgkmcnt(1)
	v_mul_f32_e32 v99, 0x3fd744fd, v114
	v_mov_b32_e32 v84, v101
	v_mov_b32_e32 v68, v85
	v_mov_b32_e32 v98, v1
	v_pk_add_f32 v[100:101], v[84:85], 0 op_sel_hi:[1,0]
	v_pk_add_f32 v[98:99], v[68:69], v[98:99]
	v_mov_b32_e32 v68, v115
	s_waitcnt lgkmcnt(0)
;   DI void operator()(f32x16 (&acc)[2][4], int grow0, int gcol0, int lane, int w, char* lds) {
;     ...
; #pragma unroll
;       for (int qq = 0; qq < 2; ++qq)
; #pragma unroll
;         for (int e = 0; e < 4; ++e) {
;           const int i = 4 * (2 * (ps & 1) + qq) + e;
;           const float* xr = (const float*)(xs + (8 * qq + 4 * hh + e) * 512) + l31;
;           float s1 = 0.f, s2 = 0.f;
; #pragma unroll
;           for (int nt = 0; nt < 4; ++nt) {
;             float v = (acc[mt][nt][i] + bia[nt]) * csc[nt];
;             float z = ALPHA * xr[nt * 32] + hs * v;
;             acc[mt][nt][i] = z; s1 += z; s2 += z * z;
;           }
;           s1 = row16_sum(s1); s2 = row16_sum(s2);
;           if ((lane & 15) == 0) { f32x2 sv = {s1, s2}; *(f32x2*)(redw + (mt * 32 + (i & 3) + 8 * (i >> 2)) * 2) = sv; }
	v_mov_b32_e32 v69, v130
	s_mov_b32 s2, s67
	v_pk_mul_f32 v[84:85], v[68:69], s[2:3] op_sel_hi:[1,0]
	v_pk_mul_f32 v[114:115], v[100:101], 0.5 op_sel_hi:[1,0]
	v_pk_fma_f32 v[68:69], v[100:101], 0.5, v[84:85] op_sel_hi:[1,0,1]
	v_mov_b32_e32 v114, v99
	v_mov_b32_e32 v132, v1
	v_mov_b32_e32 v133, v85
	v_pk_mul_f32 v[100:101], v[68:69], v[68:69]
	v_pk_add_f32 v[114:115], v[114:115], v[132:133]
	v_mov_b32_e32 v163, v99
	v_pk_mov_b32 v[84:85], v[84:85], v[100:101] op_sel:[1,0]
	v_pk_add_f32 v[100:101], v[68:69], v[114:115]
	v_pk_mul_f32 v[114:115], v[68:69], v[114:115]
	v_pk_fma_f32 v[84:85], v[98:99], v[162:163], v[84:85]
	v_mov_b32_e32 v101, v115
	v_mov_b32_e32 v117, v131
	v_pk_add_f32 v[100:101], v[100:101], v[84:85]
	v_mul_f32_e32 v84, 0x3fd744fd, v131
	v_pk_fma_f32 v[84:85], v[116:117], s[66:67], v[84:85] op_sel_hi:[1,1,0]
	s_nop 0
	v_pk_mul_f32 v[114:115], v[84:85], v[84:85]
	s_nop 0
	v_mov_b32_e32 v85, v114
	v_pk_add_f32 v[100:101], v[100:101], v[84:85]
	s_nop 1
	v_mov_b32_dpp v114, v100 quad_perm:[1,0,3,2] row_mask:0xf bank_mask:0xf bound_ctrl:1
	v_mov_b32_dpp v115, v101 quad_perm:[1,0,3,2] row_mask:0xf bank_mask:0xf bound_ctrl:1
	v_pk_add_f32 v[100:101], v[100:101], v[114:115]
	s_nop 1
	v_mov_b32_dpp v114, v100 quad_perm:[2,3,0,1] row_mask:0xf bank_mask:0xf bound_ctrl:1
	v_mov_b32_dpp v115, v101 quad_perm:[2,3,0,1] row_mask:0xf bank_mask:0xf bound_ctrl:1
	v_pk_add_f32 v[100:101], v[100:101], v[114:115]
	s_nop 1
	v_mov_b32_dpp v114, v100 row_half_mirror row_mask:0xf bank_mask:0xf bound_ctrl:1
	v_mov_b32_dpp v115, v101 row_half_mirror row_mask:0xf bank_mask:0xf bound_ctrl:1
	v_pk_add_f32 v[100:101], v[100:101], v[114:115]
	s_nop 1
	v_mov_b32_dpp v114, v100 row_mirror row_mask:0xf bank_mask:0xf bound_ctrl:1
	v_mov_b32_dpp v115, v101 row_mirror row_mask:0xf bank_mask:0xf bound_ctrl:1
	s_and_saveexec_b64 s[6:7], vcc
	v_pk_add_f32 v[100:101], v[100:101], v[114:115]
	ds_write_b64 v160, v[100:101] offset:24
	s_or_b64 exec, exec, s[6:7]
	v_add_u32_e32 v83, 0x1000, v167
	ds_read2_b32 v[100:101], v83 offset1:32
	ds_read2_b32 v[114:115], v83 offset0:64 offset1:96
	v_add_f32_e32 v85, 0, v118
	v_mov_b32_e32 v134, v102
	v_mov_b32_e32 v135, v86
	v_mul_f32_e32 v117, 0.5, v85
	s_waitcnt lgkmcnt(1)
	v_mul_f32_e32 v133, 0x3fd744fd, v100
	v_pk_add_f32 v[134:135], v[134:135], 0 op_sel_hi:[1,0]
	v_mov_b32_e32 v116, v86
	v_mov_b32_e32 v132, v1
	v_mov_b32_e32 v100, v101
	s_waitcnt lgkmcnt(0)
	v_mov_b32_e32 v101, v114
	s_mov_b32 s2, s67
	v_pk_add_f32 v[116:117], v[116:117], v[132:133]
	v_pk_mul_f32 v[132:133], v[100:101], s[2:3] op_sel_hi:[1,0]
	v_pk_mul_f32 v[136:137], v[134:135], 0.5 op_sel_hi:[1,0]
	v_pk_fma_f32 v[100:101], v[134:135], 0.5, v[132:133] op_sel_hi:[1,0,1]
	v_mov_b32_e32 v136, v117
	v_mov_b32_e32 v140, v1
	v_mov_b32_e32 v141, v133
	v_add_f32_e32 v130, 0, v70
	v_mov_b32_e32 v131, v115
	v_pk_mul_f32 v[134:135], v[100:101], v[100:101]
	v_pk_add_f32 v[136:137], v[136:137], v[140:141]
	v_mul_f32_e32 v70, 0x3fd744fd, v115
	v_mov_b32_e32 v163, v117
	v_pk_mov_b32 v[132:133], v[132:133], v[134:135] op_sel:[1,0]
	v_pk_add_f32 v[134:135], v[100:101], v[136:137]
	v_pk_mul_f32 v[136:137], v[100:101], v[136:137]
	v_pk_fma_f32 v[114:115], v[130:131], s[66:67], v[70:71] op_sel_hi:[1,1,0]
	v_pk_fma_f32 v[132:133], v[116:117], v[162:163], v[132:133]
	v_mov_b32_e32 v135, v137
	v_pk_mul_f32 v[130:131], v[114:115], v[114:115]
	v_pk_add_f32 v[132:133], v[134:135], v[132:133]
	v_mov_b32_e32 v115, v130
	v_pk_add_f32 v[130:131], v[132:133], v[114:115]
	s_nop 1
	v_mov_b32_dpp v132, v130 quad_perm:[1,0,3,2] row_mask:0xf bank_mask:0xf bound_ctrl:1
	v_mov_b32_dpp v133, v131 quad_perm:[1,0,3,2] row_mask:0xf bank_mask:0xf bound_ctrl:1
	v_pk_add_f32 v[130:131], v[130:131], v[132:133]
	s_nop 1
	v_mov_b32_dpp v132, v130 quad_perm:[2,3,0,1] row_mask:0xf bank_mask:0xf bound_ctrl:1
	v_mov_b32_dpp v133, v131 quad_perm:[2,3,0,1] row_mask:0xf bank_mask:0xf bound_ctrl:1
	v_pk_add_f32 v[130:131], v[130:131], v[132:133]
	s_nop 1
	v_mov_b32_dpp v132, v130 row_half_mirror row_mask:0xf bank_mask:0xf bound_ctrl:1
	v_mov_b32_dpp v133, v131 row_half_mirror row_mask:0xf bank_mask:0xf bound_ctrl:1
	v_pk_add_f32 v[130:131], v[130:131], v[132:133]
	s_nop 1
	v_mov_b32_dpp v132, v130 row_mirror row_mask:0xf bank_mask:0xf bound_ctrl:1
	v_mov_b32_dpp v133, v131 row_mirror row_mask:0xf bank_mask:0xf bound_ctrl:1
	s_and_saveexec_b64 s[6:7], vcc
	v_pk_add_f32 v[130:131], v[130:131], v[132:133]
	ds_write_b64 v160, v[130:131] offset:64
	s_or_b64 exec, exec, s[6:7]
	ds_read2_b32 v[130:131], v83 offset0:128 offset1:160
	ds_read2_b32 v[132:133], v83 offset0:192 offset1:224
	v_add_f32_e32 v70, 0, v119
	v_add_f32_e32 v118, 0, v71
	v_mul_f32_e32 v71, 0.5, v70
	s_waitcnt lgkmcnt(1)
	v_mul_f32_e32 v135, 0x3fd744fd, v130
	v_mov_b32_e32 v86, v103
	v_mov_b32_e32 v70, v87
	v_mov_b32_e32 v134, v1
	v_pk_add_f32 v[136:137], v[86:87], 0 op_sel_hi:[1,0]
	v_pk_add_f32 v[102:103], v[70:71], v[134:135]
	v_mov_b32_e32 v70, v131
	s_waitcnt lgkmcnt(0)
;   DI void operator()(f32x16 (&acc)[2][4], int grow0, int gcol0, int lane, int w, char* lds) {
;     ...
; #pragma unroll
;       for (int qq = 0; qq < 2; ++qq)
; #pragma unroll
;         for (int e = 0; e < 4; ++e) {
;           const int i = 4 * (2 * (ps & 1) + qq) + e;
;           const float* xr = (const float*)(xs + (8 * qq + 4 * hh + e) * 512) + l31;
;           float s1 = 0.f, s2 = 0.f;
; #pragma unroll
;           for (int nt = 0; nt < 4; ++nt) {
;             float v = (acc[mt][nt][i] + bia[nt]) * csc[nt];
;             float z = ALPHA * xr[nt * 32] + hs * v;
;             acc[mt][nt][i] = z; s1 += z; s2 += z * z;
;           }
;           s1 = row16_sum(s1); s2 = row16_sum(s2);
;           if ((lane & 15) == 0) { f32x2 sv = {s1, s2}; *(f32x2*)(redw + (mt * 32 + (i & 3) + 8 * (i >> 2)) * 2) = sv; }
	v_mov_b32_e32 v71, v132
	s_mov_b32 s2, s67
	v_pk_mul_f32 v[86:87], v[70:71], s[2:3] op_sel_hi:[1,0]
	v_pk_mul_f32 v[130:131], v[136:137], 0.5 op_sel_hi:[1,0]
	v_pk_fma_f32 v[70:71], v[136:137], 0.5, v[86:87] op_sel_hi:[1,0,1]
	v_mov_b32_e32 v130, v103
	v_mov_b32_e32 v136, v1
	v_mov_b32_e32 v137, v87
	v_pk_mul_f32 v[134:135], v[70:71], v[70:71]
	v_pk_add_f32 v[130:131], v[130:131], v[136:137]
	v_mov_b32_e32 v163, v103
	v_pk_mov_b32 v[86:87], v[86:87], v[134:135] op_sel:[1,0]
	v_pk_add_f32 v[134:135], v[70:71], v[130:131]
	v_pk_mul_f32 v[130:131], v[70:71], v[130:131]
	v_pk_fma_f32 v[86:87], v[102:103], v[162:163], v[86:87]
	v_mov_b32_e32 v135, v131
	v_mov_b32_e32 v119, v133
	v_pk_add_f32 v[130:131], v[134:135], v[86:87]
	v_mul_f32_e32 v86, 0x3fd744fd, v133
	v_pk_fma_f32 v[86:87], v[118:119], s[66:67], v[86:87] op_sel_hi:[1,1,0]
	s_nop 0
	v_pk_mul_f32 v[118:119], v[86:87], v[86:87]
	s_nop 0
	v_mov_b32_e32 v87, v118
	v_pk_add_f32 v[118:119], v[130:131], v[86:87]
	s_nop 1
	v_mov_b32_dpp v130, v118 quad_perm:[1,0,3,2] row_mask:0xf bank_mask:0xf bound_ctrl:1
	v_mov_b32_dpp v131, v119 quad_perm:[1,0,3,2] row_mask:0xf bank_mask:0xf bound_ctrl:1
	v_pk_add_f32 v[118:119], v[118:119], v[130:131]
	s_nop 1
	v_mov_b32_dpp v130, v118 quad_perm:[2,3,0,1] row_mask:0xf bank_mask:0xf bound_ctrl:1
	v_mov_b32_dpp v131, v119 quad_perm:[2,3,0,1] row_mask:0xf bank_mask:0xf bound_ctrl:1
	v_pk_add_f32 v[118:119], v[118:119], v[130:131]
	s_nop 1
	v_mov_b32_dpp v130, v118 row_half_mirror row_mask:0xf bank_mask:0xf bound_ctrl:1
	v_mov_b32_dpp v131, v119 row_half_mirror row_mask:0xf bank_mask:0xf bound_ctrl:1
	v_pk_add_f32 v[118:119], v[118:119], v[130:131]
	s_nop 1
	v_mov_b32_dpp v130, v118 row_mirror row_mask:0xf bank_mask:0xf bound_ctrl:1
	v_mov_b32_dpp v131, v119 row_mirror row_mask:0xf bank_mask:0xf bound_ctrl:1
	s_and_saveexec_b64 s[6:7], vcc
	v_pk_add_f32 v[118:119], v[118:119], v[130:131]
	ds_write_b64 v160, v[118:119] offset:72
	s_or_b64 exec, exec, s[6:7]
	v_add_u32_e32 v85, 0x1400, v167
	ds_read2_b32 v[118:119], v85 offset1:32
	ds_read2_b32 v[130:131], v85 offset0:64 offset1:96
	v_add_f32_e32 v87, 0, v120
	v_mov_b32_e32 v140, v104
	v_mov_b32_e32 v141, v88
	v_mul_f32_e32 v133, 0.5, v87
	s_waitcnt lgkmcnt(1)
	v_mul_f32_e32 v137, 0x3fd744fd, v118
	v_pk_add_f32 v[140:141], v[140:141], 0 op_sel_hi:[1,0]
	v_mov_b32_e32 v132, v88
	v_mov_b32_e32 v136, v1
	v_mov_b32_e32 v118, v119
	s_waitcnt lgkmcnt(0)
	v_mov_b32_e32 v119, v130
	s_mov_b32 s2, s67
	v_pk_add_f32 v[132:133], v[132:133], v[136:137]
	v_pk_mul_f32 v[136:137], v[118:119], s[2:3] op_sel_hi:[1,0]
	v_pk_mul_f32 v[146:147], v[140:141], 0.5 op_sel_hi:[1,0]
	v_pk_fma_f32 v[118:119], v[140:141], 0.5, v[136:137] op_sel_hi:[1,0,1]
	v_mov_b32_e32 v146, v133
	v_mov_b32_e32 v150, v1
	v_mov_b32_e32 v151, v137
	v_add_f32_e32 v134, 0, v72
	v_mov_b32_e32 v135, v131
	v_pk_mul_f32 v[140:141], v[118:119], v[118:119]
	v_pk_add_f32 v[146:147], v[146:147], v[150:151]
	v_mul_f32_e32 v72, 0x3fd744fd, v131
	v_mov_b32_e32 v163, v133
	v_pk_mov_b32 v[136:137], v[136:137], v[140:141] op_sel:[1,0]
	v_pk_add_f32 v[140:141], v[118:119], v[146:147]
	v_pk_mul_f32 v[146:147], v[118:119], v[146:147]
	v_pk_fma_f32 v[130:131], v[134:135], s[66:67], v[72:73] op_sel_hi:[1,1,0]
	v_pk_fma_f32 v[136:137], v[132:133], v[162:163], v[136:137]
	v_mov_b32_e32 v141, v147
	v_pk_mul_f32 v[134:135], v[130:131], v[130:131]
	v_pk_add_f32 v[136:137], v[140:141], v[136:137]
	v_mov_b32_e32 v131, v134
	v_pk_add_f32 v[134:135], v[136:137], v[130:131]
	s_nop 1
	v_mov_b32_dpp v136, v134 quad_perm:[1,0,3,2] row_mask:0xf bank_mask:0xf bound_ctrl:1
	v_mov_b32_dpp v137, v135 quad_perm:[1,0,3,2] row_mask:0xf bank_mask:0xf bound_ctrl:1
	v_pk_add_f32 v[134:135], v[134:135], v[136:137]
	s_nop 1
	v_mov_b32_dpp v136, v134 quad_perm:[2,3,0,1] row_mask:0xf bank_mask:0xf bound_ctrl:1
	v_mov_b32_dpp v137, v135 quad_perm:[2,3,0,1] row_mask:0xf bank_mask:0xf bound_ctrl:1
	v_pk_add_f32 v[134:135], v[134:135], v[136:137]
	s_nop 1
	v_mov_b32_dpp v136, v134 row_half_mirror row_mask:0xf bank_mask:0xf bound_ctrl:1
	v_mov_b32_dpp v137, v135 row_half_mirror row_mask:0xf bank_mask:0xf bound_ctrl:1
	v_pk_add_f32 v[134:135], v[134:135], v[136:137]
	s_nop 1
	v_mov_b32_dpp v136, v134 row_mirror row_mask:0xf bank_mask:0xf bound_ctrl:1
	v_mov_b32_dpp v137, v135 row_mirror row_mask:0xf bank_mask:0xf bound_ctrl:1
	s_and_saveexec_b64 s[6:7], vcc
	v_pk_add_f32 v[134:135], v[134:135], v[136:137]
	ds_write_b64 v160, v[134:135] offset:80
	s_or_b64 exec, exec, s[6:7]
	v_or_b32_e32 v115, 0x1600, v139
	v_add_u32_e32 v87, v138, v115
	ds_read2_b32 v[134:135], v87 offset1:32
	ds_read2_b32 v[136:137], v87 offset0:64 offset1:96
	v_add_f32_e32 v72, 0, v121
	v_add_f32_e32 v120, 0, v73
	v_mul_f32_e32 v73, 0.5, v72
	s_waitcnt lgkmcnt(1)
	v_mul_f32_e32 v141, 0x3fd744fd, v134
	v_mov_b32_e32 v88, v105
	v_mov_b32_e32 v72, v89
	v_mov_b32_e32 v140, v1
	v_pk_add_f32 v[146:147], v[88:89], 0 op_sel_hi:[1,0]
	v_pk_add_f32 v[104:105], v[72:73], v[140:141]
	v_mov_b32_e32 v72, v135
	s_waitcnt lgkmcnt(0)
;   DI void operator()(f32x16 (&acc)[2][4], int grow0, int gcol0, int lane, int w, char* lds) {
;     ...
;     for (int ps = 0; ps < 4; ++ps) {
;       const int mt = ps >> 1;
;       if (ps + 1 < 4) {
;         if (ps >= 1) asm volatile("s_waitcnt lgkmcnt(0)" ::: "memory");
;         xpass(ps + 1, grow0, gcol0, lane, w, lds);
;         if (ps >= 1) asm volatile("s_waitcnt vmcnt(8)" ::: "memory");
;       } else asm volatile("s_waitcnt vmcnt(0)" ::: "memory");
;       const char* xs = lds + (ps & 1) * 65536 + w * 8192;
; #pragma unroll
;       for (int qq = 0; qq < 2; ++qq)
; #pragma unroll
;         for (int e = 0; e < 4; ++e) {
;           const int i = 4 * (2 * (ps & 1) + qq) + e;
;           const float* xr = (const float*)(xs + (8 * qq + 4 * hh + e) * 512) + l31;
;           float s1 = 0.f, s2 = 0.f;
; #pragma unroll
;           for (int nt = 0; nt < 4; ++nt) {
;             float v = (acc[mt][nt][i] + bia[nt]) * csc[nt];
;             float z = ALPHA * xr[nt * 32] + hs * v;
;             acc[mt][nt][i] = z; s1 += z; s2 += z * z;
;           }
;           s1 = row16_sum(s1); s2 = row16_sum(s2);
;           if ((lane & 15) == 0) { f32x2 sv = {s1, s2}; *(f32x2*)(redw + (mt * 32 + (i & 3) + 8 * (i >> 2)) * 2) = sv; }
;         }
	v_mov_b32_e32 v73, v136
	s_mov_b32 s2, s67
	v_pk_mul_f32 v[88:89], v[72:73], s[2:3] op_sel_hi:[1,0]
	v_pk_mul_f32 v[134:135], v[146:147], 0.5 op_sel_hi:[1,0]
	v_pk_fma_f32 v[72:73], v[146:147], 0.5, v[88:89] op_sel_hi:[1,0,1]
	v_mov_b32_e32 v134, v105
	v_mov_b32_e32 v146, v1
	v_mov_b32_e32 v147, v89
	v_pk_mul_f32 v[140:141], v[72:73], v[72:73]
	v_pk_add_f32 v[134:135], v[134:135], v[146:147]
	v_mov_b32_e32 v163, v105
	v_pk_mov_b32 v[88:89], v[88:89], v[140:141] op_sel:[1,0]
	v_pk_add_f32 v[140:141], v[72:73], v[134:135]
	v_pk_mul_f32 v[134:135], v[72:73], v[134:135]
	v_pk_fma_f32 v[88:89], v[104:105], v[162:163], v[88:89]
	v_mov_b32_e32 v141, v135
	v_mov_b32_e32 v121, v137
	v_pk_add_f32 v[134:135], v[140:141], v[88:89]
	v_mul_f32_e32 v88, 0x3fd744fd, v137
	v_pk_fma_f32 v[88:89], v[120:121], s[66:67], v[88:89] op_sel_hi:[1,1,0]
	s_nop 0
	v_pk_mul_f32 v[120:121], v[88:89], v[88:89]
	s_nop 0
	v_mov_b32_e32 v89, v120
	v_pk_add_f32 v[120:121], v[134:135], v[88:89]
	s_nop 1
	v_mov_b32_dpp v134, v120 quad_perm:[1,0,3,2] row_mask:0xf bank_mask:0xf bound_ctrl:1
	v_mov_b32_dpp v135, v121 quad_perm:[1,0,3,2] row_mask:0xf bank_mask:0xf bound_ctrl:1
	v_pk_add_f32 v[120:121], v[120:121], v[134:135]
	s_nop 1
	v_mov_b32_dpp v134, v120 quad_perm:[2,3,0,1] row_mask:0xf bank_mask:0xf bound_ctrl:1
	v_mov_b32_dpp v135, v121 quad_perm:[2,3,0,1] row_mask:0xf bank_mask:0xf bound_ctrl:1
	v_pk_add_f32 v[120:121], v[120:121], v[134:135]
	s_nop 1
	v_mov_b32_dpp v134, v120 row_half_mirror row_mask:0xf bank_mask:0xf bound_ctrl:1
	v_mov_b32_dpp v135, v121 row_half_mirror row_mask:0xf bank_mask:0xf bound_ctrl:1
	v_pk_add_f32 v[120:121], v[120:121], v[134:135]
	s_nop 1
	v_mov_b32_dpp v134, v120 row_mirror row_mask:0xf bank_mask:0xf bound_ctrl:1
	v_mov_b32_dpp v135, v121 row_mirror row_mask:0xf bank_mask:0xf bound_ctrl:1
	s_and_saveexec_b64 s[6:7], vcc
	v_pk_add_f32 v[120:121], v[120:121], v[134:135]
	ds_write_b64 v160, v[120:121] offset:88
	s_or_b64 exec, exec, s[6:7]
	v_or_b32_e32 v120, 32, v176
	v_ashrrev_i32_e32 v121, 31, v120
	v_readlane_b32 s6, v255, 29
	v_lshlrev_b64 v[120:121], 12, v[120:121]
	v_readlane_b32 s7, v255, 30
	v_readfirstlane_b32 s2, v169
	s_lshl_b32 s2, s2, 13
	v_lshl_add_u64 v[120:121], s[6:7], 0, v[120:121]
	v_lshl_add_u64 v[120:121], v[154:155], 2, v[120:121]
	s_waitcnt lgkmcnt(0)
	v_lshl_add_u64 v[120:121], v[120:121], 0, v[0:1]
	s_mov_b32 m0, s2
	s_mov_b64 s[6:7], 0x2000
	global_load_lds_dwordx4 v[120:121], off
	v_lshl_add_u64 v[134:135], v[120:121], 0, s[6:7]
	s_or_b32 m0, s2, 0x400
	s_mov_b64 s[6:7], 0x4000
	global_load_lds_dwordx4 v[134:135], off
	v_lshl_add_u64 v[134:135], v[120:121], 0, s[6:7]
	s_or_b32 m0, s2, 0x800
	s_mov_b64 s[6:7], 0x6000
	global_load_lds_dwordx4 v[134:135], off
	v_lshl_add_u64 v[134:135], v[120:121], 0, s[6:7]
	s_or_b32 m0, s2, 0xc00
	s_mov_b64 s[6:7], 0x8000
	global_load_lds_dwordx4 v[134:135], off
	v_lshl_add_u64 v[134:135], v[120:121], 0, s[6:7]
	s_or_b32 m0, s2, 0x1000
	s_mov_b64 s[6:7], 0xa000
	global_load_lds_dwordx4 v[134:135], off
	v_lshl_add_u64 v[134:135], v[120:121], 0, s[6:7]
	s_or_b32 m0, s2, 0x1400
	s_mov_b64 s[6:7], 0xc000
	global_load_lds_dwordx4 v[134:135], off
	v_lshl_add_u64 v[134:135], v[120:121], 0, s[6:7]
	s_or_b32 m0, s2, 0x1800
	s_mov_b64 s[6:7], 0xe000
	global_load_lds_dwordx4 v[134:135], off
	v_lshl_add_u64 v[120:121], v[120:121], 0, s[6:7]
	s_or_b32 m0, s2, 0x1c00
	v_add_u32_e32 v116, 0x10000, v138
	global_load_lds_dwordx4 v[120:121], off
	s_waitcnt vmcnt(8)
	v_add_u32_e32 v89, v116, v172
	ds_read2_b32 v[120:121], v89 offset1:32
	ds_read2_b32 v[134:135], v89 offset0:64 offset1:96
	v_add_f32_e32 v98, 0, v122
	v_mov_b32_e32 v146, v106
	v_mov_b32_e32 v147, v90
	s_waitcnt lgkmcnt(0)
	v_mul_f32_e32 v137, 0x3fd744fd, v120
	v_mul_f32_e32 v139, 0.5, v98
	v_pk_add_f32 v[146:147], v[146:147], 0 op_sel_hi:[1,0]
	v_mov_b32_e32 v138, v90
	v_mov_b32_e32 v136, v1
	v_mov_b32_e32 v120, v121
	v_mov_b32_e32 v121, v134
	s_mov_b32 s2, s67
	v_pk_add_f32 v[136:137], v[138:139], v[136:137]
	v_pk_mul_f32 v[138:139], v[120:121], s[2:3] op_sel_hi:[1,0]
	v_pk_mul_f32 v[150:151], v[146:147], 0.5 op_sel_hi:[1,0]
	v_pk_fma_f32 v[120:121], v[146:147], 0.5, v[138:139] op_sel_hi:[1,0,1]
	v_mov_b32_e32 v150, v137
	v_mov_b32_e32 v156, v1
	v_mov_b32_e32 v157, v139
	v_add_f32_e32 v140, 0, v74
	v_mov_b32_e32 v141, v135
	v_pk_mul_f32 v[146:147], v[120:121], v[120:121]
	v_pk_add_f32 v[150:151], v[150:151], v[156:157]
	v_mul_f32_e32 v74, 0x3fd744fd, v135
	v_mov_b32_e32 v163, v137
	v_pk_mov_b32 v[138:139], v[138:139], v[146:147] op_sel:[1,0]
	v_pk_add_f32 v[146:147], v[120:121], v[150:151]
	v_pk_mul_f32 v[150:151], v[120:121], v[150:151]
	v_pk_fma_f32 v[134:135], v[140:141], s[66:67], v[74:75] op_sel_hi:[1,1,0]
	v_pk_fma_f32 v[138:139], v[136:137], v[162:163], v[138:139]
	v_mov_b32_e32 v147, v151
	v_pk_mul_f32 v[140:141], v[134:135], v[134:135]
	v_pk_add_f32 v[138:139], v[146:147], v[138:139]
	v_mov_b32_e32 v135, v140
	v_pk_add_f32 v[138:139], v[138:139], v[134:135]
	s_nop 1
	v_mov_b32_dpp v140, v138 quad_perm:[1,0,3,2] row_mask:0xf bank_mask:0xf bound_ctrl:1
	v_mov_b32_dpp v141, v139 quad_perm:[1,0,3,2] row_mask:0xf bank_mask:0xf bound_ctrl:1
	v_pk_add_f32 v[138:139], v[138:139], v[140:141]
	s_nop 1
	v_mov_b32_dpp v140, v138 quad_perm:[2,3,0,1] row_mask:0xf bank_mask:0xf bound_ctrl:1
	v_mov_b32_dpp v141, v139 quad_perm:[2,3,0,1] row_mask:0xf bank_mask:0xf bound_ctrl:1
	v_pk_add_f32 v[138:139], v[138:139], v[140:141]
	s_nop 1
	v_mov_b32_dpp v140, v138 row_half_mirror row_mask:0xf bank_mask:0xf bound_ctrl:1
	v_mov_b32_dpp v141, v139 row_half_mirror row_mask:0xf bank_mask:0xf bound_ctrl:1
	v_pk_add_f32 v[138:139], v[138:139], v[140:141]
	s_nop 1
	v_mov_b32_dpp v140, v138 row_mirror row_mask:0xf bank_mask:0xf bound_ctrl:1
	v_mov_b32_dpp v141, v139 row_mirror row_mask:0xf bank_mask:0xf bound_ctrl:1
	s_and_saveexec_b64 s[6:7], vcc
	v_pk_add_f32 v[138:139], v[138:139], v[140:141]
	ds_write_b64 v160, v[138:139] offset:128
	s_or_b64 exec, exec, s[6:7]
	v_or_b32_e32 v74, 0x200, v172
	v_add_u32_e32 v98, v116, v74
	ds_read2_b32 v[138:139], v98 offset1:32
	ds_read2_b32 v[140:141], v98 offset0:64 offset1:96
	v_add_f32_e32 v74, 0, v123
	v_add_f32_e32 v122, 0, v75
	v_mul_f32_e32 v75, 0.5, v74
	s_waitcnt lgkmcnt(1)
;   DI void operator()(f32x16 (&acc)[2][4], int grow0, int gcol0, int lane, int w, char* lds) {
;     ...
;         for (int e = 0; e < 4; ++e) {
;           const int i = 4 * (2 * (ps & 1) + qq) + e;
;           const float* xr = (const float*)(xs + (8 * qq + 4 * hh + e) * 512) + l31;
;           float s1 = 0.f, s2 = 0.f;
; #pragma unroll
;           for (int nt = 0; nt < 4; ++nt) {
;             float v = (acc[mt][nt][i] + bia[nt]) * csc[nt];
;             float z = ALPHA * xr[nt * 32] + hs * v;
;             acc[mt][nt][i] = z; s1 += z; s2 += z * z;
;           }
;           s1 = row16_sum(s1); s2 = row16_sum(s2);
;           if ((lane & 15) == 0) { f32x2 sv = {s1, s2}; *(f32x2*)(redw + (mt * 32 + (i & 3) + 8 * (i >> 2)) * 2) = sv; }
	v_mul_f32_e32 v147, 0x3fd744fd, v138
	v_mov_b32_e32 v90, v107
	v_mov_b32_e32 v74, v91
	v_mov_b32_e32 v146, v1
	v_pk_add_f32 v[150:151], v[90:91], 0 op_sel_hi:[1,0]
	v_pk_add_f32 v[106:107], v[74:75], v[146:147]
	v_mov_b32_e32 v74, v139
	s_waitcnt lgkmcnt(0)
	v_mov_b32_e32 v75, v140
	s_mov_b32 s2, s67
	v_pk_mul_f32 v[90:91], v[74:75], s[2:3] op_sel_hi:[1,0]
	v_pk_mul_f32 v[138:139], v[150:151], 0.5 op_sel_hi:[1,0]
	v_pk_fma_f32 v[74:75], v[150:151], 0.5, v[90:91] op_sel_hi:[1,0,1]
	v_mov_b32_e32 v138, v107
	v_mov_b32_e32 v150, v1
	v_mov_b32_e32 v151, v91
	v_pk_mul_f32 v[146:147], v[74:75], v[74:75]
	v_pk_add_f32 v[138:139], v[138:139], v[150:151]
	v_mov_b32_e32 v163, v107
	v_pk_mov_b32 v[90:91], v[90:91], v[146:147] op_sel:[1,0]
	v_pk_add_f32 v[146:147], v[74:75], v[138:139]
	v_pk_mul_f32 v[138:139], v[74:75], v[138:139]
	v_pk_fma_f32 v[90:91], v[106:107], v[162:163], v[90:91]
	v_mov_b32_e32 v147, v139
	v_mov_b32_e32 v123, v141
	v_pk_add_f32 v[138:139], v[146:147], v[90:91]
	v_mul_f32_e32 v90, 0x3fd744fd, v141
	v_pk_fma_f32 v[90:91], v[122:123], s[66:67], v[90:91] op_sel_hi:[1,1,0]
	s_nop 0
	v_pk_mul_f32 v[122:123], v[90:91], v[90:91]
	s_nop 0
	v_mov_b32_e32 v91, v122
	v_pk_add_f32 v[122:123], v[138:139], v[90:91]
	s_nop 1
	v_mov_b32_dpp v138, v122 quad_perm:[1,0,3,2] row_mask:0xf bank_mask:0xf bound_ctrl:1
	v_mov_b32_dpp v139, v123 quad_perm:[1,0,3,2] row_mask:0xf bank_mask:0xf bound_ctrl:1
	v_pk_add_f32 v[122:123], v[122:123], v[138:139]
	s_nop 1
	v_mov_b32_dpp v138, v122 quad_perm:[2,3,0,1] row_mask:0xf bank_mask:0xf bound_ctrl:1
	v_mov_b32_dpp v139, v123 quad_perm:[2,3,0,1] row_mask:0xf bank_mask:0xf bound_ctrl:1
	v_pk_add_f32 v[122:123], v[122:123], v[138:139]
	s_nop 1
	v_mov_b32_dpp v138, v122 row_half_mirror row_mask:0xf bank_mask:0xf bound_ctrl:1
	v_mov_b32_dpp v139, v123 row_half_mirror row_mask:0xf bank_mask:0xf bound_ctrl:1
	v_pk_add_f32 v[122:123], v[122:123], v[138:139]
	s_nop 1
	v_mov_b32_dpp v138, v122 row_mirror row_mask:0xf bank_mask:0xf bound_ctrl:1
	v_mov_b32_dpp v139, v123 row_mirror row_mask:0xf bank_mask:0xf bound_ctrl:1
	s_and_saveexec_b64 s[6:7], vcc
	v_pk_add_f32 v[122:123], v[122:123], v[138:139]
	ds_write_b64 v160, v[122:123] offset:136
	s_or_b64 exec, exec, s[6:7]
	v_or_b32_e32 v91, 0x400, v172
	v_add_u32_e32 v102, v116, v91
	ds_read2_b32 v[122:123], v102 offset1:32
	ds_read2_b32 v[138:139], v102 offset0:64 offset1:96
	v_add_f32_e32 v91, 0, v124
	v_mov_b32_e32 v156, v108
	v_mov_b32_e32 v157, v92
	v_mul_f32_e32 v141, 0.5, v91
	s_waitcnt lgkmcnt(1)
	v_mul_f32_e32 v151, 0x3fd744fd, v122
	v_pk_add_f32 v[156:157], v[156:157], 0 op_sel_hi:[1,0]
	v_mov_b32_e32 v140, v92
	v_mov_b32_e32 v150, v1
	v_mov_b32_e32 v122, v123
	s_waitcnt lgkmcnt(0)
	v_mov_b32_e32 v123, v138
	s_mov_b32 s2, s67
	v_pk_add_f32 v[140:141], v[140:141], v[150:151]
	v_pk_mul_f32 v[150:151], v[122:123], s[2:3] op_sel_hi:[1,0]
	v_pk_mul_f32 v[174:175], v[156:157], 0.5 op_sel_hi:[1,0]
	v_pk_fma_f32 v[122:123], v[156:157], 0.5, v[150:151] op_sel_hi:[1,0,1]
	v_mov_b32_e32 v174, v141
	v_mov_b32_e32 v178, v1
	v_mov_b32_e32 v179, v151
	v_add_f32_e32 v146, 0, v76
	v_mov_b32_e32 v147, v139
	v_pk_mul_f32 v[156:157], v[122:123], v[122:123]
	v_pk_add_f32 v[174:175], v[174:175], v[178:179]
	v_mul_f32_e32 v76, 0x3fd744fd, v139
	v_mov_b32_e32 v163, v141
	v_pk_mov_b32 v[150:151], v[150:151], v[156:157] op_sel:[1,0]
	v_pk_add_f32 v[156:157], v[122:123], v[174:175]
	v_pk_mul_f32 v[174:175], v[122:123], v[174:175]
	v_pk_fma_f32 v[138:139], v[146:147], s[66:67], v[76:77] op_sel_hi:[1,1,0]
	v_pk_fma_f32 v[150:151], v[140:141], v[162:163], v[150:151]
	v_mov_b32_e32 v157, v175
	v_pk_mul_f32 v[146:147], v[138:139], v[138:139]
	v_pk_add_f32 v[150:151], v[156:157], v[150:151]
	v_mov_b32_e32 v139, v146
	v_pk_add_f32 v[146:147], v[150:151], v[138:139]
	s_nop 1
	v_mov_b32_dpp v150, v146 quad_perm:[1,0,3,2] row_mask:0xf bank_mask:0xf bound_ctrl:1
	v_mov_b32_dpp v151, v147 quad_perm:[1,0,3,2] row_mask:0xf bank_mask:0xf bound_ctrl:1
	v_pk_add_f32 v[146:147], v[146:147], v[150:151]
	s_nop 1
	v_mov_b32_dpp v150, v146 quad_perm:[2,3,0,1] row_mask:0xf bank_mask:0xf bound_ctrl:1
	v_mov_b32_dpp v151, v147 quad_perm:[2,3,0,1] row_mask:0xf bank_mask:0xf bound_ctrl:1
	v_pk_add_f32 v[146:147], v[146:147], v[150:151]
	s_nop 1
	v_mov_b32_dpp v150, v146 row_half_mirror row_mask:0xf bank_mask:0xf bound_ctrl:1
	v_mov_b32_dpp v151, v147 row_half_mirror row_mask:0xf bank_mask:0xf bound_ctrl:1
	v_pk_add_f32 v[146:147], v[146:147], v[150:151]
	s_nop 1
	v_mov_b32_dpp v150, v146 row_mirror row_mask:0xf bank_mask:0xf bound_ctrl:1
	v_mov_b32_dpp v151, v147 row_mirror row_mask:0xf bank_mask:0xf bound_ctrl:1
	s_and_saveexec_b64 s[6:7], vcc
	v_pk_add_f32 v[146:147], v[146:147], v[150:151]
	ds_write_b64 v160, v[146:147] offset:144
	s_or_b64 exec, exec, s[6:7]
	v_add_u32_e32 v104, v116, v152
	ds_read2_b32 v[146:147], v104 offset1:32
	ds_read2_b32 v[150:151], v104 offset0:64 offset1:96
	v_add_f32_e32 v76, 0, v125
	v_add_f32_e32 v124, 0, v77
	v_mul_f32_e32 v77, 0.5, v76
	s_waitcnt lgkmcnt(1)
	v_mul_f32_e32 v153, 0x3fd744fd, v146
	v_mov_b32_e32 v92, v109
	v_mov_b32_e32 v76, v93
	v_mov_b32_e32 v152, v1
	v_pk_add_f32 v[156:157], v[92:93], 0 op_sel_hi:[1,0]
	v_pk_add_f32 v[108:109], v[76:77], v[152:153]
	v_mov_b32_e32 v76, v147
	s_waitcnt lgkmcnt(0)
;   DI void operator()(f32x16 (&acc)[2][4], int grow0, int gcol0, int lane, int w, char* lds) {
;     ...
;         for (int e = 0; e < 4; ++e) {
;           const int i = 4 * (2 * (ps & 1) + qq) + e;
;           const float* xr = (const float*)(xs + (8 * qq + 4 * hh + e) * 512) + l31;
;           float s1 = 0.f, s2 = 0.f;
; #pragma unroll
;           for (int nt = 0; nt < 4; ++nt) {
;             float v = (acc[mt][nt][i] + bia[nt]) * csc[nt];
;             float z = ALPHA * xr[nt * 32] + hs * v;
;             acc[mt][nt][i] = z; s1 += z; s2 += z * z;
;           }
;           s1 = row16_sum(s1); s2 = row16_sum(s2);
;           if ((lane & 15) == 0) { f32x2 sv = {s1, s2}; *(f32x2*)(redw + (mt * 32 + (i & 3) + 8 * (i >> 2)) * 2) = sv; }
	v_mov_b32_e32 v77, v150
	s_mov_b32 s2, s67
	v_pk_mul_f32 v[92:93], v[76:77], s[2:3] op_sel_hi:[1,0]
	v_pk_mul_f32 v[146:147], v[156:157], 0.5 op_sel_hi:[1,0]
	v_pk_fma_f32 v[76:77], v[156:157], 0.5, v[92:93] op_sel_hi:[1,0,1]
	v_mov_b32_e32 v146, v109
	v_mov_b32_e32 v156, v1
	v_mov_b32_e32 v157, v93
	v_pk_mul_f32 v[152:153], v[76:77], v[76:77]
	v_pk_add_f32 v[146:147], v[146:147], v[156:157]
	v_mov_b32_e32 v163, v109
	v_pk_mov_b32 v[92:93], v[92:93], v[152:153] op_sel:[1,0]
	v_pk_add_f32 v[152:153], v[76:77], v[146:147]
	v_pk_mul_f32 v[146:147], v[76:77], v[146:147]
	v_pk_fma_f32 v[92:93], v[108:109], v[162:163], v[92:93]
	v_mov_b32_e32 v153, v147
	v_mov_b32_e32 v125, v151
	v_pk_add_f32 v[146:147], v[152:153], v[92:93]
	v_mul_f32_e32 v92, 0x3fd744fd, v151
	v_pk_fma_f32 v[92:93], v[124:125], s[66:67], v[92:93] op_sel_hi:[1,1,0]
	s_nop 0
	v_pk_mul_f32 v[124:125], v[92:93], v[92:93]
	s_nop 0
	v_mov_b32_e32 v93, v124
	v_pk_add_f32 v[124:125], v[146:147], v[92:93]
	s_nop 1
	v_mov_b32_dpp v146, v124 quad_perm:[1,0,3,2] row_mask:0xf bank_mask:0xf bound_ctrl:1
	v_mov_b32_dpp v147, v125 quad_perm:[1,0,3,2] row_mask:0xf bank_mask:0xf bound_ctrl:1
	v_pk_add_f32 v[124:125], v[124:125], v[146:147]
	s_nop 1
	v_mov_b32_dpp v146, v124 quad_perm:[2,3,0,1] row_mask:0xf bank_mask:0xf bound_ctrl:1
	v_mov_b32_dpp v147, v125 quad_perm:[2,3,0,1] row_mask:0xf bank_mask:0xf bound_ctrl:1
	v_pk_add_f32 v[124:125], v[124:125], v[146:147]
	s_nop 1
	v_mov_b32_dpp v146, v124 row_half_mirror row_mask:0xf bank_mask:0xf bound_ctrl:1
	v_mov_b32_dpp v147, v125 row_half_mirror row_mask:0xf bank_mask:0xf bound_ctrl:1
	v_pk_add_f32 v[124:125], v[124:125], v[146:147]
	s_nop 1
	v_mov_b32_dpp v146, v124 row_mirror row_mask:0xf bank_mask:0xf bound_ctrl:1
	v_mov_b32_dpp v147, v125 row_mirror row_mask:0xf bank_mask:0xf bound_ctrl:1
	s_and_saveexec_b64 s[6:7], vcc
	v_pk_add_f32 v[124:125], v[124:125], v[146:147]
	ds_write_b64 v160, v[124:125] offset:152
	s_or_b64 exec, exec, s[6:7]
	v_or_b32_e32 v91, 0x1000, v172
	v_add_u32_e32 v93, v116, v91
	ds_read2_b32 v[124:125], v93 offset1:32
	ds_read2_b32 v[146:147], v93 offset0:64 offset1:96
	v_add_f32_e32 v91, 0, v126
	v_mov_b32_e32 v174, v110
	v_mov_b32_e32 v175, v94
	v_mul_f32_e32 v151, 0.5, v91
	s_waitcnt lgkmcnt(1)
	v_mul_f32_e32 v157, 0x3fd744fd, v124
	v_pk_add_f32 v[174:175], v[174:175], 0 op_sel_hi:[1,0]
	v_mov_b32_e32 v150, v94
	v_mov_b32_e32 v156, v1
	v_mov_b32_e32 v124, v125
	s_waitcnt lgkmcnt(0)
	v_mov_b32_e32 v125, v146
	s_mov_b32 s2, s67
	v_pk_add_f32 v[150:151], v[150:151], v[156:157]
	v_pk_mul_f32 v[156:157], v[124:125], s[2:3] op_sel_hi:[1,0]
	v_pk_mul_f32 v[178:179], v[174:175], 0.5 op_sel_hi:[1,0]
	v_pk_fma_f32 v[124:125], v[174:175], 0.5, v[156:157] op_sel_hi:[1,0,1]
	v_mov_b32_e32 v178, v151
	v_mov_b32_e32 v180, v1
	v_mov_b32_e32 v181, v157
	v_add_f32_e32 v152, 0, v78
	v_mov_b32_e32 v153, v147
	v_pk_mul_f32 v[174:175], v[124:125], v[124:125]
	v_pk_add_f32 v[178:179], v[178:179], v[180:181]
	v_mul_f32_e32 v78, 0x3fd744fd, v147
	v_mov_b32_e32 v163, v151
	v_pk_mov_b32 v[156:157], v[156:157], v[174:175] op_sel:[1,0]
	v_pk_add_f32 v[174:175], v[124:125], v[178:179]
	v_pk_mul_f32 v[178:179], v[124:125], v[178:179]
	v_pk_fma_f32 v[146:147], v[152:153], s[66:67], v[78:79] op_sel_hi:[1,1,0]
	v_pk_fma_f32 v[156:157], v[150:151], v[162:163], v[156:157]
	v_mov_b32_e32 v175, v179
	v_pk_mul_f32 v[152:153], v[146:147], v[146:147]
	v_pk_add_f32 v[156:157], v[174:175], v[156:157]
	v_mov_b32_e32 v147, v152
	v_pk_add_f32 v[152:153], v[156:157], v[146:147]
	s_nop 1
	v_mov_b32_dpp v156, v152 quad_perm:[1,0,3,2] row_mask:0xf bank_mask:0xf bound_ctrl:1
	v_mov_b32_dpp v157, v153 quad_perm:[1,0,3,2] row_mask:0xf bank_mask:0xf bound_ctrl:1
	v_pk_add_f32 v[152:153], v[152:153], v[156:157]
	s_nop 1
	v_mov_b32_dpp v156, v152 quad_perm:[2,3,0,1] row_mask:0xf bank_mask:0xf bound_ctrl:1
	v_mov_b32_dpp v157, v153 quad_perm:[2,3,0,1] row_mask:0xf bank_mask:0xf bound_ctrl:1
	v_pk_add_f32 v[152:153], v[152:153], v[156:157]
	s_nop 1
	v_mov_b32_dpp v156, v152 row_half_mirror row_mask:0xf bank_mask:0xf bound_ctrl:1
	v_mov_b32_dpp v157, v153 row_half_mirror row_mask:0xf bank_mask:0xf bound_ctrl:1
	v_pk_add_f32 v[152:153], v[152:153], v[156:157]
	s_nop 1
	v_mov_b32_dpp v156, v152 row_mirror row_mask:0xf bank_mask:0xf bound_ctrl:1
	v_mov_b32_dpp v157, v153 row_mirror row_mask:0xf bank_mask:0xf bound_ctrl:1
	s_and_saveexec_b64 s[6:7], vcc
	v_pk_add_f32 v[152:153], v[152:153], v[156:157]
	ds_write_b64 v160, v[152:153] offset:192
	s_or_b64 exec, exec, s[6:7]
	v_or_b32_e32 v78, 0x1200, v172
	v_add_u32_e32 v106, v116, v78
	ds_read2_b32 v[152:153], v106 offset1:32
	ds_read2_b32 v[156:157], v106 offset0:64 offset1:96
	v_add_f32_e32 v78, 0, v127
	v_add_f32_e32 v126, 0, v79
	v_mul_f32_e32 v79, 0.5, v78
	s_waitcnt lgkmcnt(1)
	v_mul_f32_e32 v175, 0x3fd744fd, v152
	v_mov_b32_e32 v94, v111
	v_mov_b32_e32 v78, v95
	v_mov_b32_e32 v174, v1
	v_pk_add_f32 v[178:179], v[94:95], 0 op_sel_hi:[1,0]
	v_pk_add_f32 v[110:111], v[78:79], v[174:175]
	v_mov_b32_e32 v78, v153
	s_waitcnt lgkmcnt(0)
;   DI void operator()(f32x16 (&acc)[2][4], int grow0, int gcol0, int lane, int w, char* lds) {
;     ...
;         for (int e = 0; e < 4; ++e) {
;           const int i = 4 * (2 * (ps & 1) + qq) + e;
;           const float* xr = (const float*)(xs + (8 * qq + 4 * hh + e) * 512) + l31;
;           float s1 = 0.f, s2 = 0.f;
; #pragma unroll
;           for (int nt = 0; nt < 4; ++nt) {
;             float v = (acc[mt][nt][i] + bia[nt]) * csc[nt];
;             float z = ALPHA * xr[nt * 32] + hs * v;
;             acc[mt][nt][i] = z; s1 += z; s2 += z * z;
;           }
;           s1 = row16_sum(s1); s2 = row16_sum(s2);
;           if ((lane & 15) == 0) { f32x2 sv = {s1, s2}; *(f32x2*)(redw + (mt * 32 + (i & 3) + 8 * (i >> 2)) * 2) = sv; }
	v_mov_b32_e32 v79, v156
	s_mov_b32 s2, s67
	v_pk_mul_f32 v[94:95], v[78:79], s[2:3] op_sel_hi:[1,0]
	v_pk_mul_f32 v[152:153], v[178:179], 0.5 op_sel_hi:[1,0]
	v_pk_fma_f32 v[78:79], v[178:179], 0.5, v[94:95] op_sel_hi:[1,0,1]
	v_mov_b32_e32 v152, v111
	v_mov_b32_e32 v178, v1
	v_mov_b32_e32 v179, v95
	v_pk_mul_f32 v[174:175], v[78:79], v[78:79]
	v_pk_add_f32 v[152:153], v[152:153], v[178:179]
	v_mov_b32_e32 v163, v111
	v_pk_mov_b32 v[94:95], v[94:95], v[174:175] op_sel:[1,0]
	v_pk_add_f32 v[174:175], v[78:79], v[152:153]
	v_pk_mul_f32 v[152:153], v[78:79], v[152:153]
	v_pk_fma_f32 v[94:95], v[110:111], v[162:163], v[94:95]
	v_mov_b32_e32 v175, v153
	v_mov_b32_e32 v127, v157
	v_pk_add_f32 v[152:153], v[174:175], v[94:95]
	v_mul_f32_e32 v94, 0x3fd744fd, v157
	v_pk_fma_f32 v[94:95], v[126:127], s[66:67], v[94:95] op_sel_hi:[1,1,0]
	s_nop 0
	v_pk_mul_f32 v[126:127], v[94:95], v[94:95]
	s_nop 0
	v_mov_b32_e32 v95, v126
	v_pk_add_f32 v[126:127], v[152:153], v[94:95]
	s_nop 1
	v_mov_b32_dpp v152, v126 quad_perm:[1,0,3,2] row_mask:0xf bank_mask:0xf bound_ctrl:1
	v_mov_b32_dpp v153, v127 quad_perm:[1,0,3,2] row_mask:0xf bank_mask:0xf bound_ctrl:1
	v_pk_add_f32 v[126:127], v[126:127], v[152:153]
	s_nop 1
	v_mov_b32_dpp v152, v126 quad_perm:[2,3,0,1] row_mask:0xf bank_mask:0xf bound_ctrl:1
	v_mov_b32_dpp v153, v127 quad_perm:[2,3,0,1] row_mask:0xf bank_mask:0xf bound_ctrl:1
	v_pk_add_f32 v[126:127], v[126:127], v[152:153]
	s_nop 1
	v_mov_b32_dpp v152, v126 row_half_mirror row_mask:0xf bank_mask:0xf bound_ctrl:1
	v_mov_b32_dpp v153, v127 row_half_mirror row_mask:0xf bank_mask:0xf bound_ctrl:1
	v_pk_add_f32 v[126:127], v[126:127], v[152:153]
	s_nop 1
	v_mov_b32_dpp v152, v126 row_mirror row_mask:0xf bank_mask:0xf bound_ctrl:1
	v_mov_b32_dpp v153, v127 row_mirror row_mask:0xf bank_mask:0xf bound_ctrl:1
	s_and_saveexec_b64 s[6:7], vcc
	v_pk_add_f32 v[126:127], v[126:127], v[152:153]
	ds_write_b64 v160, v[126:127] offset:200
	s_or_b64 exec, exec, s[6:7]
	v_or_b32_e32 v91, 0x1400, v172
	v_add_u32_e32 v95, v116, v91
	ds_read2_b32 v[126:127], v95 offset1:32
	ds_read2_b32 v[152:153], v95 offset0:64 offset1:96
	v_add_f32_e32 v91, 0, v128
	v_mov_b32_e32 v178, v112
	v_mov_b32_e32 v179, v96
	v_mul_f32_e32 v157, 0.5, v91
	s_waitcnt lgkmcnt(1)
	v_mul_f32_e32 v175, 0x3fd744fd, v126
	v_pk_add_f32 v[178:179], v[178:179], 0 op_sel_hi:[1,0]
	v_mov_b32_e32 v156, v96
	v_mov_b32_e32 v174, v1
	v_mov_b32_e32 v126, v127
	s_waitcnt lgkmcnt(0)
	v_mov_b32_e32 v127, v152
	s_mov_b32 s2, s67
	v_pk_add_f32 v[156:157], v[156:157], v[174:175]
	v_pk_mul_f32 v[174:175], v[126:127], s[2:3] op_sel_hi:[1,0]
	v_pk_mul_f32 v[180:181], v[178:179], 0.5 op_sel_hi:[1,0]
	v_pk_fma_f32 v[126:127], v[178:179], 0.5, v[174:175] op_sel_hi:[1,0,1]
	v_mov_b32_e32 v180, v157
	v_mov_b32_e32 v182, v1
	v_mov_b32_e32 v183, v175
	v_add_f32_e32 v172, 0, v80
	v_mov_b32_e32 v173, v153
	v_pk_mul_f32 v[178:179], v[126:127], v[126:127]
	v_pk_add_f32 v[180:181], v[180:181], v[182:183]
	v_mul_f32_e32 v80, 0x3fd744fd, v153
	v_mov_b32_e32 v163, v157
	v_pk_mov_b32 v[174:175], v[174:175], v[178:179] op_sel:[1,0]
	v_pk_add_f32 v[178:179], v[126:127], v[180:181]
	v_pk_mul_f32 v[180:181], v[126:127], v[180:181]
	v_pk_fma_f32 v[152:153], v[172:173], s[66:67], v[80:81] op_sel_hi:[1,1,0]
	v_pk_fma_f32 v[174:175], v[156:157], v[162:163], v[174:175]
	v_mov_b32_e32 v179, v181
	v_pk_mul_f32 v[172:173], v[152:153], v[152:153]
	v_pk_add_f32 v[174:175], v[178:179], v[174:175]
	v_mov_b32_e32 v153, v172
	v_pk_add_f32 v[172:173], v[174:175], v[152:153]
	s_nop 1
	v_mov_b32_dpp v174, v172 quad_perm:[1,0,3,2] row_mask:0xf bank_mask:0xf bound_ctrl:1
	v_mov_b32_dpp v175, v173 quad_perm:[1,0,3,2] row_mask:0xf bank_mask:0xf bound_ctrl:1
	v_pk_add_f32 v[172:173], v[172:173], v[174:175]
	s_nop 1
	v_mov_b32_dpp v174, v172 quad_perm:[2,3,0,1] row_mask:0xf bank_mask:0xf bound_ctrl:1
	v_mov_b32_dpp v175, v173 quad_perm:[2,3,0,1] row_mask:0xf bank_mask:0xf bound_ctrl:1
	v_pk_add_f32 v[172:173], v[172:173], v[174:175]
	s_nop 1
	v_mov_b32_dpp v174, v172 row_half_mirror row_mask:0xf bank_mask:0xf bound_ctrl:1
	v_mov_b32_dpp v175, v173 row_half_mirror row_mask:0xf bank_mask:0xf bound_ctrl:1
	v_pk_add_f32 v[172:173], v[172:173], v[174:175]
	s_nop 1
	v_mov_b32_dpp v174, v172 row_mirror row_mask:0xf bank_mask:0xf bound_ctrl:1
	v_mov_b32_dpp v175, v173 row_mirror row_mask:0xf bank_mask:0xf bound_ctrl:1
	s_and_saveexec_b64 s[6:7], vcc
	v_pk_add_f32 v[172:173], v[172:173], v[174:175]
	ds_write_b64 v160, v[172:173] offset:208
	s_or_b64 exec, exec, s[6:7]
	v_add_u32_e32 v91, v116, v115
	v_add_f32_e32 v80, 0, v129
	ds_read2_b32 v[128:129], v91 offset1:32
	ds_read2_b32 v[178:179], v91 offset0:64 offset1:96
	v_mov_b32_e32 v96, v113
	v_mul_f32_e32 v175, 0.5, v80
	v_add_f32_e32 v180, 0, v81
	s_waitcnt lgkmcnt(1)
	v_mul_f32_e32 v173, 0x3fd744fd, v128
	v_pk_add_f32 v[80:81], v[96:97], 0 op_sel_hi:[1,0]
	v_mov_b32_e32 v174, v97
	v_mov_b32_e32 v172, v1
	v_mov_b32_e32 v96, v129
	s_waitcnt lgkmcnt(0)
;   DI void xpass(int ps, int grow0, int gcol0, int lane, int w, char* lds) const {
;     char* xs = lds + (ps & 1) * 65536 + __builtin_amdgcn_readfirstlane(w) * 8192;
;     const float* xsrc = Xin + (size_t)(grow0 + (ps >> 1) * 32 + (ps & 1) * 16 + (lane >> 5)) * D_ + gcol0 + (lane & 31) * 4;
; #pragma unroll
;     for (int pc = 0; pc < 8; ++pc)
;       __builtin_amdgcn_global_load_lds((const unsigned*)(xsrc + (size_t)(2 * pc) * D_), (__attribute__((address_space(3))) unsigned*)(xs + pc * 1024), 16, 0, 0);
;   }
;   DI void operator()(f32x16 (&acc)[2][4], int grow0, int gcol0, int lane, int w, char* lds) {
;     ...
;         for (int e = 0; e < 4; ++e) {
;           const int i = 4 * (2 * (ps & 1) + qq) + e;
;           const float* xr = (const float*)(xs + (8 * qq + 4 * hh + e) * 512) + l31;
;           float s1 = 0.f, s2 = 0.f;
; #pragma unroll
;           for (int nt = 0; nt < 4; ++nt) {
;             float v = (acc[mt][nt][i] + bia[nt]) * csc[nt];
;             float z = ALPHA * xr[nt * 32] + hs * v;
;             acc[mt][nt][i] = z; s1 += z; s2 += z * z;
;           }
;           s1 = row16_sum(s1); s2 = row16_sum(s2);
;           if ((lane & 15) == 0) { f32x2 sv = {s1, s2}; *(f32x2*)(redw + (mt * 32 + (i & 3) + 8 * (i >> 2)) * 2) = sv; }
	v_mov_b32_e32 v97, v178
	s_mov_b32 s2, s67
	v_pk_add_f32 v[112:113], v[174:175], v[172:173]
	v_pk_mul_f32 v[96:97], v[96:97], s[2:3] op_sel_hi:[1,0]
	v_pk_mul_f32 v[128:129], v[80:81], 0.5 op_sel_hi:[1,0]
	v_pk_fma_f32 v[80:81], v[80:81], 0.5, v[96:97] op_sel_hi:[1,0,1]
	v_mov_b32_e32 v128, v113
	v_mov_b32_e32 v174, v1
	v_mov_b32_e32 v175, v97
	v_pk_mul_f32 v[172:173], v[80:81], v[80:81]
	v_pk_add_f32 v[128:129], v[128:129], v[174:175]
	v_mov_b32_e32 v163, v113
	v_pk_mov_b32 v[96:97], v[96:97], v[172:173] op_sel:[1,0]
	v_pk_add_f32 v[172:173], v[80:81], v[128:129]
	v_pk_mul_f32 v[128:129], v[80:81], v[128:129]
	v_pk_fma_f32 v[96:97], v[112:113], v[162:163], v[96:97]
	v_mov_b32_e32 v173, v129
	v_mov_b32_e32 v181, v179
	v_pk_add_f32 v[128:129], v[172:173], v[96:97]
	v_mul_f32_e32 v96, 0x3fd744fd, v179
	v_pk_fma_f32 v[96:97], v[180:181], s[66:67], v[96:97] op_sel_hi:[1,1,0]
	s_nop 0
	v_pk_mul_f32 v[172:173], v[96:97], v[96:97]
	s_nop 0
	v_mov_b32_e32 v97, v172
	v_pk_add_f32 v[128:129], v[128:129], v[96:97]
	s_nop 1
	v_mov_b32_dpp v172, v128 quad_perm:[1,0,3,2] row_mask:0xf bank_mask:0xf bound_ctrl:1
	v_mov_b32_dpp v173, v129 quad_perm:[1,0,3,2] row_mask:0xf bank_mask:0xf bound_ctrl:1
	v_pk_add_f32 v[128:129], v[128:129], v[172:173]
	s_nop 1
	v_mov_b32_dpp v172, v128 quad_perm:[2,3,0,1] row_mask:0xf bank_mask:0xf bound_ctrl:1
	v_mov_b32_dpp v173, v129 quad_perm:[2,3,0,1] row_mask:0xf bank_mask:0xf bound_ctrl:1
	v_pk_add_f32 v[128:129], v[128:129], v[172:173]
	s_nop 1
	v_mov_b32_dpp v172, v128 row_half_mirror row_mask:0xf bank_mask:0xf bound_ctrl:1
	v_mov_b32_dpp v173, v129 row_half_mirror row_mask:0xf bank_mask:0xf bound_ctrl:1
	v_pk_add_f32 v[128:129], v[128:129], v[172:173]
	s_nop 1
	v_mov_b32_dpp v172, v128 row_mirror row_mask:0xf bank_mask:0xf bound_ctrl:1
	v_mov_b32_dpp v173, v129 row_mirror row_mask:0xf bank_mask:0xf bound_ctrl:1
	s_and_saveexec_b64 s[6:7], vcc
	v_pk_add_f32 v[128:129], v[128:129], v[172:173]
	ds_write_b64 v160, v[128:129] offset:216
	s_or_b64 exec, exec, s[6:7]
	v_or_b32_e32 v128, 48, v176
	v_ashrrev_i32_e32 v129, 31, v128
	v_readlane_b32 s6, v255, 29
	v_lshlrev_b64 v[128:129], 12, v[128:129]
	v_readlane_b32 s7, v255, 30
	v_readfirstlane_b32 s2, v169
	s_lshl_b32 s2, s2, 13
	v_lshl_add_u64 v[128:129], s[6:7], 0, v[128:129]
	v_lshl_add_u64 v[128:129], v[154:155], 2, v[128:129]
	s_waitcnt lgkmcnt(0)
	s_add_i32 m0, s2, 0x10000
	v_lshl_add_u64 v[128:129], v[128:129], 0, v[0:1]
	s_mov_b64 s[6:7], 0x2000
	global_load_lds_dwordx4 v[128:129], off
	v_lshl_add_u64 v[172:173], v[128:129], 0, s[6:7]
	s_add_i32 m0, s2, 0x10400
	s_mov_b64 s[6:7], 0x4000
	global_load_lds_dwordx4 v[172:173], off
	v_lshl_add_u64 v[172:173], v[128:129], 0, s[6:7]
	s_add_i32 m0, s2, 0x10800
	s_mov_b64 s[6:7], 0x6000
	global_load_lds_dwordx4 v[172:173], off
	v_lshl_add_u64 v[172:173], v[128:129], 0, s[6:7]
	s_add_i32 m0, s2, 0x10c00
	s_mov_b64 s[6:7], 0x8000
	global_load_lds_dwordx4 v[172:173], off
	v_lshl_add_u64 v[172:173], v[128:129], 0, s[6:7]
	s_add_i32 m0, s2, 0x11000
	s_mov_b64 s[6:7], 0xa000
	global_load_lds_dwordx4 v[172:173], off
	v_lshl_add_u64 v[172:173], v[128:129], 0, s[6:7]
	s_add_i32 m0, s2, 0x11400
	s_mov_b64 s[6:7], 0xc000
	global_load_lds_dwordx4 v[172:173], off
	v_lshl_add_u64 v[172:173], v[128:129], 0, s[6:7]
	s_add_i32 m0, s2, 0x11800
	s_mov_b64 s[6:7], 0xe000
	global_load_lds_dwordx4 v[172:173], off
	v_lshl_add_u64 v[128:129], v[128:129], 0, s[6:7]
	s_add_i32 m0, s2, 0x11c00
	v_add_f32_e32 v0, 0, v50
	global_load_lds_dwordx4 v[128:129], off
	s_waitcnt vmcnt(8)
	ds_read2_b32 v[128:129], v167 offset1:32
	ds_read2_b32 v[172:173], v167 offset0:64 offset1:96
	v_mov_b32_e32 v180, v34
	v_mov_b32_e32 v181, v18
	v_mul_f32_e32 v177, 0.5, v0
	s_waitcnt lgkmcnt(0)
	v_mul_f32_e32 v175, 0x3fd744fd, v128
	v_pk_add_f32 v[180:181], v[180:181], 0 op_sel_hi:[1,0]
	v_mov_b32_e32 v176, v18
	v_mov_b32_e32 v174, v1
	v_mov_b32_e32 v128, v129
	v_mov_b32_e32 v129, v172
	s_mov_b32 s2, s67
	v_pk_add_f32 v[174:175], v[176:177], v[174:175]
	v_pk_mul_f32 v[176:177], v[128:129], s[2:3] op_sel_hi:[1,0]
	v_pk_mul_f32 v[182:183], v[180:181], 0.5 op_sel_hi:[1,0]
	v_pk_fma_f32 v[128:129], v[180:181], 0.5, v[176:177] op_sel_hi:[1,0,1]
	v_mov_b32_e32 v182, v175
	v_mov_b32_e32 v184, v1
	v_mov_b32_e32 v185, v177
	v_add_f32_e32 v178, 0, v2
	v_mov_b32_e32 v179, v173
	v_pk_mul_f32 v[180:181], v[128:129], v[128:129]
	v_pk_add_f32 v[182:183], v[182:183], v[184:185]
	v_mul_f32_e32 v0, 0x3fd744fd, v173
	v_mov_b32_e32 v163, v175
	v_pk_mov_b32 v[176:177], v[176:177], v[180:181] op_sel:[1,0]
	v_pk_add_f32 v[180:181], v[128:129], v[182:183]
	v_pk_mul_f32 v[182:183], v[128:129], v[182:183]
	v_pk_fma_f32 v[172:173], v[178:179], s[66:67], v[0:1] op_sel_hi:[1,1,0]
	v_pk_fma_f32 v[176:177], v[174:175], v[162:163], v[176:177]
	v_mov_b32_e32 v181, v183
	v_pk_mul_f32 v[178:179], v[172:173], v[172:173]
	v_pk_add_f32 v[176:177], v[180:181], v[176:177]
	v_mov_b32_e32 v173, v178
	v_pk_add_f32 v[176:177], v[176:177], v[172:173]
	s_nop 1
	v_mov_b32_dpp v178, v176 quad_perm:[1,0,3,2] row_mask:0xf bank_mask:0xf bound_ctrl:1
	v_mov_b32_dpp v179, v177 quad_perm:[1,0,3,2] row_mask:0xf bank_mask:0xf bound_ctrl:1
	v_pk_add_f32 v[176:177], v[176:177], v[178:179]
	s_nop 1
	v_mov_b32_dpp v178, v176 quad_perm:[2,3,0,1] row_mask:0xf bank_mask:0xf bound_ctrl:1
	v_mov_b32_dpp v179, v177 quad_perm:[2,3,0,1] row_mask:0xf bank_mask:0xf bound_ctrl:1
	v_pk_add_f32 v[176:177], v[176:177], v[178:179]
	s_nop 1
	v_mov_b32_dpp v178, v176 row_half_mirror row_mask:0xf bank_mask:0xf bound_ctrl:1
	v_mov_b32_dpp v179, v177 row_half_mirror row_mask:0xf bank_mask:0xf bound_ctrl:1
	v_pk_add_f32 v[176:177], v[176:177], v[178:179]
	s_nop 1
	v_mov_b32_dpp v178, v176 row_mirror row_mask:0xf bank_mask:0xf bound_ctrl:1
	v_mov_b32_dpp v179, v177 row_mirror row_mask:0xf bank_mask:0xf bound_ctrl:1
	s_and_saveexec_b64 s[6:7], vcc
	v_pk_add_f32 v[176:177], v[176:177], v[178:179]
	ds_write_b64 v160, v[176:177] offset:256
	s_or_b64 exec, exec, s[6:7]
	ds_read2_b32 v[176:177], v167 offset0:128 offset1:160
	ds_read2_b32 v[178:179], v167 offset0:192 offset1:224
	v_add_f32_e32 v0, 0, v51
	v_add_f32_e32 v50, 0, v3
	v_mul_f32_e32 v3, 0.5, v0
	s_waitcnt lgkmcnt(1)
;   DI void operator()(f32x16 (&acc)[2][4], int grow0, int gcol0, int lane, int w, char* lds) {
;     ...
;         for (int e = 0; e < 4; ++e) {
;           const int i = 4 * (2 * (ps & 1) + qq) + e;
;           const float* xr = (const float*)(xs + (8 * qq + 4 * hh + e) * 512) + l31;
;           float s1 = 0.f, s2 = 0.f;
; #pragma unroll
;           for (int nt = 0; nt < 4; ++nt) {
;             float v = (acc[mt][nt][i] + bia[nt]) * csc[nt];
;             float z = ALPHA * xr[nt * 32] + hs * v;
;             acc[mt][nt][i] = z; s1 += z; s2 += z * z;
;           }
;           s1 = row16_sum(s1); s2 = row16_sum(s2);
;           if ((lane & 15) == 0) { f32x2 sv = {s1, s2}; *(f32x2*)(redw + (mt * 32 + (i & 3) + 8 * (i >> 2)) * 2) = sv; }
	v_mul_f32_e32 v181, 0x3fd744fd, v176
	v_mov_b32_e32 v18, v35
	v_mov_b32_e32 v2, v19
	v_mov_b32_e32 v180, v1
	v_pk_add_f32 v[182:183], v[18:19], 0 op_sel_hi:[1,0]
	v_pk_add_f32 v[34:35], v[2:3], v[180:181]
	v_mov_b32_e32 v2, v177
	s_waitcnt lgkmcnt(0)
	v_mov_b32_e32 v3, v178
	s_mov_b32 s2, s67
	v_pk_mul_f32 v[18:19], v[2:3], s[2:3] op_sel_hi:[1,0]
	v_pk_mul_f32 v[176:177], v[182:183], 0.5 op_sel_hi:[1,0]
	v_pk_fma_f32 v[2:3], v[182:183], 0.5, v[18:19] op_sel_hi:[1,0,1]
	v_mov_b32_e32 v176, v35
	v_mov_b32_e32 v182, v1
	v_mov_b32_e32 v183, v19
	v_pk_mul_f32 v[180:181], v[2:3], v[2:3]
	v_pk_add_f32 v[176:177], v[176:177], v[182:183]
	v_mov_b32_e32 v163, v35
	v_pk_mov_b32 v[18:19], v[18:19], v[180:181] op_sel:[1,0]
	v_pk_add_f32 v[180:181], v[2:3], v[176:177]
	v_pk_mul_f32 v[176:177], v[2:3], v[176:177]
	v_mov_b32_e32 v51, v179
	v_pk_fma_f32 v[18:19], v[34:35], v[162:163], v[18:19]
	v_mov_b32_e32 v181, v177
	v_mul_f32_e32 v0, 0x3fd744fd, v179
	v_pk_add_f32 v[176:177], v[180:181], v[18:19]
	v_pk_fma_f32 v[18:19], v[50:51], s[66:67], v[0:1] op_sel_hi:[1,1,0]
	s_nop 0
	v_pk_mul_f32 v[50:51], v[18:19], v[18:19]
	s_nop 0
	v_mov_b32_e32 v19, v50
	v_pk_add_f32 v[50:51], v[176:177], v[18:19]
	s_nop 1
	v_mov_b32_dpp v176, v50 quad_perm:[1,0,3,2] row_mask:0xf bank_mask:0xf bound_ctrl:1
	v_mov_b32_dpp v177, v51 quad_perm:[1,0,3,2] row_mask:0xf bank_mask:0xf bound_ctrl:1
	v_pk_add_f32 v[50:51], v[50:51], v[176:177]
	s_nop 1
	v_mov_b32_dpp v176, v50 quad_perm:[2,3,0,1] row_mask:0xf bank_mask:0xf bound_ctrl:1
	v_mov_b32_dpp v177, v51 quad_perm:[2,3,0,1] row_mask:0xf bank_mask:0xf bound_ctrl:1
	v_pk_add_f32 v[50:51], v[50:51], v[176:177]
	s_nop 1
	v_mov_b32_dpp v176, v50 row_half_mirror row_mask:0xf bank_mask:0xf bound_ctrl:1
	v_mov_b32_dpp v177, v51 row_half_mirror row_mask:0xf bank_mask:0xf bound_ctrl:1
	v_pk_add_f32 v[50:51], v[50:51], v[176:177]
	s_nop 1
	v_mov_b32_dpp v176, v50 row_mirror row_mask:0xf bank_mask:0xf bound_ctrl:1
	v_mov_b32_dpp v177, v51 row_mirror row_mask:0xf bank_mask:0xf bound_ctrl:1
	s_and_saveexec_b64 s[6:7], vcc
	v_pk_add_f32 v[50:51], v[50:51], v[176:177]
	ds_write_b64 v160, v[50:51] offset:264
	s_or_b64 exec, exec, s[6:7]
	ds_read2_b32 v[50:51], v143 offset1:32
	ds_read2_b32 v[176:177], v143 offset0:64 offset1:96
	v_add_f32_e32 v0, 0, v52
	v_mov_b32_e32 v184, v36
	v_mov_b32_e32 v185, v20
	v_mul_f32_e32 v179, 0.5, v0
	s_waitcnt lgkmcnt(1)
	v_mul_f32_e32 v183, 0x3fd744fd, v50
	v_pk_add_f32 v[184:185], v[184:185], 0 op_sel_hi:[1,0]
	v_mov_b32_e32 v178, v20
	v_mov_b32_e32 v182, v1
	v_mov_b32_e32 v50, v51
	s_waitcnt lgkmcnt(0)
	v_mov_b32_e32 v51, v176
	s_mov_b32 s2, s67
	v_pk_add_f32 v[178:179], v[178:179], v[182:183]
	v_pk_mul_f32 v[182:183], v[50:51], s[2:3] op_sel_hi:[1,0]
	v_pk_mul_f32 v[186:187], v[184:185], 0.5 op_sel_hi:[1,0]
	v_pk_fma_f32 v[50:51], v[184:185], 0.5, v[182:183] op_sel_hi:[1,0,1]
	v_mov_b32_e32 v186, v179
	v_mov_b32_e32 v188, v1
	v_mov_b32_e32 v189, v183
	v_add_f32_e32 v180, 0, v4
	v_mov_b32_e32 v181, v177
	v_pk_mul_f32 v[184:185], v[50:51], v[50:51]
	v_pk_add_f32 v[186:187], v[186:187], v[188:189]
	v_mul_f32_e32 v0, 0x3fd744fd, v177
	v_mov_b32_e32 v163, v179
	v_pk_mov_b32 v[182:183], v[182:183], v[184:185] op_sel:[1,0]
	v_pk_add_f32 v[184:185], v[50:51], v[186:187]
	v_pk_mul_f32 v[186:187], v[50:51], v[186:187]
	v_pk_fma_f32 v[176:177], v[180:181], s[66:67], v[0:1] op_sel_hi:[1,1,0]
	v_pk_fma_f32 v[182:183], v[178:179], v[162:163], v[182:183]
	v_mov_b32_e32 v185, v187
	v_pk_mul_f32 v[180:181], v[176:177], v[176:177]
	v_pk_add_f32 v[182:183], v[184:185], v[182:183]
	v_mov_b32_e32 v177, v180
	v_pk_add_f32 v[180:181], v[182:183], v[176:177]
	s_nop 1
	v_mov_b32_dpp v182, v180 quad_perm:[1,0,3,2] row_mask:0xf bank_mask:0xf bound_ctrl:1
	v_mov_b32_dpp v183, v181 quad_perm:[1,0,3,2] row_mask:0xf bank_mask:0xf bound_ctrl:1
	v_pk_add_f32 v[180:181], v[180:181], v[182:183]
	s_nop 1
	v_mov_b32_dpp v182, v180 quad_perm:[2,3,0,1] row_mask:0xf bank_mask:0xf bound_ctrl:1
	v_mov_b32_dpp v183, v181 quad_perm:[2,3,0,1] row_mask:0xf bank_mask:0xf bound_ctrl:1
	v_pk_add_f32 v[180:181], v[180:181], v[182:183]
	s_nop 1
	v_mov_b32_dpp v182, v180 row_half_mirror row_mask:0xf bank_mask:0xf bound_ctrl:1
	v_mov_b32_dpp v183, v181 row_half_mirror row_mask:0xf bank_mask:0xf bound_ctrl:1
	v_pk_add_f32 v[180:181], v[180:181], v[182:183]
	s_nop 1
	v_mov_b32_dpp v182, v180 row_mirror row_mask:0xf bank_mask:0xf bound_ctrl:1
	v_mov_b32_dpp v183, v181 row_mirror row_mask:0xf bank_mask:0xf bound_ctrl:1
	s_and_saveexec_b64 s[6:7], vcc
	v_pk_add_f32 v[180:181], v[180:181], v[182:183]
	ds_write_b64 v160, v[180:181] offset:272
	s_or_b64 exec, exec, s[6:7]
	ds_read2_b32 v[180:181], v144 offset1:32
	ds_read2_b32 v[182:183], v144 offset0:64 offset1:96
	v_add_f32_e32 v0, 0, v53
	v_add_f32_e32 v52, 0, v5
	v_mul_f32_e32 v5, 0.5, v0
	s_waitcnt lgkmcnt(1)
	v_mul_f32_e32 v185, 0x3fd744fd, v180
	v_mov_b32_e32 v20, v37
	v_mov_b32_e32 v4, v21
	v_mov_b32_e32 v184, v1
	v_pk_add_f32 v[186:187], v[20:21], 0 op_sel_hi:[1,0]
	v_pk_add_f32 v[36:37], v[4:5], v[184:185]
	v_mov_b32_e32 v4, v181
	s_waitcnt lgkmcnt(0)
;   DI void operator()(f32x16 (&acc)[2][4], int grow0, int gcol0, int lane, int w, char* lds) {
;     ...
;         for (int e = 0; e < 4; ++e) {
;           const int i = 4 * (2 * (ps & 1) + qq) + e;
;           const float* xr = (const float*)(xs + (8 * qq + 4 * hh + e) * 512) + l31;
;           float s1 = 0.f, s2 = 0.f;
; #pragma unroll
;           for (int nt = 0; nt < 4; ++nt) {
;             float v = (acc[mt][nt][i] + bia[nt]) * csc[nt];
;             float z = ALPHA * xr[nt * 32] + hs * v;
;             acc[mt][nt][i] = z; s1 += z; s2 += z * z;
;           }
;           s1 = row16_sum(s1); s2 = row16_sum(s2);
;           if ((lane & 15) == 0) { f32x2 sv = {s1, s2}; *(f32x2*)(redw + (mt * 32 + (i & 3) + 8 * (i >> 2)) * 2) = sv; }
	v_mov_b32_e32 v5, v182
	s_mov_b32 s2, s67
	v_pk_mul_f32 v[20:21], v[4:5], s[2:3] op_sel_hi:[1,0]
	v_pk_mul_f32 v[180:181], v[186:187], 0.5 op_sel_hi:[1,0]
	v_pk_fma_f32 v[4:5], v[186:187], 0.5, v[20:21] op_sel_hi:[1,0,1]
	v_mov_b32_e32 v180, v37
	v_mov_b32_e32 v186, v1
	v_mov_b32_e32 v187, v21
	v_pk_mul_f32 v[184:185], v[4:5], v[4:5]
	v_pk_add_f32 v[180:181], v[180:181], v[186:187]
	v_mov_b32_e32 v163, v37
	v_pk_mov_b32 v[20:21], v[20:21], v[184:185] op_sel:[1,0]
	v_pk_add_f32 v[184:185], v[4:5], v[180:181]
	v_pk_mul_f32 v[180:181], v[4:5], v[180:181]
	v_mov_b32_e32 v53, v183
	v_pk_fma_f32 v[20:21], v[36:37], v[162:163], v[20:21]
	v_mov_b32_e32 v185, v181
	v_mul_f32_e32 v0, 0x3fd744fd, v183
	v_pk_add_f32 v[180:181], v[184:185], v[20:21]
	v_pk_fma_f32 v[20:21], v[52:53], s[66:67], v[0:1] op_sel_hi:[1,1,0]
	s_nop 0
	v_pk_mul_f32 v[52:53], v[20:21], v[20:21]
	s_nop 0
	v_mov_b32_e32 v21, v52
	v_pk_add_f32 v[52:53], v[180:181], v[20:21]
	s_nop 1
	v_mov_b32_dpp v180, v52 quad_perm:[1,0,3,2] row_mask:0xf bank_mask:0xf bound_ctrl:1
	v_mov_b32_dpp v181, v53 quad_perm:[1,0,3,2] row_mask:0xf bank_mask:0xf bound_ctrl:1
	v_pk_add_f32 v[52:53], v[52:53], v[180:181]
	s_nop 1
	v_mov_b32_dpp v180, v52 quad_perm:[2,3,0,1] row_mask:0xf bank_mask:0xf bound_ctrl:1
	v_mov_b32_dpp v181, v53 quad_perm:[2,3,0,1] row_mask:0xf bank_mask:0xf bound_ctrl:1
	v_pk_add_f32 v[52:53], v[52:53], v[180:181]
	s_nop 1
	v_mov_b32_dpp v180, v52 row_half_mirror row_mask:0xf bank_mask:0xf bound_ctrl:1
	v_mov_b32_dpp v181, v53 row_half_mirror row_mask:0xf bank_mask:0xf bound_ctrl:1
	v_pk_add_f32 v[52:53], v[52:53], v[180:181]
	s_nop 1
	v_mov_b32_dpp v180, v52 row_mirror row_mask:0xf bank_mask:0xf bound_ctrl:1
	v_mov_b32_dpp v181, v53 row_mirror row_mask:0xf bank_mask:0xf bound_ctrl:1
	s_and_saveexec_b64 s[6:7], vcc
	v_pk_add_f32 v[52:53], v[52:53], v[180:181]
	ds_write_b64 v160, v[52:53] offset:280
	s_or_b64 exec, exec, s[6:7]
	ds_read2_b32 v[52:53], v83 offset1:32
	ds_read2_b32 v[180:181], v83 offset0:64 offset1:96
	v_add_f32_e32 v0, 0, v54
	v_mov_b32_e32 v188, v38
	v_mov_b32_e32 v189, v22
	v_mul_f32_e32 v183, 0.5, v0
	s_waitcnt lgkmcnt(1)
	v_mul_f32_e32 v187, 0x3fd744fd, v52
	v_pk_add_f32 v[188:189], v[188:189], 0 op_sel_hi:[1,0]
	v_mov_b32_e32 v182, v22
	v_mov_b32_e32 v186, v1
	v_mov_b32_e32 v52, v53
	s_waitcnt lgkmcnt(0)
	v_mov_b32_e32 v53, v180
	s_mov_b32 s2, s67
	v_pk_add_f32 v[182:183], v[182:183], v[186:187]
	v_pk_mul_f32 v[186:187], v[52:53], s[2:3] op_sel_hi:[1,0]
	v_pk_mul_f32 v[190:191], v[188:189], 0.5 op_sel_hi:[1,0]
	v_pk_fma_f32 v[52:53], v[188:189], 0.5, v[186:187] op_sel_hi:[1,0,1]
	v_mov_b32_e32 v190, v183
	v_mov_b32_e32 v192, v1
	v_mov_b32_e32 v193, v187
	v_add_f32_e32 v184, 0, v6
	v_mov_b32_e32 v185, v181
	v_pk_mul_f32 v[188:189], v[52:53], v[52:53]
	v_pk_add_f32 v[190:191], v[190:191], v[192:193]
	v_mul_f32_e32 v0, 0x3fd744fd, v181
	v_mov_b32_e32 v163, v183
	v_pk_mov_b32 v[186:187], v[186:187], v[188:189] op_sel:[1,0]
	v_pk_add_f32 v[188:189], v[52:53], v[190:191]
	v_pk_mul_f32 v[190:191], v[52:53], v[190:191]
	v_pk_fma_f32 v[180:181], v[184:185], s[66:67], v[0:1] op_sel_hi:[1,1,0]
	v_pk_fma_f32 v[186:187], v[182:183], v[162:163], v[186:187]
	v_mov_b32_e32 v189, v191
	v_pk_mul_f32 v[184:185], v[180:181], v[180:181]
	v_pk_add_f32 v[186:187], v[188:189], v[186:187]
	v_mov_b32_e32 v181, v184
	v_pk_add_f32 v[184:185], v[186:187], v[180:181]
	s_nop 1
	v_mov_b32_dpp v186, v184 quad_perm:[1,0,3,2] row_mask:0xf bank_mask:0xf bound_ctrl:1
	v_mov_b32_dpp v187, v185 quad_perm:[1,0,3,2] row_mask:0xf bank_mask:0xf bound_ctrl:1
	v_pk_add_f32 v[184:185], v[184:185], v[186:187]
	s_nop 1
	v_mov_b32_dpp v186, v184 quad_perm:[2,3,0,1] row_mask:0xf bank_mask:0xf bound_ctrl:1
	v_mov_b32_dpp v187, v185 quad_perm:[2,3,0,1] row_mask:0xf bank_mask:0xf bound_ctrl:1
	v_pk_add_f32 v[184:185], v[184:185], v[186:187]
	s_nop 1
	v_mov_b32_dpp v186, v184 row_half_mirror row_mask:0xf bank_mask:0xf bound_ctrl:1
	v_mov_b32_dpp v187, v185 row_half_mirror row_mask:0xf bank_mask:0xf bound_ctrl:1
	v_pk_add_f32 v[184:185], v[184:185], v[186:187]
	s_nop 1
	v_mov_b32_dpp v186, v184 row_mirror row_mask:0xf bank_mask:0xf bound_ctrl:1
	v_mov_b32_dpp v187, v185 row_mirror row_mask:0xf bank_mask:0xf bound_ctrl:1
	s_and_saveexec_b64 s[6:7], vcc
	v_pk_add_f32 v[184:185], v[184:185], v[186:187]
	ds_write_b64 v160, v[184:185] offset:320
	s_or_b64 exec, exec, s[6:7]
	ds_read2_b32 v[184:185], v83 offset0:128 offset1:160
	ds_read2_b32 v[186:187], v83 offset0:192 offset1:224
	v_add_f32_e32 v0, 0, v55
	v_add_f32_e32 v54, 0, v7
	v_mul_f32_e32 v7, 0.5, v0
	s_waitcnt lgkmcnt(1)
	v_mul_f32_e32 v189, 0x3fd744fd, v184
	v_mov_b32_e32 v22, v39
	v_mov_b32_e32 v6, v23
	v_mov_b32_e32 v188, v1
	v_pk_add_f32 v[190:191], v[22:23], 0 op_sel_hi:[1,0]
	v_pk_add_f32 v[38:39], v[6:7], v[188:189]
	v_mov_b32_e32 v6, v185
	s_waitcnt lgkmcnt(0)
;   DI void operator()(f32x16 (&acc)[2][4], int grow0, int gcol0, int lane, int w, char* lds) {
;     ...
;         for (int e = 0; e < 4; ++e) {
;           const int i = 4 * (2 * (ps & 1) + qq) + e;
;           const float* xr = (const float*)(xs + (8 * qq + 4 * hh + e) * 512) + l31;
;           float s1 = 0.f, s2 = 0.f;
; #pragma unroll
;           for (int nt = 0; nt < 4; ++nt) {
;             float v = (acc[mt][nt][i] + bia[nt]) * csc[nt];
;             float z = ALPHA * xr[nt * 32] + hs * v;
;             acc[mt][nt][i] = z; s1 += z; s2 += z * z;
;           }
;           s1 = row16_sum(s1); s2 = row16_sum(s2);
;           if ((lane & 15) == 0) { f32x2 sv = {s1, s2}; *(f32x2*)(redw + (mt * 32 + (i & 3) + 8 * (i >> 2)) * 2) = sv; }
	v_mov_b32_e32 v7, v186
	s_mov_b32 s2, s67
	v_pk_mul_f32 v[22:23], v[6:7], s[2:3] op_sel_hi:[1,0]
	v_pk_mul_f32 v[184:185], v[190:191], 0.5 op_sel_hi:[1,0]
	v_pk_fma_f32 v[6:7], v[190:191], 0.5, v[22:23] op_sel_hi:[1,0,1]
	v_mov_b32_e32 v184, v39
	v_mov_b32_e32 v190, v1
	v_mov_b32_e32 v191, v23
	v_pk_mul_f32 v[188:189], v[6:7], v[6:7]
	v_pk_add_f32 v[184:185], v[184:185], v[190:191]
	v_mov_b32_e32 v163, v39
	v_pk_mov_b32 v[22:23], v[22:23], v[188:189] op_sel:[1,0]
	v_pk_add_f32 v[188:189], v[6:7], v[184:185]
	v_pk_mul_f32 v[184:185], v[6:7], v[184:185]
	v_mov_b32_e32 v55, v187
	v_pk_fma_f32 v[22:23], v[38:39], v[162:163], v[22:23]
	v_mov_b32_e32 v189, v185
	v_mul_f32_e32 v0, 0x3fd744fd, v187
	v_pk_add_f32 v[184:185], v[188:189], v[22:23]
	v_pk_fma_f32 v[22:23], v[54:55], s[66:67], v[0:1] op_sel_hi:[1,1,0]
	s_nop 0
	v_pk_mul_f32 v[54:55], v[22:23], v[22:23]
	s_nop 0
	v_mov_b32_e32 v23, v54
	v_pk_add_f32 v[54:55], v[184:185], v[22:23]
	s_nop 1
	v_mov_b32_dpp v184, v54 quad_perm:[1,0,3,2] row_mask:0xf bank_mask:0xf bound_ctrl:1
	v_mov_b32_dpp v185, v55 quad_perm:[1,0,3,2] row_mask:0xf bank_mask:0xf bound_ctrl:1
	v_pk_add_f32 v[54:55], v[54:55], v[184:185]
	s_nop 1
	v_mov_b32_dpp v184, v54 quad_perm:[2,3,0,1] row_mask:0xf bank_mask:0xf bound_ctrl:1
	v_mov_b32_dpp v185, v55 quad_perm:[2,3,0,1] row_mask:0xf bank_mask:0xf bound_ctrl:1
	v_pk_add_f32 v[54:55], v[54:55], v[184:185]
	s_nop 1
	v_mov_b32_dpp v184, v54 row_half_mirror row_mask:0xf bank_mask:0xf bound_ctrl:1
	v_mov_b32_dpp v185, v55 row_half_mirror row_mask:0xf bank_mask:0xf bound_ctrl:1
	v_pk_add_f32 v[54:55], v[54:55], v[184:185]
	s_nop 1
	v_mov_b32_dpp v184, v54 row_mirror row_mask:0xf bank_mask:0xf bound_ctrl:1
	v_mov_b32_dpp v185, v55 row_mirror row_mask:0xf bank_mask:0xf bound_ctrl:1
	s_and_saveexec_b64 s[6:7], vcc
	v_pk_add_f32 v[54:55], v[54:55], v[184:185]
	ds_write_b64 v160, v[54:55] offset:328
	s_or_b64 exec, exec, s[6:7]
	ds_read2_b32 v[54:55], v85 offset1:32
	ds_read2_b32 v[184:185], v85 offset0:64 offset1:96
	v_add_f32_e32 v0, 0, v56
	v_mov_b32_e32 v192, v40
	v_mov_b32_e32 v193, v24
	v_mul_f32_e32 v187, 0.5, v0
	s_waitcnt lgkmcnt(1)
	v_mul_f32_e32 v191, 0x3fd744fd, v54
	v_pk_add_f32 v[192:193], v[192:193], 0 op_sel_hi:[1,0]
	v_mov_b32_e32 v186, v24
	v_mov_b32_e32 v190, v1
	v_mov_b32_e32 v54, v55
	s_waitcnt lgkmcnt(0)
	v_mov_b32_e32 v55, v184
	s_mov_b32 s2, s67
	v_pk_add_f32 v[186:187], v[186:187], v[190:191]
	v_pk_mul_f32 v[190:191], v[54:55], s[2:3] op_sel_hi:[1,0]
	v_pk_mul_f32 v[194:195], v[192:193], 0.5 op_sel_hi:[1,0]
	v_pk_fma_f32 v[54:55], v[192:193], 0.5, v[190:191] op_sel_hi:[1,0,1]
	v_mov_b32_e32 v194, v187
	v_mov_b32_e32 v196, v1
	v_mov_b32_e32 v197, v191
	v_add_f32_e32 v188, 0, v8
	v_mov_b32_e32 v189, v185
	v_pk_mul_f32 v[192:193], v[54:55], v[54:55]
	v_pk_add_f32 v[194:195], v[194:195], v[196:197]
	v_mul_f32_e32 v0, 0x3fd744fd, v185
	v_mov_b32_e32 v163, v187
	v_pk_mov_b32 v[190:191], v[190:191], v[192:193] op_sel:[1,0]
	v_pk_add_f32 v[192:193], v[54:55], v[194:195]
	v_pk_mul_f32 v[194:195], v[54:55], v[194:195]
	v_pk_fma_f32 v[184:185], v[188:189], s[66:67], v[0:1] op_sel_hi:[1,1,0]
	v_pk_fma_f32 v[190:191], v[186:187], v[162:163], v[190:191]
	v_mov_b32_e32 v193, v195
	v_pk_mul_f32 v[188:189], v[184:185], v[184:185]
	v_pk_add_f32 v[190:191], v[192:193], v[190:191]
	v_mov_b32_e32 v185, v188
	v_pk_add_f32 v[188:189], v[190:191], v[184:185]
	s_nop 1
	v_mov_b32_dpp v190, v188 quad_perm:[1,0,3,2] row_mask:0xf bank_mask:0xf bound_ctrl:1
	v_mov_b32_dpp v191, v189 quad_perm:[1,0,3,2] row_mask:0xf bank_mask:0xf bound_ctrl:1
	v_pk_add_f32 v[188:189], v[188:189], v[190:191]
	s_nop 1
	v_mov_b32_dpp v190, v188 quad_perm:[2,3,0,1] row_mask:0xf bank_mask:0xf bound_ctrl:1
	v_mov_b32_dpp v191, v189 quad_perm:[2,3,0,1] row_mask:0xf bank_mask:0xf bound_ctrl:1
	v_pk_add_f32 v[188:189], v[188:189], v[190:191]
	s_nop 1
	v_mov_b32_dpp v190, v188 row_half_mirror row_mask:0xf bank_mask:0xf bound_ctrl:1
	v_mov_b32_dpp v191, v189 row_half_mirror row_mask:0xf bank_mask:0xf bound_ctrl:1
	v_pk_add_f32 v[188:189], v[188:189], v[190:191]
	s_nop 1
	v_mov_b32_dpp v190, v188 row_mirror row_mask:0xf bank_mask:0xf bound_ctrl:1
	v_mov_b32_dpp v191, v189 row_mirror row_mask:0xf bank_mask:0xf bound_ctrl:1
	s_and_saveexec_b64 s[6:7], vcc
	v_pk_add_f32 v[188:189], v[188:189], v[190:191]
	ds_write_b64 v160, v[188:189] offset:336
	s_or_b64 exec, exec, s[6:7]
	ds_read2_b32 v[188:189], v87 offset1:32
	ds_read2_b32 v[190:191], v87 offset0:64 offset1:96
	v_add_f32_e32 v0, 0, v57
	v_add_f32_e32 v56, 0, v9
	v_mul_f32_e32 v9, 0.5, v0
	s_waitcnt lgkmcnt(1)
	v_mul_f32_e32 v193, 0x3fd744fd, v188
	v_mov_b32_e32 v24, v41
	v_mov_b32_e32 v8, v25
	v_mov_b32_e32 v192, v1
	v_pk_add_f32 v[194:195], v[24:25], 0 op_sel_hi:[1,0]
	v_pk_add_f32 v[40:41], v[8:9], v[192:193]
	v_mov_b32_e32 v8, v189
	s_waitcnt lgkmcnt(0)
;   DI void operator()(f32x16 (&acc)[2][4], int grow0, int gcol0, int lane, int w, char* lds) {
;     ...
;         if (ps >= 1) asm volatile("s_waitcnt vmcnt(8)" ::: "memory");
;       } else asm volatile("s_waitcnt vmcnt(0)" ::: "memory");
;       const char* xs = lds + (ps & 1) * 65536 + w * 8192;
; #pragma unroll
;       for (int qq = 0; qq < 2; ++qq)
; #pragma unroll
;         for (int e = 0; e < 4; ++e) {
;           const int i = 4 * (2 * (ps & 1) + qq) + e;
;           const float* xr = (const float*)(xs + (8 * qq + 4 * hh + e) * 512) + l31;
;           float s1 = 0.f, s2 = 0.f;
; #pragma unroll
;           for (int nt = 0; nt < 4; ++nt) {
;             float v = (acc[mt][nt][i] + bia[nt]) * csc[nt];
;             float z = ALPHA * xr[nt * 32] + hs * v;
;             acc[mt][nt][i] = z; s1 += z; s2 += z * z;
;           }
;           s1 = row16_sum(s1); s2 = row16_sum(s2);
;           if ((lane & 15) == 0) { f32x2 sv = {s1, s2}; *(f32x2*)(redw + (mt * 32 + (i & 3) + 8 * (i >> 2)) * 2) = sv; }
	v_mov_b32_e32 v9, v190
	s_mov_b32 s2, s67
	v_pk_mul_f32 v[24:25], v[8:9], s[2:3] op_sel_hi:[1,0]
	v_pk_mul_f32 v[188:189], v[194:195], 0.5 op_sel_hi:[1,0]
	v_pk_fma_f32 v[8:9], v[194:195], 0.5, v[24:25] op_sel_hi:[1,0,1]
	v_mov_b32_e32 v188, v41
	v_mov_b32_e32 v194, v1
	v_mov_b32_e32 v195, v25
	v_pk_mul_f32 v[192:193], v[8:9], v[8:9]
	v_pk_add_f32 v[188:189], v[188:189], v[194:195]
	v_mov_b32_e32 v163, v41
	v_pk_mov_b32 v[24:25], v[24:25], v[192:193] op_sel:[1,0]
	v_pk_add_f32 v[192:193], v[8:9], v[188:189]
	v_pk_mul_f32 v[188:189], v[8:9], v[188:189]
	v_mov_b32_e32 v57, v191
	v_pk_fma_f32 v[24:25], v[40:41], v[162:163], v[24:25]
	v_mov_b32_e32 v193, v189
	v_mul_f32_e32 v0, 0x3fd744fd, v191
	v_pk_add_f32 v[188:189], v[192:193], v[24:25]
	v_pk_fma_f32 v[24:25], v[56:57], s[66:67], v[0:1] op_sel_hi:[1,1,0]
	s_nop 0
	v_pk_mul_f32 v[56:57], v[24:25], v[24:25]
	s_nop 0
	v_mov_b32_e32 v25, v56
	v_pk_add_f32 v[56:57], v[188:189], v[24:25]
	s_nop 1
	v_mov_b32_dpp v188, v56 quad_perm:[1,0,3,2] row_mask:0xf bank_mask:0xf bound_ctrl:1
	v_mov_b32_dpp v189, v57 quad_perm:[1,0,3,2] row_mask:0xf bank_mask:0xf bound_ctrl:1
	v_pk_add_f32 v[56:57], v[56:57], v[188:189]
	s_nop 1
	v_mov_b32_dpp v188, v56 quad_perm:[2,3,0,1] row_mask:0xf bank_mask:0xf bound_ctrl:1
	v_mov_b32_dpp v189, v57 quad_perm:[2,3,0,1] row_mask:0xf bank_mask:0xf bound_ctrl:1
	v_pk_add_f32 v[56:57], v[56:57], v[188:189]
	s_nop 1
	v_mov_b32_dpp v188, v56 row_half_mirror row_mask:0xf bank_mask:0xf bound_ctrl:1
	v_mov_b32_dpp v189, v57 row_half_mirror row_mask:0xf bank_mask:0xf bound_ctrl:1
	v_pk_add_f32 v[56:57], v[56:57], v[188:189]
	s_nop 1
	v_mov_b32_dpp v188, v56 row_mirror row_mask:0xf bank_mask:0xf bound_ctrl:1
	v_mov_b32_dpp v189, v57 row_mirror row_mask:0xf bank_mask:0xf bound_ctrl:1
	s_and_saveexec_b64 s[6:7], vcc
	v_pk_add_f32 v[56:57], v[56:57], v[188:189]
	ds_write_b64 v160, v[56:57] offset:344
	s_or_b64 exec, exec, s[6:7]
	s_waitcnt vmcnt(0)
	ds_read2_b32 v[56:57], v89 offset1:32
	ds_read2_b32 v[190:191], v89 offset0:64 offset1:96
	v_add_f32_e32 v0, 0, v58
	v_mul_f32_e32 v189, 0.5, v0
	v_mov_b32_e32 v188, v26
	s_waitcnt lgkmcnt(1)
	v_mul_f32_e32 v193, 0x3fd744fd, v56
	v_add_f32_e32 v56, 0, v42
	v_mul_f32_e32 v0, 0x3fd744fd, v57
	v_mov_b32_e32 v192, v1
	v_pk_fma_f32 v[56:57], v[56:57], s[66:67], v[0:1] op_sel_hi:[1,1,0]
	v_pk_add_f32 v[192:193], v[188:189], v[192:193]
	s_waitcnt lgkmcnt(0)
	v_mov_b32_e32 v188, v190
	v_mov_b32_e32 v189, v56
	v_mov_b32_e32 v196, v165
	v_mov_b32_e32 v197, v56
	v_mov_b32_e32 v163, v193
	v_pk_mul_f32 v[196:197], v[188:189], v[196:197]
	v_pk_mul_f32 v[198:199], v[192:193], v[162:163]
	v_mov_b32_e32 v200, v1
	v_pk_mov_b32 v[198:199], v[192:193], v[198:199] op_sel:[1,0]
	v_mov_b32_e32 v201, v196
	v_add_f32_e32 v194, 0, v10
	v_mov_b32_e32 v195, v191
	v_pk_fma_f32 v[188:189], v[192:193], v[162:163], v[196:197]
	v_pk_add_f32 v[196:197], v[198:199], v[200:201]
	v_mul_f32_e32 v0, 0x3fd744fd, v191
	v_pk_add_f32 v[198:199], v[56:57], v[196:197]
	v_pk_mul_f32 v[196:197], v[188:189], v[196:197] op_sel_hi:[0,1]
	v_pk_fma_f32 v[190:191], v[194:195], s[66:67], v[0:1] op_sel_hi:[1,1,0]
	v_mov_b32_e32 v199, v197
	v_pk_mul_f32 v[194:195], v[190:191], v[190:191]
	v_pk_add_f32 v[196:197], v[188:189], v[198:199]
	v_mov_b32_e32 v191, v194
	v_pk_add_f32 v[194:195], v[196:197], v[190:191]
	s_nop 1
	v_mov_b32_dpp v196, v194 quad_perm:[1,0,3,2] row_mask:0xf bank_mask:0xf bound_ctrl:1
	v_mov_b32_dpp v197, v195 quad_perm:[1,0,3,2] row_mask:0xf bank_mask:0xf bound_ctrl:1
	v_pk_add_f32 v[194:195], v[194:195], v[196:197]
	s_nop 1
	v_mov_b32_dpp v196, v194 quad_perm:[2,3,0,1] row_mask:0xf bank_mask:0xf bound_ctrl:1
	v_mov_b32_dpp v197, v195 quad_perm:[2,3,0,1] row_mask:0xf bank_mask:0xf bound_ctrl:1
	v_pk_add_f32 v[194:195], v[194:195], v[196:197]
	s_nop 1
	v_mov_b32_dpp v196, v194 row_half_mirror row_mask:0xf bank_mask:0xf bound_ctrl:1
	v_mov_b32_dpp v197, v195 row_half_mirror row_mask:0xf bank_mask:0xf bound_ctrl:1
	v_pk_add_f32 v[194:195], v[194:195], v[196:197]
	s_nop 1
	v_mov_b32_dpp v196, v194 row_mirror row_mask:0xf bank_mask:0xf bound_ctrl:1
	v_mov_b32_dpp v197, v195 row_mirror row_mask:0xf bank_mask:0xf bound_ctrl:1
	s_and_saveexec_b64 s[6:7], vcc
	v_pk_add_f32 v[194:195], v[194:195], v[196:197]
	ds_write_b64 v160, v[194:195] offset:384
	s_or_b64 exec, exec, s[6:7]
	ds_read2_b32 v[194:195], v98 offset1:32
	ds_read2_b32 v[196:197], v98 offset0:64 offset1:96
	v_add_f32_e32 v0, 0, v59
	v_add_f32_e32 v58, 0, v11
	v_mul_f32_e32 v11, 0.5, v0
	s_waitcnt lgkmcnt(1)
	v_mul_f32_e32 v199, 0x3fd744fd, v194
	v_mov_b32_e32 v26, v43
	v_mov_b32_e32 v10, v27
	v_mov_b32_e32 v198, v1
	v_pk_add_f32 v[200:201], v[26:27], 0 op_sel_hi:[1,0]
	v_pk_add_f32 v[42:43], v[10:11], v[198:199]
	v_mov_b32_e32 v10, v195
	s_waitcnt lgkmcnt(0)
;   DI void operator()(f32x16 (&acc)[2][4], int grow0, int gcol0, int lane, int w, char* lds) {
;     ...
;         for (int e = 0; e < 4; ++e) {
;           const int i = 4 * (2 * (ps & 1) + qq) + e;
;           const float* xr = (const float*)(xs + (8 * qq + 4 * hh + e) * 512) + l31;
;           float s1 = 0.f, s2 = 0.f;
; #pragma unroll
;           for (int nt = 0; nt < 4; ++nt) {
;             float v = (acc[mt][nt][i] + bia[nt]) * csc[nt];
;             float z = ALPHA * xr[nt * 32] + hs * v;
;             acc[mt][nt][i] = z; s1 += z; s2 += z * z;
;           }
;           s1 = row16_sum(s1); s2 = row16_sum(s2);
;           if ((lane & 15) == 0) { f32x2 sv = {s1, s2}; *(f32x2*)(redw + (mt * 32 + (i & 3) + 8 * (i >> 2)) * 2) = sv; }
	v_mov_b32_e32 v11, v196
	s_mov_b32 s2, s67
	v_pk_mul_f32 v[26:27], v[10:11], s[2:3] op_sel_hi:[1,0]
	v_pk_mul_f32 v[194:195], v[200:201], 0.5 op_sel_hi:[1,0]
	v_pk_fma_f32 v[10:11], v[200:201], 0.5, v[26:27] op_sel_hi:[1,0,1]
	v_mov_b32_e32 v194, v43
	v_mov_b32_e32 v200, v1
	v_mov_b32_e32 v201, v27
	v_pk_mul_f32 v[198:199], v[10:11], v[10:11]
	v_pk_add_f32 v[194:195], v[194:195], v[200:201]
	v_mov_b32_e32 v163, v43
	v_pk_mov_b32 v[26:27], v[26:27], v[198:199] op_sel:[1,0]
	v_pk_add_f32 v[198:199], v[10:11], v[194:195]
	v_pk_mul_f32 v[194:195], v[10:11], v[194:195]
	v_mov_b32_e32 v59, v197
	v_pk_fma_f32 v[26:27], v[42:43], v[162:163], v[26:27]
	v_mov_b32_e32 v199, v195
	v_mul_f32_e32 v0, 0x3fd744fd, v197
	v_pk_add_f32 v[194:195], v[198:199], v[26:27]
	v_pk_fma_f32 v[26:27], v[58:59], s[66:67], v[0:1] op_sel_hi:[1,1,0]
	s_nop 0
	v_pk_mul_f32 v[58:59], v[26:27], v[26:27]
	s_nop 0
	v_mov_b32_e32 v27, v58
	v_pk_add_f32 v[58:59], v[194:195], v[26:27]
	s_nop 1
	v_mov_b32_dpp v194, v58 quad_perm:[1,0,3,2] row_mask:0xf bank_mask:0xf bound_ctrl:1
	v_mov_b32_dpp v195, v59 quad_perm:[1,0,3,2] row_mask:0xf bank_mask:0xf bound_ctrl:1
	v_pk_add_f32 v[58:59], v[58:59], v[194:195]
	s_nop 1
	v_mov_b32_dpp v194, v58 quad_perm:[2,3,0,1] row_mask:0xf bank_mask:0xf bound_ctrl:1
	v_mov_b32_dpp v195, v59 quad_perm:[2,3,0,1] row_mask:0xf bank_mask:0xf bound_ctrl:1
	v_pk_add_f32 v[58:59], v[58:59], v[194:195]
	s_nop 1
	v_mov_b32_dpp v194, v58 row_half_mirror row_mask:0xf bank_mask:0xf bound_ctrl:1
	v_mov_b32_dpp v195, v59 row_half_mirror row_mask:0xf bank_mask:0xf bound_ctrl:1
	v_pk_add_f32 v[58:59], v[58:59], v[194:195]
	s_nop 1
	v_mov_b32_dpp v194, v58 row_mirror row_mask:0xf bank_mask:0xf bound_ctrl:1
	v_mov_b32_dpp v195, v59 row_mirror row_mask:0xf bank_mask:0xf bound_ctrl:1
	s_and_saveexec_b64 s[6:7], vcc
	v_pk_add_f32 v[58:59], v[58:59], v[194:195]
	ds_write_b64 v160, v[58:59] offset:392
	s_or_b64 exec, exec, s[6:7]
	ds_read2_b32 v[58:59], v102 offset1:32
	ds_read2_b32 v[194:195], v102 offset0:64 offset1:96
	v_add_f32_e32 v0, 0, v60
	v_mov_b32_e32 v202, v44
	v_mov_b32_e32 v203, v28
	v_mul_f32_e32 v197, 0.5, v0
	s_waitcnt lgkmcnt(1)
	v_mul_f32_e32 v201, 0x3fd744fd, v58
	v_pk_add_f32 v[202:203], v[202:203], 0 op_sel_hi:[1,0]
	v_mov_b32_e32 v196, v28
	v_mov_b32_e32 v200, v1
	v_mov_b32_e32 v58, v59
	s_waitcnt lgkmcnt(0)
	v_mov_b32_e32 v59, v194
	s_mov_b32 s2, s67
	v_pk_add_f32 v[196:197], v[196:197], v[200:201]
	v_pk_mul_f32 v[200:201], v[58:59], s[2:3] op_sel_hi:[1,0]
	v_pk_mul_f32 v[204:205], v[202:203], 0.5 op_sel_hi:[1,0]
	v_pk_fma_f32 v[58:59], v[202:203], 0.5, v[200:201] op_sel_hi:[1,0,1]
	v_mov_b32_e32 v204, v197
	v_mov_b32_e32 v206, v1
	v_mov_b32_e32 v207, v201
	v_add_f32_e32 v198, 0, v12
	v_mov_b32_e32 v199, v195
	v_pk_mul_f32 v[202:203], v[58:59], v[58:59]
	v_pk_add_f32 v[204:205], v[204:205], v[206:207]
	v_mul_f32_e32 v0, 0x3fd744fd, v195
	v_mov_b32_e32 v163, v197
	v_pk_mov_b32 v[200:201], v[200:201], v[202:203] op_sel:[1,0]
	v_pk_add_f32 v[202:203], v[58:59], v[204:205]
	v_pk_mul_f32 v[204:205], v[58:59], v[204:205]
	v_pk_fma_f32 v[194:195], v[198:199], s[66:67], v[0:1] op_sel_hi:[1,1,0]
	v_pk_fma_f32 v[200:201], v[196:197], v[162:163], v[200:201]
	v_mov_b32_e32 v203, v205
	v_pk_mul_f32 v[198:199], v[194:195], v[194:195]
	v_pk_add_f32 v[200:201], v[202:203], v[200:201]
	v_mov_b32_e32 v195, v198
	v_pk_add_f32 v[198:199], v[200:201], v[194:195]
	s_nop 1
	v_mov_b32_dpp v200, v198 quad_perm:[1,0,3,2] row_mask:0xf bank_mask:0xf bound_ctrl:1
	v_mov_b32_dpp v201, v199 quad_perm:[1,0,3,2] row_mask:0xf bank_mask:0xf bound_ctrl:1
	v_pk_add_f32 v[198:199], v[198:199], v[200:201]
	s_nop 1
	v_mov_b32_dpp v200, v198 quad_perm:[2,3,0,1] row_mask:0xf bank_mask:0xf bound_ctrl:1
	v_mov_b32_dpp v201, v199 quad_perm:[2,3,0,1] row_mask:0xf bank_mask:0xf bound_ctrl:1
	v_pk_add_f32 v[198:199], v[198:199], v[200:201]
	s_nop 1
	v_mov_b32_dpp v200, v198 row_half_mirror row_mask:0xf bank_mask:0xf bound_ctrl:1
	v_mov_b32_dpp v201, v199 row_half_mirror row_mask:0xf bank_mask:0xf bound_ctrl:1
	v_pk_add_f32 v[198:199], v[198:199], v[200:201]
	s_nop 1
	v_mov_b32_dpp v200, v198 row_mirror row_mask:0xf bank_mask:0xf bound_ctrl:1
	v_mov_b32_dpp v201, v199 row_mirror row_mask:0xf bank_mask:0xf bound_ctrl:1
	s_and_saveexec_b64 s[6:7], vcc
	v_pk_add_f32 v[198:199], v[198:199], v[200:201]
	ds_write_b64 v160, v[198:199] offset:400
	s_or_b64 exec, exec, s[6:7]
	ds_read2_b32 v[198:199], v104 offset1:32
	ds_read2_b32 v[200:201], v104 offset0:64 offset1:96
	v_add_f32_e32 v0, 0, v61
	v_add_f32_e32 v60, 0, v13
	v_mul_f32_e32 v13, 0.5, v0
	s_waitcnt lgkmcnt(1)
	v_mul_f32_e32 v203, 0x3fd744fd, v198
	v_mov_b32_e32 v28, v45
	v_mov_b32_e32 v12, v29
	v_mov_b32_e32 v202, v1
	v_pk_add_f32 v[204:205], v[28:29], 0 op_sel_hi:[1,0]
	v_pk_add_f32 v[44:45], v[12:13], v[202:203]
	v_mov_b32_e32 v12, v199
	s_waitcnt lgkmcnt(0)
;   DI void operator()(f32x16 (&acc)[2][4], int grow0, int gcol0, int lane, int w, char* lds) {
;     ...
;         for (int e = 0; e < 4; ++e) {
;           const int i = 4 * (2 * (ps & 1) + qq) + e;
;           const float* xr = (const float*)(xs + (8 * qq + 4 * hh + e) * 512) + l31;
;           float s1 = 0.f, s2 = 0.f;
; #pragma unroll
;           for (int nt = 0; nt < 4; ++nt) {
;             float v = (acc[mt][nt][i] + bia[nt]) * csc[nt];
;             float z = ALPHA * xr[nt * 32] + hs * v;
;             acc[mt][nt][i] = z; s1 += z; s2 += z * z;
;           }
;           s1 = row16_sum(s1); s2 = row16_sum(s2);
;           if ((lane & 15) == 0) { f32x2 sv = {s1, s2}; *(f32x2*)(redw + (mt * 32 + (i & 3) + 8 * (i >> 2)) * 2) = sv; }
	v_mov_b32_e32 v13, v200
	s_mov_b32 s2, s67
	v_pk_mul_f32 v[28:29], v[12:13], s[2:3] op_sel_hi:[1,0]
	v_pk_mul_f32 v[198:199], v[204:205], 0.5 op_sel_hi:[1,0]
	v_pk_fma_f32 v[12:13], v[204:205], 0.5, v[28:29] op_sel_hi:[1,0,1]
	v_mov_b32_e32 v198, v45
	v_mov_b32_e32 v204, v1
	v_mov_b32_e32 v205, v29
	v_pk_mul_f32 v[202:203], v[12:13], v[12:13]
	v_pk_add_f32 v[198:199], v[198:199], v[204:205]
	v_mov_b32_e32 v163, v45
	v_pk_mov_b32 v[28:29], v[28:29], v[202:203] op_sel:[1,0]
	v_pk_add_f32 v[202:203], v[12:13], v[198:199]
	v_pk_mul_f32 v[198:199], v[12:13], v[198:199]
	v_mov_b32_e32 v61, v201
	v_pk_fma_f32 v[28:29], v[44:45], v[162:163], v[28:29]
	v_mov_b32_e32 v203, v199
	v_mul_f32_e32 v0, 0x3fd744fd, v201
	v_pk_add_f32 v[198:199], v[202:203], v[28:29]
	v_pk_fma_f32 v[28:29], v[60:61], s[66:67], v[0:1] op_sel_hi:[1,1,0]
	s_nop 0
	v_pk_mul_f32 v[60:61], v[28:29], v[28:29]
	s_nop 0
	v_mov_b32_e32 v29, v60
	v_pk_add_f32 v[60:61], v[198:199], v[28:29]
	s_nop 1
	v_mov_b32_dpp v198, v60 quad_perm:[1,0,3,2] row_mask:0xf bank_mask:0xf bound_ctrl:1
	v_mov_b32_dpp v199, v61 quad_perm:[1,0,3,2] row_mask:0xf bank_mask:0xf bound_ctrl:1
	v_pk_add_f32 v[60:61], v[60:61], v[198:199]
	s_nop 1
	v_mov_b32_dpp v198, v60 quad_perm:[2,3,0,1] row_mask:0xf bank_mask:0xf bound_ctrl:1
	v_mov_b32_dpp v199, v61 quad_perm:[2,3,0,1] row_mask:0xf bank_mask:0xf bound_ctrl:1
	v_pk_add_f32 v[60:61], v[60:61], v[198:199]
	s_nop 1
	v_mov_b32_dpp v198, v60 row_half_mirror row_mask:0xf bank_mask:0xf bound_ctrl:1
	v_mov_b32_dpp v199, v61 row_half_mirror row_mask:0xf bank_mask:0xf bound_ctrl:1
	v_pk_add_f32 v[60:61], v[60:61], v[198:199]
	s_nop 1
	v_mov_b32_dpp v198, v60 row_mirror row_mask:0xf bank_mask:0xf bound_ctrl:1
	v_mov_b32_dpp v199, v61 row_mirror row_mask:0xf bank_mask:0xf bound_ctrl:1
	s_and_saveexec_b64 s[6:7], vcc
	v_pk_add_f32 v[60:61], v[60:61], v[198:199]
	ds_write_b64 v160, v[60:61] offset:408
	s_or_b64 exec, exec, s[6:7]
	ds_read2_b32 v[60:61], v93 offset1:32
	ds_read2_b32 v[198:199], v93 offset0:64 offset1:96
	v_add_f32_e32 v0, 0, v62
	v_mov_b32_e32 v206, v46
	v_mov_b32_e32 v207, v30
	v_mul_f32_e32 v201, 0.5, v0
	s_waitcnt lgkmcnt(1)
	v_mul_f32_e32 v205, 0x3fd744fd, v60
	v_pk_add_f32 v[206:207], v[206:207], 0 op_sel_hi:[1,0]
	v_mov_b32_e32 v200, v30
	v_mov_b32_e32 v204, v1
	v_mov_b32_e32 v60, v61
	s_waitcnt lgkmcnt(0)
	v_mov_b32_e32 v61, v198
	s_mov_b32 s2, s67
	v_pk_add_f32 v[200:201], v[200:201], v[204:205]
	v_pk_mul_f32 v[204:205], v[60:61], s[2:3] op_sel_hi:[1,0]
	v_pk_mul_f32 v[208:209], v[206:207], 0.5 op_sel_hi:[1,0]
	v_pk_fma_f32 v[60:61], v[206:207], 0.5, v[204:205] op_sel_hi:[1,0,1]
	v_mov_b32_e32 v208, v201
	v_mov_b32_e32 v212, v1
	v_mov_b32_e32 v213, v205
	v_add_f32_e32 v202, 0, v14
	v_mov_b32_e32 v203, v199
	v_pk_mul_f32 v[206:207], v[60:61], v[60:61]
	v_pk_add_f32 v[208:209], v[208:209], v[212:213]
	v_mul_f32_e32 v0, 0x3fd744fd, v199
	v_mov_b32_e32 v163, v201
	v_pk_mov_b32 v[204:205], v[204:205], v[206:207] op_sel:[1,0]
	v_pk_add_f32 v[206:207], v[60:61], v[208:209]
	v_pk_mul_f32 v[208:209], v[60:61], v[208:209]
	v_pk_fma_f32 v[198:199], v[202:203], s[66:67], v[0:1] op_sel_hi:[1,1,0]
	v_pk_fma_f32 v[204:205], v[200:201], v[162:163], v[204:205]
	v_mov_b32_e32 v207, v209
	v_pk_mul_f32 v[202:203], v[198:199], v[198:199]
	v_pk_add_f32 v[204:205], v[206:207], v[204:205]
	v_mov_b32_e32 v199, v202
	v_pk_add_f32 v[202:203], v[204:205], v[198:199]
	s_nop 1
	v_mov_b32_dpp v204, v202 quad_perm:[1,0,3,2] row_mask:0xf bank_mask:0xf bound_ctrl:1
	v_mov_b32_dpp v205, v203 quad_perm:[1,0,3,2] row_mask:0xf bank_mask:0xf bound_ctrl:1
	v_pk_add_f32 v[202:203], v[202:203], v[204:205]
	s_nop 1
	v_mov_b32_dpp v204, v202 quad_perm:[2,3,0,1] row_mask:0xf bank_mask:0xf bound_ctrl:1
	v_mov_b32_dpp v205, v203 quad_perm:[2,3,0,1] row_mask:0xf bank_mask:0xf bound_ctrl:1
	v_pk_add_f32 v[202:203], v[202:203], v[204:205]
	s_nop 1
	v_mov_b32_dpp v204, v202 row_half_mirror row_mask:0xf bank_mask:0xf bound_ctrl:1
	v_mov_b32_dpp v205, v203 row_half_mirror row_mask:0xf bank_mask:0xf bound_ctrl:1
	v_pk_add_f32 v[202:203], v[202:203], v[204:205]
	s_nop 1
	v_mov_b32_dpp v204, v202 row_mirror row_mask:0xf bank_mask:0xf bound_ctrl:1
	v_mov_b32_dpp v205, v203 row_mirror row_mask:0xf bank_mask:0xf bound_ctrl:1
	s_and_saveexec_b64 s[6:7], vcc
	v_pk_add_f32 v[202:203], v[202:203], v[204:205]
	ds_write_b64 v160, v[202:203] offset:448
	s_or_b64 exec, exec, s[6:7]
	ds_read2_b32 v[202:203], v106 offset1:32
	ds_read2_b32 v[204:205], v106 offset0:64 offset1:96
	v_add_f32_e32 v0, 0, v63
	v_add_f32_e32 v62, 0, v15
	v_mul_f32_e32 v15, 0.5, v0
	s_waitcnt lgkmcnt(1)
	v_mul_f32_e32 v207, 0x3fd744fd, v202
	v_mov_b32_e32 v30, v47
	v_mov_b32_e32 v14, v31
	v_mov_b32_e32 v206, v1
	v_pk_add_f32 v[208:209], v[30:31], 0 op_sel_hi:[1,0]
	v_pk_add_f32 v[46:47], v[14:15], v[206:207]
	v_mov_b32_e32 v14, v203
	s_waitcnt lgkmcnt(0)
;   DI void operator()(f32x16 (&acc)[2][4], int grow0, int gcol0, int lane, int w, char* lds) {
;     ...
;         for (int e = 0; e < 4; ++e) {
;           const int i = 4 * (2 * (ps & 1) + qq) + e;
;           const float* xr = (const float*)(xs + (8 * qq + 4 * hh + e) * 512) + l31;
;           float s1 = 0.f, s2 = 0.f;
; #pragma unroll
;           for (int nt = 0; nt < 4; ++nt) {
;             float v = (acc[mt][nt][i] + bia[nt]) * csc[nt];
;             float z = ALPHA * xr[nt * 32] + hs * v;
;             acc[mt][nt][i] = z; s1 += z; s2 += z * z;
;           }
;           s1 = row16_sum(s1); s2 = row16_sum(s2);
;           if ((lane & 15) == 0) { f32x2 sv = {s1, s2}; *(f32x2*)(redw + (mt * 32 + (i & 3) + 8 * (i >> 2)) * 2) = sv; }
;         }
;     }
;     __syncthreads();
;     u64_t* myslots = xstat + ((size_t)pm * 256) * 4;
	v_mov_b32_e32 v15, v204
	s_mov_b32 s2, s67
	v_pk_mul_f32 v[30:31], v[14:15], s[2:3] op_sel_hi:[1,0]
	v_pk_mul_f32 v[202:203], v[208:209], 0.5 op_sel_hi:[1,0]
	v_pk_fma_f32 v[14:15], v[208:209], 0.5, v[30:31] op_sel_hi:[1,0,1]
	v_mov_b32_e32 v202, v47
	v_mov_b32_e32 v208, v1
	v_mov_b32_e32 v209, v31
	v_pk_mul_f32 v[206:207], v[14:15], v[14:15]
	v_pk_add_f32 v[202:203], v[202:203], v[208:209]
	v_mov_b32_e32 v163, v47
	v_pk_mov_b32 v[30:31], v[30:31], v[206:207] op_sel:[1,0]
	v_pk_add_f32 v[206:207], v[14:15], v[202:203]
	v_pk_mul_f32 v[202:203], v[14:15], v[202:203]
	v_mov_b32_e32 v63, v205
	v_pk_fma_f32 v[30:31], v[46:47], v[162:163], v[30:31]
	v_mov_b32_e32 v207, v203
	v_mul_f32_e32 v0, 0x3fd744fd, v205
	v_pk_add_f32 v[202:203], v[206:207], v[30:31]
	v_pk_fma_f32 v[30:31], v[62:63], s[66:67], v[0:1] op_sel_hi:[1,1,0]
	s_nop 0
	v_pk_mul_f32 v[62:63], v[30:31], v[30:31]
	s_nop 0
	v_mov_b32_e32 v31, v62
	v_pk_add_f32 v[62:63], v[202:203], v[30:31]
	s_nop 1
	v_mov_b32_dpp v202, v62 quad_perm:[1,0,3,2] row_mask:0xf bank_mask:0xf bound_ctrl:1
	v_mov_b32_dpp v203, v63 quad_perm:[1,0,3,2] row_mask:0xf bank_mask:0xf bound_ctrl:1
	v_pk_add_f32 v[62:63], v[62:63], v[202:203]
	s_nop 1
	v_mov_b32_dpp v202, v62 quad_perm:[2,3,0,1] row_mask:0xf bank_mask:0xf bound_ctrl:1
	v_mov_b32_dpp v203, v63 quad_perm:[2,3,0,1] row_mask:0xf bank_mask:0xf bound_ctrl:1
	v_pk_add_f32 v[62:63], v[62:63], v[202:203]
	s_nop 1
	v_mov_b32_dpp v202, v62 row_half_mirror row_mask:0xf bank_mask:0xf bound_ctrl:1
	v_mov_b32_dpp v203, v63 row_half_mirror row_mask:0xf bank_mask:0xf bound_ctrl:1
	v_pk_add_f32 v[62:63], v[62:63], v[202:203]
	s_nop 1
	v_mov_b32_dpp v202, v62 row_mirror row_mask:0xf bank_mask:0xf bound_ctrl:1
	v_mov_b32_dpp v203, v63 row_mirror row_mask:0xf bank_mask:0xf bound_ctrl:1
	s_and_saveexec_b64 s[6:7], vcc
	v_pk_add_f32 v[62:63], v[62:63], v[202:203]
	ds_write_b64 v160, v[62:63] offset:456
	s_or_b64 exec, exec, s[6:7]
	ds_read2_b32 v[62:63], v95 offset1:32
	ds_read2_b32 v[202:203], v95 offset0:64 offset1:96
	v_add_f32_e32 v0, 0, v64
	v_mov_b32_e32 v212, v48
	v_mov_b32_e32 v213, v32
	v_mul_f32_e32 v205, 0.5, v0
	s_waitcnt lgkmcnt(1)
	v_mul_f32_e32 v209, 0x3fd744fd, v62
	v_pk_add_f32 v[212:213], v[212:213], 0 op_sel_hi:[1,0]
	v_mov_b32_e32 v204, v32
	v_mov_b32_e32 v208, v1
	v_mov_b32_e32 v62, v63
	s_waitcnt lgkmcnt(0)
	v_mov_b32_e32 v63, v202
	s_mov_b32 s2, s67
	v_pk_add_f32 v[204:205], v[204:205], v[208:209]
	v_pk_mul_f32 v[208:209], v[62:63], s[2:3] op_sel_hi:[1,0]
	v_pk_mul_f32 v[214:215], v[212:213], 0.5 op_sel_hi:[1,0]
	v_pk_fma_f32 v[62:63], v[212:213], 0.5, v[208:209] op_sel_hi:[1,0,1]
	v_mov_b32_e32 v214, v205
	v_mov_b32_e32 v226, v1
	v_mov_b32_e32 v227, v209
	v_add_f32_e32 v206, 0, v16
	v_mov_b32_e32 v207, v203
	v_pk_mul_f32 v[212:213], v[62:63], v[62:63]
	v_pk_add_f32 v[214:215], v[214:215], v[226:227]
	v_mul_f32_e32 v0, 0x3fd744fd, v203
	v_mov_b32_e32 v163, v205
	v_pk_mov_b32 v[208:209], v[208:209], v[212:213] op_sel:[1,0]
	v_pk_add_f32 v[212:213], v[62:63], v[214:215]
	v_pk_mul_f32 v[214:215], v[62:63], v[214:215]
	v_pk_fma_f32 v[202:203], v[206:207], s[66:67], v[0:1] op_sel_hi:[1,1,0]
	v_pk_fma_f32 v[208:209], v[204:205], v[162:163], v[208:209]
	v_mov_b32_e32 v213, v215
	v_pk_mul_f32 v[206:207], v[202:203], v[202:203]
	v_pk_add_f32 v[208:209], v[212:213], v[208:209]
	v_mov_b32_e32 v203, v206
	v_pk_add_f32 v[206:207], v[208:209], v[202:203]
	s_nop 1
	v_mov_b32_dpp v208, v206 quad_perm:[1,0,3,2] row_mask:0xf bank_mask:0xf bound_ctrl:1
	v_mov_b32_dpp v209, v207 quad_perm:[1,0,3,2] row_mask:0xf bank_mask:0xf bound_ctrl:1
	v_pk_add_f32 v[206:207], v[206:207], v[208:209]
	s_nop 1
	v_mov_b32_dpp v208, v206 quad_perm:[2,3,0,1] row_mask:0xf bank_mask:0xf bound_ctrl:1
	v_mov_b32_dpp v209, v207 quad_perm:[2,3,0,1] row_mask:0xf bank_mask:0xf bound_ctrl:1
	v_pk_add_f32 v[206:207], v[206:207], v[208:209]
	s_nop 1
	v_mov_b32_dpp v208, v206 row_half_mirror row_mask:0xf bank_mask:0xf bound_ctrl:1
	v_mov_b32_dpp v209, v207 row_half_mirror row_mask:0xf bank_mask:0xf bound_ctrl:1
	v_pk_add_f32 v[206:207], v[206:207], v[208:209]
	s_nop 1
	v_mov_b32_dpp v208, v206 row_mirror row_mask:0xf bank_mask:0xf bound_ctrl:1
	v_mov_b32_dpp v209, v207 row_mirror row_mask:0xf bank_mask:0xf bound_ctrl:1
	s_and_saveexec_b64 s[6:7], vcc
	v_pk_add_f32 v[206:207], v[206:207], v[208:209]
	ds_write_b64 v160, v[206:207] offset:464
	s_or_b64 exec, exec, s[6:7]
	v_add_f32_e32 v0, 0, v65
	ds_read2_b32 v[64:65], v91 offset1:32
	ds_read2_b32 v[212:213], v91 offset0:64 offset1:96
	v_mov_b32_e32 v32, v49
	v_mul_f32_e32 v209, 0.5, v0
	v_add_f32_e32 v214, 0, v17
	s_waitcnt lgkmcnt(1)
	v_mul_f32_e32 v207, 0x3fd744fd, v64
	v_pk_add_f32 v[16:17], v[32:33], 0 op_sel_hi:[1,0]
	v_mov_b32_e32 v208, v33
	v_mov_b32_e32 v206, v1
	v_mov_b32_e32 v32, v65
	s_waitcnt lgkmcnt(0)
	v_mov_b32_e32 v33, v212
	s_mov_b32 s2, s67
	v_pk_add_f32 v[48:49], v[208:209], v[206:207]
	v_pk_mul_f32 v[32:33], v[32:33], s[2:3] op_sel_hi:[1,0]
	v_pk_mul_f32 v[64:65], v[16:17], 0.5 op_sel_hi:[1,0]
	v_pk_fma_f32 v[16:17], v[16:17], 0.5, v[32:33] op_sel_hi:[1,0,1]
	v_mov_b32_e32 v64, v49
	v_mov_b32_e32 v208, v1
	v_mov_b32_e32 v209, v33
	v_pk_mul_f32 v[206:207], v[16:17], v[16:17]
	v_pk_add_f32 v[64:65], v[64:65], v[208:209]
	v_mov_b32_e32 v163, v49
	v_pk_mov_b32 v[32:33], v[32:33], v[206:207] op_sel:[1,0]
	v_pk_add_f32 v[206:207], v[16:17], v[64:65]
	v_pk_mul_f32 v[64:65], v[16:17], v[64:65]
	v_mov_b32_e32 v215, v213
	v_pk_fma_f32 v[32:33], v[48:49], v[162:163], v[32:33]
	v_mov_b32_e32 v207, v65
	v_mul_f32_e32 v0, 0x3fd744fd, v213
	v_pk_add_f32 v[64:65], v[206:207], v[32:33]
	v_pk_fma_f32 v[32:33], v[214:215], s[66:67], v[0:1] op_sel_hi:[1,1,0]
	s_nop 0
	v_pk_mul_f32 v[206:207], v[32:33], v[32:33]
	s_nop 0
	v_mov_b32_e32 v33, v206
	v_pk_add_f32 v[64:65], v[64:65], v[32:33]
	s_nop 1
	v_mov_b32_dpp v206, v64 quad_perm:[1,0,3,2] row_mask:0xf bank_mask:0xf bound_ctrl:1
	v_mov_b32_dpp v207, v65 quad_perm:[1,0,3,2] row_mask:0xf bank_mask:0xf bound_ctrl:1
	v_pk_add_f32 v[64:65], v[64:65], v[206:207]
	s_nop 1
	v_mov_b32_dpp v206, v64 quad_perm:[2,3,0,1] row_mask:0xf bank_mask:0xf bound_ctrl:1
	v_mov_b32_dpp v207, v65 quad_perm:[2,3,0,1] row_mask:0xf bank_mask:0xf bound_ctrl:1
	v_pk_add_f32 v[64:65], v[64:65], v[206:207]
	s_nop 1
	v_mov_b32_dpp v206, v64 row_half_mirror row_mask:0xf bank_mask:0xf bound_ctrl:1
	v_mov_b32_dpp v207, v65 row_half_mirror row_mask:0xf bank_mask:0xf bound_ctrl:1
	v_pk_add_f32 v[64:65], v[64:65], v[206:207]
	s_nop 1
	v_mov_b32_dpp v206, v64 row_mirror row_mask:0xf bank_mask:0xf bound_ctrl:1
	v_mov_b32_dpp v207, v65 row_mirror row_mask:0xf bank_mask:0xf bound_ctrl:1
	s_and_saveexec_b64 s[6:7], vcc
	v_pk_add_f32 v[64:65], v[64:65], v[206:207]
	ds_write_b64 v160, v[64:65] offset:472
	s_or_b64 exec, exec, s[6:7]
	v_ashrrev_i32_e32 v206, 8, v164
	v_ashrrev_i32_e32 v207, 31, v206
	v_lshlrev_b64 v[64:65], 13, v[206:207]
	v_lshl_add_u64 v[64:65], s[8:9], 0, v[64:65]
	v_cmp_gt_i32_e64 s[40:41], s60, v210
	v_ashrrev_i32_e32 v169, 31, v168
	s_waitcnt lgkmcnt(0)
	s_barrier
; DI void ag_st64(u64_t* p, u64_t v) { __hip_atomic_store(p, v, __ATOMIC_RELAXED, __HIP_MEMORY_SCOPE_AGENT); }
;   DI void operator()(f32x16 (&acc)[2][4], int grow0, int gcol0, int lane, int w, char* lds) {
;     ...
;     if (tid < 256) {
;       float s1 = (red[tid * 2] + red[(256 + tid) * 2]) + (red[(512 + tid) * 2] + red[(768 + tid) * 2]);
;       float s2 = (red[tid * 2 + 1] + red[(256 + tid) * 2 + 1]) + (red[(512 + tid) * 2 + 1] + red[(768 + tid) * 2 + 1]);
;       ag_st64(myslots + tid * 4 + pn, ((u64_t)__float_as_uint(s2) << 32) | (u64_t)__float_as_uint(s1));
	s_and_saveexec_b64 s[6:7], s[40:41]
	s_cbranch_execz .LBB0_359
	v_lshl_add_u32 v0, v210, 3, v221
	ds_read2st64_b64 v[212:215], v0 offset1:4
	ds_read2st64_b64 v[226:229], v0 offset0:8 offset1:12
	v_ashrrev_i32_e32 v208, 8, v154
	v_ashrrev_i32_e32 v209, 31, v208
	s_waitcnt lgkmcnt(1)
	v_mov_b32_e32 v230, v212
	s_waitcnt lgkmcnt(0)
	v_mov_b32_e32 v231, v226
	v_mov_b32_e32 v232, v214
	v_mov_b32_e32 v233, v228
	v_mov_b32_e32 v226, v213
	v_mov_b32_e32 v228, v215
	v_pk_add_f32 v[230:231], v[230:231], v[232:233]
	v_pk_add_f32 v[212:213], v[226:227], v[228:229]
	v_pk_add_f32 v[230:231], v[230:231], v[230:231] op_sel:[0,1] op_sel_hi:[1,0]
	v_pk_add_f32 v[212:213], v[212:213], v[212:213] op_sel:[0,1] op_sel_hi:[1,0]
	v_lshl_add_u64 v[214:215], v[168:169], 3, v[64:65]
	v_lshl_add_u64 v[208:209], v[208:209], 3, v[214:215]
	v_mov_b32_e32 v231, v212
	global_store_dwordx2 v[208:209], v[230:231], off sc1

; DI f32x16 zero16() { f32x16 z; for (int i = 0; i < 16; ++i) z[i] = 0.f; return z; }
; DI int launder(int x) { asm volatile("" : "+v"(x)); return x; }
; template <int BK> DI int swz(int row) { constexpr int CPR = BK / 8; return (row / (16 / CPR)) % CPR; }
; DI void wait_vm0() { asm volatile("s_waitcnt vmcnt(0)" ::: "memory"); }
;   DI void pre(int grow0, int gcol0, int lane, int w, char* lds) { xpass(0, grow0, gcol0, lane, w, lds); }
;     ...
;   const int tid = launder(threadIdx.x), lane = tid & 63, w = tid >> 6, wm = w % WM, wn = w / WM;
;   const int l31 = lane & 31, hh = lane >> 5;
;   f32x16 acc[2][NTW];
; #pragma unroll
;   for (int a = 0; a < 2; ++a)
; #pragma unroll
;     for (int b = 0; b < NTW; ++b) acc[a][b] = zero16();
;   const bf16_t* Ag = A + (size_t)row0 * lda; const bf16_t* Bg = Bt + (size_t)col0 * ldb;
;   const int wv = __builtin_amdgcn_readfirstlane(tid >> 6);
;   __syncthreads();
;   if (!pre) { stage_tile<BM, BK>(Ag, lda, lds, tid); stage_tile<BN, BK>(Bg, ldb, lds + ABYTES, tid); }
;   wait_vm0();
;   __syncthreads();
;   const int nk = K / BK;
;   for (int kt = 0; kt < nk; ++kt) {
;     char* cur = lds + (kt & 1) * STG; char* nxt = lds + ((kt + 1) & 1) * STG;
;     const bool more = kt + 1 < nk;
;     const bf16_t* An = Ag + (kt + 1) * BK; const bf16_t* Bn = Bg + (kt + 1) * BK;
;     if (!more) epi.pre(row0 + wm * 64, col0 + wn * (32 * NTW), lane, w, lds);
;     bf16x8 fa[2][2], fb[2][NTW];
; #pragma unroll
;     for (int mt = 0; mt < 2; ++mt) { int row = wm * 64 + mt * 32 + l31; fa[0][mt] = *(const bf16x8*)(cur + row * (BK * 2) + ((hh ^ swz<BK>(row)) << 4)); }
; #pragma unroll
;     for (int nt = 0; nt < NTW; ++nt) { int row = wn * (32 * NTW) + nt * 32 + l31; fb[0][nt] = *(const bf16x8*)(cur + ABYTES + row * (BK * 2) + ((hh ^ swz<BK>(row)) << 4)); }
.LBB0_381:
	v_lshrrev_b32_e32 v4, 30, v3
	v_add_u32_e32 v4, v3, v4
	v_ashrrev_i32_e32 v4, 2, v4
	v_mul_i32_i24_e32 v5, 4, v4
	v_sub_u32_e32 v3, v3, v5
	v_and_b32_e32 v5, 31, v2
	v_lshlrev_b32_e32 v7, 6, v3
	v_or_b32_e32 v7, v7, v5
	v_bfe_u32 v3, v3, 25, 1
	v_lshlrev_b32_e32 v140, 7, v7
	v_add_u32_e32 v8, v7, v3
	v_or_b32_e32 v7, 32, v7
	v_add_u32_e32 v3, v7, v3
	v_lshlrev_b32_e32 v142, 7, v7
	v_ashrrev_i32_e32 v7, 1, v3
	v_ashrrev_i32_e32 v3, 31, v3
	v_ashrrev_i32_e32 v9, 1, v8
	v_ashrrev_i32_e32 v8, 31, v8
	v_lshrrev_b32_e32 v3, 29, v3
	v_lshrrev_b32_e32 v8, 29, v8
	v_add_u32_e32 v3, v7, v3
	v_add_u32_e32 v8, v9, v8
	v_and_b32_e32 v3, -8, v3
	v_lshrrev_b32_e32 v6, 5, v2
	v_and_b32_e32 v8, -8, v8
	v_sub_u32_e32 v3, v7, v3
	v_lshl_or_b32 v5, v4, 7, v5
	v_sub_u32_e32 v8, v9, v8
	v_bitop3_b32 v7, v3, v6, 1 bitop3:0x78
	v_lshrrev_b32_e32 v4, 31, v4
	v_bitop3_b32 v9, v8, v6, 1 bitop3:0x78
	v_lshlrev_b32_e32 v144, 4, v7
	v_add_u32_e32 v7, v5, v4
	v_lshlrev_b32_e32 v141, 4, v9
	v_ashrrev_i32_e32 v9, 1, v7
	v_ashrrev_i32_e32 v7, 31, v7
	v_lshrrev_b32_e32 v7, 29, v7
	v_add_u32_e32 v7, v9, v7
	v_and_b32_e32 v7, -8, v7
	v_sub_u32_e32 v7, v9, v7
	v_bitop3_b32 v9, v7, v6, 1 bitop3:0x78
	v_lshlrev_b32_e32 v151, 4, v9
	v_or_b32_e32 v9, 32, v5
	v_lshlrev_b32_e32 v152, 7, v9
	v_add_u32_e32 v9, v9, v4
	v_ashrrev_i32_e32 v10, 1, v9
	v_ashrrev_i32_e32 v9, 31, v9
	v_lshrrev_b32_e32 v9, 29, v9
	v_add_u32_e32 v9, v10, v9
	v_and_b32_e32 v9, -8, v9
	v_sub_u32_e32 v9, v10, v9
	v_bitop3_b32 v10, v9, v6, 1 bitop3:0x78
	v_lshlrev_b32_e32 v143, 7, v5
	v_lshlrev_b32_e32 v154, 4, v10
	v_or_b32_e32 v10, 64, v5
	v_or_b32_e32 v5, 0x60, v5
	v_lshlrev_b32_e32 v153, 7, v10
	v_add_u32_e32 v10, v10, v4
	v_add_u32_e32 v4, v5, v4
	v_lshlrev_b32_e32 v156, 7, v5
	v_ashrrev_i32_e32 v5, 1, v4
	v_ashrrev_i32_e32 v4, 31, v4
	v_lshrrev_b32_e32 v4, 29, v4
	v_add_u32_e32 v4, v5, v4
	v_and_b32_e32 v4, -8, v4
	v_sub_u32_e32 v4, v5, v4
	v_bfe_u32 v2, v2, 5, 1
	v_ashrrev_i32_e32 v11, 1, v10
	v_ashrrev_i32_e32 v10, 31, v10
	v_bitop3_b32 v5, v4, v6, 1 bitop3:0x78
	v_lshrrev_b32_e32 v10, 29, v10
	v_lshlrev_b32_e32 v164, 4, v5
	v_bitop3_b32 v5, v8, v2, 2 bitop3:0x1e
	v_add_u32_e32 v10, v11, v10
	v_lshlrev_b32_e32 v161, 4, v5
	v_bitop3_b32 v5, v3, v2, 2 bitop3:0x1e
	v_and_b32_e32 v10, -8, v10
	v_lshlrev_b32_e32 v163, 4, v5
	v_bitop3_b32 v5, v7, v2, 2 bitop3:0x1e
	v_sub_u32_e32 v10, v11, v10
	v_lshlrev_b32_e32 v159, 4, v5
	v_bitop3_b32 v5, v9, v2, 2 bitop3:0x1e
	s_lshr_b32 s7, s36, 3
	v_lshlrev_b32_e32 v160, 4, v5
	v_bitop3_b32 v5, v10, v2, 2 bitop3:0x1e
	s_and_b32 s7, s7, 7
	s_lshl_b32 s30, s35, 19
	v_lshlrev_b32_e32 v157, 4, v5
	v_bitop3_b32 v5, v4, v2, 2 bitop3:0x1e
	s_lshl_b32 s7, s7, 19
	s_and_b32 s30, s30, 0x1c00000
	v_lshlrev_b32_e32 v158, 4, v5
	v_bitop3_b32 v5, v8, v2, 4 bitop3:0x1e
	s_or_b32 s7, s30, s7
	s_and_b32 s30, s34, 0xffffff00
	v_lshlrev_b32_e32 v149, 4, v5
	v_bitop3_b32 v5, v3, v2, 4 bitop3:0x1e
	s_ashr_i32 s31, s30, 31
	v_lshlrev_b32_e32 v150, 4, v5
	v_bitop3_b32 v5, v7, v2, 4 bitop3:0x1e
	s_lshl_b64 s[30:31], s[30:31], 11
	s_lshl_b32 s3, s3, 10
	v_lshlrev_b32_e32 v147, 4, v5
	v_bitop3_b32 v5, v9, v2, 4 bitop3:0x1e
	v_bitop3_b32 v3, v3, v2, 6 bitop3:0x1e
	v_lshlrev_b32_e32 v148, 4, v5
	v_bitop3_b32 v5, v10, v2, 4 bitop3:0x1e
	v_lshlrev_b32_e32 v139, 4, v3
	v_bitop3_b32 v3, v7, v2, 6 bitop3:0x1e
	s_add_u32 s42, s12, s7
	v_lshlrev_b32_e32 v145, 4, v5
	v_bitop3_b32 v5, v4, v2, 4 bitop3:0x1e
	v_lshlrev_b32_e32 v136, 4, v3
	v_bitop3_b32 v3, v9, v2, 6 bitop3:0x1e
	s_addc_u32 s43, s13, 0
	s_waitcnt vmcnt(0)
	v_lshlrev_b32_e32 v146, 4, v5
	v_bitop3_b32 v5, v8, v2, 6 bitop3:0x1e
	v_lshlrev_b32_e32 v137, 4, v3
	v_bitop3_b32 v3, v10, v2, 6 bitop3:0x1e
	v_bitop3_b32 v2, v4, v2, 6 bitop3:0x1e
	s_add_u32 s30, s40, s30
	v_bitop3_b32 v11, v10, v6, 1 bitop3:0x78
	v_lshlrev_b32_e32 v135, 4, v2
	s_addc_u32 s31, s41, s31
	v_mov_b32_e32 v2, 0
	v_lshlrev_b32_e32 v155, 4, v11
	v_lshlrev_b32_e32 v138, 4, v5
	v_lshlrev_b32_e32 v134, 4, v3
	v_lshl_add_u64 v[130:131], s[42:43], 0, v[0:1]
	v_lshl_add_u64 v[132:133], s[30:31], 0, v[0:1]
	s_mov_b64 s[30:31], 0
	s_mov_b32 s7, 0x10000
	v_mov_b32_e32 v3, v2
	v_mov_b32_e32 v4, v2
	v_mov_b32_e32 v5, v2
	v_mov_b32_e32 v6, v2
	v_mov_b32_e32 v7, v2
	v_mov_b32_e32 v8, v2
	v_mov_b32_e32 v9, v2
	v_mov_b32_e32 v10, v2
	v_mov_b32_e32 v11, v2
	v_mov_b32_e32 v12, v2
	v_mov_b32_e32 v13, v2
	v_mov_b32_e32 v14, v2
	v_mov_b32_e32 v15, v2
	v_mov_b32_e32 v16, v2
	v_mov_b32_e32 v17, v2
	v_mov_b32_e32 v18, v2
	v_mov_b32_e32 v19, v2
	v_mov_b32_e32 v20, v2
	v_mov_b32_e32 v21, v2
	v_mov_b32_e32 v22, v2
	v_mov_b32_e32 v23, v2
	v_mov_b32_e32 v24, v2
	v_mov_b32_e32 v25, v2
	v_mov_b32_e32 v26, v2
	v_mov_b32_e32 v27, v2
	v_mov_b32_e32 v28, v2
	v_mov_b32_e32 v29, v2
	v_mov_b32_e32 v30, v2
	v_mov_b32_e32 v31, v2
	v_mov_b32_e32 v32, v2
	v_mov_b32_e32 v33, v2
	v_mov_b32_e32 v34, v2
	v_mov_b32_e32 v35, v2
	v_mov_b32_e32 v36, v2
	v_mov_b32_e32 v37, v2
	v_mov_b32_e32 v38, v2
	v_mov_b32_e32 v39, v2
	v_mov_b32_e32 v40, v2
	v_mov_b32_e32 v41, v2
	v_mov_b32_e32 v42, v2
	v_mov_b32_e32 v43, v2
	v_mov_b32_e32 v44, v2
	v_mov_b32_e32 v45, v2
	v_mov_b32_e32 v46, v2
	v_mov_b32_e32 v47, v2
	v_mov_b32_e32 v48, v2
	v_mov_b32_e32 v49, v2
	v_mov_b32_e32 v50, v2
	v_mov_b32_e32 v51, v2
	v_mov_b32_e32 v52, v2
	v_mov_b32_e32 v53, v2
	v_mov_b32_e32 v54, v2
	v_mov_b32_e32 v55, v2
	v_mov_b32_e32 v56, v2
	v_mov_b32_e32 v57, v2
	v_mov_b32_e32 v58, v2
	v_mov_b32_e32 v59, v2
	v_mov_b32_e32 v60, v2
	v_mov_b32_e32 v61, v2
	v_mov_b32_e32 v62, v2
	v_mov_b32_e32 v63, v2
	v_mov_b32_e32 v64, v2
	v_mov_b32_e32 v65, v2
	v_mov_b32_e32 v66, v2
	v_mov_b32_e32 v67, v2
	v_mov_b32_e32 v68, v2
	v_mov_b32_e32 v69, v2
	v_mov_b32_e32 v70, v2
;     ...
;   f32x16 acc[2][NTW];
; #pragma unroll
;   for (int a = 0; a < 2; ++a)
; #pragma unroll
;     for (int b = 0; b < NTW; ++b) acc[a][b] = zero16();
;   const bf16_t* Ag = A + (size_t)row0 * lda; const bf16_t* Bg = Bt + (size_t)col0 * ldb;
;   const int wv = __builtin_amdgcn_readfirstlane(tid >> 6);
;   __syncthreads();
;   if (!pre) { stage_tile<BM, BK>(Ag, lda, lds, tid); stage_tile<BN, BK>(Bg, ldb, lds + ABYTES, tid); }
;   wait_vm0();
;   __syncthreads();
;   const int nk = K / BK;
;   for (int kt = 0; kt < nk; ++kt) {
;     char* cur = lds + (kt & 1) * STG; char* nxt = lds + ((kt + 1) & 1) * STG;
;     const bool more = kt + 1 < nk;
;     const bf16_t* An = Ag + (kt + 1) * BK; const bf16_t* Bn = Bg + (kt + 1) * BK;
;     if (!more) epi.pre(row0 + wm * 64, col0 + wn * (32 * NTW), lane, w, lds);
;     bf16x8 fa[2][2], fb[2][NTW];
; #pragma unroll
;     for (int mt = 0; mt < 2; ++mt) { int row = wm * 64 + mt * 32 + l31; fa[0][mt] = *(const bf16x8*)(cur + row * (BK * 2) + ((hh ^ swz<BK>(row)) << 4)); }
; #pragma unroll
;     for (int nt = 0; nt < NTW; ++nt) { int row = wn * (32 * NTW) + nt * 32 + l31; fb[0][nt] = *(const bf16x8*)(cur + ABYTES + row * (BK * 2) + ((hh ^ swz<BK>(row)) << 4)); }
; #pragma unroll
;     for (int kk = 0; kk < NKK; ++kk) {
;       if (kk + 1 < NKK) {
;         const int ch = (kk + 1) * 2 + hh;
; #pragma unroll
;         for (int mt = 0; mt < 2; ++mt) { int row = wm * 64 + mt * 32 + l31; fa[(kk + 1) & 1][mt] = *(const bf16x8*)(cur + row * (BK * 2) + ((ch ^ swz<BK>(row)) << 4)); }
; #pragma unroll
;         for (int nt = 0; nt < NTW; ++nt) { int row = wn * (32 * NTW) + nt * 32 + l31; fb[(kk + 1) & 1][nt] = *(const bf16x8*)(cur + ABYTES + row * (BK * 2) + ((ch ^ swz<BK>(row)) << 4)); }
;       }
;       if (more) {
; #pragma unroll
;         for (int q = 0; q < PPK; ++q) {
;           const int pi = kk * PPK + q;
;           if (pi < NPA) stage_piece<BM, BK>(An, lda, nxt, tid, pi, wv);
;           else if (pi < NP) stage_piece<BN, BK>(Bn, ldb, nxt + ABYTES, tid, pi - NPA, wv);
;         }
;       }
;       __builtin_amdgcn_s_setprio(1);
; #pragma unroll
;       for (int mt = 0; mt < 2; ++mt)
; #pragma unroll
;         for (int nt = 0; nt < NTW; ++nt) acc[mt][nt] = mfma(fa[kk & 1][mt], fb[kk & 1][nt], acc[mt][nt]);
;       __builtin_amdgcn_s_setprio(0);
;       __builtin_amdgcn_sched_barrier(0);
	v_mov_b32_e32 v71, v2
	v_mov_b32_e32 v72, v2
	v_mov_b32_e32 v73, v2
	v_mov_b32_e32 v74, v2
	v_mov_b32_e32 v75, v2
	v_mov_b32_e32 v76, v2
	v_mov_b32_e32 v77, v2
	v_mov_b32_e32 v78, v2
	v_mov_b32_e32 v79, v2
	v_mov_b32_e32 v80, v2
	v_mov_b32_e32 v81, v2
	v_mov_b32_e32 v82, v2
	v_mov_b32_e32 v83, v2
	v_mov_b32_e32 v84, v2
	v_mov_b32_e32 v85, v2
	v_mov_b32_e32 v86, v2
	v_mov_b32_e32 v87, v2
	v_mov_b32_e32 v88, v2
	v_mov_b32_e32 v89, v2
	v_mov_b32_e32 v90, v2
	v_mov_b32_e32 v91, v2
	v_mov_b32_e32 v92, v2
	v_mov_b32_e32 v93, v2
	v_mov_b32_e32 v94, v2
	v_mov_b32_e32 v95, v2
	v_mov_b32_e32 v96, v2
	v_mov_b32_e32 v97, v2
	v_mov_b32_e32 v98, v2
	v_mov_b32_e32 v99, v2
	v_mov_b32_e32 v100, v2
	v_mov_b32_e32 v101, v2
	v_mov_b32_e32 v102, v2
	v_mov_b32_e32 v103, v2
	v_mov_b32_e32 v104, v2
	v_mov_b32_e32 v105, v2
	v_mov_b32_e32 v106, v2
	v_mov_b32_e32 v107, v2
	v_mov_b32_e32 v108, v2
	v_mov_b32_e32 v109, v2
	v_mov_b32_e32 v110, v2
	v_mov_b32_e32 v111, v2
	v_mov_b32_e32 v112, v2
	v_mov_b32_e32 v113, v2
	v_mov_b32_e32 v114, v2
	v_mov_b32_e32 v115, v2
	v_mov_b32_e32 v116, v2
	v_mov_b32_e32 v117, v2
	v_mov_b32_e32 v118, v2
	v_mov_b32_e32 v119, v2
	v_mov_b32_e32 v120, v2
	v_mov_b32_e32 v121, v2
	v_mov_b32_e32 v122, v2
	v_mov_b32_e32 v123, v2
	v_mov_b32_e32 v124, v2
	v_mov_b32_e32 v125, v2
	v_mov_b32_e32 v126, v2
	v_mov_b32_e32 v127, v2
	v_mov_b32_e32 v128, v2
	v_mov_b32_e32 v129, v2
	s_waitcnt vmcnt(0) lgkmcnt(0)
	s_barrier
	v_add_u32_e32 v166, v140, v141
	v_add_u32_e32 v170, v142, v144
	ds_read_b128 v[166:169], v166
	v_add_u32_e32 v174, v143, v151
	ds_read_b128 v[170:173], v170
	v_add_u32_e32 v178, v152, v154
	ds_read_b128 v[174:177], v174 offset:32768
	v_add_u32_e32 v182, v153, v155
	ds_read_b128 v[178:181], v178 offset:32768
	v_add_u32_e32 v186, v156, v164
	ds_read_b128 v[182:185], v182 offset:32768
	ds_read_b128 v[186:189], v186 offset:32768
	s_and_b32 s42, s7, 0x10000
	s_add_i32 s37, s42, s3
	v_lshl_add_u64 v[214:215], v[130:131], 0, s[30:31]
	v_lshl_add_u64 v[226:227], v[132:133], 0, s[30:31]
	s_mov_b32 m0, s37
	v_lshl_add_u64 v[228:229], v[214:215], 0, s[28:29]
	global_load_lds_dwordx4 v[228:229], off
	s_add_i32 m0, s37, 0x2000
	v_lshl_add_u64 v[228:229], v[214:215], 0, s[24:25]
	global_load_lds_dwordx4 v[228:229], off
	s_add_i32 m0, s37, 0x4000
	v_lshl_add_u64 v[228:229], v[214:215], 0, s[26:27]
	global_load_lds_dwordx4 v[228:229], off
	s_add_i32 m0, s37, 0x6000
	v_lshl_add_u64 v[228:229], v[214:215], 0, s[38:39]
	global_load_lds_dwordx4 v[228:229], off
	s_add_i32 m0, s37, 0x8000
	v_lshl_add_u64 v[228:229], v[226:227], 0, s[28:29]
	global_load_lds_dwordx4 v[228:229], off
	s_add_i32 m0, s37, 0xa000
	v_lshl_add_u64 v[228:229], v[226:227], 0, s[24:25]
	global_load_lds_dwordx4 v[228:229], off
	s_add_i32 m0, s37, 0xc000
	v_lshl_add_u64 v[228:229], v[226:227], 0, s[26:27]
	global_load_lds_dwordx4 v[228:229], off
	s_add_i32 m0, s37, 0xe000
	v_lshl_add_u64 v[228:229], v[226:227], 0, s[38:39]
	global_load_lds_dwordx4 v[228:229], off
.LBB0_382:
	s_and_b32 s42, s7, 0x10000
	s_xor_b32 s100, s42, 0x10000
	v_add3_u32 v190, s100, v140, v161
	v_add3_u32 v194, s100, v142, v163
	ds_read_b128 v[190:193], v190
	v_add3_u32 v198, s100, v143, v159
	ds_read_b128 v[194:197], v194
	v_add3_u32 v202, s100, v152, v160
	ds_read_b128 v[198:201], v198 offset:32768
	v_add3_u32 v206, s100, v153, v157
	ds_read_b128 v[202:205], v202 offset:32768
	v_add3_u32 v210, s100, v156, v158
	ds_read_b128 v[206:209], v206 offset:32768
	ds_read_b128 v[210:213], v210 offset:32768
	s_waitcnt lgkmcnt(6)
	v_mfma_f32_32x32x16_bf16 v[114:129], v[166:169], v[174:177], v[114:129]
	v_mfma_f32_32x32x16_bf16 v[98:113], v[166:169], v[178:181], v[98:113]
	v_mfma_f32_32x32x16_bf16 v[82:97], v[166:169], v[182:185], v[82:97]
	v_mfma_f32_32x32x16_bf16 v[66:81], v[166:169], v[186:189], v[66:81]
	v_mfma_f32_32x32x16_bf16 v[50:65], v[170:173], v[174:177], v[50:65]
	v_mfma_f32_32x32x16_bf16 v[34:49], v[170:173], v[178:181], v[34:49]
	v_mfma_f32_32x32x16_bf16 v[18:33], v[170:173], v[182:185], v[18:33]
	v_mfma_f32_32x32x16_bf16 v[2:17], v[170:173], v[186:189], v[2:17]
	v_add3_u32 v166, s100, v140, v149
	v_add3_u32 v170, s100, v142, v150
	ds_read_b128 v[166:169], v166
	v_add3_u32 v174, s100, v143, v147
	ds_read_b128 v[170:173], v170
	v_add3_u32 v178, s100, v152, v148
	ds_read_b128 v[174:177], v174 offset:32768
	v_add3_u32 v182, s100, v153, v145
	ds_read_b128 v[178:181], v178 offset:32768
	v_add3_u32 v186, s100, v156, v146
	ds_read_b128 v[182:185], v182 offset:32768
	ds_read_b128 v[186:189], v186 offset:32768
	s_waitcnt lgkmcnt(6)
	v_mfma_f32_32x32x16_bf16 v[114:129], v[190:193], v[198:201], v[114:129]
	v_mfma_f32_32x32x16_bf16 v[98:113], v[190:193], v[202:205], v[98:113]
	v_mfma_f32_32x32x16_bf16 v[82:97], v[190:193], v[206:209], v[82:97]
	v_mfma_f32_32x32x16_bf16 v[66:81], v[190:193], v[210:213], v[66:81]
	v_mfma_f32_32x32x16_bf16 v[50:65], v[194:197], v[198:201], v[50:65]
	v_mfma_f32_32x32x16_bf16 v[34:49], v[194:197], v[202:205], v[34:49]
	v_mfma_f32_32x32x16_bf16 v[18:33], v[194:197], v[206:209], v[18:33]
	v_mfma_f32_32x32x16_bf16 v[2:17], v[194:197], v[210:213], v[2:17]
	v_add3_u32 v190, s100, v140, v138
	v_add3_u32 v194, s100, v142, v139
	ds_read_b128 v[190:193], v190
	v_add3_u32 v198, s100, v143, v136
	ds_read_b128 v[194:197], v194
	v_add3_u32 v202, s100, v152, v137
	ds_read_b128 v[198:201], v198 offset:32768
	v_add3_u32 v206, s100, v153, v134
	ds_read_b128 v[202:205], v202 offset:32768
	v_add3_u32 v210, s100, v156, v135
	ds_read_b128 v[206:209], v206 offset:32768
	ds_read_b128 v[210:213], v210 offset:32768
	s_waitcnt lgkmcnt(6)
	v_mfma_f32_32x32x16_bf16 v[114:129], v[166:169], v[174:177], v[114:129]
	v_mfma_f32_32x32x16_bf16 v[98:113], v[166:169], v[178:181], v[98:113]
	v_mfma_f32_32x32x16_bf16 v[82:97], v[166:169], v[182:185], v[82:97]
	v_mfma_f32_32x32x16_bf16 v[66:81], v[166:169], v[186:189], v[66:81]
	v_mfma_f32_32x32x16_bf16 v[50:65], v[170:173], v[174:177], v[50:65]
	v_mfma_f32_32x32x16_bf16 v[34:49], v[170:173], v[178:181], v[34:49]
	v_mfma_f32_32x32x16_bf16 v[18:33], v[170:173], v[182:185], v[18:33]
	v_mfma_f32_32x32x16_bf16 v[2:17], v[170:173], v[186:189], v[2:17]
	s_add_u32 s30, s30, 0x80
	s_addc_u32 s31, s31, 0
	s_add_i32 s7, s7, 0x10000
	s_waitcnt vmcnt(0) lgkmcnt(0)
	s_barrier
; DI f32x16 mfma(bf16x8 a, bf16x8 b, f32x16 c) { return __builtin_amdgcn_mfma_f32_32x32x16_bf16(a, b, c, 0, 0, 0); }
; template <int BK> DI int swz(int row) { constexpr int CPR = BK / 8; return (row / (16 / CPR)) % CPR; }
; DI void wait_vm0() { asm volatile("s_waitcnt vmcnt(0)" ::: "memory"); }
;   DI void pre(int grow0, int gcol0, int lane, int w, char* lds) { xpass(0, grow0, gcol0, lane, w, lds); }
;     ...
;   for (int kt = 0; kt < nk; ++kt) {
;     char* cur = lds + (kt & 1) * STG; char* nxt = lds + ((kt + 1) & 1) * STG;
;     const bool more = kt + 1 < nk;
;     const bf16_t* An = Ag + (kt + 1) * BK; const bf16_t* Bn = Bg + (kt + 1) * BK;
;     if (!more) epi.pre(row0 + wm * 64, col0 + wn * (32 * NTW), lane, w, lds);
;     bf16x8 fa[2][2], fb[2][NTW];
; #pragma unroll
;     for (int mt = 0; mt < 2; ++mt) { int row = wm * 64 + mt * 32 + l31; fa[0][mt] = *(const bf16x8*)(cur + row * (BK * 2) + ((hh ^ swz<BK>(row)) << 4)); }
; #pragma unroll
;     for (int nt = 0; nt < NTW; ++nt) { int row = wn * (32 * NTW) + nt * 32 + l31; fb[0][nt] = *(const bf16x8*)(cur + ABYTES + row * (BK * 2) + ((hh ^ swz<BK>(row)) << 4)); }
; #pragma unroll
;     for (int kk = 0; kk < NKK; ++kk) {
;       if (kk + 1 < NKK) {
;         const int ch = (kk + 1) * 2 + hh;
; #pragma unroll
;         for (int mt = 0; mt < 2; ++mt) { int row = wm * 64 + mt * 32 + l31; fa[(kk + 1) & 1][mt] = *(const bf16x8*)(cur + row * (BK * 2) + ((ch ^ swz<BK>(row)) << 4)); }
; #pragma unroll
;         for (int nt = 0; nt < NTW; ++nt) { int row = wn * (32 * NTW) + nt * 32 + l31; fb[(kk + 1) & 1][nt] = *(const bf16x8*)(cur + ABYTES + row * (BK * 2) + ((ch ^ swz<BK>(row)) << 4)); }
;       }
;       if (more) {
; #pragma unroll
;         for (int q = 0; q < PPK; ++q) {
;           const int pi = kk * PPK + q;
;           if (pi < NPA) stage_piece<BM, BK>(An, lda, nxt, tid, pi, wv);
;           else if (pi < NP) stage_piece<BN, BK>(Bn, ldb, nxt + ABYTES, tid, pi - NPA, wv);
;         }
;       }
;       __builtin_amdgcn_s_setprio(1);
; #pragma unroll
;       for (int mt = 0; mt < 2; ++mt)
; #pragma unroll
;         for (int nt = 0; nt < NTW; ++nt) acc[mt][nt] = mfma(fa[kk & 1][mt], fb[kk & 1][nt], acc[mt][nt]);
;       __builtin_amdgcn_s_setprio(0);
;       __builtin_amdgcn_sched_barrier(0);
;     }
;     wait_vm0();
;     __syncthreads();
;   }
	v_add3_u32 v166, s42, v140, v141
	v_add3_u32 v170, s42, v142, v144
	ds_read_b128 v[166:169], v166
	v_add3_u32 v174, s42, v143, v151
	ds_read_b128 v[170:173], v170
	v_add3_u32 v178, s42, v152, v154
	ds_read_b128 v[174:177], v174 offset:32768
	v_add3_u32 v182, s42, v153, v155
	ds_read_b128 v[178:181], v178 offset:32768
	v_add3_u32 v186, s42, v156, v164
	ds_read_b128 v[182:185], v182 offset:32768
	ds_read_b128 v[186:189], v186 offset:32768
	s_cmpk_eq_i32 s30, 0x780
	s_cbranch_scc1 .Lk382_exit
	s_add_i32 s37, s100, s3
	v_lshl_add_u64 v[214:215], v[130:131], 0, s[30:31]
	v_lshl_add_u64 v[226:227], v[132:133], 0, s[30:31]
	s_mov_b32 m0, s37
	v_lshl_add_u64 v[228:229], v[214:215], 0, s[28:29]
	v_mfma_f32_32x32x16_bf16 v[114:129], v[190:193], v[198:201], v[114:129]
	global_load_lds_dwordx4 v[228:229], off
	v_lshl_add_u64 v[228:229], v[214:215], 0, s[24:25]
	s_add_i32 m0, s37, 0x2000
	v_mfma_f32_32x32x16_bf16 v[98:113], v[190:193], v[202:205], v[98:113]
	global_load_lds_dwordx4 v[228:229], off
	v_lshl_add_u64 v[228:229], v[214:215], 0, s[26:27]
	s_add_i32 m0, s37, 0x4000
	v_mfma_f32_32x32x16_bf16 v[82:97], v[190:193], v[206:209], v[82:97]
	global_load_lds_dwordx4 v[228:229], off
	v_lshl_add_u64 v[228:229], v[214:215], 0, s[38:39]
	s_add_i32 m0, s37, 0x6000
	v_mfma_f32_32x32x16_bf16 v[66:81], v[190:193], v[210:213], v[66:81]
	global_load_lds_dwordx4 v[228:229], off
	v_lshl_add_u64 v[228:229], v[226:227], 0, s[28:29]
	s_add_i32 m0, s37, 0x8000
	v_mfma_f32_32x32x16_bf16 v[50:65], v[194:197], v[198:201], v[50:65]
	global_load_lds_dwordx4 v[228:229], off
	v_lshl_add_u64 v[228:229], v[226:227], 0, s[24:25]
	s_add_i32 m0, s37, 0xa000
	v_mfma_f32_32x32x16_bf16 v[34:49], v[194:197], v[202:205], v[34:49]
	global_load_lds_dwordx4 v[228:229], off
	v_lshl_add_u64 v[228:229], v[226:227], 0, s[26:27]
	s_add_i32 m0, s37, 0xc000
	v_mfma_f32_32x32x16_bf16 v[18:33], v[194:197], v[206:209], v[18:33]
	global_load_lds_dwordx4 v[228:229], off
	v_lshl_add_u64 v[228:229], v[226:227], 0, s[38:39]
	s_add_i32 m0, s37, 0xe000
	v_mfma_f32_32x32x16_bf16 v[2:17], v[194:197], v[210:213], v[2:17]
	global_load_lds_dwordx4 v[228:229], off
	s_branch .LBB0_382
.Lk382_exit:
	v_mfma_f32_32x32x16_bf16 v[114:129], v[190:193], v[198:201], v[114:129]
	v_mfma_f32_32x32x16_bf16 v[98:113], v[190:193], v[202:205], v[98:113]
	v_mfma_f32_32x32x16_bf16 v[82:97], v[190:193], v[206:209], v[82:97]
	v_mfma_f32_32x32x16_bf16 v[66:81], v[190:193], v[210:213], v[66:81]
	v_mfma_f32_32x32x16_bf16 v[50:65], v[194:197], v[198:201], v[50:65]
	v_mfma_f32_32x32x16_bf16 v[34:49], v[194:197], v[202:205], v[34:49]
	v_mfma_f32_32x32x16_bf16 v[18:33], v[194:197], v[206:209], v[18:33]
	v_mfma_f32_32x32x16_bf16 v[2:17], v[194:197], v[210:213], v[2:17]
	s_waitcnt lgkmcnt(0)
	v_add_u32_e32 v0, 0x10000, v140
	v_add_u32_e32 v198, 0x10000, v142
	v_add_u32_e32 v130, v0, v141
	v_add_u32_e32 v140, v198, v144
	v_add_u32_e32 v199, 0x18000, v143
	v_add_u32_e32 v200, 0x18000, v152
	ds_read_b128 v[130:133], v130
	ds_read_b128 v[166:169], v140
	v_add_u32_e32 v140, v199, v151
	v_add_u32_e32 v144, v200, v154
	v_add_u32_e32 v201, 0x18000, v153
	ds_read_b128 v[140:143], v140
	ds_read_b128 v[170:173], v144
	v_add_u32_e32 v144, v201, v155
	v_add_u32_e32 v202, 0x18000, v156
	v_add_u32_e32 v151, v202, v164
	ds_read_b128 v[152:155], v144
	ds_read_b128 v[174:177], v151
	v_add_u32_e32 v144, v0, v161
	v_add_u32_e32 v151, v198, v163
	ds_read_b128 v[178:181], v144
	ds_read_b128 v[182:185], v151
	v_add_u32_e32 v144, v199, v159
	v_add_u32_e32 v151, v200, v160
	ds_read_b128 v[186:189], v144
	ds_read_b128 v[190:193], v151
	v_add_u32_e32 v144, v201, v157
	v_add_u32_e32 v151, v202, v158
	ds_read_b128 v[156:159], v144
	ds_read_b128 v[194:197], v151
	s_add_i32 s36, s36, s94
	s_cmpk_gt_i32 s36, 0x4ff
	s_cselect_b64 s[42:43], -1, 0
	s_cmpk_lt_i32 s36, 0x500
	s_setprio 1
	s_waitcnt lgkmcnt(9)
	v_mfma_f32_32x32x16_bf16 v[114:129], v[130:133], v[140:143], v[114:129]
	s_waitcnt lgkmcnt(8)
	v_mfma_f32_32x32x16_bf16 v[98:113], v[130:133], v[170:173], v[98:113]
	s_waitcnt lgkmcnt(7)
	v_mfma_f32_32x32x16_bf16 v[82:97], v[130:133], v[152:155], v[82:97]
	s_waitcnt lgkmcnt(6)
	v_mfma_f32_32x32x16_bf16 v[66:81], v[130:133], v[174:177], v[66:81]
	v_mfma_f32_32x32x16_bf16 v[50:65], v[166:169], v[140:143], v[50:65]
	v_mfma_f32_32x32x16_bf16 v[34:49], v[166:169], v[170:173], v[34:49]
	v_mfma_f32_32x32x16_bf16 v[18:33], v[166:169], v[152:155], v[18:33]
	v_mfma_f32_32x32x16_bf16 v[2:17], v[166:169], v[174:177], v[2:17]
	s_setprio 0
	v_add_u32_e32 v130, v0, v149
	v_add_u32_e32 v140, v198, v150
	v_add_u32_e32 v144, v199, v147
	ds_read_b128 v[130:133], v130
	ds_read_b128 v[140:143], v140
	v_add_u32_e32 v147, v200, v148
	ds_read_b128 v[148:151], v144
	ds_read_b128 v[152:155], v147
	v_add_u32_e32 v144, v201, v145
	v_add_u32_e32 v160, v202, v146
	ds_read_b128 v[144:147], v144
	ds_read_b128 v[166:169], v160
	s_setprio 1
	s_waitcnt lgkmcnt(9)
; DI f32x16 mfma(bf16x8 a, bf16x8 b, f32x16 c) { return __builtin_amdgcn_mfma_f32_32x32x16_bf16(a, b, c, 0, 0, 0); }
; DI int launder(int x) { asm volatile("" : "+v"(x)); return x; }
; template <int BK> DI int swz(int row) { constexpr int CPR = BK / 8; return (row / (16 / CPR)) % CPR; }
; DI void wait_vm0() { asm volatile("s_waitcnt vmcnt(0)" ::: "memory"); }
;     ...
;     for (int kk = 0; kk < NKK; ++kk) {
;       if (kk + 1 < NKK) {
;         const int ch = (kk + 1) * 2 + hh;
; #pragma unroll
;         for (int mt = 0; mt < 2; ++mt) { int row = wm * 64 + mt * 32 + l31; fa[(kk + 1) & 1][mt] = *(const bf16x8*)(cur + row * (BK * 2) + ((ch ^ swz<BK>(row)) << 4)); }
; #pragma unroll
;         for (int nt = 0; nt < NTW; ++nt) { int row = wn * (32 * NTW) + nt * 32 + l31; fb[(kk + 1) & 1][nt] = *(const bf16x8*)(cur + ABYTES + row * (BK * 2) + ((ch ^ swz<BK>(row)) << 4)); }
;       }
;       if (more) {
; #pragma unroll
;         for (int q = 0; q < PPK; ++q) {
;           const int pi = kk * PPK + q;
;           if (pi < NPA) stage_piece<BM, BK>(An, lda, nxt, tid, pi, wv);
;           else if (pi < NP) stage_piece<BN, BK>(Bn, ldb, nxt + ABYTES, tid, pi - NPA, wv);
;         }
;       }
;       __builtin_amdgcn_s_setprio(1);
; #pragma unroll
;       for (int mt = 0; mt < 2; ++mt)
; #pragma unroll
;         for (int nt = 0; nt < NTW; ++nt) acc[mt][nt] = mfma(fa[kk & 1][mt], fb[kk & 1][nt], acc[mt][nt]);
;       __builtin_amdgcn_s_setprio(0);
;       __builtin_amdgcn_sched_barrier(0);
;     }
;     wait_vm0();
;     __syncthreads();
;   }
;   if (has_next) { const int tid3 = launder(threadIdx.x); stage_tile<BM, BK>(A + (size_t)row0n * lda, lda, lds, tid3); stage_tile<BN, BK>(Bt + (size_t)col0n * ldb, ldb, lds + ABYTES, tid3); }
	v_mfma_f32_32x32x16_bf16 v[114:129], v[178:181], v[186:189], v[114:129]
	s_waitcnt lgkmcnt(8)
	v_mfma_f32_32x32x16_bf16 v[98:113], v[178:181], v[190:193], v[98:113]
	s_waitcnt lgkmcnt(7)
	v_mfma_f32_32x32x16_bf16 v[82:97], v[178:181], v[156:159], v[82:97]
	s_waitcnt lgkmcnt(6)
	v_mfma_f32_32x32x16_bf16 v[66:81], v[178:181], v[194:197], v[66:81]
	v_mfma_f32_32x32x16_bf16 v[50:65], v[182:185], v[186:189], v[50:65]
	v_mfma_f32_32x32x16_bf16 v[34:49], v[182:185], v[190:193], v[34:49]
	v_mfma_f32_32x32x16_bf16 v[18:33], v[182:185], v[156:159], v[18:33]
	v_mfma_f32_32x32x16_bf16 v[2:17], v[182:185], v[194:197], v[2:17]
	s_setprio 0
	v_add_u32_e32 v0, v0, v138
	v_add_u32_e32 v138, v198, v139
	ds_read_b128 v[156:159], v0
	ds_read_b128 v[170:173], v138
	v_add_u32_e32 v0, v199, v136
	v_add_u32_e32 v160, v200, v137
	ds_read_b128 v[136:139], v0
	ds_read_b128 v[174:177], v160
	v_add_u32_e32 v0, v201, v134
	v_add_u32_e32 v134, v202, v135
	ds_read_b128 v[178:181], v0
	ds_read_b128 v[182:185], v134
	s_setprio 1
	s_waitcnt lgkmcnt(9)
	v_mfma_f32_32x32x16_bf16 v[114:129], v[130:133], v[148:151], v[114:129]
	s_waitcnt lgkmcnt(8)
	v_mfma_f32_32x32x16_bf16 v[98:113], v[130:133], v[152:155], v[98:113]
	s_waitcnt lgkmcnt(7)
	v_mfma_f32_32x32x16_bf16 v[82:97], v[130:133], v[144:147], v[82:97]
	s_waitcnt lgkmcnt(6)
	v_mfma_f32_32x32x16_bf16 v[66:81], v[130:133], v[166:169], v[66:81]
	v_mfma_f32_32x32x16_bf16 v[50:65], v[140:143], v[148:151], v[50:65]
	v_mfma_f32_32x32x16_bf16 v[34:49], v[140:143], v[152:155], v[34:49]
	v_mfma_f32_32x32x16_bf16 v[18:33], v[140:143], v[144:147], v[18:33]
	v_mfma_f32_32x32x16_bf16 v[2:17], v[140:143], v[166:169], v[2:17]
	s_setprio 0
	s_setprio 1
	s_waitcnt lgkmcnt(3)
	v_mfma_f32_32x32x16_bf16 v[114:129], v[156:159], v[136:139], v[114:129]
	s_waitcnt lgkmcnt(2)
	v_mfma_f32_32x32x16_bf16 v[98:113], v[156:159], v[174:177], v[98:113]
	s_waitcnt lgkmcnt(1)
	v_mfma_f32_32x32x16_bf16 v[82:97], v[156:159], v[178:181], v[82:97]
	s_waitcnt lgkmcnt(0)
	v_mfma_f32_32x32x16_bf16 v[66:81], v[156:159], v[182:185], v[66:81]
	v_mfma_f32_32x32x16_bf16 v[50:65], v[170:173], v[136:139], v[50:65]
	v_mfma_f32_32x32x16_bf16 v[34:49], v[170:173], v[174:177], v[34:49]
	v_mfma_f32_32x32x16_bf16 v[18:33], v[170:173], v[178:181], v[18:33]
	v_mfma_f32_32x32x16_bf16 v[2:17], v[170:173], v[182:185], v[2:17]
	s_setprio 0
	s_waitcnt vmcnt(0)
	s_barrier
	s_cbranch_scc0 .LBB0_378
	v_mov_b32_e32 v132, v216
	s_lshl_b32 s3, s36, 3
	v_ashrrev_i32_e32 v0, 31, v132
	v_lshrrev_b32_e32 v130, 29, v0
	v_lshrrev_b32_e32 v0, 28, v0
	v_add_u32_e32 v0, v132, v0
	v_ashrrev_i32_e32 v0, 4, v0
	s_and_b32 s3, s3, 56
	s_bfe_u32 s7, s36, 0x30003
	v_lshrrev_b32_e32 v133, 29, v0
	s_or_b32 s3, s3, s7
	s_lshl_b32 s7, s36, 2
	v_add_u32_e32 v130, v132, v130
	v_add_u32_e32 v133, v0, v133
	s_and_b32 s30, s7, 0xffffff00
	s_lshl_b32 s3, s3, 19
	v_and_b32_e32 v131, 0xffffff8, v130
	v_and_b32_e32 v133, 0xffffff8, v133
	s_add_u32 s44, s12, s3
	v_sub_u32_e32 v131, v132, v131
	v_sub_u32_e32 v0, v0, v133
	v_lshlrev_b32_e32 v130, 8, v130
	v_readfirstlane_b32 s3, v132
	s_addc_u32 s45, s13, 0
	v_xor_b32_e32 v0, v0, v131
	v_and_b32_e32 v130, 0xfffff800, v130
	s_lshl_b32 s3, s3, 4
	v_lshl_add_u32 v0, v0, 4, v130
	s_and_b32 s3, s3, 0xfffffc00
	v_lshl_add_u64 v[130:131], s[44:45], 0, v[0:1]
	s_mov_b32 m0, s3
	v_lshl_add_u64 v[132:133], v[130:131], 0, s[58:59]
	global_load_lds_dwordx4 v0, s[44:45]
	s_add_i32 m0, s3, 0x2000
	s_ashr_i32 s31, s30, 31
	global_load_lds_dwordx4 v[132:133], off
	v_lshl_add_u64 v[132:133], v[130:131], 0, s[48:49]
	s_add_i32 m0, s3, 0x4000
	s_lshl_b64 s[30:31], s[30:31], 11
	global_load_lds_dwordx4 v[132:133], off
	s_add_i32 m0, s3, 0x6000
	s_add_u32 s30, s40, s30
	v_lshl_add_u64 v[130:131], v[130:131], 0, s[50:51]
	s_addc_u32 s31, s41, s31
	global_load_lds_dwordx4 v[130:131], off
	v_lshl_add_u64 v[130:131], s[30:31], 0, v[0:1]
	s_add_i32 m0, s3, 0x8000
	v_lshl_add_u64 v[132:133], v[130:131], 0, s[58:59]
	global_load_lds_dwordx4 v0, s[30:31]
	s_add_i32 m0, s3, 0xa000
	s_nop 0
	global_load_lds_dwordx4 v[132:133], off
	v_lshl_add_u64 v[132:133], v[130:131], 0, s[48:49]
	s_add_i32 m0, s3, 0xc000
	v_lshl_add_u64 v[130:131], v[130:131], 0, s[50:51]
	global_load_lds_dwordx4 v[132:133], off
	s_add_i32 m0, s3, 0xe000
	s_nop 0
	global_load_lds_dwordx4 v[130:131], off
	s_branch .LBB0_378

; DI f32x16 zero16() { f32x16 z; for (int i = 0; i < 16; ++i) z[i] = 0.f; return z; }
; DI int launder(int x) { asm volatile("" : "+v"(x)); return x; }
; template <int BK> DI int swz(int row) { constexpr int CPR = BK / 8; return (row / (16 / CPR)) % CPR; }
; DI void wait_vm0() { asm volatile("s_waitcnt vmcnt(0)" ::: "memory"); }
;   DI void pre(int grow0, int gcol0, int lane, int w, char* lds) { xpass(0, grow0, gcol0, lane, w, lds); }
;     ...
;   const int tid = launder(threadIdx.x), lane = tid & 63, w = tid >> 6, wm = w % WM, wn = w / WM;
;   const int l31 = lane & 31, hh = lane >> 5;
;   f32x16 acc[2][NTW];
; #pragma unroll
;   for (int a = 0; a < 2; ++a)
; #pragma unroll
;     for (int b = 0; b < NTW; ++b) acc[a][b] = zero16();
;   const bf16_t* Ag = A + (size_t)row0 * lda; const bf16_t* Bg = Bt + (size_t)col0 * ldb;
;   const int wv = __builtin_amdgcn_readfirstlane(tid >> 6);
;   __syncthreads();
;   if (!pre) { stage_tile<BM, BK>(Ag, lda, lds, tid); stage_tile<BN, BK>(Bg, ldb, lds + ABYTES, tid); }
;   wait_vm0();
;   __syncthreads();
;   const int nk = K / BK;
;   for (int kt = 0; kt < nk; ++kt) {
;     char* cur = lds + (kt & 1) * STG; char* nxt = lds + ((kt + 1) & 1) * STG;
;     const bool more = kt + 1 < nk;
;     const bf16_t* An = Ag + (kt + 1) * BK; const bf16_t* Bn = Bg + (kt + 1) * BK;
;     if (!more) epi.pre(row0 + wm * 64, col0 + wn * (32 * NTW), lane, w, lds);
;     bf16x8 fa[2][2], fb[2][NTW];
; #pragma unroll
;     for (int mt = 0; mt < 2; ++mt) { int row = wm * 64 + mt * 32 + l31; fa[0][mt] = *(const bf16x8*)(cur + row * (BK * 2) + ((hh ^ swz<BK>(row)) << 4)); }
; #pragma unroll
;     for (int nt = 0; nt < NTW; ++nt) { int row = wn * (32 * NTW) + nt * 32 + l31; fb[0][nt] = *(const bf16x8*)(cur + ABYTES + row * (BK * 2) + ((hh ^ swz<BK>(row)) << 4)); }
.LBB0_438:
	v_lshrrev_b32_e32 v4, 30, v3
	v_add_u32_e32 v4, v3, v4
	v_ashrrev_i32_e32 v4, 2, v4
	v_mul_i32_i24_e32 v5, 4, v4
	v_sub_u32_e32 v3, v3, v5
	v_and_b32_e32 v5, 31, v2
	v_lshlrev_b32_e32 v7, 6, v3
	v_or_b32_e32 v7, v7, v5
	v_bfe_u32 v3, v3, 25, 1
	v_lshlrev_b32_e32 v140, 7, v7
	v_add_u32_e32 v8, v7, v3
	v_or_b32_e32 v7, 32, v7
	v_add_u32_e32 v3, v7, v3
	v_lshlrev_b32_e32 v142, 7, v7
	v_ashrrev_i32_e32 v7, 1, v3
	v_ashrrev_i32_e32 v3, 31, v3
	v_ashrrev_i32_e32 v9, 1, v8
	v_ashrrev_i32_e32 v8, 31, v8
	v_lshrrev_b32_e32 v3, 29, v3
	v_lshrrev_b32_e32 v8, 29, v8
	v_add_u32_e32 v3, v7, v3
	v_add_u32_e32 v8, v9, v8
	v_and_b32_e32 v3, -8, v3
	v_lshrrev_b32_e32 v6, 5, v2
	v_and_b32_e32 v8, -8, v8
	v_sub_u32_e32 v3, v7, v3
	v_lshl_or_b32 v5, v4, 7, v5
	v_sub_u32_e32 v8, v9, v8
	v_bitop3_b32 v7, v3, v6, 1 bitop3:0x78
	v_lshrrev_b32_e32 v4, 31, v4
	v_bitop3_b32 v9, v8, v6, 1 bitop3:0x78
	v_lshlrev_b32_e32 v144, 4, v7
	v_add_u32_e32 v7, v5, v4
	v_lshlrev_b32_e32 v141, 4, v9
	v_ashrrev_i32_e32 v9, 1, v7
	v_ashrrev_i32_e32 v7, 31, v7
	v_lshrrev_b32_e32 v7, 29, v7
	v_add_u32_e32 v7, v9, v7
	v_and_b32_e32 v7, -8, v7
	v_sub_u32_e32 v7, v9, v7
	v_bitop3_b32 v9, v7, v6, 1 bitop3:0x78
	v_lshlrev_b32_e32 v151, 4, v9
	v_or_b32_e32 v9, 32, v5
	v_lshlrev_b32_e32 v152, 7, v9
	v_add_u32_e32 v9, v9, v4
	v_ashrrev_i32_e32 v10, 1, v9
	v_ashrrev_i32_e32 v9, 31, v9
	v_lshrrev_b32_e32 v9, 29, v9
	v_add_u32_e32 v9, v10, v9
	v_and_b32_e32 v9, -8, v9
	v_sub_u32_e32 v9, v10, v9
	v_bitop3_b32 v10, v9, v6, 1 bitop3:0x78
	v_lshlrev_b32_e32 v143, 7, v5
	v_lshlrev_b32_e32 v154, 4, v10
	v_or_b32_e32 v10, 64, v5
	v_or_b32_e32 v5, 0x60, v5
	v_lshlrev_b32_e32 v153, 7, v10
	v_add_u32_e32 v10, v10, v4
	v_add_u32_e32 v4, v5, v4
	v_lshlrev_b32_e32 v156, 7, v5
	v_ashrrev_i32_e32 v5, 1, v4
	v_ashrrev_i32_e32 v4, 31, v4
	v_lshrrev_b32_e32 v4, 29, v4
	v_add_u32_e32 v4, v5, v4
	v_and_b32_e32 v4, -8, v4
	v_sub_u32_e32 v4, v5, v4
	s_lshr_b32 s7, s36, 3
	v_bfe_u32 v2, v2, 5, 1
	v_ashrrev_i32_e32 v11, 1, v10
	v_ashrrev_i32_e32 v10, 31, v10
	v_bitop3_b32 v5, v4, v6, 1 bitop3:0x78
	s_and_b32 s7, s7, 7
	s_lshl_b32 s30, s35, 19
	v_lshrrev_b32_e32 v10, 29, v10
	v_lshlrev_b32_e32 v164, 4, v5
	v_bitop3_b32 v5, v8, v2, 2 bitop3:0x1e
	s_lshl_b32 s7, s7, 19
	s_and_b32 s30, s30, 0x1c00000
	v_add_u32_e32 v10, v11, v10
	v_lshlrev_b32_e32 v161, 4, v5
	v_bitop3_b32 v5, v3, v2, 2 bitop3:0x1e
	s_or_b32 s7, s30, s7
	s_and_b32 s30, s34, 0xffffff00
	v_and_b32_e32 v10, -8, v10
	v_lshlrev_b32_e32 v163, 4, v5
	v_bitop3_b32 v5, v7, v2, 2 bitop3:0x1e
	s_ashr_i32 s31, s30, 31
	v_sub_u32_e32 v10, v11, v10
	v_lshlrev_b32_e32 v159, 4, v5
	v_bitop3_b32 v5, v9, v2, 2 bitop3:0x1e
	s_lshl_b64 s[30:31], s[30:31], 11
	s_lshl_b32 s3, s3, 10
	v_lshlrev_b32_e32 v160, 4, v5
	v_bitop3_b32 v5, v10, v2, 2 bitop3:0x1e
	v_lshlrev_b32_e32 v157, 4, v5
	v_bitop3_b32 v5, v4, v2, 2 bitop3:0x1e
	s_add_u32 s40, s12, s7
	v_lshlrev_b32_e32 v158, 4, v5
	v_bitop3_b32 v5, v8, v2, 4 bitop3:0x1e
	s_addc_u32 s41, s13, 0
	s_waitcnt vmcnt(0)
	s_waitcnt vmcnt(0) lgkmcnt(0)
	s_barrier
	v_lshlrev_b32_e32 v149, 4, v5
	v_bitop3_b32 v5, v3, v2, 4 bitop3:0x1e
	v_lshl_add_u64 v[130:131], s[40:41], 0, v[0:1]
	s_load_dwordx4 s[40:43], s[0:1], 0x1a0
	v_lshlrev_b32_e32 v150, 4, v5
	v_bitop3_b32 v5, v7, v2, 4 bitop3:0x1e
	v_lshlrev_b32_e32 v147, 4, v5
	v_bitop3_b32 v5, v9, v2, 4 bitop3:0x1e
	v_bitop3_b32 v3, v3, v2, 6 bitop3:0x1e
	v_lshlrev_b32_e32 v148, 4, v5
	v_bitop3_b32 v5, v10, v2, 4 bitop3:0x1e
	v_lshlrev_b32_e32 v139, 4, v3
	v_bitop3_b32 v3, v7, v2, 6 bitop3:0x1e
	v_lshlrev_b32_e32 v145, 4, v5
	v_bitop3_b32 v5, v4, v2, 4 bitop3:0x1e
	v_lshlrev_b32_e32 v136, 4, v3
	v_bitop3_b32 v3, v9, v2, 6 bitop3:0x1e
	v_lshlrev_b32_e32 v146, 4, v5
	v_bitop3_b32 v5, v8, v2, 6 bitop3:0x1e
	v_lshlrev_b32_e32 v137, 4, v3
	v_bitop3_b32 v3, v10, v2, 6 bitop3:0x1e
	v_bitop3_b32 v2, v4, v2, 6 bitop3:0x1e
	s_waitcnt lgkmcnt(0)
	s_add_u32 s30, s42, s30
	v_bitop3_b32 v11, v10, v6, 1 bitop3:0x78
	v_lshlrev_b32_e32 v135, 4, v2
	s_addc_u32 s31, s43, s31
	v_mov_b32_e32 v2, 0
	v_lshlrev_b32_e32 v155, 4, v11
	v_lshlrev_b32_e32 v138, 4, v5
	v_lshlrev_b32_e32 v134, 4, v3
	v_lshl_add_u64 v[132:133], s[30:31], 0, v[0:1]
	s_mov_b64 s[30:31], 0
	s_mov_b32 s7, 0x10000
	v_mov_b32_e32 v3, v2
	v_mov_b32_e32 v4, v2
	v_mov_b32_e32 v5, v2
	v_mov_b32_e32 v6, v2
	v_mov_b32_e32 v7, v2
	v_mov_b32_e32 v8, v2
	v_mov_b32_e32 v9, v2
	v_mov_b32_e32 v10, v2
	v_mov_b32_e32 v11, v2
	v_mov_b32_e32 v12, v2
	v_mov_b32_e32 v13, v2
	v_mov_b32_e32 v14, v2
	v_mov_b32_e32 v15, v2
	v_mov_b32_e32 v16, v2
	v_mov_b32_e32 v17, v2
	v_mov_b32_e32 v18, v2
	v_mov_b32_e32 v19, v2
	v_mov_b32_e32 v20, v2
	v_mov_b32_e32 v21, v2
	v_mov_b32_e32 v22, v2
	v_mov_b32_e32 v23, v2
	v_mov_b32_e32 v24, v2
	v_mov_b32_e32 v25, v2
	v_mov_b32_e32 v26, v2
	v_mov_b32_e32 v27, v2
	v_mov_b32_e32 v28, v2
	v_mov_b32_e32 v29, v2
	v_mov_b32_e32 v30, v2
	v_mov_b32_e32 v31, v2
	v_mov_b32_e32 v32, v2
	v_mov_b32_e32 v33, v2
	v_mov_b32_e32 v66, v2
	v_mov_b32_e32 v67, v2
	v_mov_b32_e32 v68, v2
	v_mov_b32_e32 v69, v2
	v_mov_b32_e32 v70, v2
	v_mov_b32_e32 v71, v2
	v_mov_b32_e32 v72, v2
	v_mov_b32_e32 v73, v2
	v_mov_b32_e32 v74, v2
	v_mov_b32_e32 v75, v2
	v_mov_b32_e32 v76, v2
	v_mov_b32_e32 v77, v2
	v_mov_b32_e32 v78, v2
	v_mov_b32_e32 v79, v2
	v_mov_b32_e32 v80, v2
	v_mov_b32_e32 v81, v2
	v_mov_b32_e32 v82, v2
	v_mov_b32_e32 v83, v2
	v_mov_b32_e32 v84, v2
	v_mov_b32_e32 v85, v2
	v_mov_b32_e32 v86, v2
	v_mov_b32_e32 v87, v2
	v_mov_b32_e32 v88, v2
	v_mov_b32_e32 v89, v2
	v_mov_b32_e32 v90, v2
	v_mov_b32_e32 v91, v2
	v_mov_b32_e32 v92, v2
	v_mov_b32_e32 v93, v2
	v_mov_b32_e32 v94, v2
	v_mov_b32_e32 v95, v2
	v_mov_b32_e32 v96, v2
	v_mov_b32_e32 v97, v2
;     ...
;   f32x16 acc[2][NTW];
; #pragma unroll
;   for (int a = 0; a < 2; ++a)
; #pragma unroll
;     for (int b = 0; b < NTW; ++b) acc[a][b] = zero16();
;   const bf16_t* Ag = A + (size_t)row0 * lda; const bf16_t* Bg = Bt + (size_t)col0 * ldb;
;   const int wv = __builtin_amdgcn_readfirstlane(tid >> 6);
;   __syncthreads();
;   if (!pre) { stage_tile<BM, BK>(Ag, lda, lds, tid); stage_tile<BN, BK>(Bg, ldb, lds + ABYTES, tid); }
;   wait_vm0();
;   __syncthreads();
;   const int nk = K / BK;
;   for (int kt = 0; kt < nk; ++kt) {
;     char* cur = lds + (kt & 1) * STG; char* nxt = lds + ((kt + 1) & 1) * STG;
;     const bool more = kt + 1 < nk;
;     const bf16_t* An = Ag + (kt + 1) * BK; const bf16_t* Bn = Bg + (kt + 1) * BK;
;     if (!more) epi.pre(row0 + wm * 64, col0 + wn * (32 * NTW), lane, w, lds);
;     bf16x8 fa[2][2], fb[2][NTW];
; #pragma unroll
;     for (int mt = 0; mt < 2; ++mt) { int row = wm * 64 + mt * 32 + l31; fa[0][mt] = *(const bf16x8*)(cur + row * (BK * 2) + ((hh ^ swz<BK>(row)) << 4)); }
; #pragma unroll
;     for (int nt = 0; nt < NTW; ++nt) { int row = wn * (32 * NTW) + nt * 32 + l31; fb[0][nt] = *(const bf16x8*)(cur + ABYTES + row * (BK * 2) + ((hh ^ swz<BK>(row)) << 4)); }
; #pragma unroll
;     for (int kk = 0; kk < NKK; ++kk) {
;       if (kk + 1 < NKK) {
;         const int ch = (kk + 1) * 2 + hh;
; #pragma unroll
;         for (int mt = 0; mt < 2; ++mt) { int row = wm * 64 + mt * 32 + l31; fa[(kk + 1) & 1][mt] = *(const bf16x8*)(cur + row * (BK * 2) + ((ch ^ swz<BK>(row)) << 4)); }
; #pragma unroll
;         for (int nt = 0; nt < NTW; ++nt) { int row = wn * (32 * NTW) + nt * 32 + l31; fb[(kk + 1) & 1][nt] = *(const bf16x8*)(cur + ABYTES + row * (BK * 2) + ((ch ^ swz<BK>(row)) << 4)); }
;       }
;       if (more) {
; #pragma unroll
;         for (int q = 0; q < PPK; ++q) {
;           const int pi = kk * PPK + q;
;           if (pi < NPA) stage_piece<BM, BK>(An, lda, nxt, tid, pi, wv);
;           else if (pi < NP) stage_piece<BN, BK>(Bn, ldb, nxt + ABYTES, tid, pi - NPA, wv);
;         }
;       }
;       __builtin_amdgcn_s_setprio(1);
; #pragma unroll
;       for (int mt = 0; mt < 2; ++mt)
; #pragma unroll
;         for (int nt = 0; nt < NTW; ++nt) acc[mt][nt] = mfma(fa[kk & 1][mt], fb[kk & 1][nt], acc[mt][nt]);
;       __builtin_amdgcn_s_setprio(0);
;       __builtin_amdgcn_sched_barrier(0);
	v_mov_b32_e32 v34, v2
	v_mov_b32_e32 v35, v2
	v_mov_b32_e32 v36, v2
	v_mov_b32_e32 v37, v2
	v_mov_b32_e32 v38, v2
	v_mov_b32_e32 v39, v2
	v_mov_b32_e32 v40, v2
	v_mov_b32_e32 v41, v2
	v_mov_b32_e32 v42, v2
	v_mov_b32_e32 v43, v2
	v_mov_b32_e32 v44, v2
	v_mov_b32_e32 v45, v2
	v_mov_b32_e32 v46, v2
	v_mov_b32_e32 v47, v2
	v_mov_b32_e32 v48, v2
	v_mov_b32_e32 v49, v2
	v_mov_b32_e32 v50, v2
	v_mov_b32_e32 v51, v2
	v_mov_b32_e32 v52, v2
	v_mov_b32_e32 v53, v2
	v_mov_b32_e32 v54, v2
	v_mov_b32_e32 v55, v2
	v_mov_b32_e32 v56, v2
	v_mov_b32_e32 v57, v2
	v_mov_b32_e32 v58, v2
	v_mov_b32_e32 v59, v2
	v_mov_b32_e32 v60, v2
	v_mov_b32_e32 v61, v2
	v_mov_b32_e32 v62, v2
	v_mov_b32_e32 v63, v2
	v_mov_b32_e32 v64, v2
	v_mov_b32_e32 v65, v2
	v_mov_b32_e32 v98, v2
	v_mov_b32_e32 v99, v2
	v_mov_b32_e32 v100, v2
	v_mov_b32_e32 v101, v2
	v_mov_b32_e32 v102, v2
	v_mov_b32_e32 v103, v2
	v_mov_b32_e32 v104, v2
	v_mov_b32_e32 v105, v2
	v_mov_b32_e32 v106, v2
	v_mov_b32_e32 v107, v2
	v_mov_b32_e32 v108, v2
	v_mov_b32_e32 v109, v2
	v_mov_b32_e32 v110, v2
	v_mov_b32_e32 v111, v2
	v_mov_b32_e32 v112, v2
	v_mov_b32_e32 v113, v2
	v_mov_b32_e32 v114, v2
	v_mov_b32_e32 v115, v2
	v_mov_b32_e32 v116, v2
	v_mov_b32_e32 v117, v2
	v_mov_b32_e32 v118, v2
	v_mov_b32_e32 v119, v2
	v_mov_b32_e32 v120, v2
	v_mov_b32_e32 v121, v2
	v_mov_b32_e32 v122, v2
	v_mov_b32_e32 v123, v2
	v_mov_b32_e32 v124, v2
	v_mov_b32_e32 v125, v2
	v_mov_b32_e32 v126, v2
	v_mov_b32_e32 v127, v2
	v_mov_b32_e32 v128, v2
	v_mov_b32_e32 v129, v2
	v_add_u32_e32 v166, v140, v141
	v_add_u32_e32 v170, v142, v144
	ds_read_b128 v[166:169], v166
	v_add_u32_e32 v174, v143, v151
	ds_read_b128 v[170:173], v170
	v_add_u32_e32 v178, v152, v154
	ds_read_b128 v[174:177], v174 offset:32768
	v_add_u32_e32 v182, v153, v155
	ds_read_b128 v[178:181], v178 offset:32768
	v_add_u32_e32 v186, v156, v164
	ds_read_b128 v[182:185], v182 offset:32768
	ds_read_b128 v[186:189], v186 offset:32768
	s_and_b32 s40, s7, 0x10000
	s_add_i32 s37, s40, s3
	v_lshl_add_u64 v[214:215], v[130:131], 0, s[30:31]
	v_lshl_add_u64 v[226:227], v[132:133], 0, s[30:31]
	s_mov_b32 m0, s37
	v_lshl_add_u64 v[228:229], v[214:215], 0, s[28:29]
	global_load_lds_dwordx4 v[228:229], off
	s_add_i32 m0, s37, 0x2000
	v_lshl_add_u64 v[228:229], v[214:215], 0, s[24:25]
	global_load_lds_dwordx4 v[228:229], off
	s_add_i32 m0, s37, 0x4000
	v_lshl_add_u64 v[228:229], v[214:215], 0, s[26:27]
	global_load_lds_dwordx4 v[228:229], off
	s_add_i32 m0, s37, 0x6000
	v_lshl_add_u64 v[228:229], v[214:215], 0, s[38:39]
	global_load_lds_dwordx4 v[228:229], off
	s_add_i32 m0, s37, 0x8000
	v_lshl_add_u64 v[228:229], v[226:227], 0, s[28:29]
	global_load_lds_dwordx4 v[228:229], off
	s_add_i32 m0, s37, 0xa000
	v_lshl_add_u64 v[228:229], v[226:227], 0, s[24:25]
	global_load_lds_dwordx4 v[228:229], off
	s_add_i32 m0, s37, 0xc000
	v_lshl_add_u64 v[228:229], v[226:227], 0, s[26:27]
	global_load_lds_dwordx4 v[228:229], off
	s_add_i32 m0, s37, 0xe000
	v_lshl_add_u64 v[228:229], v[226:227], 0, s[38:39]
	global_load_lds_dwordx4 v[228:229], off
.LBB0_439:
	s_and_b32 s40, s7, 0x10000
	s_xor_b32 s100, s40, 0x10000
	v_add3_u32 v190, s100, v140, v161
	v_add3_u32 v194, s100, v142, v163
	ds_read_b128 v[190:193], v190
	v_add3_u32 v198, s100, v143, v159
	ds_read_b128 v[194:197], v194
	v_add3_u32 v202, s100, v152, v160
	ds_read_b128 v[198:201], v198 offset:32768
	v_add3_u32 v206, s100, v153, v157
	ds_read_b128 v[202:205], v202 offset:32768
	v_add3_u32 v210, s100, v156, v158
	ds_read_b128 v[206:209], v206 offset:32768
	ds_read_b128 v[210:213], v210 offset:32768
	s_waitcnt lgkmcnt(6)
	v_mfma_f32_32x32x16_bf16 v[114:129], v[166:169], v[174:177], v[114:129]
	v_mfma_f32_32x32x16_bf16 v[98:113], v[166:169], v[178:181], v[98:113]
	v_mfma_f32_32x32x16_bf16 v[50:65], v[166:169], v[182:185], v[50:65]
	v_mfma_f32_32x32x16_bf16 v[34:49], v[166:169], v[186:189], v[34:49]
	v_mfma_f32_32x32x16_bf16 v[82:97], v[170:173], v[174:177], v[82:97]
	v_mfma_f32_32x32x16_bf16 v[66:81], v[170:173], v[178:181], v[66:81]
	v_mfma_f32_32x32x16_bf16 v[18:33], v[170:173], v[182:185], v[18:33]
	v_mfma_f32_32x32x16_bf16 v[2:17], v[170:173], v[186:189], v[2:17]
	v_add3_u32 v166, s100, v140, v149
	v_add3_u32 v170, s100, v142, v150
	ds_read_b128 v[166:169], v166
	v_add3_u32 v174, s100, v143, v147
	ds_read_b128 v[170:173], v170
	v_add3_u32 v178, s100, v152, v148
	ds_read_b128 v[174:177], v174 offset:32768
	v_add3_u32 v182, s100, v153, v145
	ds_read_b128 v[178:181], v178 offset:32768
	v_add3_u32 v186, s100, v156, v146
	ds_read_b128 v[182:185], v182 offset:32768
	ds_read_b128 v[186:189], v186 offset:32768
	s_waitcnt lgkmcnt(6)
	v_mfma_f32_32x32x16_bf16 v[114:129], v[190:193], v[198:201], v[114:129]
	v_mfma_f32_32x32x16_bf16 v[98:113], v[190:193], v[202:205], v[98:113]
	v_mfma_f32_32x32x16_bf16 v[50:65], v[190:193], v[206:209], v[50:65]
	v_mfma_f32_32x32x16_bf16 v[34:49], v[190:193], v[210:213], v[34:49]
	v_mfma_f32_32x32x16_bf16 v[82:97], v[194:197], v[198:201], v[82:97]
	v_mfma_f32_32x32x16_bf16 v[66:81], v[194:197], v[202:205], v[66:81]
	v_mfma_f32_32x32x16_bf16 v[18:33], v[194:197], v[206:209], v[18:33]
	v_mfma_f32_32x32x16_bf16 v[2:17], v[194:197], v[210:213], v[2:17]
	v_add3_u32 v190, s100, v140, v138
	v_add3_u32 v194, s100, v142, v139
	ds_read_b128 v[190:193], v190
	v_add3_u32 v198, s100, v143, v136
	ds_read_b128 v[194:197], v194
	v_add3_u32 v202, s100, v152, v137
	ds_read_b128 v[198:201], v198 offset:32768
	v_add3_u32 v206, s100, v153, v134
	ds_read_b128 v[202:205], v202 offset:32768
	v_add3_u32 v210, s100, v156, v135
	ds_read_b128 v[206:209], v206 offset:32768
	ds_read_b128 v[210:213], v210 offset:32768
	s_waitcnt lgkmcnt(6)
	v_mfma_f32_32x32x16_bf16 v[114:129], v[166:169], v[174:177], v[114:129]
	v_mfma_f32_32x32x16_bf16 v[98:113], v[166:169], v[178:181], v[98:113]
	v_mfma_f32_32x32x16_bf16 v[50:65], v[166:169], v[182:185], v[50:65]
	v_mfma_f32_32x32x16_bf16 v[34:49], v[166:169], v[186:189], v[34:49]
	v_mfma_f32_32x32x16_bf16 v[82:97], v[170:173], v[174:177], v[82:97]
	v_mfma_f32_32x32x16_bf16 v[66:81], v[170:173], v[178:181], v[66:81]
	v_mfma_f32_32x32x16_bf16 v[18:33], v[170:173], v[182:185], v[18:33]
	v_mfma_f32_32x32x16_bf16 v[2:17], v[170:173], v[186:189], v[2:17]
	s_add_u32 s30, s30, 0x80
	s_addc_u32 s31, s31, 0
	s_add_i32 s7, s7, 0x10000
	s_waitcnt vmcnt(0) lgkmcnt(0)
	s_barrier
; DI f32x16 mfma(bf16x8 a, bf16x8 b, f32x16 c) { return __builtin_amdgcn_mfma_f32_32x32x16_bf16(a, b, c, 0, 0, 0); }
; template <int BK> DI int swz(int row) { constexpr int CPR = BK / 8; return (row / (16 / CPR)) % CPR; }
; DI void wait_vm0() { asm volatile("s_waitcnt vmcnt(0)" ::: "memory"); }
;   DI void pre(int grow0, int gcol0, int lane, int w, char* lds) { xpass(0, grow0, gcol0, lane, w, lds); }
;     ...
;   for (int kt = 0; kt < nk; ++kt) {
;     char* cur = lds + (kt & 1) * STG; char* nxt = lds + ((kt + 1) & 1) * STG;
;     const bool more = kt + 1 < nk;
;     const bf16_t* An = Ag + (kt + 1) * BK; const bf16_t* Bn = Bg + (kt + 1) * BK;
;     if (!more) epi.pre(row0 + wm * 64, col0 + wn * (32 * NTW), lane, w, lds);
;     bf16x8 fa[2][2], fb[2][NTW];
; #pragma unroll
;     for (int mt = 0; mt < 2; ++mt) { int row = wm * 64 + mt * 32 + l31; fa[0][mt] = *(const bf16x8*)(cur + row * (BK * 2) + ((hh ^ swz<BK>(row)) << 4)); }
; #pragma unroll
;     for (int nt = 0; nt < NTW; ++nt) { int row = wn * (32 * NTW) + nt * 32 + l31; fb[0][nt] = *(const bf16x8*)(cur + ABYTES + row * (BK * 2) + ((hh ^ swz<BK>(row)) << 4)); }
; #pragma unroll
;     for (int kk = 0; kk < NKK; ++kk) {
;       if (kk + 1 < NKK) {
;         const int ch = (kk + 1) * 2 + hh;
; #pragma unroll
;         for (int mt = 0; mt < 2; ++mt) { int row = wm * 64 + mt * 32 + l31; fa[(kk + 1) & 1][mt] = *(const bf16x8*)(cur + row * (BK * 2) + ((ch ^ swz<BK>(row)) << 4)); }
; #pragma unroll
;         for (int nt = 0; nt < NTW; ++nt) { int row = wn * (32 * NTW) + nt * 32 + l31; fb[(kk + 1) & 1][nt] = *(const bf16x8*)(cur + ABYTES + row * (BK * 2) + ((ch ^ swz<BK>(row)) << 4)); }
;       }
;       if (more) {
; #pragma unroll
;         for (int q = 0; q < PPK; ++q) {
;           const int pi = kk * PPK + q;
;           if (pi < NPA) stage_piece<BM, BK>(An, lda, nxt, tid, pi, wv);
;           else if (pi < NP) stage_piece<BN, BK>(Bn, ldb, nxt + ABYTES, tid, pi - NPA, wv);
;         }
;       }
;       __builtin_amdgcn_s_setprio(1);
; #pragma unroll
;       for (int mt = 0; mt < 2; ++mt)
; #pragma unroll
;         for (int nt = 0; nt < NTW; ++nt) acc[mt][nt] = mfma(fa[kk & 1][mt], fb[kk & 1][nt], acc[mt][nt]);
;       __builtin_amdgcn_s_setprio(0);
;       __builtin_amdgcn_sched_barrier(0);
;     }
;     wait_vm0();
;     __syncthreads();
;   }
	v_add3_u32 v166, s40, v140, v141
	v_add3_u32 v170, s40, v142, v144
	ds_read_b128 v[166:169], v166
	v_add3_u32 v174, s40, v143, v151
	ds_read_b128 v[170:173], v170
	v_add3_u32 v178, s40, v152, v154
	ds_read_b128 v[174:177], v174 offset:32768
	v_add3_u32 v182, s40, v153, v155
	ds_read_b128 v[178:181], v178 offset:32768
	v_add3_u32 v186, s40, v156, v164
	ds_read_b128 v[182:185], v182 offset:32768
	ds_read_b128 v[186:189], v186 offset:32768
	s_cmpk_eq_i32 s30, 0x780
	s_cbranch_scc1 .Lk439_exit
	s_add_i32 s37, s100, s3
	v_lshl_add_u64 v[214:215], v[130:131], 0, s[30:31]
	v_lshl_add_u64 v[226:227], v[132:133], 0, s[30:31]
	s_mov_b32 m0, s37
	v_lshl_add_u64 v[228:229], v[214:215], 0, s[28:29]
	v_mfma_f32_32x32x16_bf16 v[114:129], v[190:193], v[198:201], v[114:129]
	global_load_lds_dwordx4 v[228:229], off
	v_lshl_add_u64 v[228:229], v[214:215], 0, s[24:25]
	s_add_i32 m0, s37, 0x2000
	v_mfma_f32_32x32x16_bf16 v[98:113], v[190:193], v[202:205], v[98:113]
	global_load_lds_dwordx4 v[228:229], off
	v_lshl_add_u64 v[228:229], v[214:215], 0, s[26:27]
	s_add_i32 m0, s37, 0x4000
	v_mfma_f32_32x32x16_bf16 v[50:65], v[190:193], v[206:209], v[50:65]
	global_load_lds_dwordx4 v[228:229], off
	v_lshl_add_u64 v[228:229], v[214:215], 0, s[38:39]
	s_add_i32 m0, s37, 0x6000
	v_mfma_f32_32x32x16_bf16 v[34:49], v[190:193], v[210:213], v[34:49]
	global_load_lds_dwordx4 v[228:229], off
	v_lshl_add_u64 v[228:229], v[226:227], 0, s[28:29]
	s_add_i32 m0, s37, 0x8000
	v_mfma_f32_32x32x16_bf16 v[82:97], v[194:197], v[198:201], v[82:97]
	global_load_lds_dwordx4 v[228:229], off
	v_lshl_add_u64 v[228:229], v[226:227], 0, s[24:25]
	s_add_i32 m0, s37, 0xa000
	v_mfma_f32_32x32x16_bf16 v[66:81], v[194:197], v[202:205], v[66:81]
	global_load_lds_dwordx4 v[228:229], off
	v_lshl_add_u64 v[228:229], v[226:227], 0, s[26:27]
	s_add_i32 m0, s37, 0xc000
	v_mfma_f32_32x32x16_bf16 v[18:33], v[194:197], v[206:209], v[18:33]
	global_load_lds_dwordx4 v[228:229], off
	v_lshl_add_u64 v[228:229], v[226:227], 0, s[38:39]
	s_add_i32 m0, s37, 0xe000
	v_mfma_f32_32x32x16_bf16 v[2:17], v[194:197], v[210:213], v[2:17]
	global_load_lds_dwordx4 v[228:229], off
	s_branch .LBB0_439
.Lk439_exit:
	v_mfma_f32_32x32x16_bf16 v[114:129], v[190:193], v[198:201], v[114:129]
	v_mfma_f32_32x32x16_bf16 v[98:113], v[190:193], v[202:205], v[98:113]
	v_mfma_f32_32x32x16_bf16 v[50:65], v[190:193], v[206:209], v[50:65]
	v_mfma_f32_32x32x16_bf16 v[34:49], v[190:193], v[210:213], v[34:49]
	v_mfma_f32_32x32x16_bf16 v[82:97], v[194:197], v[198:201], v[82:97]
	v_mfma_f32_32x32x16_bf16 v[66:81], v[194:197], v[202:205], v[66:81]
	v_mfma_f32_32x32x16_bf16 v[18:33], v[194:197], v[206:209], v[18:33]
	v_mfma_f32_32x32x16_bf16 v[2:17], v[194:197], v[210:213], v[2:17]
	s_waitcnt lgkmcnt(0)
	v_add_u32_e32 v0, 0x10000, v140
	v_add_u32_e32 v198, 0x10000, v142
	v_add_u32_e32 v130, v0, v141
	v_add_u32_e32 v140, v198, v144
	v_add_u32_e32 v199, 0x18000, v143
	v_add_u32_e32 v200, 0x18000, v152
	ds_read_b128 v[130:133], v130
	ds_read_b128 v[166:169], v140
	v_add_u32_e32 v140, v199, v151
	v_add_u32_e32 v144, v200, v154
	v_add_u32_e32 v201, 0x18000, v153
	ds_read_b128 v[140:143], v140
	ds_read_b128 v[170:173], v144
	v_add_u32_e32 v144, v201, v155
	v_add_u32_e32 v202, 0x18000, v156
	v_add_u32_e32 v151, v202, v164
	ds_read_b128 v[152:155], v144
	ds_read_b128 v[174:177], v151
	v_add_u32_e32 v144, v0, v161
	v_add_u32_e32 v151, v198, v163
	ds_read_b128 v[178:181], v144
	ds_read_b128 v[182:185], v151
	v_add_u32_e32 v144, v199, v159
	v_add_u32_e32 v151, v200, v160
	ds_read_b128 v[186:189], v144
	ds_read_b128 v[190:193], v151
	v_add_u32_e32 v144, v201, v157
	v_add_u32_e32 v151, v202, v158
	ds_read_b128 v[156:159], v144
	ds_read_b128 v[194:197], v151
	s_add_i32 s36, s36, s94
	s_cmpk_gt_i32 s36, 0x5ff
	s_cselect_b64 s[42:43], -1, 0
	s_cmpk_lt_i32 s36, 0x600
	s_setprio 1
	s_waitcnt lgkmcnt(9)
	v_mfma_f32_32x32x16_bf16 v[114:129], v[130:133], v[140:143], v[114:129]
	s_waitcnt lgkmcnt(8)
	v_mfma_f32_32x32x16_bf16 v[98:113], v[130:133], v[170:173], v[98:113]
	s_waitcnt lgkmcnt(7)
	v_mfma_f32_32x32x16_bf16 v[50:65], v[130:133], v[152:155], v[50:65]
	s_waitcnt lgkmcnt(6)
	v_mfma_f32_32x32x16_bf16 v[34:49], v[130:133], v[174:177], v[34:49]
	v_mfma_f32_32x32x16_bf16 v[82:97], v[166:169], v[140:143], v[82:97]
	v_mfma_f32_32x32x16_bf16 v[66:81], v[166:169], v[170:173], v[66:81]
	v_mfma_f32_32x32x16_bf16 v[18:33], v[166:169], v[152:155], v[18:33]
	v_mfma_f32_32x32x16_bf16 v[2:17], v[166:169], v[174:177], v[2:17]
	s_setprio 0
	v_add_u32_e32 v130, v0, v149
	v_add_u32_e32 v140, v198, v150
	v_add_u32_e32 v144, v199, v147
	ds_read_b128 v[130:133], v130
	ds_read_b128 v[140:143], v140
	v_add_u32_e32 v147, v200, v148
	ds_read_b128 v[148:151], v144
	ds_read_b128 v[152:155], v147
	v_add_u32_e32 v144, v201, v145
	v_add_u32_e32 v160, v202, v146
	ds_read_b128 v[144:147], v144
	ds_read_b128 v[166:169], v160
	s_setprio 1
	s_waitcnt lgkmcnt(9)
; DI f32x16 mfma(bf16x8 a, bf16x8 b, f32x16 c) { return __builtin_amdgcn_mfma_f32_32x32x16_bf16(a, b, c, 0, 0, 0); }
; DI int launder(int x) { asm volatile("" : "+v"(x)); return x; }
; template <int BK> DI int swz(int row) { constexpr int CPR = BK / 8; return (row / (16 / CPR)) % CPR; }
; DI void wait_vm0() { asm volatile("s_waitcnt vmcnt(0)" ::: "memory"); }
;     ...
;     for (int kk = 0; kk < NKK; ++kk) {
;       if (kk + 1 < NKK) {
;         const int ch = (kk + 1) * 2 + hh;
; #pragma unroll
;         for (int mt = 0; mt < 2; ++mt) { int row = wm * 64 + mt * 32 + l31; fa[(kk + 1) & 1][mt] = *(const bf16x8*)(cur + row * (BK * 2) + ((ch ^ swz<BK>(row)) << 4)); }
; #pragma unroll
;         for (int nt = 0; nt < NTW; ++nt) { int row = wn * (32 * NTW) + nt * 32 + l31; fb[(kk + 1) & 1][nt] = *(const bf16x8*)(cur + ABYTES + row * (BK * 2) + ((ch ^ swz<BK>(row)) << 4)); }
;       }
;       if (more) {
; #pragma unroll
;         for (int q = 0; q < PPK; ++q) {
;           const int pi = kk * PPK + q;
;           if (pi < NPA) stage_piece<BM, BK>(An, lda, nxt, tid, pi, wv);
;           else if (pi < NP) stage_piece<BN, BK>(Bn, ldb, nxt + ABYTES, tid, pi - NPA, wv);
;         }
;       }
;       __builtin_amdgcn_s_setprio(1);
; #pragma unroll
;       for (int mt = 0; mt < 2; ++mt)
; #pragma unroll
;         for (int nt = 0; nt < NTW; ++nt) acc[mt][nt] = mfma(fa[kk & 1][mt], fb[kk & 1][nt], acc[mt][nt]);
;       __builtin_amdgcn_s_setprio(0);
;       __builtin_amdgcn_sched_barrier(0);
;     }
;     wait_vm0();
;     __syncthreads();
;   }
;   if (has_next) { const int tid3 = launder(threadIdx.x); stage_tile<BM, BK>(A + (size_t)row0n * lda, lda, lds, tid3); stage_tile<BN, BK>(Bt + (size_t)col0n * ldb, ldb, lds + ABYTES, tid3); }
	v_mfma_f32_32x32x16_bf16 v[114:129], v[178:181], v[186:189], v[114:129]
	s_waitcnt lgkmcnt(8)
	v_mfma_f32_32x32x16_bf16 v[98:113], v[178:181], v[190:193], v[98:113]
	s_waitcnt lgkmcnt(7)
	v_mfma_f32_32x32x16_bf16 v[50:65], v[178:181], v[156:159], v[50:65]
	s_waitcnt lgkmcnt(6)
	v_mfma_f32_32x32x16_bf16 v[34:49], v[178:181], v[194:197], v[34:49]
	v_mfma_f32_32x32x16_bf16 v[82:97], v[182:185], v[186:189], v[82:97]
	v_mfma_f32_32x32x16_bf16 v[66:81], v[182:185], v[190:193], v[66:81]
	v_mfma_f32_32x32x16_bf16 v[18:33], v[182:185], v[156:159], v[18:33]
	v_mfma_f32_32x32x16_bf16 v[2:17], v[182:185], v[194:197], v[2:17]
	s_setprio 0
	v_add_u32_e32 v0, v0, v138
	v_add_u32_e32 v138, v198, v139
	ds_read_b128 v[156:159], v0
	ds_read_b128 v[170:173], v138
	v_add_u32_e32 v0, v199, v136
	v_add_u32_e32 v160, v200, v137
	ds_read_b128 v[136:139], v0
	ds_read_b128 v[174:177], v160
	v_add_u32_e32 v0, v201, v134
	v_add_u32_e32 v134, v202, v135
	ds_read_b128 v[178:181], v0
	ds_read_b128 v[182:185], v134
	s_setprio 1
	s_waitcnt lgkmcnt(9)
	v_mfma_f32_32x32x16_bf16 v[114:129], v[130:133], v[148:151], v[114:129]
	s_waitcnt lgkmcnt(8)
	v_mfma_f32_32x32x16_bf16 v[98:113], v[130:133], v[152:155], v[98:113]
	s_waitcnt lgkmcnt(7)
	v_mfma_f32_32x32x16_bf16 v[50:65], v[130:133], v[144:147], v[50:65]
	s_waitcnt lgkmcnt(6)
	v_mfma_f32_32x32x16_bf16 v[34:49], v[130:133], v[166:169], v[34:49]
	v_mfma_f32_32x32x16_bf16 v[82:97], v[140:143], v[148:151], v[82:97]
	v_mfma_f32_32x32x16_bf16 v[66:81], v[140:143], v[152:155], v[66:81]
	v_mfma_f32_32x32x16_bf16 v[18:33], v[140:143], v[144:147], v[18:33]
	v_mfma_f32_32x32x16_bf16 v[2:17], v[140:143], v[166:169], v[2:17]
	s_setprio 0
	s_setprio 1
	s_waitcnt lgkmcnt(3)
	v_mfma_f32_32x32x16_bf16 v[114:129], v[156:159], v[136:139], v[114:129]
	s_waitcnt lgkmcnt(2)
	v_mfma_f32_32x32x16_bf16 v[98:113], v[156:159], v[174:177], v[98:113]
	s_waitcnt lgkmcnt(1)
	v_mfma_f32_32x32x16_bf16 v[50:65], v[156:159], v[178:181], v[50:65]
	s_waitcnt lgkmcnt(0)
	v_mfma_f32_32x32x16_bf16 v[34:49], v[156:159], v[182:185], v[34:49]
	v_mfma_f32_32x32x16_bf16 v[82:97], v[170:173], v[136:139], v[82:97]
	v_mfma_f32_32x32x16_bf16 v[66:81], v[170:173], v[174:177], v[66:81]
	v_mfma_f32_32x32x16_bf16 v[18:33], v[170:173], v[178:181], v[18:33]
	v_mfma_f32_32x32x16_bf16 v[2:17], v[170:173], v[182:185], v[2:17]
	s_setprio 0
	s_waitcnt vmcnt(0)
	s_barrier
	s_cbranch_scc0 .LBB0_442
	v_mov_b32_e32 v132, v216
	s_lshl_b32 s3, s36, 3
	v_ashrrev_i32_e32 v0, 31, v132
	v_lshrrev_b32_e32 v130, 29, v0
	v_lshrrev_b32_e32 v0, 28, v0
	v_add_u32_e32 v0, v132, v0
	v_ashrrev_i32_e32 v0, 4, v0
	s_and_b32 s3, s3, 56
	s_bfe_u32 s7, s36, 0x30003
	v_lshrrev_b32_e32 v133, 29, v0
	s_or_b32 s3, s3, s7
	s_lshl_b32 s7, s36, 2
	v_add_u32_e32 v130, v132, v130
	v_add_u32_e32 v133, v0, v133
	s_and_b32 s30, s7, 0xffffff00
	s_lshl_b32 s3, s3, 19
	v_and_b32_e32 v131, 0xffffff8, v130
	v_and_b32_e32 v133, 0xffffff8, v133
	s_add_u32 s40, s12, s3
	v_sub_u32_e32 v131, v132, v131
	v_sub_u32_e32 v0, v0, v133
	v_lshlrev_b32_e32 v130, 8, v130
	v_readfirstlane_b32 s3, v132
	s_addc_u32 s41, s13, 0
	v_xor_b32_e32 v0, v0, v131
	v_and_b32_e32 v130, 0xfffff800, v130
	s_lshl_b32 s3, s3, 4
	v_lshl_add_u32 v0, v0, 4, v130
	s_and_b32 s3, s3, 0xfffffc00
	s_load_dwordx4 s[44:47], s[0:1], 0x1a0
	v_lshl_add_u64 v[130:131], s[40:41], 0, v[0:1]
	s_mov_b32 m0, s3
	v_lshl_add_u64 v[132:133], v[130:131], 0, s[58:59]
	global_load_lds_dwordx4 v0, s[40:41]
	s_add_i32 m0, s3, 0x2000
	s_ashr_i32 s31, s30, 31
	global_load_lds_dwordx4 v[132:133], off
	v_lshl_add_u64 v[132:133], v[130:131], 0, s[48:49]
	s_add_i32 m0, s3, 0x4000
	s_lshl_b64 s[30:31], s[30:31], 11
	global_load_lds_dwordx4 v[132:133], off
	s_add_i32 m0, s3, 0x6000
	s_waitcnt lgkmcnt(0)
	s_add_u32 s30, s46, s30
	v_lshl_add_u64 v[130:131], v[130:131], 0, s[50:51]
	s_addc_u32 s31, s47, s31
	global_load_lds_dwordx4 v[130:131], off
	v_lshl_add_u64 v[130:131], s[30:31], 0, v[0:1]
	s_add_i32 m0, s3, 0x8000
	v_lshl_add_u64 v[132:133], v[130:131], 0, s[58:59]
	global_load_lds_dwordx4 v0, s[30:31]
	s_add_i32 m0, s3, 0xa000
	s_nop 0
	global_load_lds_dwordx4 v[132:133], off
	v_lshl_add_u64 v[132:133], v[130:131], 0, s[48:49]
	s_add_i32 m0, s3, 0xc000
	v_lshl_add_u64 v[130:131], v[130:131], 0, s[50:51]
	global_load_lds_dwordx4 v[132:133], off
	s_add_i32 m0, s3, 0xe000
	s_nop 0
	global_load_lds_dwordx4 v[130:131], off

; DI f32x16 mfma(bf16x8 a, bf16x8 b, f32x16 c) { return __builtin_amdgcn_mfma_f32_32x32x16_bf16(a, b, c, 0, 0, 0); }
; DI int launder(int x) { asm volatile("" : "+v"(x)); return x; }
; template <int BK> DI int swz(int row) { constexpr int CPR = BK / 8; return (row / (16 / CPR)) % CPR; }
; DI void wait_vm0() { asm volatile("s_waitcnt vmcnt(0)" ::: "memory"); }
;     ...
;     for (int kk = 0; kk < NKK; ++kk) {
;       if (kk + 1 < NKK) {
;         const int ch = (kk + 1) * 2 + hh;
; #pragma unroll
;         for (int mt = 0; mt < 2; ++mt) { int row = wm * 64 + mt * 32 + l31; fa[(kk + 1) & 1][mt] = *(const bf16x8*)(cur + row * (BK * 2) + ((ch ^ swz<BK>(row)) << 4)); }
; #pragma unroll
;         for (int nt = 0; nt < NTW; ++nt) { int row = wn * (32 * NTW) + nt * 32 + l31; fb[(kk + 1) & 1][nt] = *(const bf16x8*)(cur + ABYTES + row * (BK * 2) + ((ch ^ swz<BK>(row)) << 4)); }
;       }
;       if (more) {
; #pragma unroll
;         for (int q = 0; q < PPK; ++q) {
;           const int pi = kk * PPK + q;
;           if (pi < NPA) stage_piece<BM, BK>(An, lda, nxt, tid, pi, wv);
;           else if (pi < NP) stage_piece<BN, BK>(Bn, ldb, nxt + ABYTES, tid, pi - NPA, wv);
;         }
;       }
;       __builtin_amdgcn_s_setprio(1);
; #pragma unroll
;       for (int mt = 0; mt < 2; ++mt)
; #pragma unroll
;         for (int nt = 0; nt < NTW; ++nt) acc[mt][nt] = mfma(fa[kk & 1][mt], fb[kk & 1][nt], acc[mt][nt]);
;       __builtin_amdgcn_s_setprio(0);
;       __builtin_amdgcn_sched_barrier(0);
;     }
;     wait_vm0();
;     __syncthreads();
;   }
;   if (has_next) { const int tid3 = launder(threadIdx.x); stage_tile<BM, BK>(A + (size_t)row0n * lda, lda, lds, tid3); stage_tile<BN, BK>(Bt + (size_t)col0n * ldb, ldb, lds + ABYTES, tid3); }
.Lk519_exit:
	v_mfma_f32_32x32x16_bf16 v[114:129], v[190:193], v[198:201], v[114:129]
	v_mfma_f32_32x32x16_bf16 v[98:113], v[190:193], v[202:205], v[98:113]
	v_mfma_f32_32x32x16_bf16 v[82:97], v[190:193], v[206:209], v[82:97]
	v_mfma_f32_32x32x16_bf16 v[66:81], v[190:193], v[210:213], v[66:81]
	v_mfma_f32_32x32x16_bf16 v[50:65], v[194:197], v[198:201], v[50:65]
	v_mfma_f32_32x32x16_bf16 v[34:49], v[194:197], v[202:205], v[34:49]
	v_mfma_f32_32x32x16_bf16 v[18:33], v[194:197], v[206:209], v[18:33]
	v_mfma_f32_32x32x16_bf16 v[2:17], v[194:197], v[210:213], v[2:17]
	s_waitcnt lgkmcnt(0)
	v_add_u32_e32 v0, 0x10000, v140
	v_add_u32_e32 v198, 0x10000, v142
	v_add_u32_e32 v130, v0, v141
	v_add_u32_e32 v140, v198, v144
	v_add_u32_e32 v199, 0x18000, v143
	v_add_u32_e32 v200, 0x18000, v152
	ds_read_b128 v[130:133], v130
	ds_read_b128 v[166:169], v140
	v_add_u32_e32 v140, v199, v151
	v_add_u32_e32 v144, v200, v154
	v_add_u32_e32 v201, 0x18000, v153
	ds_read_b128 v[140:143], v140
	ds_read_b128 v[170:173], v144
	v_add_u32_e32 v144, v201, v155
	v_add_u32_e32 v202, 0x18000, v156
	v_add_u32_e32 v151, v202, v164
	ds_read_b128 v[152:155], v144
	ds_read_b128 v[174:177], v151
	v_add_u32_e32 v144, v0, v161
	v_add_u32_e32 v151, v198, v163
	ds_read_b128 v[178:181], v144
	ds_read_b128 v[182:185], v151
	v_add_u32_e32 v144, v199, v159
	v_add_u32_e32 v151, v200, v160
	ds_read_b128 v[186:189], v144
	ds_read_b128 v[190:193], v151
	v_add_u32_e32 v144, v201, v157
	v_add_u32_e32 v151, v202, v158
	ds_read_b128 v[156:159], v144
	ds_read_b128 v[194:197], v151
	s_add_i32 s36, s36, s94
	s_cmpk_gt_i32 s36, 0x2ff
	s_cselect_b64 s[42:43], -1, 0
	s_cmpk_lt_i32 s36, 0x300
	s_setprio 1
	s_waitcnt lgkmcnt(9)
	v_mfma_f32_32x32x16_bf16 v[114:129], v[130:133], v[140:143], v[114:129]
	s_waitcnt lgkmcnt(8)
	v_mfma_f32_32x32x16_bf16 v[98:113], v[130:133], v[170:173], v[98:113]
	s_waitcnt lgkmcnt(7)
	v_mfma_f32_32x32x16_bf16 v[82:97], v[130:133], v[152:155], v[82:97]
	s_waitcnt lgkmcnt(6)
	v_mfma_f32_32x32x16_bf16 v[66:81], v[130:133], v[174:177], v[66:81]
	v_mfma_f32_32x32x16_bf16 v[50:65], v[166:169], v[140:143], v[50:65]
	v_mfma_f32_32x32x16_bf16 v[34:49], v[166:169], v[170:173], v[34:49]
	v_mfma_f32_32x32x16_bf16 v[18:33], v[166:169], v[152:155], v[18:33]
	v_mfma_f32_32x32x16_bf16 v[2:17], v[166:169], v[174:177], v[2:17]
	s_setprio 0
	v_add_u32_e32 v130, v0, v149
	v_add_u32_e32 v140, v198, v150
	v_add_u32_e32 v144, v199, v147
	ds_read_b128 v[130:133], v130
	ds_read_b128 v[140:143], v140
	v_add_u32_e32 v147, v200, v148
	ds_read_b128 v[148:151], v144
	ds_read_b128 v[152:155], v147
	v_add_u32_e32 v144, v201, v145
	v_add_u32_e32 v160, v202, v146
	ds_read_b128 v[144:147], v144
	ds_read_b128 v[166:169], v160
	s_setprio 1
	s_waitcnt lgkmcnt(9)
	v_mfma_f32_32x32x16_bf16 v[114:129], v[178:181], v[186:189], v[114:129]
	s_waitcnt lgkmcnt(8)
	v_mfma_f32_32x32x16_bf16 v[98:113], v[178:181], v[190:193], v[98:113]
	s_waitcnt lgkmcnt(7)
	v_mfma_f32_32x32x16_bf16 v[82:97], v[178:181], v[156:159], v[82:97]
	s_waitcnt lgkmcnt(6)
	v_mfma_f32_32x32x16_bf16 v[66:81], v[178:181], v[194:197], v[66:81]
	v_mfma_f32_32x32x16_bf16 v[50:65], v[182:185], v[186:189], v[50:65]
	v_mfma_f32_32x32x16_bf16 v[34:49], v[182:185], v[190:193], v[34:49]
	v_mfma_f32_32x32x16_bf16 v[18:33], v[182:185], v[156:159], v[18:33]
	v_mfma_f32_32x32x16_bf16 v[2:17], v[182:185], v[194:197], v[2:17]
	s_setprio 0
	v_add_u32_e32 v0, v0, v138
	v_add_u32_e32 v138, v198, v139
	ds_read_b128 v[156:159], v0
	ds_read_b128 v[170:173], v138
	v_add_u32_e32 v0, v199, v136
	v_add_u32_e32 v160, v200, v137
	ds_read_b128 v[136:139], v0
	ds_read_b128 v[174:177], v160
	v_add_u32_e32 v0, v201, v134
	v_add_u32_e32 v134, v202, v135
	ds_read_b128 v[178:181], v0
	ds_read_b128 v[182:185], v134
	s_setprio 1
	s_waitcnt lgkmcnt(9)
	v_mfma_f32_32x32x16_bf16 v[114:129], v[130:133], v[148:151], v[114:129]
	s_waitcnt lgkmcnt(8)
	v_mfma_f32_32x32x16_bf16 v[98:113], v[130:133], v[152:155], v[98:113]
	s_waitcnt lgkmcnt(7)
	v_mfma_f32_32x32x16_bf16 v[82:97], v[130:133], v[144:147], v[82:97]
	s_waitcnt lgkmcnt(6)
	v_mfma_f32_32x32x16_bf16 v[66:81], v[130:133], v[166:169], v[66:81]
	v_mfma_f32_32x32x16_bf16 v[50:65], v[140:143], v[148:151], v[50:65]
	v_mfma_f32_32x32x16_bf16 v[34:49], v[140:143], v[152:155], v[34:49]
	v_mfma_f32_32x32x16_bf16 v[18:33], v[140:143], v[144:147], v[18:33]
	v_mfma_f32_32x32x16_bf16 v[2:17], v[140:143], v[166:169], v[2:17]
	s_setprio 0
	s_setprio 1
	s_waitcnt lgkmcnt(3)
	v_mfma_f32_32x32x16_bf16 v[114:129], v[156:159], v[136:139], v[114:129]
	s_waitcnt lgkmcnt(2)
	v_mfma_f32_32x32x16_bf16 v[98:113], v[156:159], v[174:177], v[98:113]
	s_waitcnt lgkmcnt(1)
	v_mfma_f32_32x32x16_bf16 v[82:97], v[156:159], v[178:181], v[82:97]
	s_waitcnt lgkmcnt(0)
	v_mfma_f32_32x32x16_bf16 v[66:81], v[156:159], v[182:185], v[66:81]
	v_mfma_f32_32x32x16_bf16 v[50:65], v[170:173], v[136:139], v[50:65]
	v_mfma_f32_32x32x16_bf16 v[34:49], v[170:173], v[174:177], v[34:49]
	v_mfma_f32_32x32x16_bf16 v[18:33], v[170:173], v[178:181], v[18:33]
	v_mfma_f32_32x32x16_bf16 v[2:17], v[170:173], v[182:185], v[2:17]
	s_setprio 0
	s_waitcnt vmcnt(0)
	s_barrier
	s_cbranch_scc0 .LBB0_522
	v_mov_b32_e32 v132, v216
	s_lshl_b32 s3, s36, 3
	v_ashrrev_i32_e32 v0, 31, v132
	v_lshrrev_b32_e32 v130, 29, v0
	v_lshrrev_b32_e32 v0, 28, v0
	v_add_u32_e32 v0, v132, v0
	v_ashrrev_i32_e32 v0, 4, v0
	s_and_b32 s3, s3, 56
	s_bfe_u32 s7, s36, 0x30003
	v_lshrrev_b32_e32 v133, 29, v0
	s_or_b32 s3, s3, s7
	s_lshl_b32 s7, s36, 2
	v_add_u32_e32 v130, v132, v130
	v_add_u32_e32 v133, v0, v133
	s_and_b32 s30, s7, 0xffffff00
	s_lshl_b32 s3, s3, 19
	v_and_b32_e32 v131, 0xffffff8, v130
	v_and_b32_e32 v133, 0xffffff8, v133
	s_add_u32 s44, s12, s3
	v_sub_u32_e32 v131, v132, v131
	v_sub_u32_e32 v0, v0, v133
	v_lshlrev_b32_e32 v130, 8, v130
	v_readfirstlane_b32 s3, v132
	s_addc_u32 s45, s13, 0
	v_xor_b32_e32 v0, v0, v131
	v_and_b32_e32 v130, 0xfffff800, v130
	s_lshl_b32 s3, s3, 4
	v_lshl_add_u32 v0, v0, 4, v130
	s_and_b32 s3, s3, 0xfffffc00
	v_lshl_add_u64 v[130:131], s[44:45], 0, v[0:1]
	s_mov_b32 m0, s3
	v_lshl_add_u64 v[132:133], v[130:131], 0, s[58:59]
	global_load_lds_dwordx4 v0, s[44:45]
	s_add_i32 m0, s3, 0x2000
	s_ashr_i32 s31, s30, 31
	global_load_lds_dwordx4 v[132:133], off
	v_lshl_add_u64 v[132:133], v[130:131], 0, s[48:49]
	s_add_i32 m0, s3, 0x4000
	s_lshl_b64 s[30:31], s[30:31], 11
	global_load_lds_dwordx4 v[132:133], off
	s_add_i32 m0, s3, 0x6000
	s_add_u32 s30, s40, s30
	v_lshl_add_u64 v[130:131], v[130:131], 0, s[50:51]
	s_addc_u32 s31, s41, s31
	global_load_lds_dwordx4 v[130:131], off
	v_lshl_add_u64 v[130:131], s[30:31], 0, v[0:1]
	s_add_i32 m0, s3, 0x8000
	v_lshl_add_u64 v[132:133], v[130:131], 0, s[58:59]
	global_load_lds_dwordx4 v0, s[30:31]
	s_add_i32 m0, s3, 0xa000
	s_nop 0
	global_load_lds_dwordx4 v[132:133], off
	v_lshl_add_u64 v[132:133], v[130:131], 0, s[48:49]
	s_add_i32 m0, s3, 0xc000
	v_lshl_add_u64 v[130:131], v[130:131], 0, s[50:51]
	global_load_lds_dwordx4 v[132:133], off
	s_add_i32 m0, s3, 0xe000
	s_nop 0
	global_load_lds_dwordx4 v[130:131], off

;   DI void pre(int grow0, int gcol0, int lane, int w, char* lds) { xpass(0, grow0, gcol0, lane, w, lds); }
;     ...
;   const bf16_t* Ag = A + (size_t)row0 * lda; const bf16_t* Bg = Bt + (size_t)col0 * ldb;
;   const int wv = __builtin_amdgcn_readfirstlane(tid >> 6);
;   __syncthreads();
;   if (!pre) { stage_tile<BM, BK>(Ag, lda, lds, tid); stage_tile<BN, BK>(Bg, ldb, lds + ABYTES, tid); }
; __global__ void __launch_bounds__(NT) fwd_megakernel(Params p) {
;     ...
;         for (int t = blockIdx.x; t < 256; t += gridDim.x) {
;           int layer = t >> 6, pm = t & 7, pn = (t >> 3) & 7;
;           EpiXkv e{p.Kx + (size_t)layer * 2048 * D_, p.Vxt + (size_t)layer * 32 * 256 * 256};
;           gemm_tile<4, 64>(p.memb, D_, p.wxkv[layer], D_, D_, pm * 256, pn * 256, lds, e);
.LBB0_626:
	s_lshl_b32 s2, s37, 11
	s_ashr_i32 s6, s40, 6
	s_and_b32 s41, s2, 0x380000
	s_lshl_b32 s2, s36, 11
	s_ashr_i32 s7, s6, 31
	s_and_b32 s35, s2, 0x380000
	s_lshl_b64 s[2:3], s[6:7], 3
	s_add_u32 s2, s0, s2
	s_addc_u32 s3, s1, s3
	v_mov_b32_e32 v4, v216
	s_load_dwordx2 s[30:31], s[2:3], 0x1d8
	s_lshl_b32 s2, s40, 8
	s_and_b32 s2, s2, 0x700
	v_ashrrev_i32_e32 v0, 6, v4
	s_lshl_b32 s3, s40, 5
	v_lshrrev_b32_e32 v2, 30, v0
	s_and_b32 s3, s3, 0x700
	s_waitcnt lgkmcnt(0)
	v_add_u32_e32 v6, v0, v2
	s_lshl_b32 s34, s2, 11
	v_ashrrev_i32_e32 v7, 2, v6
	s_add_u32 s42, s14, s34
	v_mul_i32_i24_e32 v2, 4, v7
	s_addc_u32 s43, s15, 0
	s_lshl_b32 s34, s3, 11
	v_sub_u32_e32 v9, v0, v2
	s_add_u32 s44, s30, s34
	v_readfirstlane_b32 s34, v0
	v_ashrrev_i32_e32 v0, 31, v4
	v_lshrrev_b32_e32 v2, 29, v0
	v_lshrrev_b32_e32 v0, 28, v0
	v_add_u32_e32 v0, v4, v0
	v_ashrrev_i32_e32 v0, 4, v0
	v_lshrrev_b32_e32 v5, 29, v0
	v_add_u32_e32 v2, v4, v2
	v_add_u32_e32 v5, v0, v5
	v_and_b32_e32 v3, 0xffffff8, v2
	v_and_b32_e32 v5, 0xffffff8, v5
	v_sub_u32_e32 v3, v4, v3
	v_sub_u32_e32 v0, v0, v5
	v_lshlrev_b32_e32 v2, 8, v2
	v_readfirstlane_b32 s46, v4
	s_addc_u32 s45, s31, 0
	v_xor_b32_e32 v0, v0, v3
	v_and_b32_e32 v2, 0xfffff800, v2
	s_lshl_b32 s46, s46, 4
	v_lshl_add_u32 v0, v0, 4, v2
	s_and_b32 s46, s46, 0xfffffc00
	v_lshl_add_u64 v[2:3], s[42:43], 0, v[0:1]
	s_mov_b32 m0, s46
	v_lshrrev_b32_e32 v8, 5, v4
	v_and_b32_e32 v10, 31, v4
	v_bfe_u32 v11, v4, 5, 1
	s_waitcnt vmcnt(0)
	s_barrier
	global_load_lds_dwordx4 v0, s[42:43]
	v_lshl_add_u64 v[4:5], v[2:3], 0, s[58:59]
	s_add_i32 m0, s46, 0x2000
	s_lshl_b32 s34, s34, 10
	global_load_lds_dwordx4 v[4:5], off
	v_lshl_add_u64 v[4:5], v[2:3], 0, s[48:49]
	s_add_i32 m0, s46, 0x4000
	v_lshl_add_u64 v[2:3], v[2:3], 0, s[50:51]
	global_load_lds_dwordx4 v[4:5], off
	s_add_i32 m0, s46, 0x6000
	s_nop 0
	global_load_lds_dwordx4 v[2:3], off
	v_lshl_add_u64 v[2:3], s[44:45], 0, v[0:1]
	s_add_i32 m0, s46, 0x8000
	v_lshl_add_u64 v[4:5], v[2:3], 0, s[58:59]
	global_load_lds_dwordx4 v0, s[44:45]
	s_add_i32 m0, s46, 0xa000
	s_nop 0
	global_load_lds_dwordx4 v[4:5], off
	v_lshl_add_u64 v[4:5], v[2:3], 0, s[48:49]
	s_add_i32 m0, s46, 0xc000
	v_lshl_add_u64 v[2:3], v[2:3], 0, s[50:51]
	global_load_lds_dwordx4 v[4:5], off
	s_add_i32 m0, s46, 0xe000
	v_bfe_u32 v4, v9, 25, 1
	global_load_lds_dwordx4 v[2:3], off
	v_lshlrev_b32_e32 v2, 6, v9
	v_or_b32_e32 v2, v2, v10
	v_lshlrev_b32_e32 v136, 7, v2
	v_add_u32_e32 v5, v2, v4
	v_or_b32_e32 v2, 32, v2
	v_lshlrev_b32_e32 v142, 7, v2
	v_add_u32_e32 v2, v2, v4
	v_ashrrev_i32_e32 v4, 1, v2
	v_ashrrev_i32_e32 v2, 31, v2
	v_lshrrev_b32_e32 v2, 29, v2
	v_lshl_or_b32 v3, v7, 7, v10
	v_ashrrev_i32_e32 v7, 1, v5
	v_ashrrev_i32_e32 v5, 31, v5
	v_add_u32_e32 v2, v4, v2
	v_lshrrev_b32_e32 v5, 29, v5
	v_and_b32_e32 v2, -8, v2
	v_add_u32_e32 v5, v7, v5
	v_sub_u32_e32 v2, v4, v2
	v_and_b32_e32 v5, -8, v5
	v_bitop3_b32 v4, v2, v8, 1 bitop3:0x78
	v_sub_u32_e32 v5, v7, v5
	v_lshlrev_b32_e32 v144, 4, v4
	v_lshrrev_b32_e32 v4, 31, v6
	v_bitop3_b32 v7, v5, v8, 1 bitop3:0x78
	v_add_u32_e32 v6, v3, v4
	v_lshlrev_b32_e32 v141, 4, v7
	v_ashrrev_i32_e32 v7, 1, v6
	v_ashrrev_i32_e32 v6, 31, v6
	v_lshrrev_b32_e32 v6, 29, v6
	v_add_u32_e32 v6, v7, v6
	v_and_b32_e32 v6, -8, v6
	v_sub_u32_e32 v6, v7, v6
	v_bitop3_b32 v7, v6, v8, 1 bitop3:0x78
	v_lshlrev_b32_e32 v151, 4, v7
	v_or_b32_e32 v7, 32, v3
	v_lshlrev_b32_e32 v152, 7, v7
	v_add_u32_e32 v7, v7, v4
	v_ashrrev_i32_e32 v9, 1, v7
	v_ashrrev_i32_e32 v7, 31, v7
	v_lshrrev_b32_e32 v7, 29, v7
	v_add_u32_e32 v7, v9, v7
	v_and_b32_e32 v7, -8, v7
	v_sub_u32_e32 v7, v9, v7
	v_bitop3_b32 v9, v7, v8, 1 bitop3:0x78
	v_lshlrev_b32_e32 v143, 7, v3
	v_lshlrev_b32_e32 v154, 4, v9
	v_or_b32_e32 v9, 64, v3
	v_or_b32_e32 v3, 0x60, v3
	v_lshlrev_b32_e32 v156, 7, v3
	v_add_u32_e32 v3, v3, v4
	v_lshlrev_b32_e32 v153, 7, v9
	v_add_u32_e32 v9, v9, v4
	v_ashrrev_i32_e32 v4, 1, v3
	v_ashrrev_i32_e32 v3, 31, v3
	v_lshrrev_b32_e32 v3, 29, v3
	v_add_u32_e32 v3, v4, v3
	v_and_b32_e32 v3, -8, v3
	v_sub_u32_e32 v3, v4, v3
	v_ashrrev_i32_e32 v10, 1, v9
	v_ashrrev_i32_e32 v9, 31, v9
	v_bitop3_b32 v4, v3, v8, 1 bitop3:0x78
	v_lshrrev_b32_e32 v9, 29, v9
	v_lshlrev_b32_e32 v164, 4, v4
	v_bitop3_b32 v4, v5, v11, 2 bitop3:0x1e
	v_add_u32_e32 v9, v10, v9
	v_lshlrev_b32_e32 v161, 4, v4
	v_bitop3_b32 v4, v2, v11, 2 bitop3:0x1e
	v_and_b32_e32 v9, -8, v9
	v_lshlrev_b32_e32 v163, 4, v4
	v_bitop3_b32 v4, v6, v11, 2 bitop3:0x1e
	v_sub_u32_e32 v9, v10, v9
	v_lshlrev_b32_e32 v159, 4, v4
	v_bitop3_b32 v4, v7, v11, 2 bitop3:0x1e
	v_lshlrev_b32_e32 v160, 4, v4
	v_bitop3_b32 v4, v9, v11, 2 bitop3:0x1e
	v_lshlrev_b32_e32 v157, 4, v4
	v_bitop3_b32 v4, v3, v11, 2 bitop3:0x1e
	v_lshlrev_b32_e32 v158, 4, v4
	v_bitop3_b32 v4, v5, v11, 4 bitop3:0x1e
	v_lshlrev_b32_e32 v149, 4, v4
	v_bitop3_b32 v4, v2, v11, 4 bitop3:0x1e
	v_bitop3_b32 v2, v2, v11, 6 bitop3:0x1e
	v_lshlrev_b32_e32 v150, 4, v4
	v_bitop3_b32 v4, v6, v11, 4 bitop3:0x1e
	v_lshlrev_b32_e32 v140, 4, v2
	v_bitop3_b32 v2, v6, v11, 6 bitop3:0x1e
	v_lshlrev_b32_e32 v147, 4, v4
	v_bitop3_b32 v4, v7, v11, 4 bitop3:0x1e
	v_lshlrev_b32_e32 v137, 4, v2
	v_bitop3_b32 v2, v7, v11, 6 bitop3:0x1e
	s_add_u32 s42, s14, s41
	v_lshlrev_b32_e32 v148, 4, v4
	v_bitop3_b32 v4, v9, v11, 4 bitop3:0x1e
	v_lshlrev_b32_e32 v138, 4, v2
	v_bitop3_b32 v2, v9, v11, 6 bitop3:0x1e
	s_addc_u32 s43, s15, 0
	s_waitcnt vmcnt(0)
; DI f32x16 zero16() { f32x16 z; for (int i = 0; i < 16; ++i) z[i] = 0.f; return z; }
; template <int BK> DI int swz(int row) { constexpr int CPR = BK / 8; return (row / (16 / CPR)) % CPR; }
; DI void wait_vm0() { asm volatile("s_waitcnt vmcnt(0)" ::: "memory"); }
;   DI void pre(int grow0, int gcol0, int lane, int w, char* lds) { xpass(0, grow0, gcol0, lane, w, lds); }
;     ...
;   f32x16 acc[2][NTW];
; #pragma unroll
;   for (int a = 0; a < 2; ++a)
; #pragma unroll
;     for (int b = 0; b < NTW; ++b) acc[a][b] = zero16();
;   const bf16_t* Ag = A + (size_t)row0 * lda; const bf16_t* Bg = Bt + (size_t)col0 * ldb;
;   const int wv = __builtin_amdgcn_readfirstlane(tid >> 6);
;   __syncthreads();
;   if (!pre) { stage_tile<BM, BK>(Ag, lda, lds, tid); stage_tile<BN, BK>(Bg, ldb, lds + ABYTES, tid); }
;   wait_vm0();
;   __syncthreads();
;   const int nk = K / BK;
;   for (int kt = 0; kt < nk; ++kt) {
;     char* cur = lds + (kt & 1) * STG; char* nxt = lds + ((kt + 1) & 1) * STG;
;     const bool more = kt + 1 < nk;
;     const bf16_t* An = Ag + (kt + 1) * BK; const bf16_t* Bn = Bg + (kt + 1) * BK;
;     if (!more) epi.pre(row0 + wm * 64, col0 + wn * (32 * NTW), lane, w, lds);
;     bf16x8 fa[2][2], fb[2][NTW];
; #pragma unroll
;     for (int mt = 0; mt < 2; ++mt) { int row = wm * 64 + mt * 32 + l31; fa[0][mt] = *(const bf16x8*)(cur + row * (BK * 2) + ((hh ^ swz<BK>(row)) << 4)); }
; #pragma unroll
;     for (int nt = 0; nt < NTW; ++nt) { int row = wn * (32 * NTW) + nt * 32 + l31; fb[0][nt] = *(const bf16x8*)(cur + ABYTES + row * (BK * 2) + ((hh ^ swz<BK>(row)) << 4)); }
; #pragma unroll
;     for (int kk = 0; kk < NKK; ++kk) {
;       if (kk + 1 < NKK) {
;         const int ch = (kk + 1) * 2 + hh;
; #pragma unroll
;         for (int mt = 0; mt < 2; ++mt) { int row = wm * 64 + mt * 32 + l31; fa[(kk + 1) & 1][mt] = *(const bf16x8*)(cur + row * (BK * 2) + ((ch ^ swz<BK>(row)) << 4)); }
; #pragma unroll
;         for (int nt = 0; nt < NTW; ++nt) { int row = wn * (32 * NTW) + nt * 32 + l31; fb[(kk + 1) & 1][nt] = *(const bf16x8*)(cur + ABYTES + row * (BK * 2) + ((ch ^ swz<BK>(row)) << 4)); }
;       }
;       if (more) {
; #pragma unroll
;         for (int q = 0; q < PPK; ++q) {
;           const int pi = kk * PPK + q;
;           if (pi < NPA) stage_piece<BM, BK>(An, lda, nxt, tid, pi, wv);
	v_lshlrev_b32_e32 v145, 4, v4
	v_bitop3_b32 v4, v3, v11, 4 bitop3:0x1e
	v_lshlrev_b32_e32 v134, 4, v2
	v_bitop3_b32 v2, v3, v11, 6 bitop3:0x1e
	s_add_u32 s30, s30, s35
	v_bitop3_b32 v10, v9, v8, 1 bitop3:0x78
	v_lshlrev_b32_e32 v146, 4, v4
	v_bitop3_b32 v4, v5, v11, 6 bitop3:0x1e
	v_lshlrev_b32_e32 v135, 4, v2
	s_addc_u32 s31, s31, 0
	v_mov_b32_e32 v2, 0
	v_lshlrev_b32_e32 v155, 4, v10
	v_lshlrev_b32_e32 v139, 4, v4
	v_lshl_add_u64 v[130:131], s[42:43], 0, v[0:1]
	v_lshl_add_u64 v[132:133], s[30:31], 0, v[0:1]
	s_mov_b64 s[30:31], 0
	s_mov_b32 s35, 0x10000
	v_mov_b32_e32 v3, v2
	v_mov_b32_e32 v4, v2
	v_mov_b32_e32 v5, v2
	v_mov_b32_e32 v6, v2
	v_mov_b32_e32 v7, v2
	v_mov_b32_e32 v8, v2
	v_mov_b32_e32 v9, v2
	v_mov_b32_e32 v10, v2
	v_mov_b32_e32 v11, v2
	v_mov_b32_e32 v12, v2
	v_mov_b32_e32 v13, v2
	v_mov_b32_e32 v14, v2
	v_mov_b32_e32 v15, v2
	v_mov_b32_e32 v16, v2
	v_mov_b32_e32 v17, v2
	v_mov_b32_e32 v18, v2
	v_mov_b32_e32 v19, v2
	v_mov_b32_e32 v20, v2
	v_mov_b32_e32 v21, v2
	v_mov_b32_e32 v22, v2
	v_mov_b32_e32 v23, v2
	v_mov_b32_e32 v24, v2
	v_mov_b32_e32 v25, v2
	v_mov_b32_e32 v26, v2
	v_mov_b32_e32 v27, v2
	v_mov_b32_e32 v28, v2
	v_mov_b32_e32 v29, v2
	v_mov_b32_e32 v30, v2
	v_mov_b32_e32 v31, v2
	v_mov_b32_e32 v32, v2
	v_mov_b32_e32 v33, v2
	v_mov_b32_e32 v34, v2
	v_mov_b32_e32 v35, v2
	v_mov_b32_e32 v36, v2
	v_mov_b32_e32 v37, v2
	v_mov_b32_e32 v38, v2
	v_mov_b32_e32 v39, v2
	v_mov_b32_e32 v40, v2
	v_mov_b32_e32 v41, v2
	v_mov_b32_e32 v42, v2
	v_mov_b32_e32 v43, v2
	v_mov_b32_e32 v44, v2
	v_mov_b32_e32 v45, v2
	v_mov_b32_e32 v46, v2
	v_mov_b32_e32 v47, v2
	v_mov_b32_e32 v48, v2
	v_mov_b32_e32 v49, v2
	v_mov_b32_e32 v50, v2
	v_mov_b32_e32 v51, v2
	v_mov_b32_e32 v52, v2
	v_mov_b32_e32 v53, v2
	v_mov_b32_e32 v54, v2
	v_mov_b32_e32 v55, v2
	v_mov_b32_e32 v56, v2
	v_mov_b32_e32 v57, v2
	v_mov_b32_e32 v58, v2
	v_mov_b32_e32 v59, v2
	v_mov_b32_e32 v60, v2
	v_mov_b32_e32 v61, v2
	v_mov_b32_e32 v62, v2
	v_mov_b32_e32 v63, v2
	v_mov_b32_e32 v64, v2
	v_mov_b32_e32 v65, v2
	v_mov_b32_e32 v66, v2
	v_mov_b32_e32 v67, v2
	v_mov_b32_e32 v68, v2
	v_mov_b32_e32 v69, v2
	v_mov_b32_e32 v70, v2
	v_mov_b32_e32 v71, v2
	v_mov_b32_e32 v72, v2
	v_mov_b32_e32 v73, v2
	v_mov_b32_e32 v74, v2
	v_mov_b32_e32 v75, v2
	v_mov_b32_e32 v76, v2
	v_mov_b32_e32 v77, v2
	v_mov_b32_e32 v78, v2
	v_mov_b32_e32 v79, v2
	v_mov_b32_e32 v80, v2
	v_mov_b32_e32 v81, v2
	v_mov_b32_e32 v82, v2
	v_mov_b32_e32 v83, v2
	v_mov_b32_e32 v84, v2
	v_mov_b32_e32 v85, v2
	v_mov_b32_e32 v86, v2
	v_mov_b32_e32 v87, v2
	v_mov_b32_e32 v88, v2
	v_mov_b32_e32 v89, v2
	v_mov_b32_e32 v90, v2
	v_mov_b32_e32 v91, v2
	v_mov_b32_e32 v92, v2
	v_mov_b32_e32 v93, v2
	v_mov_b32_e32 v94, v2
	v_mov_b32_e32 v95, v2
	v_mov_b32_e32 v96, v2
	v_mov_b32_e32 v97, v2
	v_mov_b32_e32 v98, v2
	v_mov_b32_e32 v99, v2
	v_mov_b32_e32 v100, v2
	v_mov_b32_e32 v101, v2
	v_mov_b32_e32 v102, v2
	v_mov_b32_e32 v103, v2
	v_mov_b32_e32 v104, v2
	v_mov_b32_e32 v105, v2
	v_mov_b32_e32 v106, v2
	v_mov_b32_e32 v107, v2
	v_mov_b32_e32 v108, v2
	v_mov_b32_e32 v109, v2
	v_mov_b32_e32 v110, v2
	v_mov_b32_e32 v111, v2
	v_mov_b32_e32 v112, v2
	v_mov_b32_e32 v113, v2
	v_mov_b32_e32 v114, v2
	v_mov_b32_e32 v115, v2
	v_mov_b32_e32 v116, v2
	v_mov_b32_e32 v117, v2
	v_mov_b32_e32 v118, v2
	v_mov_b32_e32 v119, v2
	v_mov_b32_e32 v120, v2
	v_mov_b32_e32 v121, v2
	v_mov_b32_e32 v122, v2
	v_mov_b32_e32 v123, v2
	v_mov_b32_e32 v124, v2
	v_mov_b32_e32 v125, v2
	v_mov_b32_e32 v126, v2
	v_mov_b32_e32 v127, v2
	v_mov_b32_e32 v128, v2
	v_mov_b32_e32 v129, v2
	s_waitcnt vmcnt(0) lgkmcnt(0)
	s_barrier
	v_add_u32_e32 v166, v136, v141
	v_add_u32_e32 v170, v142, v144
	ds_read_b128 v[166:169], v166
	v_add_u32_e32 v174, v143, v151
	ds_read_b128 v[170:173], v170
	v_add_u32_e32 v178, v152, v154
	ds_read_b128 v[174:177], v174 offset:32768
	v_add_u32_e32 v182, v153, v155
	ds_read_b128 v[178:181], v178 offset:32768
	v_add_u32_e32 v186, v156, v164
	ds_read_b128 v[182:185], v182 offset:32768
	ds_read_b128 v[186:189], v186 offset:32768
	s_and_b32 s42, s35, 0x10000
	s_add_i32 s41, s42, s34
	v_lshl_add_u64 v[214:215], v[130:131], 0, s[30:31]
	v_lshl_add_u64 v[226:227], v[132:133], 0, s[30:31]
	s_mov_b32 m0, s41
	v_lshl_add_u64 v[228:229], v[214:215], 0, s[28:29]
	global_load_lds_dwordx4 v[228:229], off
	s_add_i32 m0, s41, 0x2000
	v_lshl_add_u64 v[228:229], v[214:215], 0, s[24:25]
	global_load_lds_dwordx4 v[228:229], off
	s_add_i32 m0, s41, 0x4000
	v_lshl_add_u64 v[228:229], v[214:215], 0, s[26:27]
	global_load_lds_dwordx4 v[228:229], off
	s_add_i32 m0, s41, 0x6000
	v_lshl_add_u64 v[228:229], v[214:215], 0, s[38:39]
	global_load_lds_dwordx4 v[228:229], off
	s_add_i32 m0, s41, 0x8000
	v_lshl_add_u64 v[228:229], v[226:227], 0, s[28:29]
	global_load_lds_dwordx4 v[228:229], off
	s_add_i32 m0, s41, 0xa000
	v_lshl_add_u64 v[228:229], v[226:227], 0, s[24:25]
	global_load_lds_dwordx4 v[228:229], off
	s_add_i32 m0, s41, 0xc000
	v_lshl_add_u64 v[228:229], v[226:227], 0, s[26:27]
	global_load_lds_dwordx4 v[228:229], off
	s_add_i32 m0, s41, 0xe000
	v_lshl_add_u64 v[228:229], v[226:227], 0, s[38:39]
	global_load_lds_dwordx4 v[228:229], off
; template <int ROWS, int BK>
; DI void stage_piece(const bf16_t* g, int ld, char* l, int tid, int i, int wv) {
;   constexpr int CPR = BK / 8, TOT = ROWS * CPR;
;   const int row0 = tid / CPR, pc = tid % CPR; const int c = pc ^ swz<BK>(row0);
;   const unsigned voff = (unsigned)(row0 * ld + c * 8) * 2u;
;   if (TOT % NT == 0 || tid + i * NT < TOT) {
;     const char* gb = (const char*)g + (size_t)i * (NT / CPR) * ld * 2;
;     ...
;   for (int kt = 0; kt < nk; ++kt) {
;     char* cur = lds + (kt & 1) * STG; char* nxt = lds + ((kt + 1) & 1) * STG;
;     const bool more = kt + 1 < nk;
;     const bf16_t* An = Ag + (kt + 1) * BK; const bf16_t* Bn = Bg + (kt + 1) * BK;
;     if (!more) epi.pre(row0 + wm * 64, col0 + wn * (32 * NTW), lane, w, lds);
;     bf16x8 fa[2][2], fb[2][NTW];
; #pragma unroll
;     for (int mt = 0; mt < 2; ++mt) { int row = wm * 64 + mt * 32 + l31; fa[0][mt] = *(const bf16x8*)(cur + row * (BK * 2) + ((hh ^ swz<BK>(row)) << 4)); }
; #pragma unroll
;     for (int nt = 0; nt < NTW; ++nt) { int row = wn * (32 * NTW) + nt * 32 + l31; fb[0][nt] = *(const bf16x8*)(cur + ABYTES + row * (BK * 2) + ((hh ^ swz<BK>(row)) << 4)); }
; #pragma unroll
;     for (int kk = 0; kk < NKK; ++kk) {
;       if (kk + 1 < NKK) {
;         const int ch = (kk + 1) * 2 + hh;
; #pragma unroll
;         for (int mt = 0; mt < 2; ++mt) { int row = wm * 64 + mt * 32 + l31; fa[(kk + 1) & 1][mt] = *(const bf16x8*)(cur + row * (BK * 2) + ((ch ^ swz<BK>(row)) << 4)); }
; #pragma unroll
;         for (int nt = 0; nt < NTW; ++nt) { int row = wn * (32 * NTW) + nt * 32 + l31; fb[(kk + 1) & 1][nt] = *(const bf16x8*)(cur + ABYTES + row * (BK * 2) + ((ch ^ swz<BK>(row)) << 4)); }
;       }
;       if (more) {
; #pragma unroll
;         for (int q = 0; q < PPK; ++q) {
;           const int pi = kk * PPK + q;
;           if (pi < NPA) stage_piece<BM, BK>(An, lda, nxt, tid, pi, wv);
;           else if (pi < NP) stage_piece<BN, BK>(Bn, ldb, nxt + ABYTES, tid, pi - NPA, wv);
;         }
;       }
;       __builtin_amdgcn_s_setprio(1);
; #pragma unroll
;       for (int mt = 0; mt < 2; ++mt)
; #pragma unroll
;         for (int nt = 0; nt < NTW; ++nt) acc[mt][nt] = mfma(fa[kk & 1][mt], fb[kk & 1][nt], acc[mt][nt]);
;       __builtin_amdgcn_s_setprio(0);
;       __builtin_amdgcn_sched_barrier(0);
;     }
;     wait_vm0();
;     __syncthreads();
.LBB0_627:
	s_and_b32 s42, s35, 0x10000
	s_xor_b32 s100, s42, 0x10000
	v_add3_u32 v190, s100, v136, v161
	v_add3_u32 v194, s100, v142, v163
	ds_read_b128 v[190:193], v190
	v_add3_u32 v198, s100, v143, v159
	ds_read_b128 v[194:197], v194
	v_add3_u32 v202, s100, v152, v160
	ds_read_b128 v[198:201], v198 offset:32768
	v_add3_u32 v206, s100, v153, v157
	ds_read_b128 v[202:205], v202 offset:32768
	v_add3_u32 v210, s100, v156, v158
	ds_read_b128 v[206:209], v206 offset:32768
	ds_read_b128 v[210:213], v210 offset:32768
	s_waitcnt lgkmcnt(6)
	v_mfma_f32_32x32x16_bf16 v[114:129], v[166:169], v[174:177], v[114:129]
	v_mfma_f32_32x32x16_bf16 v[98:113], v[166:169], v[178:181], v[98:113]
	v_mfma_f32_32x32x16_bf16 v[82:97], v[166:169], v[182:185], v[82:97]
	v_mfma_f32_32x32x16_bf16 v[66:81], v[166:169], v[186:189], v[66:81]
	v_mfma_f32_32x32x16_bf16 v[50:65], v[170:173], v[174:177], v[50:65]
	v_mfma_f32_32x32x16_bf16 v[34:49], v[170:173], v[178:181], v[34:49]
	v_mfma_f32_32x32x16_bf16 v[18:33], v[170:173], v[182:185], v[18:33]
	v_mfma_f32_32x32x16_bf16 v[2:17], v[170:173], v[186:189], v[2:17]
	v_add3_u32 v166, s100, v136, v149
	v_add3_u32 v170, s100, v142, v150
	ds_read_b128 v[166:169], v166
	v_add3_u32 v174, s100, v143, v147
	ds_read_b128 v[170:173], v170
	v_add3_u32 v178, s100, v152, v148
	ds_read_b128 v[174:177], v174 offset:32768
	v_add3_u32 v182, s100, v153, v145
	ds_read_b128 v[178:181], v178 offset:32768
	v_add3_u32 v186, s100, v156, v146
	ds_read_b128 v[182:185], v182 offset:32768
	ds_read_b128 v[186:189], v186 offset:32768
	s_waitcnt lgkmcnt(6)
	v_mfma_f32_32x32x16_bf16 v[114:129], v[190:193], v[198:201], v[114:129]
	v_mfma_f32_32x32x16_bf16 v[98:113], v[190:193], v[202:205], v[98:113]
	v_mfma_f32_32x32x16_bf16 v[82:97], v[190:193], v[206:209], v[82:97]
	v_mfma_f32_32x32x16_bf16 v[66:81], v[190:193], v[210:213], v[66:81]
	v_mfma_f32_32x32x16_bf16 v[50:65], v[194:197], v[198:201], v[50:65]
	v_mfma_f32_32x32x16_bf16 v[34:49], v[194:197], v[202:205], v[34:49]
	v_mfma_f32_32x32x16_bf16 v[18:33], v[194:197], v[206:209], v[18:33]
	v_mfma_f32_32x32x16_bf16 v[2:17], v[194:197], v[210:213], v[2:17]
	v_add3_u32 v190, s100, v136, v139
	v_add3_u32 v194, s100, v142, v140
	ds_read_b128 v[190:193], v190
	v_add3_u32 v198, s100, v143, v137
	ds_read_b128 v[194:197], v194
	v_add3_u32 v202, s100, v152, v138
	ds_read_b128 v[198:201], v198 offset:32768
	v_add3_u32 v206, s100, v153, v134
	ds_read_b128 v[202:205], v202 offset:32768
	v_add3_u32 v210, s100, v156, v135
	ds_read_b128 v[206:209], v206 offset:32768
	ds_read_b128 v[210:213], v210 offset:32768
	s_waitcnt lgkmcnt(6)
	v_mfma_f32_32x32x16_bf16 v[114:129], v[166:169], v[174:177], v[114:129]
	v_mfma_f32_32x32x16_bf16 v[98:113], v[166:169], v[178:181], v[98:113]
	v_mfma_f32_32x32x16_bf16 v[82:97], v[166:169], v[182:185], v[82:97]
	v_mfma_f32_32x32x16_bf16 v[66:81], v[166:169], v[186:189], v[66:81]
	v_mfma_f32_32x32x16_bf16 v[50:65], v[170:173], v[174:177], v[50:65]
	v_mfma_f32_32x32x16_bf16 v[34:49], v[170:173], v[178:181], v[34:49]
	v_mfma_f32_32x32x16_bf16 v[18:33], v[170:173], v[182:185], v[18:33]
	v_mfma_f32_32x32x16_bf16 v[2:17], v[170:173], v[186:189], v[2:17]
	s_add_u32 s30, s30, 0x80
	s_addc_u32 s31, s31, 0
	s_add_i32 s35, s35, 0x10000
	s_waitcnt vmcnt(0) lgkmcnt(0)
	s_barrier
	v_add3_u32 v166, s42, v136, v141
	v_add3_u32 v170, s42, v142, v144
	ds_read_b128 v[166:169], v166
	v_add3_u32 v174, s42, v143, v151
	ds_read_b128 v[170:173], v170
	v_add3_u32 v178, s42, v152, v154
	ds_read_b128 v[174:177], v174 offset:32768
	v_add3_u32 v182, s42, v153, v155
	ds_read_b128 v[178:181], v178 offset:32768
	v_add3_u32 v186, s42, v156, v164
	ds_read_b128 v[182:185], v182 offset:32768
	ds_read_b128 v[186:189], v186 offset:32768
	s_cmpk_lg_i32 s30, 0x780
	s_cbranch_scc0 .Lk627_exit
	s_add_i32 s41, s100, s34
	v_lshl_add_u64 v[214:215], v[130:131], 0, s[30:31]
	v_lshl_add_u64 v[226:227], v[132:133], 0, s[30:31]
	s_mov_b32 m0, s41
	v_lshl_add_u64 v[228:229], v[214:215], 0, s[28:29]
	v_mfma_f32_32x32x16_bf16 v[114:129], v[190:193], v[198:201], v[114:129]
	global_load_lds_dwordx4 v[228:229], off
	v_lshl_add_u64 v[228:229], v[214:215], 0, s[24:25]
	s_add_i32 m0, s41, 0x2000
	v_mfma_f32_32x32x16_bf16 v[98:113], v[190:193], v[202:205], v[98:113]
	global_load_lds_dwordx4 v[228:229], off
	v_lshl_add_u64 v[228:229], v[214:215], 0, s[26:27]
	s_add_i32 m0, s41, 0x4000
	v_mfma_f32_32x32x16_bf16 v[82:97], v[190:193], v[206:209], v[82:97]
	global_load_lds_dwordx4 v[228:229], off
	v_lshl_add_u64 v[228:229], v[214:215], 0, s[38:39]
	s_add_i32 m0, s41, 0x6000
	v_mfma_f32_32x32x16_bf16 v[66:81], v[190:193], v[210:213], v[66:81]
	global_load_lds_dwordx4 v[228:229], off
	v_lshl_add_u64 v[228:229], v[226:227], 0, s[28:29]
	s_add_i32 m0, s41, 0x8000
	v_mfma_f32_32x32x16_bf16 v[50:65], v[194:197], v[198:201], v[50:65]
	global_load_lds_dwordx4 v[228:229], off
	v_lshl_add_u64 v[228:229], v[226:227], 0, s[24:25]
	s_add_i32 m0, s41, 0xa000
	v_mfma_f32_32x32x16_bf16 v[34:49], v[194:197], v[202:205], v[34:49]
	global_load_lds_dwordx4 v[228:229], off
	v_lshl_add_u64 v[228:229], v[226:227], 0, s[26:27]
	s_add_i32 m0, s41, 0xc000
	v_mfma_f32_32x32x16_bf16 v[18:33], v[194:197], v[206:209], v[18:33]
	global_load_lds_dwordx4 v[228:229], off
	v_lshl_add_u64 v[228:229], v[226:227], 0, s[38:39]
	s_add_i32 m0, s41, 0xe000
	v_mfma_f32_32x32x16_bf16 v[2:17], v[194:197], v[210:213], v[2:17]
	global_load_lds_dwordx4 v[228:229], off
	s_branch .LBB0_627
; DI bf16_t f2bf(float x) { return (bf16_t)(pack2(x, 0.f) & 0xffffu); }
; DI int crow(int i, int hh) { return (i & 3) + 8 * (i >> 2) + 4 * hh; }
; DI f32x16 mfma(bf16x8 a, bf16x8 b, f32x16 c) { return __builtin_amdgcn_mfma_f32_32x32x16_bf16(a, b, c, 0, 0, 0); }
;     ...
;     for (int mt = 0; mt < 2; ++mt) { int row = wm * 64 + mt * 32 + l31; fa[0][mt] = *(const bf16x8*)(cur + row * (BK * 2) + ((hh ^ swz<BK>(row)) << 4)); }
; #pragma unroll
;     for (int nt = 0; nt < NTW; ++nt) { int row = wn * (32 * NTW) + nt * 32 + l31; fb[0][nt] = *(const bf16x8*)(cur + ABYTES + row * (BK * 2) + ((hh ^ swz<BK>(row)) << 4)); }
; #pragma unroll
;     for (int kk = 0; kk < NKK; ++kk) {
;       if (kk + 1 < NKK) {
;         const int ch = (kk + 1) * 2 + hh;
; #pragma unroll
;         for (int mt = 0; mt < 2; ++mt) { int row = wm * 64 + mt * 32 + l31; fa[(kk + 1) & 1][mt] = *(const bf16x8*)(cur + row * (BK * 2) + ((ch ^ swz<BK>(row)) << 4)); }
; #pragma unroll
;         for (int nt = 0; nt < NTW; ++nt) { int row = wn * (32 * NTW) + nt * 32 + l31; fb[(kk + 1) & 1][nt] = *(const bf16x8*)(cur + ABYTES + row * (BK * 2) + ((ch ^ swz<BK>(row)) << 4)); }
;       }
;       if (more) {
; #pragma unroll
;         for (int q = 0; q < PPK; ++q) {
;           const int pi = kk * PPK + q;
;           if (pi < NPA) stage_piece<BM, BK>(An, lda, nxt, tid, pi, wv);
;           else if (pi < NP) stage_piece<BN, BK>(Bn, ldb, nxt + ABYTES, tid, pi - NPA, wv);
;         }
;       }
;       __builtin_amdgcn_s_setprio(1);
; #pragma unroll
;       for (int mt = 0; mt < 2; ++mt)
; #pragma unroll
;         for (int nt = 0; nt < NTW; ++nt) acc[mt][nt] = mfma(fa[kk & 1][mt], fb[kk & 1][nt], acc[mt][nt]);
;       __builtin_amdgcn_s_setprio(0);
;       __builtin_amdgcn_sched_barrier(0);
;     }
;     wait_vm0();
;     __syncthreads();
;   DI void operator()(f32x16 (&acc)[2][4], int grow0, int gcol0, int lane, int w, char* lds) {
;     const int l31 = lane & 31, hh = lane >> 5;
;     if (gcol0 < 1024) {
; #pragma unroll
;       for (int mt = 0; mt < 2; ++mt)
; #pragma unroll
;         for (int nt = 0; nt < 4; ++nt)
; #pragma unroll
;           for (int i = 0; i < 16; ++i) { int row = grow0 + mt * 32 + crow(i, hh); Kx[(size_t)row * D_ + gcol0 + nt * 32 + l31] = f2bf(acc[mt][nt][i]); }
;     } else {
;       const int cin = gcol0 - 1024, h = cin >> 8, b = grow0 >> 8, m0 = grow0 & 255;
.Lk627_exit:
	v_mfma_f32_32x32x16_bf16 v[114:129], v[190:193], v[198:201], v[114:129]
	v_mfma_f32_32x32x16_bf16 v[98:113], v[190:193], v[202:205], v[98:113]
	v_mfma_f32_32x32x16_bf16 v[82:97], v[190:193], v[206:209], v[82:97]
	v_mfma_f32_32x32x16_bf16 v[66:81], v[190:193], v[210:213], v[66:81]
	v_mfma_f32_32x32x16_bf16 v[50:65], v[194:197], v[198:201], v[50:65]
	v_mfma_f32_32x32x16_bf16 v[34:49], v[194:197], v[202:205], v[34:49]
	v_mfma_f32_32x32x16_bf16 v[18:33], v[194:197], v[206:209], v[18:33]
	v_mfma_f32_32x32x16_bf16 v[2:17], v[194:197], v[210:213], v[2:17]
	s_waitcnt lgkmcnt(0)
	v_add_u32_e32 v0, 0x10000, v136
	v_add_u32_e32 v136, 0x10000, v142
	v_add_u32_e32 v130, v0, v141
	v_add_u32_e32 v141, v136, v144
	ds_read_b128 v[130:133], v130
	ds_read_b128 v[166:169], v141
	v_add_u32_e32 v141, 0x18000, v143
	v_add_u32_e32 v142, v141, v151
	v_add_u32_e32 v202, 0x18000, v152
	v_add_u32_e32 v203, 0x18000, v153
	v_add_u32_e32 v143, v202, v154
	ds_read_b128 v[170:173], v142
	ds_read_b128 v[174:177], v143
	v_add_u32_e32 v142, v203, v155
	v_add_u32_e32 v204, 0x18000, v156
	v_add_u32_e32 v143, v204, v164
	ds_read_b128 v[152:155], v142
	ds_read_b128 v[178:181], v143
	v_add_u32_e32 v142, v0, v161
	v_add_u32_e32 v143, v136, v163
	ds_read_b128 v[182:185], v142
	ds_read_b128 v[186:189], v143
	v_add_u32_e32 v142, v141, v159
	v_add_u32_e32 v143, v202, v160
	ds_read_b128 v[190:193], v142
	ds_read_b128 v[194:197], v143
	v_add_u32_e32 v142, v203, v157
	v_add_u32_e32 v143, v204, v158
	ds_read_b128 v[156:159], v142
	ds_read_b128 v[198:201], v143
	s_lshl_b64 s[30:31], s[6:7], 22
	s_setprio 1
	s_waitcnt lgkmcnt(9)
	v_mfma_f32_32x32x16_bf16 v[114:129], v[130:133], v[170:173], v[114:129]
	s_waitcnt lgkmcnt(8)
	v_mfma_f32_32x32x16_bf16 v[98:113], v[130:133], v[174:177], v[98:113]
	s_waitcnt lgkmcnt(7)
	v_mfma_f32_32x32x16_bf16 v[82:97], v[130:133], v[152:155], v[82:97]
	s_waitcnt lgkmcnt(6)
	v_mfma_f32_32x32x16_bf16 v[66:81], v[130:133], v[178:181], v[66:81]
	v_mfma_f32_32x32x16_bf16 v[50:65], v[166:169], v[170:173], v[50:65]
	v_mfma_f32_32x32x16_bf16 v[34:49], v[166:169], v[174:177], v[34:49]
	v_mfma_f32_32x32x16_bf16 v[18:33], v[166:169], v[152:155], v[18:33]
	v_mfma_f32_32x32x16_bf16 v[2:17], v[166:169], v[178:181], v[2:17]
	s_setprio 0
	v_add_u32_e32 v130, v0, v149
	v_add_u32_e32 v142, v136, v150
	ds_read_b128 v[130:133], v130
	ds_read_b128 v[150:153], v142
	v_add_u32_e32 v142, v141, v147
	v_add_u32_e32 v143, v202, v148
	ds_read_b128 v[166:169], v142
	ds_read_b128 v[170:173], v143
	v_add_u32_e32 v142, v203, v145
	v_add_u32_e32 v146, v204, v146
	ds_read_b128 v[142:145], v142
	ds_read_b128 v[146:149], v146
	s_setprio 1
	s_waitcnt lgkmcnt(9)
	v_mfma_f32_32x32x16_bf16 v[114:129], v[182:185], v[190:193], v[114:129]
	s_waitcnt lgkmcnt(8)
	v_mfma_f32_32x32x16_bf16 v[98:113], v[182:185], v[194:197], v[98:113]
	s_waitcnt lgkmcnt(7)
	v_mfma_f32_32x32x16_bf16 v[82:97], v[182:185], v[156:159], v[82:97]
	s_waitcnt lgkmcnt(6)
	v_mfma_f32_32x32x16_bf16 v[66:81], v[182:185], v[198:201], v[66:81]
	v_mfma_f32_32x32x16_bf16 v[50:65], v[186:189], v[190:193], v[50:65]
	v_mfma_f32_32x32x16_bf16 v[34:49], v[186:189], v[194:197], v[34:49]
	v_mfma_f32_32x32x16_bf16 v[18:33], v[186:189], v[156:159], v[18:33]
	v_mfma_f32_32x32x16_bf16 v[2:17], v[186:189], v[198:201], v[2:17]
	s_setprio 0
	v_add_u32_e32 v0, v0, v139
	v_add_u32_e32 v136, v136, v140
	ds_read_b128 v[154:157], v0
	ds_read_b128 v[158:161], v136
	v_add_u32_e32 v0, v141, v137
	v_add_u32_e32 v140, v202, v138
	ds_read_b128 v[136:139], v0
	ds_read_b128 v[174:177], v140
	v_add_u32_e32 v0, v203, v134
	v_add_u32_e32 v134, v204, v135
	ds_read_b128 v[178:181], v0
	ds_read_b128 v[182:185], v134
	s_setprio 1
	s_waitcnt lgkmcnt(9)
	v_mfma_f32_32x32x16_bf16 v[114:129], v[130:133], v[166:169], v[114:129]
	s_waitcnt lgkmcnt(8)
	v_mfma_f32_32x32x16_bf16 v[98:113], v[130:133], v[170:173], v[98:113]
	s_waitcnt lgkmcnt(7)
	v_mfma_f32_32x32x16_bf16 v[82:97], v[130:133], v[142:145], v[82:97]
	s_waitcnt lgkmcnt(6)
	v_mfma_f32_32x32x16_bf16 v[66:81], v[130:133], v[146:149], v[66:81]
	v_mfma_f32_32x32x16_bf16 v[50:65], v[150:153], v[166:169], v[50:65]
	v_mfma_f32_32x32x16_bf16 v[34:49], v[150:153], v[170:173], v[34:49]
	v_mfma_f32_32x32x16_bf16 v[18:33], v[150:153], v[142:145], v[18:33]
	v_mfma_f32_32x32x16_bf16 v[2:17], v[150:153], v[146:149], v[2:17]
	s_setprio 0
	s_setprio 1
	s_waitcnt lgkmcnt(3)
	v_mfma_f32_32x32x16_bf16 v[114:129], v[154:157], v[136:139], v[114:129]
	s_waitcnt lgkmcnt(2)
	v_mfma_f32_32x32x16_bf16 v[98:113], v[154:157], v[174:177], v[98:113]
	s_waitcnt lgkmcnt(1)
	v_mfma_f32_32x32x16_bf16 v[82:97], v[154:157], v[178:181], v[82:97]
	s_waitcnt lgkmcnt(0)
	v_mfma_f32_32x32x16_bf16 v[66:81], v[154:157], v[182:185], v[66:81]
	v_mfma_f32_32x32x16_bf16 v[50:65], v[158:161], v[136:139], v[50:65]
	v_mfma_f32_32x32x16_bf16 v[34:49], v[158:161], v[174:177], v[34:49]
	v_mfma_f32_32x32x16_bf16 v[18:33], v[158:161], v[178:181], v[18:33]
	v_mfma_f32_32x32x16_bf16 v[2:17], v[158:161], v[182:185], v[2:17]
	s_setprio 0
	v_mov_b32_e32 v135, v216
	s_waitcnt vmcnt(0)
	s_barrier
	s_nop 0
	v_ashrrev_i32_e32 v134, 6, v135
	v_lshrrev_b32_e32 v0, 30, v134
	v_add_u32_e32 v0, v134, v0
	v_ashrrev_i32_e32 v130, 2, v0
	v_mul_i32_i24_e32 v0, 4, v130
	v_sub_u32_e32 v0, v134, v0
	v_lshlrev_b32_e32 v136, 6, v0
	v_lshl_add_u32 v132, v130, 7, s3
	v_add_u32_e32 v0, s2, v136
	v_and_b32_e32 v131, 31, v135
	v_bfe_u32 v133, v135, 5, 1
	v_cmp_lt_i32_e32 vcc, s57, v132
	s_and_saveexec_b64 s[2:3], vcc
	s_xor_b64 s[6:7], exec, s[2:3]
	s_cbranch_execz .LBB0_630
; DI unsigned pack2(float lo, float hi) { f32x2 v = {lo, hi}; bf2_t r = __builtin_convertvector(v, bf2_t); return __builtin_bit_cast(unsigned, r); }
; DI void tr_put(char* stg, int erow, const f32x16& v, int hh, float mul) {
; #pragma unroll
;   for (int qd = 0; qd < 4; ++qd) {
;     u32x2 pk; pk.x = pack2(v[4 * qd] * mul, v[4 * qd + 1] * mul); pk.y = pack2(v[4 * qd + 2] * mul, v[4 * qd + 3] * mul);
;     *(u32x2*)(stg + erow * 64 + (8 * qd + 4 * hh) * 2) = pk;
;   }
; }
; template <int R>
; DI void tr_flush(const char* stg, int row0, bf16_t* g, size_t grs, int lane) {
;   const int r0 = lane >> 2, ch = lane & 3;
; #pragma unroll
;   for (int it = 0; it < R / 16; ++it) {
;     const int r = it * 16 + r0;
;     u32x4 v = *(const u32x4*)(stg + (row0 + r) * 64 + ch * 16);
;     *(u32x4*)((char*)(g + (size_t)r * grs) + ch * 16) = v;
;   }
; }
;   DI void operator()(f32x16 (&acc)[2][4], int grow0, int gcol0, int lane, int w, char* lds) {
;     ...
;       const int cin = gcol0 - 1024, h = cin >> 8, b = grow0 >> 8, m0 = grow0 & 255;
;       char* stg = tr_stage(lds, w);
; #pragma unroll
;       for (int mt = 0; mt < 2; ++mt) {
; #pragma unroll
;         for (int nt = 0; nt < 4; ++nt) tr_put(stg, nt * 32 + l31, acc[mt][nt], hh, 1.f);
;         tr_flush<128>(stg, 0, Vxt + ((size_t)(b * 4 + h) * 256 + (cin & 255)) * 256 + m0 + mt * 32, 256, lane);
;       }
	v_add_u32_e32 v132, 0xfffffc00, v132
	v_lshl_add_u32 v134, v134, 13, v224
	v_lshlrev_b32_e32 v131, 6, v131
	v_lshlrev_b32_e32 v133, 3, v133
	v_ashrrev_i32_e32 v0, 6, v0
	v_lshrrev_b32_e32 v132, 8, v132
	v_or3_b32 v131, v134, v131, v133
	v_and_b32_e32 v0, -4, v0
	v_cvt_pk_bf16_f32 v66, v66, v67
	v_cvt_pk_bf16_f32 v67, v68, v69
	v_add_u32_e32 v132, v132, v0
	ds_write_b64 v131, v[66:67] offset:6144
	v_cvt_pk_bf16_f32 v66, v70, v71
	v_cvt_pk_bf16_f32 v67, v72, v73
	v_and_b32_e32 v135, 63, v135
	s_add_u32 s34, s74, s30
	v_ashrrev_i32_e32 v133, 31, v132
	v_cvt_pk_bf16_f32 v114, v114, v115
	v_cvt_pk_bf16_f32 v115, v116, v117
	ds_write_b64 v131, v[66:67] offset:6160
	v_cvt_pk_bf16_f32 v66, v74, v75
	v_cvt_pk_bf16_f32 v67, v76, v77
	s_addc_u32 s35, s75, s31
	v_lshlrev_b64 v[132:133], 17, v[132:133]
	v_lshlrev_b32_e32 v0, 4, v135
	ds_write_b64 v131, v[114:115]
	v_cvt_pk_bf16_f32 v114, v118, v119
	v_cvt_pk_bf16_f32 v115, v120, v121
	ds_write_b64 v131, v[66:67] offset:6176
	v_cvt_pk_bf16_f32 v66, v78, v79
	v_cvt_pk_bf16_f32 v67, v80, v81
	v_lshlrev_b32_e32 v68, 16, v130
	v_and_b32_e32 v136, 0xc0, v136
	v_lshrrev_b32_e32 v137, 2, v135
	v_and_b32_e32 v0, 48, v0
	ds_write_b64 v131, v[114:115] offset:16
	v_cvt_pk_bf16_f32 v114, v122, v123
	v_cvt_pk_bf16_f32 v115, v124, v125
	ds_write_b64 v131, v[66:67] offset:6192
	v_lshl_add_u64 v[66:67], s[34:35], 0, v[132:133]
	v_and_b32_e32 v68, 0x10000, v68
	v_mov_b32_e32 v69, v1
	v_or_b32_e32 v134, v134, v0
	v_or_b32_e32 v138, 16, v137
	ds_write_b64 v131, v[114:115] offset:32
	v_cvt_pk_bf16_f32 v114, v126, v127
	v_cvt_pk_bf16_f32 v115, v128, v129
	v_lshl_add_u64 v[66:67], v[66:67], 0, v[68:69]
	v_lshlrev_b32_e32 v68, 1, v136
	v_lshl_or_b32 v139, v138, 6, v134
	ds_write_b64 v131, v[114:115] offset:48
	v_lshl_add_u64 v[70:71], v[66:67], 0, v[68:69]
	v_cvt_pk_bf16_f32 v98, v98, v99
	v_cvt_pk_bf16_f32 v99, v100, v101
	v_lshl_add_u64 v[74:75], v[70:71], 0, v[0:1]
	ds_read_b128 v[70:73], v139
	ds_write_b64 v131, v[98:99] offset:2048
	v_cvt_pk_bf16_f32 v98, v102, v103
	v_cvt_pk_bf16_f32 v99, v104, v105
	ds_write_b64 v131, v[98:99] offset:2064
	v_cvt_pk_bf16_f32 v98, v106, v107
	v_cvt_pk_bf16_f32 v99, v108, v109
	v_lshlrev_b32_e32 v0, 9, v137
	v_or_b32_e32 v142, 48, v137
	ds_write_b64 v131, v[98:99] offset:2080
	v_cvt_pk_bf16_f32 v98, v110, v111
	v_cvt_pk_bf16_f32 v99, v112, v113
	v_lshl_add_u64 v[76:77], v[74:75], 0, v[0:1]
	v_lshlrev_b32_e32 v0, 9, v138
	v_lshl_or_b32 v143, v142, 6, v134
	ds_write_b64 v131, v[98:99] offset:2096
	v_lshl_add_u64 v[78:79], v[74:75], 0, v[0:1]
	v_cvt_pk_bf16_f32 v82, v82, v83
	v_cvt_pk_bf16_f32 v83, v84, v85
	s_waitcnt lgkmcnt(4)
	global_store_dwordx4 v[78:79], v[70:73], off
	ds_read_b128 v[70:73], v143
	v_or_b32_e32 v140, 32, v137
	ds_write_b64 v131, v[82:83] offset:4096
	v_cvt_pk_bf16_f32 v82, v86, v87
	v_cvt_pk_bf16_f32 v83, v88, v89
	ds_write_b64 v131, v[82:83] offset:4112
	v_cvt_pk_bf16_f32 v82, v90, v91
	v_cvt_pk_bf16_f32 v83, v92, v93
	v_lshlrev_b32_e32 v0, 9, v140
	v_or_b32_e32 v146, 0x50, v137
	ds_write_b64 v131, v[82:83] offset:4128
	v_cvt_pk_bf16_f32 v82, v94, v95
	v_cvt_pk_bf16_f32 v83, v96, v97
	v_lshl_add_u64 v[80:81], v[74:75], 0, v[0:1]
	v_lshlrev_b32_e32 v0, 9, v142
	v_lshl_or_b32 v135, v137, 6, v134
	v_lshl_or_b32 v147, v146, 6, v134
	ds_write_b64 v131, v[82:83] offset:4144
	v_lshl_add_u64 v[82:83], v[74:75], 0, v[0:1]
	ds_read_b128 v[66:69], v135
	s_waitcnt lgkmcnt(5)
	global_store_dwordx4 v[82:83], v[70:73], off
	ds_read_b128 v[70:73], v147
	v_or_b32_e32 v144, 64, v137
	v_lshlrev_b32_e32 v0, 9, v144
	v_or_b32_e32 v148, 0x60, v137
	v_or_b32_e32 v150, 0x70, v137
	v_lshl_add_u64 v[84:85], v[74:75], 0, v[0:1]
	v_lshlrev_b32_e32 v0, 9, v146
	v_lshl_or_b32 v141, v140, 6, v134
	v_lshl_or_b32 v145, v144, 6, v134
	v_lshl_or_b32 v149, v148, 6, v134
	v_lshl_or_b32 v134, v150, 6, v134
	v_lshl_add_u64 v[86:87], v[74:75], 0, v[0:1]
	s_waitcnt lgkmcnt(0)
	global_store_dwordx4 v[86:87], v[70:73], off
	ds_read_b128 v[70:73], v134
	global_store_dwordx4 v[76:77], v[66:69], off
	ds_read_b128 v[66:69], v141
	v_cvt_pk_bf16_f32 v50, v50, v51
	v_cvt_pk_bf16_f32 v51, v52, v53
	v_cvt_pk_bf16_f32 v34, v34, v35
	v_cvt_pk_bf16_f32 v35, v36, v37
	s_waitcnt lgkmcnt(0)
	global_store_dwordx4 v[80:81], v[66:69], off
	ds_read_b128 v[66:69], v145
	v_cvt_pk_bf16_f32 v18, v18, v19
	v_cvt_pk_bf16_f32 v19, v20, v21
	v_lshlrev_b32_e32 v0, 9, v148
	ds_write_b64 v131, v[50:51]
	s_waitcnt lgkmcnt(1)
	global_store_dwordx4 v[84:85], v[66:69], off
	ds_read_b128 v[66:69], v149
	v_cvt_pk_bf16_f32 v50, v54, v55
	v_cvt_pk_bf16_f32 v51, v56, v57
	ds_write_b64 v131, v[34:35] offset:2048
	v_cvt_pk_bf16_f32 v34, v38, v39
	v_cvt_pk_bf16_f32 v35, v40, v41
	ds_write_b64 v131, v[18:19] offset:4096
	v_cvt_pk_bf16_f32 v18, v22, v23
	v_cvt_pk_bf16_f32 v19, v24, v25
	v_cvt_pk_bf16_f32 v2, v2, v3
	v_cvt_pk_bf16_f32 v3, v4, v5
	v_lshl_add_u64 v[88:89], v[74:75], 0, v[0:1]
	v_lshlrev_b32_e32 v0, 9, v150
	ds_write_b64 v131, v[50:51] offset:16
	v_cvt_pk_bf16_f32 v50, v58, v59
	v_cvt_pk_bf16_f32 v51, v60, v61
	ds_write_b64 v131, v[34:35] offset:2064
	v_cvt_pk_bf16_f32 v34, v42, v43
	v_cvt_pk_bf16_f32 v35, v44, v45
	ds_write_b64 v131, v[18:19] offset:4112
	v_cvt_pk_bf16_f32 v18, v26, v27
	v_cvt_pk_bf16_f32 v19, v28, v29
	ds_write_b64 v131, v[2:3] offset:6144
	v_cvt_pk_bf16_f32 v2, v6, v7
	v_cvt_pk_bf16_f32 v3, v8, v9
	s_waitcnt lgkmcnt(6)
	global_store_dwordx4 v[88:89], v[66:69], off
	ds_write_b64 v131, v[50:51] offset:32
	v_cvt_pk_bf16_f32 v50, v62, v63
	v_lshl_add_u64 v[66:67], v[74:75], 0, v[0:1]
	v_cvt_pk_bf16_f32 v51, v64, v65
	ds_write_b64 v131, v[34:35] offset:2080
	v_cvt_pk_bf16_f32 v34, v46, v47
	v_cvt_pk_bf16_f32 v35, v48, v49
	ds_write_b64 v131, v[18:19] offset:4128
	v_cvt_pk_bf16_f32 v18, v30, v31
	v_cvt_pk_bf16_f32 v19, v32, v33
	ds_write_b64 v131, v[2:3] offset:6160
	v_cvt_pk_bf16_f32 v2, v10, v11
	v_cvt_pk_bf16_f32 v3, v12, v13
	global_store_dwordx4 v[66:67], v[70:73], off
	ds_write_b64 v131, v[50:51] offset:48
	ds_write_b64 v131, v[34:35] offset:2096
	ds_write_b64 v131, v[18:19] offset:4144
	ds_write_b64 v131, v[2:3] offset:6176
	ds_read_b128 v[2:5], v135
	ds_read_b128 v[6:9], v139
	ds_read_b128 v[10:13], v141
	v_cvt_pk_bf16_f32 v14, v14, v15
	v_cvt_pk_bf16_f32 v15, v16, v17
	ds_write_b64 v131, v[14:15] offset:6192
	s_waitcnt lgkmcnt(3)
	global_store_dwordx4 v[76:77], v[2:5], off offset:64
	s_waitcnt lgkmcnt(2)
	global_store_dwordx4 v[78:79], v[6:9], off offset:64
	s_waitcnt lgkmcnt(1)
	global_store_dwordx4 v[80:81], v[10:13], off offset:64
	ds_read_b128 v[2:5], v143
	ds_read_b128 v[6:9], v145
	ds_read_b128 v[10:13], v147
	ds_read_b128 v[14:17], v149
	ds_read_b128 v[18:21], v134
	s_waitcnt lgkmcnt(4)
	global_store_dwordx4 v[82:83], v[2:5], off offset:64
	s_waitcnt lgkmcnt(3)
	global_store_dwordx4 v[84:85], v[6:9], off offset:64
	s_waitcnt lgkmcnt(2)
	global_store_dwordx4 v[86:87], v[10:13], off offset:64
	s_waitcnt lgkmcnt(1)
	global_store_dwordx4 v[88:89], v[14:17], off offset:64
	s_waitcnt lgkmcnt(0)
	global_store_dwordx4 v[66:67], v[18:21], off offset:64
